# unit boundary: each wave group drops one barrier (younger: its last MFMA segment's; older: the next unit's first), older group's first MFMA segment no longer waits for the younger group's epilogue
# speedup vs baseline: 1.0102x; 1.0102x over previous
; #define G_STAGE(bufoff, gbase, o0, h64) do { \
;         __builtin_amdgcn_global_load_lds((const unsigned*)((const char*)(gbase) + (o0)), (LAS unsigned*)(lds + (bufoff) + ldsw), 16, 0, 0); \
;         __builtin_amdgcn_global_load_lds((const unsigned*)((const char*)(gbase) + (h64) + (o0)), (LAS unsigned*)(lds + (bufoff) + ldsw + 8192), 16, 0, 0); } while (0)
; #define G_LDA(dst, b, h) do { _Pragma("unroll") for (int m = 0; m < 4; ++m) _Pragma("unroll") for (int k = 0; k < 2; ++k) dst[m][k] = *(const LAS bf16x8*)(lds + G_SA(b, h) + aoff + m * 2048 + k * 1024); } while (0)
; #define G_LDB(dst, b, h) do { _Pragma("unroll") for (int n = 0; n < 2; ++n) _Pragma("unroll") for (int k = 0; k < 2; ++k) dst[n][k] = *(const LAS bf16x8*)(lds + G_SB(b, h) + boff + n * 2048 + k * 1024); } while (0)
; #define G_WAIT_L(n) asm volatile("s_waitcnt lgkmcnt(" #n ")" ::: "memory")
; #define G_BAR __builtin_amdgcn_s_barrier()
; #define G_SCHED __builtin_amdgcn_sched_barrier(0)
;     ...
;         for (int t = 0; t < nt; t += 2) {
;             const bool last = (t == nt - 2);
;             const char* a1 = cA + (size_t)(t + 1) * ckA;
;             const char* a2 = last ? nA : cA + (size_t)(t + 2) * ckA; const char* b2 = last ? nB : cB + (size_t)(t + 2) * kB;
;             const char* a3 = a2 + ckA; const char* b3 = b2 + kB;
;             G_LDB(B0, 0, 0); G_SCHED; G_LDA(At, 0, 0); G_STAGE(G_SA(1, 1), a1 + chA, cA0, qA);
;             G_WAIT_L(8); G_BAR; G_WAIT_L(0); G_MMA(0, 0, At, B0); G_BAR; G_SCHED;
;     ...
;         if (!(cs.kind == K_MG_B && cur.aux < 2))
; #pragma unroll
;         for (int a = 0; a < 2; ++a)
; #pragma unroll
;             for (int b = 0; b < 2; ++b)
; #pragma unroll
;                 for (int m = 0; m < 4; ++m)
; #pragma unroll
;                     for (int n = 0; n < 2; ++n) acc[a][b][m][n] = (f32x4){0.f, 0.f, 0.f, 0.f};
;         cur = nxt; cA = nA; cB = nB; ++ui;
.LBB0_211:
	s_add_u32 s2, s2, 0x40080
	s_addc_u32 s3, s3, 0
	s_add_u32 s7, s22, 0x100
	v_mov_b64_e32 v[8:9], 0
	s_addc_u32 s22, s23, 0
	s_mov_b32 s23, -2
	v_mov_b64_e32 v[10:11], 0
	v_mov_b64_e32 v[12:13], 0
	v_mov_b64_e32 v[14:15], 0
	v_mov_b64_e32 v[24:25], 0
	v_mov_b64_e32 v[26:27], 0
	v_mov_b64_e32 v[28:29], 0
	v_mov_b64_e32 v[30:31], 0
	v_mov_b64_e32 v[40:41], 0
	v_mov_b64_e32 v[42:43], 0
	v_mov_b64_e32 v[44:45], 0
	v_mov_b64_e32 v[46:47], 0
	v_mov_b64_e32 v[56:57], 0
	v_mov_b64_e32 v[58:59], 0
	v_mov_b64_e32 v[60:61], 0
	v_mov_b64_e32 v[62:63], 0
	v_mov_b64_e32 v[16:17], 0
	v_mov_b64_e32 v[18:19], 0
	v_mov_b64_e32 v[20:21], 0
	v_mov_b64_e32 v[22:23], 0
	v_mov_b64_e32 v[32:33], 0
	v_mov_b64_e32 v[34:35], 0
	v_mov_b64_e32 v[36:37], 0
	v_mov_b64_e32 v[38:39], 0
	v_mov_b64_e32 v[48:49], 0
	v_mov_b64_e32 v[50:51], 0
	v_mov_b64_e32 v[52:53], 0
	v_mov_b64_e32 v[54:55], 0
	v_mov_b64_e32 v[64:65], 0
	v_mov_b64_e32 v[66:67], 0
	v_mov_b64_e32 v[68:69], 0
	v_mov_b64_e32 v[70:71], 0
	v_mov_b64_e32 v[72:73], 0
	v_mov_b64_e32 v[74:75], 0
	v_mov_b64_e32 v[76:77], 0
	v_mov_b64_e32 v[78:79], 0
	v_mov_b64_e32 v[88:89], 0
	v_mov_b64_e32 v[90:91], 0
	v_mov_b64_e32 v[92:93], 0
	v_mov_b64_e32 v[94:95], 0
	v_mov_b64_e32 v[104:105], 0
	v_mov_b64_e32 v[106:107], 0
	v_mov_b64_e32 v[108:109], 0
	v_mov_b64_e32 v[110:111], 0
	v_mov_b64_e32 v[120:121], 0
	v_mov_b64_e32 v[122:123], 0
	v_mov_b64_e32 v[124:125], 0
	v_mov_b64_e32 v[126:127], 0
	v_mov_b64_e32 v[80:81], 0
	v_mov_b64_e32 v[82:83], 0
	v_mov_b64_e32 v[84:85], 0
	v_mov_b64_e32 v[86:87], 0
	v_mov_b64_e32 v[96:97], 0
	v_mov_b64_e32 v[98:99], 0
	v_mov_b64_e32 v[100:101], 0
	v_mov_b64_e32 v[102:103], 0
	v_mov_b64_e32 v[112:113], 0
	v_mov_b64_e32 v[114:115], 0
	v_mov_b64_e32 v[116:117], 0
	v_mov_b64_e32 v[118:119], 0
	v_mov_b64_e32 v[128:129], 0
	v_mov_b64_e32 v[130:131], 0
	v_mov_b64_e32 v[132:133], 0
	v_mov_b64_e32 v[134:135], 0
	s_mov_b64 s[52:53], 0x40000
	s_mov_b64 s[54:55], 0x60000
	s_mov_b64 s[58:59], 0x20080
	s_mov_b64 s[62:63], 0x40080
	s_mov_b64 s[64:65], 0x60080
	s_cmp_eq_u32 s101, 2
	s_cselect_b32 s101, 0, s101
.LBB0_212:
	s_add_u32 s4, s2, 0xfffc0080
	s_addc_u32 s5, s3, -1
	s_add_i32 s41, 0, 0x10000
	v_add_u32_e32 v0, s41, v167
	ds_read_b128 v[136:139], v0
	ds_read_b128 v[144:147], v0 offset:1024
	ds_read_b128 v[148:151], v0 offset:2048
	ds_read_b128 v[152:155], v0 offset:3072
	s_cmp_eq_u32 s23, 12
	s_cselect_b32 s43, s19, s5
	s_cselect_b32 s42, s18, s4
	s_cselect_b32 s51, s21, s22
	s_cselect_b32 s50, s20, s7
	v_lshl_add_u64 v[164:165], s[2:3], 0, v[142:143]
	s_add_i32 m0, s27, 0xc000
	ds_read_b128 v[156:159], v172
	ds_read_b128 v[160:163], v172 offset:1024
	ds_read_b128 v[174:177], v172 offset:2048
	ds_read_b128 v[178:181], v172 offset:3072
	ds_read_b128 v[182:185], v172 offset:4096
	ds_read_b128 v[196:199], v172 offset:5120
	ds_read_b128 v[200:203], v172 offset:6144
	ds_read_b128 v[204:207], v172 offset:7168
	global_load_lds_dwordx4 v[164:165], off
	v_lshl_add_u64 v[164:165], v[164:165], 0, s[0:1]
	s_add_i32 m0, s27, 0xe000
	s_nop 0
	global_load_lds_dwordx4 v[164:165], off
	s_waitcnt lgkmcnt(8)
	s_cmp_eq_u32 s101, 1
	s_cbranch_scc1 .Ldb_WIN_sk
	s_barrier
.Ldb_WIN_sk:
	s_mov_b32 s101, 0
	s_waitcnt lgkmcnt(0)
	v_mfma_f32_16x16x32_bf16 v[132:135], v[136:139], v[156:159], v[132:135]
	v_mfma_f32_16x16x32_bf16 v[128:131], v[148:151], v[156:159], v[128:131]
	v_mfma_f32_16x16x32_bf16 v[116:119], v[136:139], v[174:177], v[116:119]
	v_mfma_f32_16x16x32_bf16 v[112:115], v[148:151], v[174:177], v[112:115]
	v_mfma_f32_16x16x32_bf16 v[100:103], v[136:139], v[182:185], v[100:103]
	v_mfma_f32_16x16x32_bf16 v[96:99], v[148:151], v[182:185], v[96:99]
	v_mfma_f32_16x16x32_bf16 v[84:87], v[136:139], v[200:203], v[84:87]
	v_mfma_f32_16x16x32_bf16 v[80:83], v[148:151], v[200:203], v[80:83]
	v_mfma_f32_16x16x32_bf16 v[132:135], v[144:147], v[160:163], v[132:135]
	v_mfma_f32_16x16x32_bf16 v[128:131], v[152:155], v[160:163], v[128:131]
	v_mfma_f32_16x16x32_bf16 v[116:119], v[144:147], v[178:181], v[116:119]
	v_mfma_f32_16x16x32_bf16 v[112:115], v[152:155], v[178:181], v[112:115]
	v_mfma_f32_16x16x32_bf16 v[100:103], v[144:147], v[196:199], v[100:103]
	v_mfma_f32_16x16x32_bf16 v[96:99], v[152:155], v[196:199], v[96:99]
	v_mfma_f32_16x16x32_bf16 v[84:87], v[144:147], v[204:207], v[84:87]
	v_mfma_f32_16x16x32_bf16 v[80:83], v[152:155], v[204:207], v[80:83]
	s_barrier
	s_add_i32 s4, 0, 0x14000
	s_add_i32 s5, s41, s26
	v_add_u32_e32 v0, s4, v167
	v_lshl_add_u64 v[164:165], s[50:51], 0, v[140:141]
	s_mov_b32 m0, s5
	ds_read_b128 v[208:211], v0
	ds_read_b128 v[212:215], v0 offset:1024
	ds_read_b128 v[216:219], v0 offset:2048
	ds_read_b128 v[220:223], v0 offset:3072
	global_load_lds_dwordx4 v[164:165], off
	v_lshl_add_u64 v[224:225], v[164:165], 0, s[0:1]
	s_add_i32 m0, s5, 0x2000
	s_nop 0
	global_load_lds_dwordx4 v[224:225], off
	s_barrier
	s_waitcnt lgkmcnt(0)
	v_mfma_f32_16x16x32_bf16 v[124:127], v[208:211], v[156:159], v[124:127]
	v_mfma_f32_16x16x32_bf16 v[120:123], v[216:219], v[156:159], v[120:123]
	v_mfma_f32_16x16x32_bf16 v[108:111], v[208:211], v[174:177], v[108:111]
	v_mfma_f32_16x16x32_bf16 v[104:107], v[216:219], v[174:177], v[104:107]
	v_mfma_f32_16x16x32_bf16 v[92:95], v[208:211], v[182:185], v[92:95]
	v_mfma_f32_16x16x32_bf16 v[88:91], v[216:219], v[182:185], v[88:91]
	v_mfma_f32_16x16x32_bf16 v[76:79], v[208:211], v[200:203], v[76:79]
	v_mfma_f32_16x16x32_bf16 v[72:75], v[216:219], v[200:203], v[72:75]
	v_mfma_f32_16x16x32_bf16 v[124:127], v[212:215], v[160:163], v[124:127]
	v_mfma_f32_16x16x32_bf16 v[120:123], v[220:223], v[160:163], v[120:123]
	v_mfma_f32_16x16x32_bf16 v[108:111], v[212:215], v[178:181], v[108:111]
	v_mfma_f32_16x16x32_bf16 v[104:107], v[220:223], v[178:181], v[104:107]
	v_mfma_f32_16x16x32_bf16 v[92:95], v[212:215], v[196:199], v[92:95]
	v_mfma_f32_16x16x32_bf16 v[88:91], v[220:223], v[196:199], v[88:91]
	v_mfma_f32_16x16x32_bf16 v[76:79], v[212:215], v[204:207], v[76:79]
	v_mfma_f32_16x16x32_bf16 v[72:75], v[220:223], v[204:207], v[72:75]
	s_barrier
; #define G_STAGE(bufoff, gbase, o0, h64) do { \
;         __builtin_amdgcn_global_load_lds((const unsigned*)((const char*)(gbase) + (o0)), (LAS unsigned*)(lds + (bufoff) + ldsw), 16, 0, 0); \
;         __builtin_amdgcn_global_load_lds((const unsigned*)((const char*)(gbase) + (h64) + (o0)), (LAS unsigned*)(lds + (bufoff) + ldsw + 8192), 16, 0, 0); } while (0)
; #define G_LDA(dst, b, h) do { _Pragma("unroll") for (int m = 0; m < 4; ++m) _Pragma("unroll") for (int k = 0; k < 2; ++k) dst[m][k] = *(const LAS bf16x8*)(lds + G_SA(b, h) + aoff + m * 2048 + k * 1024); } while (0)
; #define G_LDB(dst, b, h) do { _Pragma("unroll") for (int n = 0; n < 2; ++n) _Pragma("unroll") for (int k = 0; k < 2; ++k) dst[n][k] = *(const LAS bf16x8*)(lds + G_SB(b, h) + boff + n * 2048 + k * 1024); } while (0)
; #define G_WAIT_V(n) asm volatile("s_waitcnt vmcnt(" #n ")" ::: "memory")
; #define G_WAIT_L(n) asm volatile("s_waitcnt lgkmcnt(" #n ")" ::: "memory")
; #define G_BAR __builtin_amdgcn_s_barrier()
; #define G_SCHED __builtin_amdgcn_sched_barrier(0)
;     ...
;             G_LDB(B0, 0, 0); G_SCHED; G_LDA(At, 0, 0); G_STAGE(G_SA(1, 1), a1 + chA, cA0, qA);
;             G_WAIT_L(8); G_BAR; G_WAIT_L(0); G_MMA(0, 0, At, B0); G_BAR; G_SCHED;
;             G_LDB(B1, 0, 1); G_STAGE(G_SB(0, 0), b2, cB0, qB);
;             G_BAR; G_WAIT_L(0); G_MMA(0, 1, At, B1); G_BAR;
;             G_LDA(At, 0, 1); G_STAGE(G_SA(0, 0), a2, cA0, qA);
;             G_BAR; G_WAIT_L(0); G_MMA(1, 0, At, B0); G_BAR; G_SCHED;
;             G_STAGE(G_SB(0, 1), b2 + chB, cB0, qB);
;             G_WAIT_V(6); G_BAR; G_MMA(1, 1, At, B1); G_BAR;
;             G_LDB(B0, 1, 0); G_SCHED; G_LDA(At, 1, 0); G_STAGE(G_SA(0, 1), a2 + chA, cA0, qA);
;             G_WAIT_L(8); G_BAR; G_WAIT_L(0); G_MMA(0, 0, At, B0); G_BAR; G_SCHED;
;             G_LDB(B1, 1, 1); G_STAGE(G_SB(1, 0), b3, cB0, qB);
;             G_BAR; G_WAIT_L(0); G_MMA(0, 1, At, B1); G_BAR;
;             G_LDA(At, 1, 1); G_STAGE(G_SA(1, 0), a3, cA0, qA);
;             G_BAR; G_WAIT_L(0); G_MMA(1, 0, At, B0); G_BAR; G_SCHED;
;             G_STAGE(G_SB(1, 1), b3 + chB, cB0, qB);
;             G_WAIT_V(6); G_BAR; G_MMA(1, 1, At, B1); G_BAR;
	s_mov_b32 m0, s27
	v_lshl_add_u64 v[224:225], s[42:43], 0, v[2:3]
	ds_read_b128 v[156:159], v172 offset:16384
	ds_read_b128 v[160:163], v172 offset:17408
	ds_read_b128 v[174:177], v172 offset:18432
	ds_read_b128 v[178:181], v172 offset:19456
	ds_read_b128 v[182:185], v172 offset:20480
	ds_read_b128 v[196:199], v172 offset:21504
	ds_read_b128 v[200:203], v172 offset:22528
	ds_read_b128 v[204:207], v172 offset:23552
	global_load_lds_dwordx4 v[224:225], off
	v_lshl_add_u64 v[226:227], v[224:225], 0, s[0:1]
	s_mov_b32 m0, s28
	s_nop 0
	global_load_lds_dwordx4 v[226:227], off
	s_barrier
	s_waitcnt lgkmcnt(0)
	v_mfma_f32_16x16x32_bf16 v[68:71], v[136:139], v[156:159], v[68:71]
	v_mfma_f32_16x16x32_bf16 v[64:67], v[148:151], v[156:159], v[64:67]
	v_mfma_f32_16x16x32_bf16 v[52:55], v[136:139], v[174:177], v[52:55]
	v_mfma_f32_16x16x32_bf16 v[48:51], v[148:151], v[174:177], v[48:51]
	v_mfma_f32_16x16x32_bf16 v[36:39], v[136:139], v[182:185], v[36:39]
	v_mfma_f32_16x16x32_bf16 v[32:35], v[148:151], v[182:185], v[32:35]
	v_mfma_f32_16x16x32_bf16 v[20:23], v[136:139], v[200:203], v[20:23]
	v_mfma_f32_16x16x32_bf16 v[16:19], v[148:151], v[200:203], v[16:19]
	v_mfma_f32_16x16x32_bf16 v[68:71], v[144:147], v[160:163], v[68:71]
	v_mfma_f32_16x16x32_bf16 v[64:67], v[152:155], v[160:163], v[64:67]
	v_mfma_f32_16x16x32_bf16 v[52:55], v[144:147], v[178:181], v[52:55]
	v_mfma_f32_16x16x32_bf16 v[48:51], v[152:155], v[178:181], v[48:51]
	v_mfma_f32_16x16x32_bf16 v[36:39], v[144:147], v[196:199], v[36:39]
	v_mfma_f32_16x16x32_bf16 v[32:35], v[152:155], v[196:199], v[32:35]
	v_mfma_f32_16x16x32_bf16 v[20:23], v[144:147], v[204:207], v[20:23]
	v_mfma_f32_16x16x32_bf16 v[16:19], v[152:155], v[204:207], v[16:19]
	s_barrier
	s_add_i32 s4, s4, s26
	v_lshl_add_u64 v[136:137], v[164:165], 0, s[52:53]
	s_mov_b32 m0, s4
	s_nop 0
	global_load_lds_dwordx4 v[136:137], off
	v_lshl_add_u64 v[136:137], v[164:165], 0, s[54:55]
	s_add_i32 m0, s4, 0x2000
	s_nop 0
	global_load_lds_dwordx4 v[136:137], off
	s_waitcnt vmcnt(6)
	s_barrier
	v_mfma_f32_16x16x32_bf16 v[60:63], v[208:211], v[156:159], v[60:63]
	v_mfma_f32_16x16x32_bf16 v[56:59], v[216:219], v[156:159], v[56:59]
	v_mfma_f32_16x16x32_bf16 v[44:47], v[208:211], v[174:177], v[44:47]
	v_mfma_f32_16x16x32_bf16 v[40:43], v[216:219], v[174:177], v[40:43]
	v_mfma_f32_16x16x32_bf16 v[28:31], v[208:211], v[182:185], v[28:31]
	v_mfma_f32_16x16x32_bf16 v[24:27], v[216:219], v[182:185], v[24:27]
	v_mfma_f32_16x16x32_bf16 v[12:15], v[208:211], v[200:203], v[12:15]
	v_mfma_f32_16x16x32_bf16 v[8:11], v[216:219], v[200:203], v[8:11]
	v_mfma_f32_16x16x32_bf16 v[60:63], v[212:215], v[160:163], v[60:63]
	v_mfma_f32_16x16x32_bf16 v[56:59], v[220:223], v[160:163], v[56:59]
	v_mfma_f32_16x16x32_bf16 v[44:47], v[212:215], v[178:181], v[44:47]
	v_mfma_f32_16x16x32_bf16 v[40:43], v[220:223], v[178:181], v[40:43]
	v_mfma_f32_16x16x32_bf16 v[28:31], v[212:215], v[196:199], v[28:31]
	v_mfma_f32_16x16x32_bf16 v[24:27], v[220:223], v[196:199], v[24:27]
	v_mfma_f32_16x16x32_bf16 v[12:15], v[212:215], v[204:207], v[12:15]
	v_mfma_f32_16x16x32_bf16 v[8:11], v[220:223], v[204:207], v[8:11]
	s_barrier
	s_add_i32 s4, 0, 0x18000
	v_add_u32_e32 v0, s4, v167
	ds_read_b128 v[136:139], v0
	ds_read_b128 v[144:147], v0 offset:1024
	ds_read_b128 v[148:151], v0 offset:2048
	ds_read_b128 v[152:155], v0 offset:3072
	s_mov_b32 m0, s29
	v_lshl_add_u64 v[208:209], v[224:225], 0, s[52:53]
	ds_read_b128 v[156:159], v172 offset:32768
	ds_read_b128 v[160:163], v172 offset:33792
	ds_read_b128 v[174:177], v172 offset:34816
	ds_read_b128 v[178:181], v172 offset:35840
	ds_read_b128 v[182:185], v172 offset:36864
	ds_read_b128 v[196:199], v172 offset:37888
	ds_read_b128 v[200:203], v172 offset:38912
	ds_read_b128 v[204:207], v172 offset:39936
	global_load_lds_dwordx4 v[208:209], off
	v_lshl_add_u64 v[208:209], v[224:225], 0, s[54:55]
	s_mov_b32 m0, s30
	s_nop 0
	global_load_lds_dwordx4 v[208:209], off
	s_waitcnt lgkmcnt(8)
	s_barrier
	s_waitcnt lgkmcnt(0)
	v_mfma_f32_16x16x32_bf16 v[132:135], v[136:139], v[156:159], v[132:135]
	v_mfma_f32_16x16x32_bf16 v[128:131], v[148:151], v[156:159], v[128:131]
	v_mfma_f32_16x16x32_bf16 v[116:119], v[136:139], v[174:177], v[116:119]
	v_mfma_f32_16x16x32_bf16 v[112:115], v[148:151], v[174:177], v[112:115]
	v_mfma_f32_16x16x32_bf16 v[100:103], v[136:139], v[182:185], v[100:103]
	v_mfma_f32_16x16x32_bf16 v[96:99], v[148:151], v[182:185], v[96:99]
	v_mfma_f32_16x16x32_bf16 v[84:87], v[136:139], v[200:203], v[84:87]
	v_mfma_f32_16x16x32_bf16 v[80:83], v[148:151], v[200:203], v[80:83]
	v_mfma_f32_16x16x32_bf16 v[132:135], v[144:147], v[160:163], v[132:135]
	v_mfma_f32_16x16x32_bf16 v[128:131], v[152:155], v[160:163], v[128:131]
	v_mfma_f32_16x16x32_bf16 v[116:119], v[144:147], v[178:181], v[116:119]
	v_mfma_f32_16x16x32_bf16 v[112:115], v[152:155], v[178:181], v[112:115]
	v_mfma_f32_16x16x32_bf16 v[100:103], v[144:147], v[196:199], v[100:103]
	v_mfma_f32_16x16x32_bf16 v[96:99], v[152:155], v[196:199], v[96:99]
	v_mfma_f32_16x16x32_bf16 v[84:87], v[144:147], v[204:207], v[84:87]
	v_mfma_f32_16x16x32_bf16 v[80:83], v[152:155], v[204:207], v[80:83]
	s_barrier
; #define G_STAGE(bufoff, gbase, o0, h64) do { \
;         __builtin_amdgcn_global_load_lds((const unsigned*)((const char*)(gbase) + (o0)), (LAS unsigned*)(lds + (bufoff) + ldsw), 16, 0, 0); \
;         __builtin_amdgcn_global_load_lds((const unsigned*)((const char*)(gbase) + (h64) + (o0)), (LAS unsigned*)(lds + (bufoff) + ldsw + 8192), 16, 0, 0); } while (0)
; #define G_LDA(dst, b, h) do { _Pragma("unroll") for (int m = 0; m < 4; ++m) _Pragma("unroll") for (int k = 0; k < 2; ++k) dst[m][k] = *(const LAS bf16x8*)(lds + G_SA(b, h) + aoff + m * 2048 + k * 1024); } while (0)
; #define G_LDB(dst, b, h) do { _Pragma("unroll") for (int n = 0; n < 2; ++n) _Pragma("unroll") for (int k = 0; k < 2; ++k) dst[n][k] = *(const LAS bf16x8*)(lds + G_SB(b, h) + boff + n * 2048 + k * 1024); } while (0)
; #define G_WAIT_V(n) asm volatile("s_waitcnt vmcnt(" #n ")" ::: "memory")
; #define G_WAIT_L(n) asm volatile("s_waitcnt lgkmcnt(" #n ")" ::: "memory")
; #define G_BAR __builtin_amdgcn_s_barrier()
; #define G_SCHED __builtin_amdgcn_sched_barrier(0)
;     ...
;             G_WAIT_L(8); G_BAR; G_WAIT_L(0); G_MMA(0, 0, At, B0); G_BAR; G_SCHED;
;             G_LDB(B1, 1, 1); G_STAGE(G_SB(1, 0), b3, cB0, qB);
;             G_BAR; G_WAIT_L(0); G_MMA(0, 1, At, B1); G_BAR;
;             G_LDA(At, 1, 1); G_STAGE(G_SA(1, 0), a3, cA0, qA);
;             G_BAR; G_WAIT_L(0); G_MMA(1, 0, At, B0); G_BAR; G_SCHED;
;             G_STAGE(G_SB(1, 1), b3 + chB, cB0, qB);
;             G_WAIT_V(6); G_BAR; G_MMA(1, 1, At, B1); G_BAR;
;         }
;         E.template run<cs.kind>(acc, cur, tid);
;         if (!has_next) break;
	s_add_i32 s5, 0, 0x1c000
	s_add_i32 s4, s4, s26
	v_add_u32_e32 v0, s5, v167
	v_lshl_add_u64 v[226:227], v[164:165], 0, s[46:47]
	s_mov_b32 m0, s4
	ds_read_b128 v[208:211], v0
	ds_read_b128 v[212:215], v0 offset:1024
	ds_read_b128 v[216:219], v0 offset:2048
	ds_read_b128 v[220:223], v0 offset:3072
	global_load_lds_dwordx4 v[226:227], off
	v_lshl_add_u64 v[226:227], v[164:165], 0, s[58:59]
	s_add_i32 m0, s4, 0x2000
	s_nop 0
	global_load_lds_dwordx4 v[226:227], off
	s_barrier
	s_waitcnt lgkmcnt(0)
	v_mfma_f32_16x16x32_bf16 v[124:127], v[208:211], v[156:159], v[124:127]
	v_mfma_f32_16x16x32_bf16 v[120:123], v[216:219], v[156:159], v[120:123]
	v_mfma_f32_16x16x32_bf16 v[108:111], v[208:211], v[174:177], v[108:111]
	v_mfma_f32_16x16x32_bf16 v[104:107], v[216:219], v[174:177], v[104:107]
	v_mfma_f32_16x16x32_bf16 v[92:95], v[208:211], v[182:185], v[92:95]
	v_mfma_f32_16x16x32_bf16 v[88:91], v[216:219], v[182:185], v[88:91]
	v_mfma_f32_16x16x32_bf16 v[76:79], v[208:211], v[200:203], v[76:79]
	v_mfma_f32_16x16x32_bf16 v[72:75], v[216:219], v[200:203], v[72:75]
	v_mfma_f32_16x16x32_bf16 v[124:127], v[212:215], v[160:163], v[124:127]
	v_mfma_f32_16x16x32_bf16 v[120:123], v[220:223], v[160:163], v[120:123]
	v_mfma_f32_16x16x32_bf16 v[108:111], v[212:215], v[178:181], v[108:111]
	v_mfma_f32_16x16x32_bf16 v[104:107], v[220:223], v[178:181], v[104:107]
	v_mfma_f32_16x16x32_bf16 v[92:95], v[212:215], v[196:199], v[92:95]
	v_mfma_f32_16x16x32_bf16 v[88:91], v[220:223], v[196:199], v[88:91]
	v_mfma_f32_16x16x32_bf16 v[76:79], v[212:215], v[204:207], v[76:79]
	v_mfma_f32_16x16x32_bf16 v[72:75], v[220:223], v[204:207], v[72:75]
	s_barrier
	s_mov_b32 m0, s31
	v_lshl_add_u64 v[226:227], v[224:225], 0, s[46:47]
	ds_read_b128 v[156:159], v172 offset:49152
	ds_read_b128 v[160:163], v172 offset:50176
	ds_read_b128 v[174:177], v172 offset:51200
	ds_read_b128 v[178:181], v172 offset:52224
	ds_read_b128 v[182:185], v172 offset:53248
	ds_read_b128 v[196:199], v172 offset:54272
	ds_read_b128 v[200:203], v172 offset:55296
	ds_read_b128 v[204:207], v172 offset:56320
	global_load_lds_dwordx4 v[226:227], off
	v_lshl_add_u64 v[224:225], v[224:225], 0, s[58:59]
	s_mov_b32 m0, s34
	s_nop 0
	global_load_lds_dwordx4 v[224:225], off
	s_barrier
	s_waitcnt lgkmcnt(0)
	v_mfma_f32_16x16x32_bf16 v[68:71], v[136:139], v[156:159], v[68:71]
	v_mfma_f32_16x16x32_bf16 v[64:67], v[148:151], v[156:159], v[64:67]
	v_mfma_f32_16x16x32_bf16 v[52:55], v[136:139], v[174:177], v[52:55]
	v_mfma_f32_16x16x32_bf16 v[48:51], v[148:151], v[174:177], v[48:51]
	v_mfma_f32_16x16x32_bf16 v[36:39], v[136:139], v[182:185], v[36:39]
	v_mfma_f32_16x16x32_bf16 v[32:35], v[148:151], v[182:185], v[32:35]
	v_mfma_f32_16x16x32_bf16 v[20:23], v[136:139], v[200:203], v[20:23]
	v_mfma_f32_16x16x32_bf16 v[16:19], v[148:151], v[200:203], v[16:19]
	v_mfma_f32_16x16x32_bf16 v[68:71], v[144:147], v[160:163], v[68:71]
	v_mfma_f32_16x16x32_bf16 v[64:67], v[152:155], v[160:163], v[64:67]
	v_mfma_f32_16x16x32_bf16 v[52:55], v[144:147], v[178:181], v[52:55]
	v_mfma_f32_16x16x32_bf16 v[48:51], v[152:155], v[178:181], v[48:51]
	v_mfma_f32_16x16x32_bf16 v[36:39], v[144:147], v[196:199], v[36:39]
	v_mfma_f32_16x16x32_bf16 v[32:35], v[152:155], v[196:199], v[32:35]
	v_mfma_f32_16x16x32_bf16 v[20:23], v[144:147], v[204:207], v[20:23]
	v_mfma_f32_16x16x32_bf16 v[16:19], v[152:155], v[204:207], v[16:19]
	s_barrier
	s_add_i32 s4, s5, s26
	v_lshl_add_u64 v[136:137], v[164:165], 0, s[62:63]
	s_mov_b32 m0, s4
	s_nop 0
	global_load_lds_dwordx4 v[136:137], off
	v_lshl_add_u64 v[136:137], v[164:165], 0, s[64:65]
	s_add_i32 m0, s4, 0x2000
	s_nop 0
	global_load_lds_dwordx4 v[136:137], off
	s_add_i32 s23, s23, 2
	s_add_u32 s2, s2, 0x100
	s_addc_u32 s3, s3, 0
	s_add_u32 s7, s7, 0x100
	s_addc_u32 s22, s22, 0
	s_cmp_gt_u32 s23, 13
	s_waitcnt vmcnt(6)
	s_barrier
	v_mfma_f32_16x16x32_bf16 v[60:63], v[208:211], v[156:159], v[60:63]
	v_mfma_f32_16x16x32_bf16 v[56:59], v[216:219], v[156:159], v[56:59]
	v_mfma_f32_16x16x32_bf16 v[44:47], v[208:211], v[174:177], v[44:47]
	v_mfma_f32_16x16x32_bf16 v[40:43], v[216:219], v[174:177], v[40:43]
	v_mfma_f32_16x16x32_bf16 v[28:31], v[208:211], v[182:185], v[28:31]
	v_mfma_f32_16x16x32_bf16 v[24:27], v[216:219], v[182:185], v[24:27]
	v_mfma_f32_16x16x32_bf16 v[12:15], v[208:211], v[200:203], v[12:15]
	v_mfma_f32_16x16x32_bf16 v[8:11], v[216:219], v[200:203], v[8:11]
	v_mfma_f32_16x16x32_bf16 v[60:63], v[212:215], v[160:163], v[60:63]
	v_mfma_f32_16x16x32_bf16 v[56:59], v[220:223], v[160:163], v[56:59]
	v_mfma_f32_16x16x32_bf16 v[44:47], v[212:215], v[178:181], v[44:47]
	v_mfma_f32_16x16x32_bf16 v[40:43], v[220:223], v[178:181], v[40:43]
	v_mfma_f32_16x16x32_bf16 v[28:31], v[212:215], v[196:199], v[28:31]
	v_mfma_f32_16x16x32_bf16 v[24:27], v[220:223], v[196:199], v[24:27]
	v_mfma_f32_16x16x32_bf16 v[12:15], v[212:215], v[204:207], v[12:15]
	v_mfma_f32_16x16x32_bf16 v[8:11], v[220:223], v[204:207], v[8:11]
	s_cbranch_scc0 .Ldb_WIN_cont
	v_readfirstlane_b32 s101, v186
	s_cmpk_gt_u32 s101, 0xff
	s_cbranch_scc1 .Ldb_WIN_young
	s_barrier
	s_mov_b32 s101, 1
	s_branch .Ldb_WIN_exit
.Ldb_WIN_young:
	s_mov_b32 s101, 2
	s_branch .Ldb_WIN_exit

; #define G_WAIT_V(n) asm volatile("s_waitcnt vmcnt(" #n ")" ::: "memory")
; #define G_BAR __builtin_amdgcn_s_barrier()
;     ...
;     G_WAIT_V(0);
;     if (wr == 0) G_BAR;
;     G_BAR;
.LBB0_341:
	s_cmp_eq_u32 s101, 2
	s_cbranch_scc0 .Ldbj_WIN_pe
	s_barrier
.Ldbj_WIN_pe:
	s_mov_b32 s101, 0
	s_waitcnt vmcnt(0)
	s_cmpk_gt_u32 s24, 0xff
	s_cbranch_scc1 .LBB0_343
	s_barrier

; #define G_STAGE(bufoff, gbase, o0, h64) do { \
;         __builtin_amdgcn_global_load_lds((const unsigned*)((const char*)(gbase) + (o0)), (LAS unsigned*)(lds + (bufoff) + ldsw), 16, 0, 0); \
;         __builtin_amdgcn_global_load_lds((const unsigned*)((const char*)(gbase) + (h64) + (o0)), (LAS unsigned*)(lds + (bufoff) + ldsw + 8192), 16, 0, 0); } while (0)
; #define G_LDA(dst, b, h) do { _Pragma("unroll") for (int m = 0; m < 4; ++m) _Pragma("unroll") for (int k = 0; k < 2; ++k) dst[m][k] = *(const LAS bf16x8*)(lds + G_SA(b, h) + aoff + m * 2048 + k * 1024); } while (0)
; #define G_LDB(dst, b, h) do { _Pragma("unroll") for (int n = 0; n < 2; ++n) _Pragma("unroll") for (int k = 0; k < 2; ++k) dst[n][k] = *(const LAS bf16x8*)(lds + G_SB(b, h) + boff + n * 2048 + k * 1024); } while (0)
; #define G_WAIT_L(n) asm volatile("s_waitcnt lgkmcnt(" #n ")" ::: "memory")
; #define G_BAR __builtin_amdgcn_s_barrier()
; #define G_SCHED __builtin_amdgcn_sched_barrier(0)
;     ...
;         for (int t = 0; t < nt; t += 2) {
;             const bool last = (t == nt - 2);
;             const char* a1 = cA + (size_t)(t + 1) * ckA;
;             const char* a2 = last ? nA : cA + (size_t)(t + 2) * ckA; const char* b2 = last ? nB : cB + (size_t)(t + 2) * kB;
;             const char* a3 = a2 + ckA; const char* b3 = b2 + kB;
;             G_LDB(B0, 0, 0); G_SCHED; G_LDA(At, 0, 0); G_STAGE(G_SA(1, 1), a1 + chA, cA0, qA);
;             G_WAIT_L(8); G_BAR; G_WAIT_L(0); G_MMA(0, 0, At, B0); G_BAR; G_SCHED;
;             G_LDB(B1, 0, 1); G_STAGE(G_SB(0, 0), b2, cB0, qB);
;             G_BAR; G_WAIT_L(0); G_MMA(0, 1, At, B1); G_BAR;
;             G_LDA(At, 0, 1); G_STAGE(G_SA(0, 0), a2, cA0, qA);
;             G_BAR; G_WAIT_L(0); G_MMA(1, 0, At, B0); G_BAR; G_SCHED;
;     ...
;         for (int a = 0; a < 2; ++a)
; #pragma unroll
;             for (int b = 0; b < 2; ++b)
; #pragma unroll
;                 for (int m = 0; m < 4; ++m)
; #pragma unroll
;                     for (int n = 0; n < 2; ++n) acc[a][b][m][n] = (f32x4){0.f, 0.f, 0.f, 0.f};
.LBB0_449:
	s_add_u32 s6, s22, 0x20080
	s_addc_u32 s7, s23, 0
	s_add_u32 s19, s20, 0x100
	v_mov_b64_e32 v[8:9], 0
	s_addc_u32 s20, s21, 0
	s_mov_b32 s21, -2
	v_mov_b64_e32 v[10:11], 0
	v_mov_b64_e32 v[12:13], 0
	v_mov_b64_e32 v[14:15], 0
	v_mov_b64_e32 v[24:25], 0
	v_mov_b64_e32 v[26:27], 0
	v_mov_b64_e32 v[28:29], 0
	v_mov_b64_e32 v[30:31], 0
	v_mov_b64_e32 v[40:41], 0
	v_mov_b64_e32 v[42:43], 0
	v_mov_b64_e32 v[44:45], 0
	v_mov_b64_e32 v[46:47], 0
	v_mov_b64_e32 v[56:57], 0
	v_mov_b64_e32 v[58:59], 0
	v_mov_b64_e32 v[60:61], 0
	v_mov_b64_e32 v[62:63], 0
	v_mov_b64_e32 v[16:17], 0
	v_mov_b64_e32 v[18:19], 0
	v_mov_b64_e32 v[20:21], 0
	v_mov_b64_e32 v[22:23], 0
	v_mov_b64_e32 v[32:33], 0
	v_mov_b64_e32 v[34:35], 0
	v_mov_b64_e32 v[36:37], 0
	v_mov_b64_e32 v[38:39], 0
	v_mov_b64_e32 v[48:49], 0
	v_mov_b64_e32 v[50:51], 0
	v_mov_b64_e32 v[52:53], 0
	v_mov_b64_e32 v[54:55], 0
	v_mov_b64_e32 v[64:65], 0
	v_mov_b64_e32 v[66:67], 0
	v_mov_b64_e32 v[68:69], 0
	v_mov_b64_e32 v[70:71], 0
	v_mov_b64_e32 v[72:73], 0
	v_mov_b64_e32 v[74:75], 0
	v_mov_b64_e32 v[76:77], 0
	v_mov_b64_e32 v[78:79], 0
	v_mov_b64_e32 v[88:89], 0
	v_mov_b64_e32 v[90:91], 0
	v_mov_b64_e32 v[92:93], 0
	v_mov_b64_e32 v[94:95], 0
	v_mov_b64_e32 v[104:105], 0
	v_mov_b64_e32 v[106:107], 0
	v_mov_b64_e32 v[108:109], 0
	v_mov_b64_e32 v[110:111], 0
	v_mov_b64_e32 v[120:121], 0
	v_mov_b64_e32 v[122:123], 0
	v_mov_b64_e32 v[124:125], 0
	v_mov_b64_e32 v[126:127], 0
	v_mov_b64_e32 v[80:81], 0
	v_mov_b64_e32 v[82:83], 0
	v_mov_b64_e32 v[84:85], 0
	v_mov_b64_e32 v[86:87], 0
	v_mov_b64_e32 v[96:97], 0
	v_mov_b64_e32 v[98:99], 0
	v_mov_b64_e32 v[100:101], 0
	v_mov_b64_e32 v[102:103], 0
	v_mov_b64_e32 v[112:113], 0
	v_mov_b64_e32 v[114:115], 0
	v_mov_b64_e32 v[116:117], 0
	v_mov_b64_e32 v[118:119], 0
	v_mov_b64_e32 v[128:129], 0
	v_mov_b64_e32 v[130:131], 0
	v_mov_b64_e32 v[132:133], 0
	v_mov_b64_e32 v[134:135], 0
	s_mov_b64 s[50:51], 0x20080
	s_mov_b64 s[52:53], 0x10000
	s_mov_b64 s[54:55], 0x30000
	s_mov_b64 s[58:59], 0x10080
	s_mov_b64 s[62:63], 0x30080
	s_cmp_eq_u32 s101, 2
	s_cselect_b32 s101, 0, s101
.LBB0_450:
	s_add_u32 s4, s6, 0xfffe0080
	s_addc_u32 s5, s7, -1
	s_add_i32 s41, 0, 0x10000
	v_add_u32_e32 v0, s41, v145
	ds_read_b128 v[140:143], v0
	ds_read_b128 v[148:151], v0 offset:1024
	ds_read_b128 v[152:155], v0 offset:2048
	ds_read_b128 v[156:159], v0 offset:3072
	s_cmp_eq_u32 s21, 4
	s_cselect_b32 s23, s11, s5
	s_cselect_b32 s22, s10, s4
	s_cselect_b32 s43, s17, s20
	s_cselect_b32 s42, s16, s19
	v_lshl_add_u64 v[184:185], s[6:7], 0, v[138:139]
	s_add_i32 m0, s27, 0xc000
	ds_read_b128 v[160:163], v146
	ds_read_b128 v[164:167], v146 offset:1024
	ds_read_b128 v[172:175], v146 offset:2048
	ds_read_b128 v[176:179], v146 offset:3072
	ds_read_b128 v[180:183], v146 offset:4096
	ds_read_b128 v[196:199], v146 offset:5120
	ds_read_b128 v[200:203], v146 offset:6144
	ds_read_b128 v[204:207], v146 offset:7168
	global_load_lds_dwordx4 v[184:185], off
	v_lshl_add_u64 v[184:185], v[184:185], 0, s[52:53]
	s_add_i32 m0, s27, 0xe000
	s_nop 0
	global_load_lds_dwordx4 v[184:185], off
	s_waitcnt lgkmcnt(8)
	s_cmp_eq_u32 s101, 1
	s_cbranch_scc1 .Ldb_SSM1_sk
	s_barrier
.Ldb_SSM1_sk:
	s_mov_b32 s101, 0
	s_waitcnt lgkmcnt(0)
	v_mfma_f32_16x16x32_bf16 v[132:135], v[140:143], v[160:163], v[132:135]
	v_mfma_f32_16x16x32_bf16 v[128:131], v[152:155], v[160:163], v[128:131]
	v_mfma_f32_16x16x32_bf16 v[116:119], v[140:143], v[172:175], v[116:119]
	v_mfma_f32_16x16x32_bf16 v[112:115], v[152:155], v[172:175], v[112:115]
	v_mfma_f32_16x16x32_bf16 v[100:103], v[140:143], v[180:183], v[100:103]
	v_mfma_f32_16x16x32_bf16 v[96:99], v[152:155], v[180:183], v[96:99]
	v_mfma_f32_16x16x32_bf16 v[84:87], v[140:143], v[200:203], v[84:87]
	v_mfma_f32_16x16x32_bf16 v[80:83], v[152:155], v[200:203], v[80:83]
	v_mfma_f32_16x16x32_bf16 v[132:135], v[148:151], v[164:167], v[132:135]
	v_mfma_f32_16x16x32_bf16 v[128:131], v[156:159], v[164:167], v[128:131]
	v_mfma_f32_16x16x32_bf16 v[116:119], v[148:151], v[176:179], v[116:119]
	v_mfma_f32_16x16x32_bf16 v[112:115], v[156:159], v[176:179], v[112:115]
	v_mfma_f32_16x16x32_bf16 v[100:103], v[148:151], v[196:199], v[100:103]
	v_mfma_f32_16x16x32_bf16 v[96:99], v[156:159], v[196:199], v[96:99]
	v_mfma_f32_16x16x32_bf16 v[84:87], v[148:151], v[204:207], v[84:87]
	v_mfma_f32_16x16x32_bf16 v[80:83], v[156:159], v[204:207], v[80:83]
	s_barrier
	s_add_i32 s4, 0, 0x14000
	s_add_i32 s5, s41, s26
	v_add_u32_e32 v0, s4, v145
	v_lshl_add_u64 v[184:185], s[42:43], 0, v[136:137]
	s_mov_b32 m0, s5
	ds_read_b128 v[208:211], v0
	ds_read_b128 v[212:215], v0 offset:1024
	ds_read_b128 v[216:219], v0 offset:2048
	ds_read_b128 v[220:223], v0 offset:3072
	global_load_lds_dwordx4 v[184:185], off
	v_lshl_add_u64 v[224:225], v[184:185], 0, s[52:53]
	s_add_i32 m0, s5, 0x2000
	s_nop 0
	global_load_lds_dwordx4 v[224:225], off
	s_barrier
	s_waitcnt lgkmcnt(0)
	v_mfma_f32_16x16x32_bf16 v[124:127], v[208:211], v[160:163], v[124:127]
	v_mfma_f32_16x16x32_bf16 v[120:123], v[216:219], v[160:163], v[120:123]
	v_mfma_f32_16x16x32_bf16 v[108:111], v[208:211], v[172:175], v[108:111]
	v_mfma_f32_16x16x32_bf16 v[104:107], v[216:219], v[172:175], v[104:107]
	v_mfma_f32_16x16x32_bf16 v[92:95], v[208:211], v[180:183], v[92:95]
	v_mfma_f32_16x16x32_bf16 v[88:91], v[216:219], v[180:183], v[88:91]
	v_mfma_f32_16x16x32_bf16 v[76:79], v[208:211], v[200:203], v[76:79]
	v_mfma_f32_16x16x32_bf16 v[72:75], v[216:219], v[200:203], v[72:75]
	v_mfma_f32_16x16x32_bf16 v[124:127], v[212:215], v[164:167], v[124:127]
	v_mfma_f32_16x16x32_bf16 v[120:123], v[220:223], v[164:167], v[120:123]
	v_mfma_f32_16x16x32_bf16 v[108:111], v[212:215], v[176:179], v[108:111]
	v_mfma_f32_16x16x32_bf16 v[104:107], v[220:223], v[176:179], v[104:107]
	v_mfma_f32_16x16x32_bf16 v[92:95], v[212:215], v[196:199], v[92:95]
	v_mfma_f32_16x16x32_bf16 v[88:91], v[220:223], v[196:199], v[88:91]
	v_mfma_f32_16x16x32_bf16 v[76:79], v[212:215], v[204:207], v[76:79]
	v_mfma_f32_16x16x32_bf16 v[72:75], v[220:223], v[204:207], v[72:75]
	s_barrier
; #define G_STAGE(bufoff, gbase, o0, h64) do { \
;         __builtin_amdgcn_global_load_lds((const unsigned*)((const char*)(gbase) + (o0)), (LAS unsigned*)(lds + (bufoff) + ldsw), 16, 0, 0); \
;         __builtin_amdgcn_global_load_lds((const unsigned*)((const char*)(gbase) + (h64) + (o0)), (LAS unsigned*)(lds + (bufoff) + ldsw + 8192), 16, 0, 0); } while (0)
; #define G_LDA(dst, b, h) do { _Pragma("unroll") for (int m = 0; m < 4; ++m) _Pragma("unroll") for (int k = 0; k < 2; ++k) dst[m][k] = *(const LAS bf16x8*)(lds + G_SA(b, h) + aoff + m * 2048 + k * 1024); } while (0)
; #define G_LDB(dst, b, h) do { _Pragma("unroll") for (int n = 0; n < 2; ++n) _Pragma("unroll") for (int k = 0; k < 2; ++k) dst[n][k] = *(const LAS bf16x8*)(lds + G_SB(b, h) + boff + n * 2048 + k * 1024); } while (0)
; #define G_WAIT_V(n) asm volatile("s_waitcnt vmcnt(" #n ")" ::: "memory")
; #define G_WAIT_L(n) asm volatile("s_waitcnt lgkmcnt(" #n ")" ::: "memory")
; #define G_BAR __builtin_amdgcn_s_barrier()
; #define G_SCHED __builtin_amdgcn_sched_barrier(0)
;     ...
;             G_STAGE(G_SB(0, 1), b2 + chB, cB0, qB);
;             G_WAIT_V(6); G_BAR; G_MMA(1, 1, At, B1); G_BAR;
;             G_LDB(B0, 1, 0); G_SCHED; G_LDA(At, 1, 0); G_STAGE(G_SA(0, 1), a2 + chA, cA0, qA);
;             G_WAIT_L(8); G_BAR; G_WAIT_L(0); G_MMA(0, 0, At, B0); G_BAR; G_SCHED;
;             G_LDB(B1, 1, 1); G_STAGE(G_SB(1, 0), b3, cB0, qB);
;             G_BAR; G_WAIT_L(0); G_MMA(0, 1, At, B1); G_BAR;
;             G_LDA(At, 1, 1); G_STAGE(G_SA(1, 0), a3, cA0, qA);
;             G_BAR; G_WAIT_L(0); G_MMA(1, 0, At, B0); G_BAR; G_SCHED;
	s_mov_b32 m0, s27
	v_lshl_add_u64 v[224:225], s[22:23], 0, v[2:3]
	ds_read_b128 v[160:163], v146 offset:16384
	ds_read_b128 v[164:167], v146 offset:17408
	ds_read_b128 v[172:175], v146 offset:18432
	ds_read_b128 v[176:179], v146 offset:19456
	ds_read_b128 v[180:183], v146 offset:20480
	ds_read_b128 v[196:199], v146 offset:21504
	ds_read_b128 v[200:203], v146 offset:22528
	ds_read_b128 v[204:207], v146 offset:23552
	global_load_lds_dwordx4 v[224:225], off
	v_lshl_add_u64 v[226:227], v[224:225], 0, s[52:53]
	s_mov_b32 m0, s28
	s_nop 0
	global_load_lds_dwordx4 v[226:227], off
	s_barrier
	s_waitcnt lgkmcnt(0)
	v_mfma_f32_16x16x32_bf16 v[68:71], v[140:143], v[160:163], v[68:71]
	v_mfma_f32_16x16x32_bf16 v[64:67], v[152:155], v[160:163], v[64:67]
	v_mfma_f32_16x16x32_bf16 v[52:55], v[140:143], v[172:175], v[52:55]
	v_mfma_f32_16x16x32_bf16 v[48:51], v[152:155], v[172:175], v[48:51]
	v_mfma_f32_16x16x32_bf16 v[36:39], v[140:143], v[180:183], v[36:39]
	v_mfma_f32_16x16x32_bf16 v[32:35], v[152:155], v[180:183], v[32:35]
	v_mfma_f32_16x16x32_bf16 v[20:23], v[140:143], v[200:203], v[20:23]
	v_mfma_f32_16x16x32_bf16 v[16:19], v[152:155], v[200:203], v[16:19]
	v_mfma_f32_16x16x32_bf16 v[68:71], v[148:151], v[164:167], v[68:71]
	v_mfma_f32_16x16x32_bf16 v[64:67], v[156:159], v[164:167], v[64:67]
	v_mfma_f32_16x16x32_bf16 v[52:55], v[148:151], v[176:179], v[52:55]
	v_mfma_f32_16x16x32_bf16 v[48:51], v[156:159], v[176:179], v[48:51]
	v_mfma_f32_16x16x32_bf16 v[36:39], v[148:151], v[196:199], v[36:39]
	v_mfma_f32_16x16x32_bf16 v[32:35], v[156:159], v[196:199], v[32:35]
	v_mfma_f32_16x16x32_bf16 v[20:23], v[148:151], v[204:207], v[20:23]
	v_mfma_f32_16x16x32_bf16 v[16:19], v[156:159], v[204:207], v[16:19]
	s_barrier
	s_add_i32 s4, s4, s26
	v_lshl_add_u64 v[140:141], v[184:185], 0, s[0:1]
	s_mov_b32 m0, s4
	s_nop 0
	global_load_lds_dwordx4 v[140:141], off
	v_lshl_add_u64 v[140:141], v[184:185], 0, s[54:55]
	s_add_i32 m0, s4, 0x2000
	s_nop 0
	global_load_lds_dwordx4 v[140:141], off
	s_waitcnt vmcnt(6)
	s_barrier
	v_mfma_f32_16x16x32_bf16 v[60:63], v[208:211], v[160:163], v[60:63]
	v_mfma_f32_16x16x32_bf16 v[56:59], v[216:219], v[160:163], v[56:59]
	v_mfma_f32_16x16x32_bf16 v[44:47], v[208:211], v[172:175], v[44:47]
	v_mfma_f32_16x16x32_bf16 v[40:43], v[216:219], v[172:175], v[40:43]
	v_mfma_f32_16x16x32_bf16 v[28:31], v[208:211], v[180:183], v[28:31]
	v_mfma_f32_16x16x32_bf16 v[24:27], v[216:219], v[180:183], v[24:27]
	v_mfma_f32_16x16x32_bf16 v[12:15], v[208:211], v[200:203], v[12:15]
	v_mfma_f32_16x16x32_bf16 v[8:11], v[216:219], v[200:203], v[8:11]
	v_mfma_f32_16x16x32_bf16 v[60:63], v[212:215], v[164:167], v[60:63]
	v_mfma_f32_16x16x32_bf16 v[56:59], v[220:223], v[164:167], v[56:59]
	v_mfma_f32_16x16x32_bf16 v[44:47], v[212:215], v[176:179], v[44:47]
	v_mfma_f32_16x16x32_bf16 v[40:43], v[220:223], v[176:179], v[40:43]
	v_mfma_f32_16x16x32_bf16 v[28:31], v[212:215], v[196:199], v[28:31]
	v_mfma_f32_16x16x32_bf16 v[24:27], v[220:223], v[196:199], v[24:27]
	v_mfma_f32_16x16x32_bf16 v[12:15], v[212:215], v[204:207], v[12:15]
	v_mfma_f32_16x16x32_bf16 v[8:11], v[220:223], v[204:207], v[8:11]
	s_barrier
	s_add_i32 s4, 0, 0x18000
	v_add_u32_e32 v0, s4, v145
	ds_read_b128 v[140:143], v0
	ds_read_b128 v[148:151], v0 offset:1024
	ds_read_b128 v[152:155], v0 offset:2048
	ds_read_b128 v[156:159], v0 offset:3072
	s_mov_b32 m0, s29
	v_lshl_add_u64 v[208:209], v[224:225], 0, s[0:1]
	ds_read_b128 v[160:163], v146 offset:32768
	ds_read_b128 v[164:167], v146 offset:33792
	ds_read_b128 v[172:175], v146 offset:34816
	ds_read_b128 v[176:179], v146 offset:35840
	ds_read_b128 v[180:183], v146 offset:36864
	ds_read_b128 v[196:199], v146 offset:37888
	ds_read_b128 v[200:203], v146 offset:38912
	ds_read_b128 v[204:207], v146 offset:39936
	global_load_lds_dwordx4 v[208:209], off
	v_lshl_add_u64 v[208:209], v[224:225], 0, s[54:55]
	s_mov_b32 m0, s30
	s_nop 0
	global_load_lds_dwordx4 v[208:209], off
	s_waitcnt lgkmcnt(8)
	s_barrier
	s_waitcnt lgkmcnt(0)
	v_mfma_f32_16x16x32_bf16 v[132:135], v[140:143], v[160:163], v[132:135]
	v_mfma_f32_16x16x32_bf16 v[128:131], v[152:155], v[160:163], v[128:131]
	v_mfma_f32_16x16x32_bf16 v[116:119], v[140:143], v[172:175], v[116:119]
	v_mfma_f32_16x16x32_bf16 v[112:115], v[152:155], v[172:175], v[112:115]
	v_mfma_f32_16x16x32_bf16 v[100:103], v[140:143], v[180:183], v[100:103]
	v_mfma_f32_16x16x32_bf16 v[96:99], v[152:155], v[180:183], v[96:99]
	v_mfma_f32_16x16x32_bf16 v[84:87], v[140:143], v[200:203], v[84:87]
	v_mfma_f32_16x16x32_bf16 v[80:83], v[152:155], v[200:203], v[80:83]
	v_mfma_f32_16x16x32_bf16 v[132:135], v[148:151], v[164:167], v[132:135]
	v_mfma_f32_16x16x32_bf16 v[128:131], v[156:159], v[164:167], v[128:131]
	v_mfma_f32_16x16x32_bf16 v[116:119], v[148:151], v[176:179], v[116:119]
	v_mfma_f32_16x16x32_bf16 v[112:115], v[156:159], v[176:179], v[112:115]
	v_mfma_f32_16x16x32_bf16 v[100:103], v[148:151], v[196:199], v[100:103]
	v_mfma_f32_16x16x32_bf16 v[96:99], v[156:159], v[196:199], v[96:99]
	v_mfma_f32_16x16x32_bf16 v[84:87], v[148:151], v[204:207], v[84:87]
	v_mfma_f32_16x16x32_bf16 v[80:83], v[156:159], v[204:207], v[80:83]
	s_barrier
; #define G_STAGE(bufoff, gbase, o0, h64) do { \
;         __builtin_amdgcn_global_load_lds((const unsigned*)((const char*)(gbase) + (o0)), (LAS unsigned*)(lds + (bufoff) + ldsw), 16, 0, 0); \
;         __builtin_amdgcn_global_load_lds((const unsigned*)((const char*)(gbase) + (h64) + (o0)), (LAS unsigned*)(lds + (bufoff) + ldsw + 8192), 16, 0, 0); } while (0)
; #define G_LDA(dst, b, h) do { _Pragma("unroll") for (int m = 0; m < 4; ++m) _Pragma("unroll") for (int k = 0; k < 2; ++k) dst[m][k] = *(const LAS bf16x8*)(lds + G_SA(b, h) + aoff + m * 2048 + k * 1024); } while (0)
; #define G_WAIT_V(n) asm volatile("s_waitcnt vmcnt(" #n ")" ::: "memory")
; #define G_WAIT_L(n) asm volatile("s_waitcnt lgkmcnt(" #n ")" ::: "memory")
; #define G_BAR __builtin_amdgcn_s_barrier()
; #define G_SCHED __builtin_amdgcn_sched_barrier(0)
;     ...
;             G_LDA(At, 1, 1); G_STAGE(G_SA(1, 0), a3, cA0, qA);
;             G_BAR; G_WAIT_L(0); G_MMA(1, 0, At, B0); G_BAR; G_SCHED;
;             G_STAGE(G_SB(1, 1), b3 + chB, cB0, qB);
;             G_WAIT_V(6); G_BAR; G_MMA(1, 1, At, B1); G_BAR;
;         }
;         E.template run<cs.kind>(acc, cur, tid);
;         if (!has_next) break;
	s_add_i32 s5, 0, 0x1c000
	s_add_i32 s4, s4, s26
	v_add_u32_e32 v0, s5, v145
	v_lshl_add_u64 v[226:227], v[184:185], 0, s[46:47]
	s_mov_b32 m0, s4
	ds_read_b128 v[208:211], v0
	ds_read_b128 v[212:215], v0 offset:1024
	ds_read_b128 v[216:219], v0 offset:2048
	ds_read_b128 v[220:223], v0 offset:3072
	global_load_lds_dwordx4 v[226:227], off
	v_lshl_add_u64 v[226:227], v[184:185], 0, s[58:59]
	s_add_i32 m0, s4, 0x2000
	s_nop 0
	global_load_lds_dwordx4 v[226:227], off
	s_barrier
	s_waitcnt lgkmcnt(0)
	v_mfma_f32_16x16x32_bf16 v[124:127], v[208:211], v[160:163], v[124:127]
	v_mfma_f32_16x16x32_bf16 v[120:123], v[216:219], v[160:163], v[120:123]
	v_mfma_f32_16x16x32_bf16 v[108:111], v[208:211], v[172:175], v[108:111]
	v_mfma_f32_16x16x32_bf16 v[104:107], v[216:219], v[172:175], v[104:107]
	v_mfma_f32_16x16x32_bf16 v[92:95], v[208:211], v[180:183], v[92:95]
	v_mfma_f32_16x16x32_bf16 v[88:91], v[216:219], v[180:183], v[88:91]
	v_mfma_f32_16x16x32_bf16 v[76:79], v[208:211], v[200:203], v[76:79]
	v_mfma_f32_16x16x32_bf16 v[72:75], v[216:219], v[200:203], v[72:75]
	v_mfma_f32_16x16x32_bf16 v[124:127], v[212:215], v[164:167], v[124:127]
	v_mfma_f32_16x16x32_bf16 v[120:123], v[220:223], v[164:167], v[120:123]
	v_mfma_f32_16x16x32_bf16 v[108:111], v[212:215], v[176:179], v[108:111]
	v_mfma_f32_16x16x32_bf16 v[104:107], v[220:223], v[176:179], v[104:107]
	v_mfma_f32_16x16x32_bf16 v[92:95], v[212:215], v[196:199], v[92:95]
	v_mfma_f32_16x16x32_bf16 v[88:91], v[220:223], v[196:199], v[88:91]
	v_mfma_f32_16x16x32_bf16 v[76:79], v[212:215], v[204:207], v[76:79]
	v_mfma_f32_16x16x32_bf16 v[72:75], v[220:223], v[204:207], v[72:75]
	s_barrier
	s_mov_b32 m0, s31
	v_lshl_add_u64 v[226:227], v[224:225], 0, s[46:47]
	ds_read_b128 v[160:163], v146 offset:49152
	ds_read_b128 v[164:167], v146 offset:50176
	ds_read_b128 v[172:175], v146 offset:51200
	ds_read_b128 v[176:179], v146 offset:52224
	ds_read_b128 v[180:183], v146 offset:53248
	ds_read_b128 v[196:199], v146 offset:54272
	ds_read_b128 v[200:203], v146 offset:55296
	ds_read_b128 v[204:207], v146 offset:56320
	global_load_lds_dwordx4 v[226:227], off
	v_lshl_add_u64 v[224:225], v[224:225], 0, s[58:59]
	s_mov_b32 m0, s33
	s_nop 0
	global_load_lds_dwordx4 v[224:225], off
	s_barrier
	s_waitcnt lgkmcnt(0)
	v_mfma_f32_16x16x32_bf16 v[68:71], v[140:143], v[160:163], v[68:71]
	v_mfma_f32_16x16x32_bf16 v[64:67], v[152:155], v[160:163], v[64:67]
	v_mfma_f32_16x16x32_bf16 v[52:55], v[140:143], v[172:175], v[52:55]
	v_mfma_f32_16x16x32_bf16 v[48:51], v[152:155], v[172:175], v[48:51]
	v_mfma_f32_16x16x32_bf16 v[36:39], v[140:143], v[180:183], v[36:39]
	v_mfma_f32_16x16x32_bf16 v[32:35], v[152:155], v[180:183], v[32:35]
	v_mfma_f32_16x16x32_bf16 v[20:23], v[140:143], v[200:203], v[20:23]
	v_mfma_f32_16x16x32_bf16 v[16:19], v[152:155], v[200:203], v[16:19]
	v_mfma_f32_16x16x32_bf16 v[68:71], v[148:151], v[164:167], v[68:71]
	v_mfma_f32_16x16x32_bf16 v[64:67], v[156:159], v[164:167], v[64:67]
	v_mfma_f32_16x16x32_bf16 v[52:55], v[148:151], v[176:179], v[52:55]
	v_mfma_f32_16x16x32_bf16 v[48:51], v[156:159], v[176:179], v[48:51]
	v_mfma_f32_16x16x32_bf16 v[36:39], v[148:151], v[196:199], v[36:39]
	v_mfma_f32_16x16x32_bf16 v[32:35], v[156:159], v[196:199], v[32:35]
	v_mfma_f32_16x16x32_bf16 v[20:23], v[148:151], v[204:207], v[20:23]
	v_mfma_f32_16x16x32_bf16 v[16:19], v[156:159], v[204:207], v[16:19]
	s_barrier
	s_add_i32 s4, s5, s26
	v_lshl_add_u64 v[140:141], v[184:185], 0, s[50:51]
	s_mov_b32 m0, s4
	s_nop 0
	global_load_lds_dwordx4 v[140:141], off
	v_lshl_add_u64 v[140:141], v[184:185], 0, s[62:63]
	s_add_i32 m0, s4, 0x2000
	s_nop 0
	global_load_lds_dwordx4 v[140:141], off
	s_add_i32 s21, s21, 2
	s_add_u32 s6, s6, 0x100
	s_addc_u32 s7, s7, 0
	s_add_u32 s19, s19, 0x100
	s_addc_u32 s20, s20, 0
	s_cmp_gt_u32 s21, 5
	s_waitcnt vmcnt(6)
	s_barrier
	v_mfma_f32_16x16x32_bf16 v[60:63], v[208:211], v[160:163], v[60:63]
	v_mfma_f32_16x16x32_bf16 v[56:59], v[216:219], v[160:163], v[56:59]
	v_mfma_f32_16x16x32_bf16 v[44:47], v[208:211], v[172:175], v[44:47]
	v_mfma_f32_16x16x32_bf16 v[40:43], v[216:219], v[172:175], v[40:43]
	v_mfma_f32_16x16x32_bf16 v[28:31], v[208:211], v[180:183], v[28:31]
	v_mfma_f32_16x16x32_bf16 v[24:27], v[216:219], v[180:183], v[24:27]
	v_mfma_f32_16x16x32_bf16 v[12:15], v[208:211], v[200:203], v[12:15]
	v_mfma_f32_16x16x32_bf16 v[8:11], v[216:219], v[200:203], v[8:11]
	v_mfma_f32_16x16x32_bf16 v[60:63], v[212:215], v[164:167], v[60:63]
	v_mfma_f32_16x16x32_bf16 v[56:59], v[220:223], v[164:167], v[56:59]
	v_mfma_f32_16x16x32_bf16 v[44:47], v[212:215], v[176:179], v[44:47]
	v_mfma_f32_16x16x32_bf16 v[40:43], v[220:223], v[176:179], v[40:43]
	v_mfma_f32_16x16x32_bf16 v[28:31], v[212:215], v[196:199], v[28:31]
	v_mfma_f32_16x16x32_bf16 v[24:27], v[220:223], v[196:199], v[24:27]
	v_mfma_f32_16x16x32_bf16 v[12:15], v[212:215], v[204:207], v[12:15]
	v_mfma_f32_16x16x32_bf16 v[8:11], v[220:223], v[204:207], v[8:11]
	s_cbranch_scc0 .Ldb_SSM1_cont
	v_readfirstlane_b32 s101, v186
	s_cmpk_gt_u32 s101, 0xff
	s_cbranch_scc1 .Ldb_SSM1_young
	s_barrier
	s_mov_b32 s101, 1
	s_branch .Ldb_SSM1_exit

; #define G_STAGE(bufoff, gbase, o0, h64) do { \
;         __builtin_amdgcn_global_load_lds((const unsigned*)((const char*)(gbase) + (o0)), (LAS unsigned*)(lds + (bufoff) + ldsw), 16, 0, 0); \
;         __builtin_amdgcn_global_load_lds((const unsigned*)((const char*)(gbase) + (h64) + (o0)), (LAS unsigned*)(lds + (bufoff) + ldsw + 8192), 16, 0, 0); } while (0)
; #define G_LDA(dst, b, h) do { _Pragma("unroll") for (int m = 0; m < 4; ++m) _Pragma("unroll") for (int k = 0; k < 2; ++k) dst[m][k] = *(const LAS bf16x8*)(lds + G_SA(b, h) + aoff + m * 2048 + k * 1024); } while (0)
; #define G_LDB(dst, b, h) do { _Pragma("unroll") for (int n = 0; n < 2; ++n) _Pragma("unroll") for (int k = 0; k < 2; ++k) dst[n][k] = *(const LAS bf16x8*)(lds + G_SB(b, h) + boff + n * 2048 + k * 1024); } while (0)
; #define G_WAIT_L(n) asm volatile("s_waitcnt lgkmcnt(" #n ")" ::: "memory")
; #define G_BAR __builtin_amdgcn_s_barrier()
; #define G_SCHED __builtin_amdgcn_sched_barrier(0)
;     ...
;     f32x4 acc[2][2][4][2];
; #pragma unroll
;     for (int a = 0; a < 2; ++a)
; #pragma unroll
;         for (int b = 0; b < 2; ++b)
; #pragma unroll
;             for (int m = 0; m < 4; ++m)
; #pragma unroll
;                 for (int n = 0; n < 2; ++n) acc[a][b][m][n] = (f32x4){0.f, 0.f, 0.f, 0.f};
;     ...
;         for (int t = 0; t < nt; t += 2) {
;             const bool last = (t == nt - 2);
;             const char* a1 = cA + (size_t)(t + 1) * ckA;
;             const char* a2 = last ? nA : cA + (size_t)(t + 2) * ckA; const char* b2 = last ? nB : cB + (size_t)(t + 2) * kB;
;             const char* a3 = a2 + ckA; const char* b3 = b2 + kB;
;             G_LDB(B0, 0, 0); G_SCHED; G_LDA(At, 0, 0); G_STAGE(G_SA(1, 1), a1 + chA, cA0, qA);
;             G_WAIT_L(8); G_BAR; G_WAIT_L(0); G_MMA(0, 0, At, B0); G_BAR; G_SCHED;
;             G_LDB(B1, 0, 1); G_STAGE(G_SB(0, 0), b2, cB0, qB);
;             G_BAR; G_WAIT_L(0); G_MMA(0, 1, At, B1); G_BAR;
;             G_LDA(At, 0, 1); G_STAGE(G_SA(0, 0), a2, cA0, qA);
;             G_BAR; G_WAIT_L(0); G_MMA(1, 0, At, B0); G_BAR; G_SCHED;
.LBB0_741:
	v_mov_b64_e32 v[8:9], 0
	s_mov_b64 s[30:31], 0
	s_mov_b64 s[24:25], -1
	s_mov_b64 s[26:27], 0
	v_mov_b64_e32 v[10:11], 0
	v_mov_b64_e32 v[12:13], 0
	v_mov_b64_e32 v[14:15], 0
	v_mov_b64_e32 v[24:25], 0
	v_mov_b64_e32 v[26:27], 0
	v_mov_b64_e32 v[28:29], 0
	v_mov_b64_e32 v[30:31], 0
	v_mov_b64_e32 v[40:41], 0
	v_mov_b64_e32 v[42:43], 0
	v_mov_b64_e32 v[44:45], 0
	v_mov_b64_e32 v[46:47], 0
	v_mov_b64_e32 v[64:65], 0
	v_mov_b64_e32 v[66:67], 0
	v_mov_b64_e32 v[68:69], 0
	v_mov_b64_e32 v[70:71], 0
	v_mov_b64_e32 v[16:17], 0
	v_mov_b64_e32 v[18:19], 0
	v_mov_b64_e32 v[20:21], 0
	v_mov_b64_e32 v[22:23], 0
	v_mov_b64_e32 v[32:33], 0
	v_mov_b64_e32 v[34:35], 0
	v_mov_b64_e32 v[36:37], 0
	v_mov_b64_e32 v[38:39], 0
	v_mov_b64_e32 v[48:49], 0
	v_mov_b64_e32 v[50:51], 0
	v_mov_b64_e32 v[52:53], 0
	v_mov_b64_e32 v[54:55], 0
	v_mov_b64_e32 v[72:73], 0
	v_mov_b64_e32 v[74:75], 0
	v_mov_b64_e32 v[76:77], 0
	v_mov_b64_e32 v[78:79], 0
	v_mov_b64_e32 v[80:81], 0
	v_mov_b64_e32 v[82:83], 0
	v_mov_b64_e32 v[84:85], 0
	v_mov_b64_e32 v[86:87], 0
	v_mov_b64_e32 v[96:97], 0
	v_mov_b64_e32 v[98:99], 0
	v_mov_b64_e32 v[100:101], 0
	v_mov_b64_e32 v[102:103], 0
	v_mov_b64_e32 v[112:113], 0
	v_mov_b64_e32 v[114:115], 0
	v_mov_b64_e32 v[116:117], 0
	v_mov_b64_e32 v[118:119], 0
	v_mov_b64_e32 v[128:129], 0
	v_mov_b64_e32 v[130:131], 0
	v_mov_b64_e32 v[132:133], 0
	v_mov_b64_e32 v[134:135], 0
	v_mov_b64_e32 v[88:89], 0
	v_mov_b64_e32 v[90:91], 0
	v_mov_b64_e32 v[92:93], 0
	v_mov_b64_e32 v[94:95], 0
	v_mov_b64_e32 v[104:105], 0
	v_mov_b64_e32 v[106:107], 0
	v_mov_b64_e32 v[108:109], 0
	v_mov_b64_e32 v[110:111], 0
	v_mov_b64_e32 v[120:121], 0
	v_mov_b64_e32 v[122:123], 0
	v_mov_b64_e32 v[124:125], 0
	v_mov_b64_e32 v[126:127], 0
	v_mov_b64_e32 v[136:137], 0
	v_mov_b64_e32 v[138:139], 0
	v_mov_b64_e32 v[140:141], 0
	v_mov_b64_e32 v[142:143], 0
	s_mov_b64 s[82:83], 0x10000
	s_mov_b64 s[84:85], 0x10080
	s_mov_b64 s[86:87], 0x200000
	s_mov_b64 s[88:89], 0x100000
	s_mov_b64 s[92:93], 0x8000
	s_mov_b64 s[94:95], 0x18000
	s_mov_b64 s[96:97], 0x300000
	s_mov_b64 s[70:71], 0x8080
	s_mov_b64 s[68:69], 0x100080
	s_mov_b64 s[28:29], 0x18080
	s_cmp_eq_u32 s101, 2
	s_cselect_b32 s101, 0, s101
.LBB0_742:
	s_add_u32 s36, s2, s30
	s_addc_u32 s37, s3, s31
	s_add_u32 s19, s36, 0x100
	s_addc_u32 s35, s37, 0
	s_and_b64 s[4:5], s[26:27], exec
	s_cselect_b32 s34, s12, s19
	s_cselect_b32 s35, s13, s35
	s_add_u32 s4, s20, s30
	s_addc_u32 s5, s21, s31
	s_add_u32 s19, s4, 0x100
	s_addc_u32 s30, s5, 0
	s_add_i32 s44, 0, 0x10000
	v_add_u32_e32 v0, s44, v183
	ds_read_b128 v[56:59], v0
	ds_read_b128 v[60:63], v0 offset:1024
	ds_read_b128 v[144:147], v0 offset:2048
	ds_read_b128 v[148:151], v0 offset:3072
	s_and_b64 s[4:5], s[26:27], exec
	s_cselect_b32 s26, s16, s19
	s_cselect_b32 s27, s17, s30
	s_add_i32 s48, 0, 0x14000
	s_add_i32 s31, 0, 0x18000
	s_add_i32 s19, 0, 0x1c000
	s_add_i32 s49, s44, s38
	s_add_i32 s63, s48, s38
	s_add_i32 s30, s31, s38
	s_add_i32 s65, s19, s38
	s_add_i32 m0, s43, 0xc000
	s_add_i32 s45, s43, 0xe000
	s_add_i32 s66, s49, 0x2000
	s_add_i32 s62, s63, 0x2000
	s_add_i32 s67, s30, 0x2000
	s_add_i32 s64, s65, 0x2000
	v_lshl_add_u64 v[166:167], s[36:37], 0, v[160:161]
	s_mov_b64 s[4:5], 0x200080
	v_lshl_add_u64 v[180:181], v[166:167], 0, s[4:5]
	s_mov_b64 s[4:5], 0x300080
	ds_read_b128 v[152:155], v184
	ds_read_b128 v[156:159], v184 offset:1024
	ds_read_b128 v[162:165], v184 offset:2048
	ds_read_b128 v[172:175], v184 offset:3072
	ds_read_b128 v[176:179], v184 offset:4096
	ds_read_b128 v[196:199], v184 offset:5120
	ds_read_b128 v[200:203], v184 offset:6144
	ds_read_b128 v[204:207], v184 offset:7168
	global_load_lds_dwordx4 v[180:181], off
	v_lshl_add_u64 v[166:167], v[166:167], 0, s[4:5]
	s_mov_b32 m0, s45
	s_nop 0
	global_load_lds_dwordx4 v[166:167], off
	s_waitcnt lgkmcnt(8)
	s_cmp_eq_u32 s101, 1
	s_cbranch_scc1 .Ldb_SSM2_sk
	s_barrier
.Ldb_SSM2_sk:
	s_mov_b32 s101, 0
	s_waitcnt lgkmcnt(0)
	v_mfma_f32_16x16x32_bf16 v[140:143], v[56:59], v[152:155], v[140:143]
	v_mfma_f32_16x16x32_bf16 v[136:139], v[144:147], v[152:155], v[136:139]
	v_mfma_f32_16x16x32_bf16 v[124:127], v[56:59], v[162:165], v[124:127]
	v_mfma_f32_16x16x32_bf16 v[120:123], v[144:147], v[162:165], v[120:123]
	v_mfma_f32_16x16x32_bf16 v[108:111], v[56:59], v[176:179], v[108:111]
	v_mfma_f32_16x16x32_bf16 v[104:107], v[144:147], v[176:179], v[104:107]
	v_mfma_f32_16x16x32_bf16 v[92:95], v[56:59], v[200:203], v[92:95]
	v_mfma_f32_16x16x32_bf16 v[88:91], v[144:147], v[200:203], v[88:91]
	v_mfma_f32_16x16x32_bf16 v[140:143], v[60:63], v[156:159], v[140:143]
	v_mfma_f32_16x16x32_bf16 v[136:139], v[148:151], v[156:159], v[136:139]
	v_mfma_f32_16x16x32_bf16 v[124:127], v[60:63], v[172:175], v[124:127]
	v_mfma_f32_16x16x32_bf16 v[120:123], v[148:151], v[172:175], v[120:123]
	v_mfma_f32_16x16x32_bf16 v[108:111], v[60:63], v[196:199], v[108:111]
	v_mfma_f32_16x16x32_bf16 v[104:107], v[148:151], v[196:199], v[104:107]
	v_mfma_f32_16x16x32_bf16 v[92:95], v[60:63], v[204:207], v[92:95]
	v_mfma_f32_16x16x32_bf16 v[88:91], v[148:151], v[204:207], v[88:91]
	s_barrier
	s_mov_b32 m0, s49
	v_add_u32_e32 v0, s48, v183
	v_lshl_add_u64 v[166:167], s[26:27], 0, v[2:3]
	ds_read_b128 v[208:211], v0
	ds_read_b128 v[212:215], v0 offset:1024
	ds_read_b128 v[216:219], v0 offset:2048
	ds_read_b128 v[220:223], v0 offset:3072
	global_load_lds_dwordx4 v[166:167], off
	v_lshl_add_u64 v[180:181], v[166:167], 0, s[92:93]
	s_mov_b32 m0, s66
	s_nop 0
	global_load_lds_dwordx4 v[180:181], off
	s_barrier
; #define G_STAGE(bufoff, gbase, o0, h64) do { \
;         __builtin_amdgcn_global_load_lds((const unsigned*)((const char*)(gbase) + (o0)), (LAS unsigned*)(lds + (bufoff) + ldsw), 16, 0, 0); \
;         __builtin_amdgcn_global_load_lds((const unsigned*)((const char*)(gbase) + (h64) + (o0)), (LAS unsigned*)(lds + (bufoff) + ldsw + 8192), 16, 0, 0); } while (0)
; #define G_LDA(dst, b, h) do { _Pragma("unroll") for (int m = 0; m < 4; ++m) _Pragma("unroll") for (int k = 0; k < 2; ++k) dst[m][k] = *(const LAS bf16x8*)(lds + G_SA(b, h) + aoff + m * 2048 + k * 1024); } while (0)
; #define G_LDB(dst, b, h) do { _Pragma("unroll") for (int n = 0; n < 2; ++n) _Pragma("unroll") for (int k = 0; k < 2; ++k) dst[n][k] = *(const LAS bf16x8*)(lds + G_SB(b, h) + boff + n * 2048 + k * 1024); } while (0)
; #define G_WAIT_V(n) asm volatile("s_waitcnt vmcnt(" #n ")" ::: "memory")
; #define G_WAIT_L(n) asm volatile("s_waitcnt lgkmcnt(" #n ")" ::: "memory")
; #define G_BAR __builtin_amdgcn_s_barrier()
; #define G_SCHED __builtin_amdgcn_sched_barrier(0)
;     ...
;             G_BAR; G_WAIT_L(0); G_MMA(0, 1, At, B1); G_BAR;
;             G_LDA(At, 0, 1); G_STAGE(G_SA(0, 0), a2, cA0, qA);
;             G_BAR; G_WAIT_L(0); G_MMA(1, 0, At, B0); G_BAR; G_SCHED;
;             G_STAGE(G_SB(0, 1), b2 + chB, cB0, qB);
;             G_WAIT_V(6); G_BAR; G_MMA(1, 1, At, B1); G_BAR;
;             G_LDB(B0, 1, 0); G_SCHED; G_LDA(At, 1, 0); G_STAGE(G_SA(0, 1), a2 + chA, cA0, qA);
;             G_WAIT_L(8); G_BAR; G_WAIT_L(0); G_MMA(0, 0, At, B0); G_BAR; G_SCHED;
;             G_LDB(B1, 1, 1); G_STAGE(G_SB(1, 0), b3, cB0, qB);
;             G_BAR; G_WAIT_L(0); G_MMA(0, 1, At, B1); G_BAR;
	s_waitcnt lgkmcnt(0)
	v_mfma_f32_16x16x32_bf16 v[132:135], v[208:211], v[152:155], v[132:135]
	v_mfma_f32_16x16x32_bf16 v[128:131], v[216:219], v[152:155], v[128:131]
	v_mfma_f32_16x16x32_bf16 v[116:119], v[208:211], v[162:165], v[116:119]
	v_mfma_f32_16x16x32_bf16 v[112:115], v[216:219], v[162:165], v[112:115]
	v_mfma_f32_16x16x32_bf16 v[100:103], v[208:211], v[176:179], v[100:103]
	v_mfma_f32_16x16x32_bf16 v[96:99], v[216:219], v[176:179], v[96:99]
	v_mfma_f32_16x16x32_bf16 v[84:87], v[208:211], v[200:203], v[84:87]
	v_mfma_f32_16x16x32_bf16 v[80:83], v[216:219], v[200:203], v[80:83]
	v_mfma_f32_16x16x32_bf16 v[132:135], v[212:215], v[156:159], v[132:135]
	v_mfma_f32_16x16x32_bf16 v[128:131], v[220:223], v[156:159], v[128:131]
	v_mfma_f32_16x16x32_bf16 v[116:119], v[212:215], v[172:175], v[116:119]
	v_mfma_f32_16x16x32_bf16 v[112:115], v[220:223], v[172:175], v[112:115]
	v_mfma_f32_16x16x32_bf16 v[100:103], v[212:215], v[196:199], v[100:103]
	v_mfma_f32_16x16x32_bf16 v[96:99], v[220:223], v[196:199], v[96:99]
	v_mfma_f32_16x16x32_bf16 v[84:87], v[212:215], v[204:207], v[84:87]
	v_mfma_f32_16x16x32_bf16 v[80:83], v[220:223], v[204:207], v[80:83]
	s_barrier
	s_mov_b32 m0, s43
	v_lshl_add_u64 v[180:181], s[34:35], 0, v[160:161]
	ds_read_b128 v[152:155], v184 offset:16384
	ds_read_b128 v[156:159], v184 offset:17408
	ds_read_b128 v[162:165], v184 offset:18432
	ds_read_b128 v[172:175], v184 offset:19456
	ds_read_b128 v[176:179], v184 offset:20480
	ds_read_b128 v[196:199], v184 offset:21504
	ds_read_b128 v[200:203], v184 offset:22528
	ds_read_b128 v[204:207], v184 offset:23552
	global_load_lds_dwordx4 v[180:181], off
	v_lshl_add_u64 v[224:225], v[180:181], 0, s[88:89]
	s_mov_b32 m0, s50
	s_nop 0
	global_load_lds_dwordx4 v[224:225], off
	s_barrier
	s_waitcnt lgkmcnt(0)
	v_mfma_f32_16x16x32_bf16 v[76:79], v[56:59], v[152:155], v[76:79]
	v_mfma_f32_16x16x32_bf16 v[72:75], v[144:147], v[152:155], v[72:75]
	v_mfma_f32_16x16x32_bf16 v[52:55], v[56:59], v[162:165], v[52:55]
	v_mfma_f32_16x16x32_bf16 v[48:51], v[144:147], v[162:165], v[48:51]
	v_mfma_f32_16x16x32_bf16 v[36:39], v[56:59], v[176:179], v[36:39]
	v_mfma_f32_16x16x32_bf16 v[32:35], v[144:147], v[176:179], v[32:35]
	v_mfma_f32_16x16x32_bf16 v[20:23], v[56:59], v[200:203], v[20:23]
	v_mfma_f32_16x16x32_bf16 v[16:19], v[144:147], v[200:203], v[16:19]
	v_mfma_f32_16x16x32_bf16 v[76:79], v[60:63], v[156:159], v[76:79]
	v_mfma_f32_16x16x32_bf16 v[72:75], v[148:151], v[156:159], v[72:75]
	v_mfma_f32_16x16x32_bf16 v[52:55], v[60:63], v[172:175], v[52:55]
	v_mfma_f32_16x16x32_bf16 v[48:51], v[148:151], v[172:175], v[48:51]
	v_mfma_f32_16x16x32_bf16 v[36:39], v[60:63], v[196:199], v[36:39]
	v_mfma_f32_16x16x32_bf16 v[32:35], v[148:151], v[196:199], v[32:35]
	v_mfma_f32_16x16x32_bf16 v[20:23], v[60:63], v[204:207], v[20:23]
	v_mfma_f32_16x16x32_bf16 v[16:19], v[148:151], v[204:207], v[16:19]
	s_barrier
	s_mov_b32 m0, s63
	v_lshl_add_u64 v[56:57], v[166:167], 0, s[82:83]
	global_load_lds_dwordx4 v[56:57], off
	v_lshl_add_u64 v[56:57], v[166:167], 0, s[94:95]
	s_mov_b32 m0, s62
	s_nop 0
	global_load_lds_dwordx4 v[56:57], off
	s_waitcnt vmcnt(6)
	s_barrier
	v_mfma_f32_16x16x32_bf16 v[44:47], v[208:211], v[162:165], v[44:47]
	v_mfma_f32_16x16x32_bf16 v[40:43], v[216:219], v[162:165], v[40:43]
	v_mfma_f32_16x16x32_bf16 v[28:31], v[208:211], v[176:179], v[28:31]
	v_mfma_f32_16x16x32_bf16 v[24:27], v[216:219], v[176:179], v[24:27]
	v_mfma_f32_16x16x32_bf16 v[12:15], v[208:211], v[200:203], v[12:15]
	v_mfma_f32_16x16x32_bf16 v[8:11], v[216:219], v[200:203], v[8:11]
	v_mfma_f32_16x16x32_bf16 v[56:59], v[208:211], v[152:155], v[68:71]
	v_mfma_f32_16x16x32_bf16 v[60:63], v[216:219], v[152:155], v[64:67]
	v_mfma_f32_16x16x32_bf16 v[44:47], v[212:215], v[172:175], v[44:47]
	v_mfma_f32_16x16x32_bf16 v[40:43], v[220:223], v[172:175], v[40:43]
	v_mfma_f32_16x16x32_bf16 v[28:31], v[212:215], v[196:199], v[28:31]
	v_mfma_f32_16x16x32_bf16 v[24:27], v[220:223], v[196:199], v[24:27]
	v_mfma_f32_16x16x32_bf16 v[12:15], v[212:215], v[204:207], v[12:15]
	v_mfma_f32_16x16x32_bf16 v[8:11], v[220:223], v[204:207], v[8:11]
	v_mfma_f32_16x16x32_bf16 v[56:59], v[212:215], v[156:159], v[56:59]
	v_mfma_f32_16x16x32_bf16 v[60:63], v[220:223], v[156:159], v[60:63]
	s_barrier
	v_add_u32_e32 v0, s31, v183
	ds_read_b128 v[64:67], v0
	ds_read_b128 v[68:71], v0 offset:1024
	ds_read_b128 v[144:147], v0 offset:2048
	ds_read_b128 v[148:151], v0 offset:3072
	s_mov_b32 m0, s51
	v_lshl_add_u64 v[208:209], v[180:181], 0, s[86:87]
	ds_read_b128 v[152:155], v184 offset:32768
	ds_read_b128 v[156:159], v184 offset:33792
	ds_read_b128 v[162:165], v184 offset:34816
	ds_read_b128 v[172:175], v184 offset:35840
	ds_read_b128 v[176:179], v184 offset:36864
	ds_read_b128 v[196:199], v184 offset:37888
	ds_read_b128 v[200:203], v184 offset:38912
	ds_read_b128 v[204:207], v184 offset:39936
	global_load_lds_dwordx4 v[208:209], off
	v_lshl_add_u64 v[208:209], v[180:181], 0, s[96:97]
	s_mov_b32 m0, s52
	s_nop 0
	global_load_lds_dwordx4 v[208:209], off
	s_waitcnt lgkmcnt(8)
	s_barrier
; #define G_STAGE(bufoff, gbase, o0, h64) do { \
;         __builtin_amdgcn_global_load_lds((const unsigned*)((const char*)(gbase) + (o0)), (LAS unsigned*)(lds + (bufoff) + ldsw), 16, 0, 0); \
;         __builtin_amdgcn_global_load_lds((const unsigned*)((const char*)(gbase) + (h64) + (o0)), (LAS unsigned*)(lds + (bufoff) + ldsw + 8192), 16, 0, 0); } while (0)
; #define G_LDA(dst, b, h) do { _Pragma("unroll") for (int m = 0; m < 4; ++m) _Pragma("unroll") for (int k = 0; k < 2; ++k) dst[m][k] = *(const LAS bf16x8*)(lds + G_SA(b, h) + aoff + m * 2048 + k * 1024); } while (0)
; #define G_WAIT_V(n) asm volatile("s_waitcnt vmcnt(" #n ")" ::: "memory")
; #define G_WAIT_L(n) asm volatile("s_waitcnt lgkmcnt(" #n ")" ::: "memory")
; #define G_BAR __builtin_amdgcn_s_barrier()
; #define G_SCHED __builtin_amdgcn_sched_barrier(0)
;     ...
;             G_BAR; G_WAIT_L(0); G_MMA(0, 1, At, B1); G_BAR;
;             G_LDA(At, 1, 1); G_STAGE(G_SA(1, 0), a3, cA0, qA);
;             G_BAR; G_WAIT_L(0); G_MMA(1, 0, At, B0); G_BAR; G_SCHED;
;             G_STAGE(G_SB(1, 1), b3 + chB, cB0, qB);
;             G_WAIT_V(6); G_BAR; G_MMA(1, 1, At, B1); G_BAR;
;         }
;         E.template run<cs.kind>(acc, cur, tid);
;         if (!has_next) break;
	s_waitcnt lgkmcnt(0)
	v_mfma_f32_16x16x32_bf16 v[140:143], v[64:67], v[152:155], v[140:143]
	v_mfma_f32_16x16x32_bf16 v[136:139], v[144:147], v[152:155], v[136:139]
	v_mfma_f32_16x16x32_bf16 v[124:127], v[64:67], v[162:165], v[124:127]
	v_mfma_f32_16x16x32_bf16 v[120:123], v[144:147], v[162:165], v[120:123]
	v_mfma_f32_16x16x32_bf16 v[108:111], v[64:67], v[176:179], v[108:111]
	v_mfma_f32_16x16x32_bf16 v[104:107], v[144:147], v[176:179], v[104:107]
	v_mfma_f32_16x16x32_bf16 v[92:95], v[64:67], v[200:203], v[92:95]
	v_mfma_f32_16x16x32_bf16 v[88:91], v[144:147], v[200:203], v[88:91]
	v_mfma_f32_16x16x32_bf16 v[140:143], v[68:71], v[156:159], v[140:143]
	v_mfma_f32_16x16x32_bf16 v[136:139], v[148:151], v[156:159], v[136:139]
	v_mfma_f32_16x16x32_bf16 v[124:127], v[68:71], v[172:175], v[124:127]
	v_mfma_f32_16x16x32_bf16 v[120:123], v[148:151], v[172:175], v[120:123]
	v_mfma_f32_16x16x32_bf16 v[108:111], v[68:71], v[196:199], v[108:111]
	v_mfma_f32_16x16x32_bf16 v[104:107], v[148:151], v[196:199], v[104:107]
	v_mfma_f32_16x16x32_bf16 v[92:95], v[68:71], v[204:207], v[92:95]
	v_mfma_f32_16x16x32_bf16 v[88:91], v[148:151], v[204:207], v[88:91]
	s_barrier
	s_mov_b32 m0, s30
	v_add_u32_e32 v0, s19, v183
	v_lshl_add_u64 v[224:225], v[166:167], 0, s[46:47]
	ds_read_b128 v[208:211], v0
	ds_read_b128 v[212:215], v0 offset:1024
	ds_read_b128 v[216:219], v0 offset:2048
	ds_read_b128 v[220:223], v0 offset:3072
	global_load_lds_dwordx4 v[224:225], off
	v_lshl_add_u64 v[224:225], v[166:167], 0, s[70:71]
	s_mov_b32 m0, s67
	s_nop 0
	global_load_lds_dwordx4 v[224:225], off
	s_barrier
	s_waitcnt lgkmcnt(0)
	v_mfma_f32_16x16x32_bf16 v[132:135], v[208:211], v[152:155], v[132:135]
	v_mfma_f32_16x16x32_bf16 v[128:131], v[216:219], v[152:155], v[128:131]
	v_mfma_f32_16x16x32_bf16 v[116:119], v[208:211], v[162:165], v[116:119]
	v_mfma_f32_16x16x32_bf16 v[112:115], v[216:219], v[162:165], v[112:115]
	v_mfma_f32_16x16x32_bf16 v[100:103], v[208:211], v[176:179], v[100:103]
	v_mfma_f32_16x16x32_bf16 v[96:99], v[216:219], v[176:179], v[96:99]
	v_mfma_f32_16x16x32_bf16 v[84:87], v[208:211], v[200:203], v[84:87]
	v_mfma_f32_16x16x32_bf16 v[80:83], v[216:219], v[200:203], v[80:83]
	v_mfma_f32_16x16x32_bf16 v[132:135], v[212:215], v[156:159], v[132:135]
	v_mfma_f32_16x16x32_bf16 v[128:131], v[220:223], v[156:159], v[128:131]
	v_mfma_f32_16x16x32_bf16 v[116:119], v[212:215], v[172:175], v[116:119]
	v_mfma_f32_16x16x32_bf16 v[112:115], v[220:223], v[172:175], v[112:115]
	v_mfma_f32_16x16x32_bf16 v[100:103], v[212:215], v[196:199], v[100:103]
	v_mfma_f32_16x16x32_bf16 v[96:99], v[220:223], v[196:199], v[96:99]
	v_mfma_f32_16x16x32_bf16 v[84:87], v[212:215], v[204:207], v[84:87]
	v_mfma_f32_16x16x32_bf16 v[80:83], v[220:223], v[204:207], v[80:83]
	s_barrier
	s_mov_b32 m0, s53
	v_lshl_add_u64 v[224:225], v[180:181], 0, s[46:47]
	ds_read_b128 v[152:155], v184 offset:49152
	ds_read_b128 v[156:159], v184 offset:50176
	ds_read_b128 v[162:165], v184 offset:51200
	ds_read_b128 v[172:175], v184 offset:52224
	ds_read_b128 v[176:179], v184 offset:53248
	ds_read_b128 v[196:199], v184 offset:54272
	ds_read_b128 v[200:203], v184 offset:55296
	ds_read_b128 v[204:207], v184 offset:56320
	global_load_lds_dwordx4 v[224:225], off
	v_lshl_add_u64 v[180:181], v[180:181], 0, s[68:69]
	s_mov_b32 m0, s54
	s_nop 0
	global_load_lds_dwordx4 v[180:181], off
	s_barrier
	s_waitcnt lgkmcnt(0)
	v_mfma_f32_16x16x32_bf16 v[76:79], v[64:67], v[152:155], v[76:79]
	v_mfma_f32_16x16x32_bf16 v[72:75], v[144:147], v[152:155], v[72:75]
	v_mfma_f32_16x16x32_bf16 v[52:55], v[64:67], v[162:165], v[52:55]
	v_mfma_f32_16x16x32_bf16 v[48:51], v[144:147], v[162:165], v[48:51]
	v_mfma_f32_16x16x32_bf16 v[36:39], v[64:67], v[176:179], v[36:39]
	v_mfma_f32_16x16x32_bf16 v[32:35], v[144:147], v[176:179], v[32:35]
	v_mfma_f32_16x16x32_bf16 v[20:23], v[64:67], v[200:203], v[20:23]
	v_mfma_f32_16x16x32_bf16 v[16:19], v[144:147], v[200:203], v[16:19]
	v_mfma_f32_16x16x32_bf16 v[76:79], v[68:71], v[156:159], v[76:79]
	v_mfma_f32_16x16x32_bf16 v[72:75], v[148:151], v[156:159], v[72:75]
	v_mfma_f32_16x16x32_bf16 v[52:55], v[68:71], v[172:175], v[52:55]
	v_mfma_f32_16x16x32_bf16 v[48:51], v[148:151], v[172:175], v[48:51]
	v_mfma_f32_16x16x32_bf16 v[36:39], v[68:71], v[196:199], v[36:39]
	v_mfma_f32_16x16x32_bf16 v[32:35], v[148:151], v[196:199], v[32:35]
	v_mfma_f32_16x16x32_bf16 v[20:23], v[68:71], v[204:207], v[20:23]
	v_mfma_f32_16x16x32_bf16 v[16:19], v[148:151], v[204:207], v[16:19]
	s_barrier
	s_mov_b32 m0, s65
	v_lshl_add_u64 v[64:65], v[166:167], 0, s[84:85]
	global_load_lds_dwordx4 v[64:65], off
	v_lshl_add_u64 v[64:65], v[166:167], 0, s[28:29]
	s_mov_b32 m0, s64
	s_nop 0
	global_load_lds_dwordx4 v[64:65], off
	s_waitcnt vmcnt(6)
	s_barrier
	v_mfma_f32_16x16x32_bf16 v[56:59], v[208:211], v[152:155], v[56:59]
	v_mfma_f32_16x16x32_bf16 v[68:71], v[212:215], v[156:159], v[56:59]
	v_mfma_f32_16x16x32_bf16 v[56:59], v[216:219], v[152:155], v[60:63]
	v_mfma_f32_16x16x32_bf16 v[44:47], v[208:211], v[162:165], v[44:47]
	v_mfma_f32_16x16x32_bf16 v[40:43], v[216:219], v[162:165], v[40:43]
	v_mfma_f32_16x16x32_bf16 v[28:31], v[208:211], v[176:179], v[28:31]
	v_mfma_f32_16x16x32_bf16 v[24:27], v[216:219], v[176:179], v[24:27]
	v_mfma_f32_16x16x32_bf16 v[12:15], v[208:211], v[200:203], v[12:15]
	v_mfma_f32_16x16x32_bf16 v[8:11], v[216:219], v[200:203], v[8:11]
	v_mfma_f32_16x16x32_bf16 v[64:67], v[220:223], v[156:159], v[56:59]
	v_mfma_f32_16x16x32_bf16 v[44:47], v[212:215], v[172:175], v[44:47]
	v_mfma_f32_16x16x32_bf16 v[40:43], v[220:223], v[172:175], v[40:43]
	v_mfma_f32_16x16x32_bf16 v[28:31], v[212:215], v[196:199], v[28:31]
	v_mfma_f32_16x16x32_bf16 v[24:27], v[220:223], v[196:199], v[24:27]
	v_mfma_f32_16x16x32_bf16 v[12:15], v[212:215], v[204:207], v[12:15]
	v_mfma_f32_16x16x32_bf16 v[8:11], v[220:223], v[204:207], v[8:11]
	s_andn2_b64 vcc, exec, s[24:25]
	s_mov_b64 s[26:27], -1
	s_mov_b64 s[24:25], 0
	s_mov_b64 s[30:31], 0x100
	s_cbranch_vccz .Ldb_SSM2_cont
	v_readfirstlane_b32 s101, v186
	s_cmpk_gt_u32 s101, 0xff
	s_cbranch_scc1 .Ldb_SSM2_young
	s_barrier
	s_mov_b32 s101, 1
	s_branch .Ldb_SSM2_exit

; __device__ __forceinline__ float gelu_tanh(float y) { const float z = 1.5957691216057308f * (y + 0.044715f * y * y * y); return y * sigmoidf_(z); }
; __device__ __forceinline__ u32x4 pack8(const f32x4 a, const f32x4 b) { u32x4 w; w.x = cvt_pk_bf16(a[0], a[1]); w.y = cvt_pk_bf16(a[2], a[3]); w.z = cvt_pk_bf16(b[0], b[1]); w.w = cvt_pk_bf16(b[2], b[3]); return w; }
; __device__ __forceinline__ void unpack8(const u32x4 w, f32x4& a, f32x4& b) { a[0] = bf_lo(w.x); a[1] = bf_hi(w.x); a[2] = bf_lo(w.y); a[3] = bf_hi(w.y); b[0] = bf_lo(w.z); b[1] = bf_hi(w.z); b[2] = bf_lo(w.w); b[3] = bf_hi(w.w); }
;     template <int KIND> __device__ __forceinline__ void run(f32x4 (&acc)[2][2][4][2], const Unit& u, int tid_in) const {
;     ...
;         if constexpr (KIND == K_SSM2) { const int g = u.aux; const int ch = g * 16 + 8 * (fq & 1); const f32x4 d0 = *(const f32x4*)(dskip + ch), d1 = *(const f32x4*)(dskip + ch + 4);
; #pragma unroll
;             for (int ai = 0; ai < 2; ++ai)
; #pragma unroll
;                 for (int mh = 0; mh < 2; ++mh) { u32x4 yv[2][2], uv[2][2];
; #pragma unroll
;                     for (int ml = 0; ml < 2; ++ml) { int R = rbase + ai * 128 + (mh * 2 + ml) * 16; asm volatile("" : "+v"(R));
; #pragma unroll
;                         for (int bj = 0; bj < 2; ++bj) { const int t = 16 * u.pn + 8 * bj + 2 * wc + (fq >> 1); const size_t tok = (size_t)R * LCH + t;
;                             yv[ml][bj] = *(const u32x4*)(yi + ((size_t)g * T_TOK + tok) * 16 + 8 * (fq & 1)); uv[ml][bj] = *(const u32x4*)((const bf16_t*)x + ((size_t)g * T_TOK + tok) * 16 + 8 * (fq & 1)); } }
; #pragma unroll
;                     for (int ml = 0; ml < 2; ++ml) { const int m = mh * 2 + ml; int R = rbase + ai * 128 + m * 16; asm volatile("" : "+v"(R));
; #pragma unroll
;                         for (int bj = 0; bj < 2; ++bj) { const int t = 16 * u.pn + 8 * bj + 2 * wc + (fq >> 1); const size_t tok = (size_t)R * LCH + t;
;                             f32x4 y0, y1, u0, u1; unpack8(yv[ml][bj], y0, y1); unpack8(uv[ml][bj], u0, u1);
;                             y0 = acc[ai][bj][m][0] + y0 + d0 * u0; y1 = acc[ai][bj][m][1] + y1 + d1 * u1;
; #pragma unroll
;                             for (int j = 0; j < 4; ++j) { y0[j] = gelu_tanh(y0[j]); y1[j] = gelu_tanh(y1[j]); }
;                             *(u32x4*)(yi + ((size_t)g * T_TOK + tok) * 16 + 8 * (fq & 1)) = pack8(y0, y1); } }
.Ldb_SSM2_exit:
	v_mov_b32_e32 v0, v182
	s_lshl_b32 s3, s23, 8
	v_readfirstlane_b32 s2, v0
	s_ashr_i32 s4, s2, 2
	v_lshrrev_b32_e32 v56, 1, v0
	s_andn2_b32 s4, s4, 63
	v_and_b32_e32 v144, 8, v56
	s_add_i32 s4, s4, s3
	v_lshl_or_b32 v56, s22, 4, v144
	s_lshr_b32 s2, s2, 5
	v_and_or_b32 v185, v0, 15, s4
	v_ashrrev_i32_e32 v57, 31, v56
	s_and_b32 s2, s2, 6
	v_lshrrev_b32_e32 v0, 5, v0
	v_lshl_add_u64 v[60:61], v[56:57], 2, s[6:7]
	v_and_or_b32 v145, v0, 1, s2
	v_lshlrev_b32_e32 v0, 1, v144
	v_mov_b32_e32 v144, v185
	global_load_dwordx4 v[56:59], v[60:61], off offset:16
	s_nop 0
	global_load_dwordx4 v[60:63], v[60:61], off
	s_ashr_i32 s23, s22, 31
	v_lshl_or_b32 v212, s33, 4, v145
	v_ashrrev_i32_e32 v145, 31, v144
	s_lshl_b64 s[20:21], s[22:23], 19
	v_lshlrev_b64 v[144:145], 9, v[144:145]
	v_ashrrev_i32_e32 v213, 31, v212
	v_lshl_add_u64 v[144:145], v[144:145], 0, s[20:21]
	v_lshlrev_b64 v[172:173], 4, v[212:213]
	v_lshl_add_u64 v[146:147], v[144:145], 0, v[172:173]
	v_lshl_add_u64 v[164:165], s[10:11], 0, v[0:1]
	v_lshlrev_b64 v[146:147], 1, v[146:147]
	v_lshl_add_u64 v[148:149], v[164:165], 0, v[146:147]
	v_lshl_add_u64 v[166:167], s[8:9], 0, v[0:1]
	global_load_dwordx4 v[196:199], v[148:149], off
	v_lshl_add_u64 v[146:147], v[166:167], 0, v[146:147]
	global_load_dwordx4 v[200:203], v[146:147], off
	v_or_b32_e32 v176, 8, v212
	v_ashrrev_i32_e32 v177, 31, v176
	v_lshlrev_b64 v[174:175], 4, v[176:177]
	v_lshl_add_u64 v[144:145], v[174:175], 0, v[144:145]
	v_lshlrev_b64 v[144:145], 1, v[144:145]
	v_lshl_add_u64 v[148:149], v[164:165], 0, v[144:145]
	v_lshl_add_u64 v[144:145], v[166:167], 0, v[144:145]
	global_load_dwordx4 v[204:207], v[148:149], off
	global_load_dwordx4 v[208:211], v[144:145], off
	v_or_b32_e32 v178, 16, v185
	s_lshl_b64 s[2:3], s[22:23], 20
	v_mov_b32_e32 v146, v178
	s_add_u32 s2, s10, s2
	s_addc_u32 s3, s11, s3
	v_ashrrev_i32_e32 v147, 31, v146
	v_lshlrev_b64 v[144:145], 9, v[146:147]
	v_lshl_add_u64 v[162:163], s[2:3], 0, v[0:1]
	v_lshl_add_u64 v[144:145], v[144:145], 0, s[20:21]
	v_lshl_add_u64 v[146:147], v[144:145], 0, v[172:173]
	v_lshl_add_u64 v[144:145], v[144:145], 0, v[174:175]
	v_lshlrev_b64 v[146:147], 1, v[146:147]
	v_lshlrev_b64 v[144:145], 1, v[144:145]
	v_lshl_add_u64 v[148:149], v[164:165], 0, v[146:147]
	v_lshl_add_u64 v[146:147], v[166:167], 0, v[146:147]
	v_lshl_add_u64 v[150:151], v[164:165], 0, v[144:145]
	v_lshl_add_u64 v[144:145], v[166:167], 0, v[144:145]
	global_load_dwordx4 v[156:159], v[148:149], off
	global_load_dwordx4 v[152:155], v[146:147], off
	s_nop 0
	global_load_dwordx4 v[148:151], v[150:151], off
	s_nop 0
	global_load_dwordx4 v[144:147], v[144:145], off
	v_mov_b32_e32 v180, v185
	v_readlane_b32 s48, v230, 5
	v_ashrrev_i32_e32 v181, 31, v180
	v_lshlrev_b64 v[180:181], 10, v[180:181]
	v_lshl_add_u64 v[180:181], v[162:163], 0, v[180:181]
	v_readlane_b32 s49, v230, 6
	v_readlane_b32 s44, v230, 7
	s_and_b64 vcc, exec, s[14:15]
	s_mov_b32 s22, s18
	s_mov_b32 s33, s59
	s_mov_b32 s23, s58
	s_mov_b64 s[2:3], s[12:13]
	v_readlane_b32 s45, v230, 8
	s_movk_i32 s49, 0x4000
	s_mov_b64 s[68:69], 0x18080
	s_mov_b64 s[70:71], 0x800
	s_mov_b64 s[82:83], 0x1800
	s_mov_b64 s[84:85], 0x400800
	s_mov_b64 s[86:87], 0x58000
	s_mov_b64 s[88:89], 0xb0000
	s_mov_b64 s[64:65], 0x108000
	s_mov_b64 s[66:67], 0x58080
	s_mov_b32 s28, s74
	s_waitcnt vmcnt(0)
	v_lshlrev_b32_e32 v214, 16, v196
	v_and_b32_e32 v215, 0xffff0000, v196
	v_lshlrev_b32_e32 v216, 16, v198
	v_and_b32_e32 v217, 0xffff0000, v198
	v_lshlrev_b32_e32 v218, 16, v200
	v_and_b32_e32 v219, 0xffff0000, v200
	v_lshlrev_b32_e32 v220, 16, v202
	v_and_b32_e32 v221, 0xffff0000, v202
	v_pk_add_f32 v[140:141], v[140:141], v[214:215]
	v_pk_add_f32 v[136:137], v[136:137], v[216:217]
	v_pk_fma_f32 v[140:141], v[60:61], v[218:219], v[140:141]
	v_pk_fma_f32 v[136:137], v[56:57], v[220:221], v[136:137]
	v_mul_f32_e32 v0, 0x3d372713, v140
	v_mul_f32_e32 v179, 0x3d372713, v136
	v_mul_f32_e32 v195, 0x3d372713, v141
	v_mul_f32_e32 v0, v140, v0
	v_mul_f32_e32 v179, v136, v179
	v_mul_f32_e32 v195, v141, v195
	v_fma_f32 v0, v140, v0, v140
	v_fma_f32 v179, v136, v179, v136
	v_fma_f32 v195, v141, v195, v141
	v_mul_f32_e32 v0, 0x3fcc422a, v0
	v_mul_f32_e32 v179, 0x3fcc422a, v179
	v_mul_f32_e32 v195, 0x3fcc422a, v195
	v_mul_f32_e32 v0, 0xbfb8aa3b, v0
	v_mul_f32_e32 v179, 0xbfb8aa3b, v179
	v_mul_f32_e32 v195, 0xbfb8aa3b, v195
	v_exp_f32_e32 v0, v0
	v_exp_f32_e32 v179, v179
	v_exp_f32_e32 v195, v195
	v_lshlrev_b32_e32 v196, 16, v197
	v_and_b32_e32 v197, 0xffff0000, v197
	v_pk_add_f32 v[142:143], v[142:143], v[196:197]
	v_add_f32_e32 v0, 1.0, v0
	v_add_f32_e32 v179, 1.0, v179
	v_add_f32_e32 v195, 1.0, v195
	v_mul_f32_e32 v196, 0x3d372713, v137
	v_rcp_f32_e32 v0, v0
	v_rcp_f32_e32 v179, v179
	v_rcp_f32_e32 v195, v195
	v_mul_f32_e32 v196, v137, v196
	v_lshlrev_b32_e32 v198, 16, v199
	v_and_b32_e32 v199, 0xffff0000, v199
	v_fma_f32 v196, v137, v196, v137
	v_lshlrev_b32_e32 v200, 16, v201
	v_and_b32_e32 v201, 0xffff0000, v201
	v_lshlrev_b32_e32 v202, 16, v203
	v_and_b32_e32 v203, 0xffff0000, v203
	v_pk_add_f32 v[138:139], v[138:139], v[198:199]
	v_mul_f32_e32 v196, 0x3fcc422a, v196
	v_pk_fma_f32 v[142:143], v[62:63], v[200:201], v[142:143]
	v_pk_fma_f32 v[138:139], v[58:59], v[202:203], v[138:139]
	v_mul_f32_e32 v196, 0xbfb8aa3b, v196
	v_exp_f32_e32 v196, v196
	v_mul_f32_e32 v0, v140, v0
	v_mul_f32_e32 v136, v136, v179
	v_mul_f32_e32 v140, v141, v195
	v_mul_f32_e32 v179, 0x3d372713, v142
	v_mul_f32_e32 v195, 0x3d372713, v138
	v_mul_f32_e32 v179, v142, v179
	v_mul_f32_e32 v195, v138, v195
	v_fma_f32 v179, v142, v179, v142
	v_fma_f32 v195, v138, v195, v138
	v_mul_f32_e32 v179, 0x3fcc422a, v179
; __device__ __forceinline__ float gelu_tanh(float y) { const float z = 1.5957691216057308f * (y + 0.044715f * y * y * y); return y * sigmoidf_(z); }
; __device__ __forceinline__ u32x4 pack8(const f32x4 a, const f32x4 b) { u32x4 w; w.x = cvt_pk_bf16(a[0], a[1]); w.y = cvt_pk_bf16(a[2], a[3]); w.z = cvt_pk_bf16(b[0], b[1]); w.w = cvt_pk_bf16(b[2], b[3]); return w; }
; __device__ __forceinline__ void unpack8(const u32x4 w, f32x4& a, f32x4& b) { a[0] = bf_lo(w.x); a[1] = bf_hi(w.x); a[2] = bf_lo(w.y); a[3] = bf_hi(w.y); b[0] = bf_lo(w.z); b[1] = bf_hi(w.z); b[2] = bf_lo(w.w); b[3] = bf_hi(w.w); }
;     template <int KIND> __device__ __forceinline__ void run(f32x4 (&acc)[2][2][4][2], const Unit& u, int tid_in) const {
;     ...
;                         for (int bj = 0; bj < 2; ++bj) { const int t = 16 * u.pn + 8 * bj + 2 * wc + (fq >> 1); const size_t tok = (size_t)R * LCH + t;
;                             yv[ml][bj] = *(const u32x4*)(yi + ((size_t)g * T_TOK + tok) * 16 + 8 * (fq & 1)); uv[ml][bj] = *(const u32x4*)((const bf16_t*)x + ((size_t)g * T_TOK + tok) * 16 + 8 * (fq & 1)); } }
; #pragma unroll
;                     for (int ml = 0; ml < 2; ++ml) { const int m = mh * 2 + ml; int R = rbase + ai * 128 + m * 16; asm volatile("" : "+v"(R));
; #pragma unroll
;                         for (int bj = 0; bj < 2; ++bj) { const int t = 16 * u.pn + 8 * bj + 2 * wc + (fq >> 1); const size_t tok = (size_t)R * LCH + t;
;                             f32x4 y0, y1, u0, u1; unpack8(yv[ml][bj], y0, y1); unpack8(uv[ml][bj], u0, u1);
;                             y0 = acc[ai][bj][m][0] + y0 + d0 * u0; y1 = acc[ai][bj][m][1] + y1 + d1 * u1;
; #pragma unroll
;                             for (int j = 0; j < 4; ++j) { y0[j] = gelu_tanh(y0[j]); y1[j] = gelu_tanh(y1[j]); }
;                             *(u32x4*)(yi + ((size_t)g * T_TOK + tok) * 16 + 8 * (fq & 1)) = pack8(y0, y1); } }
	v_mul_f32_e32 v195, 0x3fcc422a, v195
	v_add_f32_e32 v141, 1.0, v196
	v_mul_f32_e32 v179, 0xbfb8aa3b, v179
	v_mul_f32_e32 v195, 0xbfb8aa3b, v195
	v_rcp_f32_e32 v141, v141
	v_exp_f32_e32 v179, v179
	v_exp_f32_e32 v195, v195
	v_mul_f32_e32 v196, 0x3d372713, v139
	v_mul_f32_e32 v137, v137, v141
	v_add_f32_e32 v141, 1.0, v179
	v_add_f32_e32 v179, 1.0, v195
	v_mul_f32_e32 v195, 0x3d372713, v143
	v_mul_f32_e32 v195, v143, v195
	v_mul_f32_e32 v196, v139, v196
	v_fma_f32 v195, v143, v195, v143
	v_fma_f32 v196, v139, v196, v139
	v_mul_f32_e32 v195, 0x3fcc422a, v195
	v_mul_f32_e32 v196, 0x3fcc422a, v196
	v_mul_f32_e32 v195, 0xbfb8aa3b, v195
	v_mul_f32_e32 v196, 0xbfb8aa3b, v196
	v_exp_f32_e32 v195, v195
	v_exp_f32_e32 v196, v196
	v_rcp_f32_e32 v141, v141
	v_rcp_f32_e32 v179, v179
	v_add_f32_e32 v195, 1.0, v195
	v_add_f32_e32 v196, 1.0, v196
	v_rcp_f32_e32 v195, v195
	v_rcp_f32_e32 v196, v196
	v_mul_f32_e32 v141, v142, v141
	v_mul_f32_e32 v142, v138, v179
	v_mul_f32_e32 v143, v143, v195
	v_mul_f32_e32 v179, v139, v196
	v_cvt_pk_bf16_f32 v138, v0, v140
	v_cvt_pk_bf16_f32 v139, v141, v143
	v_cvt_pk_bf16_f32 v140, v136, v137
	v_lshlrev_b64 v[136:137], 5, v[212:213]
	v_cvt_pk_bf16_f32 v141, v142, v179
	v_lshl_add_u64 v[142:143], v[180:181], 0, v[136:137]
	global_store_dwordx4 v[142:143], v[138:141], off
	v_lshlrev_b32_e32 v142, 16, v206
	v_and_b32_e32 v143, 0xffff0000, v206
	v_lshlrev_b32_e32 v138, 16, v204
	v_and_b32_e32 v139, 0xffff0000, v204
	v_lshlrev_b32_e32 v198, 16, v208
	v_and_b32_e32 v199, 0xffff0000, v208
	v_lshlrev_b32_e32 v202, 16, v210
	v_and_b32_e32 v203, 0xffff0000, v210
	v_pk_add_f32 v[132:133], v[132:133], v[138:139]
	v_pk_add_f32 v[128:129], v[128:129], v[142:143]
	v_pk_fma_f32 v[132:133], v[60:61], v[198:199], v[132:133]
	v_pk_fma_f32 v[128:129], v[56:57], v[202:203], v[128:129]
	v_mul_f32_e32 v0, 0x3d372713, v132
	v_mul_f32_e32 v138, 0x3d372713, v128
	v_mul_f32_e32 v139, 0x3d372713, v133
	v_mul_f32_e32 v0, v132, v0
	v_mul_f32_e32 v138, v128, v138
	v_mul_f32_e32 v139, v133, v139
	v_fma_f32 v0, v132, v0, v132
	v_fma_f32 v138, v128, v138, v128
	v_fma_f32 v139, v133, v139, v133
	v_mul_f32_e32 v0, 0x3fcc422a, v0
	v_mul_f32_e32 v138, 0x3fcc422a, v138
	v_mul_f32_e32 v139, 0x3fcc422a, v139
	v_mul_f32_e32 v0, 0xbfb8aa3b, v0
	v_mul_f32_e32 v138, 0xbfb8aa3b, v138
	v_mul_f32_e32 v139, 0xbfb8aa3b, v139
	v_exp_f32_e32 v0, v0
	v_exp_f32_e32 v138, v138
	v_exp_f32_e32 v139, v139
	v_lshlrev_b32_e32 v140, 16, v205
	v_and_b32_e32 v141, 0xffff0000, v205
	v_pk_add_f32 v[134:135], v[134:135], v[140:141]
	v_add_f32_e32 v0, 1.0, v0
	v_add_f32_e32 v138, 1.0, v138
	v_add_f32_e32 v139, 1.0, v139
	v_mul_f32_e32 v140, 0x3d372713, v129
	v_rcp_f32_e32 v0, v0
	v_rcp_f32_e32 v138, v138
	v_rcp_f32_e32 v139, v139
	v_mul_f32_e32 v140, v129, v140
	v_lshlrev_b32_e32 v196, 16, v207
	v_and_b32_e32 v197, 0xffff0000, v207
	v_fma_f32 v140, v129, v140, v129
	v_lshlrev_b32_e32 v200, 16, v209
	v_and_b32_e32 v201, 0xffff0000, v209
	v_lshlrev_b32_e32 v204, 16, v211
	v_and_b32_e32 v205, 0xffff0000, v211
	v_pk_add_f32 v[130:131], v[130:131], v[196:197]
	v_mul_f32_e32 v140, 0x3fcc422a, v140
	v_pk_fma_f32 v[134:135], v[62:63], v[200:201], v[134:135]
	v_pk_fma_f32 v[130:131], v[58:59], v[204:205], v[130:131]
	v_mul_f32_e32 v140, 0xbfb8aa3b, v140
	v_exp_f32_e32 v140, v140
	v_mul_f32_e32 v0, v132, v0
	v_mul_f32_e32 v128, v128, v138
	v_mul_f32_e32 v132, v133, v139
	v_mul_f32_e32 v138, 0x3d372713, v134
	v_mul_f32_e32 v139, 0x3d372713, v130
	v_mul_f32_e32 v138, v134, v138
	v_mul_f32_e32 v139, v130, v139
	v_fma_f32 v138, v134, v138, v134
	v_fma_f32 v139, v130, v139, v130
	v_mul_f32_e32 v138, 0x3fcc422a, v138
	v_mul_f32_e32 v139, 0x3fcc422a, v139
	v_add_f32_e32 v133, 1.0, v140
	v_mul_f32_e32 v138, 0xbfb8aa3b, v138
	v_mul_f32_e32 v139, 0xbfb8aa3b, v139
	v_rcp_f32_e32 v133, v133
	v_exp_f32_e32 v138, v138
	v_exp_f32_e32 v139, v139
	v_mul_f32_e32 v140, 0x3d372713, v131
	v_mul_f32_e32 v129, v129, v133
	v_add_f32_e32 v133, 1.0, v138
	v_add_f32_e32 v138, 1.0, v139
	v_mul_f32_e32 v139, 0x3d372713, v135
	v_mul_f32_e32 v139, v135, v139
	v_mul_f32_e32 v140, v131, v140
	v_fma_f32 v139, v135, v139, v135
	v_fma_f32 v140, v131, v140, v131
	v_mul_f32_e32 v139, 0x3fcc422a, v139
	v_mul_f32_e32 v140, 0x3fcc422a, v140
	v_mul_f32_e32 v139, 0xbfb8aa3b, v139
	v_mul_f32_e32 v140, 0xbfb8aa3b, v140
	v_exp_f32_e32 v139, v139
	v_exp_f32_e32 v140, v140
	v_rcp_f32_e32 v133, v133
	v_rcp_f32_e32 v138, v138
	v_add_f32_e32 v139, 1.0, v139
	v_add_f32_e32 v140, 1.0, v140
	v_rcp_f32_e32 v139, v139
	v_rcp_f32_e32 v140, v140
	v_mul_f32_e32 v133, v134, v133
	v_mul_f32_e32 v134, v130, v138
	v_mul_f32_e32 v135, v135, v139
	v_mul_f32_e32 v138, v131, v140
	v_cvt_pk_bf16_f32 v130, v0, v132
	v_cvt_pk_bf16_f32 v131, v133, v135
	v_cvt_pk_bf16_f32 v132, v128, v129
	v_lshlrev_b64 v[128:129], 5, v[176:177]
	v_cvt_pk_bf16_f32 v133, v134, v138
	v_lshl_add_u64 v[134:135], v[180:181], 0, v[128:129]
	global_store_dwordx4 v[134:135], v[130:133], off
	v_lshlrev_b32_e32 v138, 16, v158
	v_and_b32_e32 v139, 0xffff0000, v158
	v_lshlrev_b32_e32 v132, 16, v156
	v_and_b32_e32 v133, 0xffff0000, v156
	v_lshlrev_b32_e32 v134, 16, v157
	v_and_b32_e32 v135, 0xffff0000, v157
	v_lshlrev_b32_e32 v142, 16, v152
	v_and_b32_e32 v143, 0xffff0000, v152
	v_lshlrev_b32_e32 v156, 16, v154
	v_and_b32_e32 v157, 0xffff0000, v154
	v_pk_add_f32 v[124:125], v[124:125], v[132:133]
	v_pk_add_f32 v[120:121], v[120:121], v[138:139]
	v_pk_fma_f32 v[124:125], v[60:61], v[142:143], v[124:125]
	v_pk_fma_f32 v[120:121], v[56:57], v[156:157], v[120:121]
	v_mul_f32_e32 v0, 0x3d372713, v124
	v_mul_f32_e32 v132, 0x3d372713, v120
	v_mul_f32_e32 v133, 0x3d372713, v125
	v_mul_f32_e32 v0, v124, v0
; __device__ __forceinline__ float gelu_tanh(float y) { const float z = 1.5957691216057308f * (y + 0.044715f * y * y * y); return y * sigmoidf_(z); }
; __device__ __forceinline__ u32x4 pack8(const f32x4 a, const f32x4 b) { u32x4 w; w.x = cvt_pk_bf16(a[0], a[1]); w.y = cvt_pk_bf16(a[2], a[3]); w.z = cvt_pk_bf16(b[0], b[1]); w.w = cvt_pk_bf16(b[2], b[3]); return w; }
; __device__ __forceinline__ void unpack8(const u32x4 w, f32x4& a, f32x4& b) { a[0] = bf_lo(w.x); a[1] = bf_hi(w.x); a[2] = bf_lo(w.y); a[3] = bf_hi(w.y); b[0] = bf_lo(w.z); b[1] = bf_hi(w.z); b[2] = bf_lo(w.w); b[3] = bf_hi(w.w); }
;     template <int KIND> __device__ __forceinline__ void run(f32x4 (&acc)[2][2][4][2], const Unit& u, int tid_in) const {
;     ...
;                         for (int bj = 0; bj < 2; ++bj) { const int t = 16 * u.pn + 8 * bj + 2 * wc + (fq >> 1); const size_t tok = (size_t)R * LCH + t;
;                             yv[ml][bj] = *(const u32x4*)(yi + ((size_t)g * T_TOK + tok) * 16 + 8 * (fq & 1)); uv[ml][bj] = *(const u32x4*)((const bf16_t*)x + ((size_t)g * T_TOK + tok) * 16 + 8 * (fq & 1)); } }
; #pragma unroll
;                     for (int ml = 0; ml < 2; ++ml) { const int m = mh * 2 + ml; int R = rbase + ai * 128 + m * 16; asm volatile("" : "+v"(R));
; #pragma unroll
;                         for (int bj = 0; bj < 2; ++bj) { const int t = 16 * u.pn + 8 * bj + 2 * wc + (fq >> 1); const size_t tok = (size_t)R * LCH + t;
;                             f32x4 y0, y1, u0, u1; unpack8(yv[ml][bj], y0, y1); unpack8(uv[ml][bj], u0, u1);
;                             y0 = acc[ai][bj][m][0] + y0 + d0 * u0; y1 = acc[ai][bj][m][1] + y1 + d1 * u1;
; #pragma unroll
;                             for (int j = 0; j < 4; ++j) { y0[j] = gelu_tanh(y0[j]); y1[j] = gelu_tanh(y1[j]); }
;                             *(u32x4*)(yi + ((size_t)g * T_TOK + tok) * 16 + 8 * (fq & 1)) = pack8(y0, y1); } }
	v_mul_f32_e32 v132, v120, v132
	v_mul_f32_e32 v133, v125, v133
	v_fma_f32 v0, v124, v0, v124
	v_fma_f32 v132, v120, v132, v120
	v_fma_f32 v133, v125, v133, v125
	v_mul_f32_e32 v0, 0x3fcc422a, v0
	v_mul_f32_e32 v132, 0x3fcc422a, v132
	v_mul_f32_e32 v133, 0x3fcc422a, v133
	v_mul_f32_e32 v0, 0xbfb8aa3b, v0
	v_mul_f32_e32 v132, 0xbfb8aa3b, v132
	v_mul_f32_e32 v133, 0xbfb8aa3b, v133
	v_exp_f32_e32 v0, v0
	v_exp_f32_e32 v132, v132
	v_exp_f32_e32 v133, v133
	v_pk_add_f32 v[126:127], v[126:127], v[134:135]
	v_add_f32_e32 v0, 1.0, v0
	v_add_f32_e32 v132, 1.0, v132
	v_add_f32_e32 v133, 1.0, v133
	v_mul_f32_e32 v134, 0x3d372713, v121
	v_rcp_f32_e32 v0, v0
	v_rcp_f32_e32 v132, v132
	v_rcp_f32_e32 v133, v133
	v_mul_f32_e32 v134, v121, v134
	v_lshlrev_b32_e32 v140, 16, v159
	v_and_b32_e32 v141, 0xffff0000, v159
	v_fma_f32 v134, v121, v134, v121
	v_lshlrev_b32_e32 v152, 16, v153
	v_and_b32_e32 v153, 0xffff0000, v153
	v_lshlrev_b32_e32 v154, 16, v155
	v_and_b32_e32 v155, 0xffff0000, v155
	v_pk_add_f32 v[122:123], v[122:123], v[140:141]
	v_mul_f32_e32 v134, 0x3fcc422a, v134
	v_pk_fma_f32 v[126:127], v[62:63], v[152:153], v[126:127]
	v_pk_fma_f32 v[122:123], v[58:59], v[154:155], v[122:123]
	v_mul_f32_e32 v134, 0xbfb8aa3b, v134
	v_exp_f32_e32 v134, v134
	v_mul_f32_e32 v0, v124, v0
	v_mul_f32_e32 v124, v120, v132
	v_mul_f32_e32 v120, v125, v133
	v_mul_f32_e32 v132, 0x3d372713, v126
	v_mul_f32_e32 v133, 0x3d372713, v122
	v_mul_f32_e32 v132, v126, v132
	v_mul_f32_e32 v133, v122, v133
	v_fma_f32 v132, v126, v132, v126
	v_fma_f32 v133, v122, v133, v122
	v_mul_f32_e32 v132, 0x3fcc422a, v132
	v_mul_f32_e32 v133, 0x3fcc422a, v133
	v_add_f32_e32 v125, 1.0, v134
	v_mul_f32_e32 v132, 0xbfb8aa3b, v132
	v_mul_f32_e32 v133, 0xbfb8aa3b, v133
	v_rcp_f32_e32 v125, v125
	v_exp_f32_e32 v132, v132
	v_exp_f32_e32 v133, v133
	v_mul_f32_e32 v134, 0x3d372713, v123
	v_mul_f32_e32 v125, v121, v125
	v_add_f32_e32 v121, 1.0, v132
	v_add_f32_e32 v132, 1.0, v133
	v_mul_f32_e32 v133, 0x3d372713, v127
	v_mul_f32_e32 v133, v127, v133
	v_fma_f32 v133, v127, v133, v127
	v_mul_f32_e32 v134, v123, v134
	v_mul_f32_e32 v133, 0x3fcc422a, v133
	v_fma_f32 v134, v123, v134, v123
	v_mul_f32_e32 v133, 0xbfb8aa3b, v133
	v_mul_f32_e32 v134, 0x3fcc422a, v134
	v_exp_f32_e32 v133, v133
	v_mul_f32_e32 v134, 0xbfb8aa3b, v134
	v_exp_f32_e32 v134, v134
	v_rcp_f32_e32 v121, v121
	v_add_f32_e32 v133, 1.0, v133
	v_rcp_f32_e32 v132, v132
	v_rcp_f32_e32 v133, v133
	v_add_f32_e32 v134, 1.0, v134
	v_rcp_f32_e32 v134, v134
	v_mul_f32_e32 v121, v126, v121
	v_ashrrev_i32_e32 v179, 31, v178
	v_lshlrev_b64 v[130:131], 10, v[178:179]
	v_lshl_add_u64 v[130:131], v[162:163], 0, v[130:131]
	v_mul_f32_e32 v126, v122, v132
	v_mul_f32_e32 v122, v127, v133
	v_mul_f32_e32 v123, v123, v134
	v_cvt_pk_bf16_f32 v120, v0, v120
	v_cvt_pk_bf16_f32 v121, v121, v122
	v_cvt_pk_bf16_f32 v122, v124, v125
	v_lshl_add_u64 v[124:125], v[130:131], 0, v[136:137]
	v_cvt_pk_bf16_f32 v123, v126, v123
	global_store_dwordx4 v[124:125], v[120:123], off
	v_lshlrev_b32_e32 v124, 16, v150
	v_and_b32_e32 v125, 0xffff0000, v150
	v_lshlrev_b32_e32 v120, 16, v148
	v_and_b32_e32 v121, 0xffff0000, v148
	v_lshlrev_b32_e32 v132, 16, v144
	v_and_b32_e32 v133, 0xffff0000, v144
	v_lshlrev_b32_e32 v138, 16, v146
	v_and_b32_e32 v139, 0xffff0000, v146
	v_pk_add_f32 v[116:117], v[116:117], v[120:121]
	v_pk_add_f32 v[112:113], v[112:113], v[124:125]
	v_pk_fma_f32 v[116:117], v[60:61], v[132:133], v[116:117]
	v_pk_fma_f32 v[112:113], v[56:57], v[138:139], v[112:113]
	v_mul_f32_e32 v0, 0x3d372713, v116
	v_mul_f32_e32 v120, 0x3d372713, v112
	v_mul_f32_e32 v121, 0x3d372713, v117
	v_mul_f32_e32 v0, v116, v0
	v_mul_f32_e32 v120, v112, v120
	v_mul_f32_e32 v121, v117, v121
	v_fma_f32 v0, v116, v0, v116
	v_fma_f32 v120, v112, v120, v112
	v_fma_f32 v121, v117, v121, v117
	v_mul_f32_e32 v0, 0x3fcc422a, v0
	v_mul_f32_e32 v120, 0x3fcc422a, v120
	v_mul_f32_e32 v121, 0x3fcc422a, v121
	v_mul_f32_e32 v0, 0xbfb8aa3b, v0
	v_mul_f32_e32 v120, 0xbfb8aa3b, v120
	v_mul_f32_e32 v121, 0xbfb8aa3b, v121
	v_exp_f32_e32 v0, v0
	v_exp_f32_e32 v120, v120
	v_exp_f32_e32 v121, v121
	v_lshlrev_b32_e32 v122, 16, v149
	v_and_b32_e32 v123, 0xffff0000, v149
	v_pk_add_f32 v[118:119], v[118:119], v[122:123]
	v_add_f32_e32 v0, 1.0, v0
	v_add_f32_e32 v120, 1.0, v120
	v_add_f32_e32 v121, 1.0, v121
	v_mul_f32_e32 v122, 0x3d372713, v113
	v_rcp_f32_e32 v0, v0
	v_rcp_f32_e32 v120, v120
	v_rcp_f32_e32 v121, v121
	v_mul_f32_e32 v122, v113, v122
	v_lshlrev_b32_e32 v126, 16, v151
	v_and_b32_e32 v127, 0xffff0000, v151
	v_fma_f32 v122, v113, v122, v113
	v_lshlrev_b32_e32 v134, 16, v145
	v_and_b32_e32 v135, 0xffff0000, v145
	v_lshlrev_b32_e32 v140, 16, v147
	v_and_b32_e32 v141, 0xffff0000, v147
	v_pk_add_f32 v[114:115], v[114:115], v[126:127]
	v_mul_f32_e32 v122, 0x3fcc422a, v122
	v_pk_fma_f32 v[118:119], v[62:63], v[134:135], v[118:119]
	v_pk_fma_f32 v[114:115], v[58:59], v[140:141], v[114:115]
	v_mul_f32_e32 v122, 0xbfb8aa3b, v122
	v_exp_f32_e32 v122, v122
	v_mul_f32_e32 v0, v116, v0
	v_mul_f32_e32 v116, v112, v120
	v_mul_f32_e32 v112, v117, v121
	v_mul_f32_e32 v120, 0x3d372713, v118
	v_mul_f32_e32 v121, 0x3d372713, v114
	v_mul_f32_e32 v120, v118, v120
	v_mul_f32_e32 v121, v114, v121
	v_fma_f32 v120, v118, v120, v118
	v_fma_f32 v121, v114, v121, v114
	v_mul_f32_e32 v120, 0x3fcc422a, v120
	v_mul_f32_e32 v121, 0x3fcc422a, v121
	v_add_f32_e32 v117, 1.0, v122
	v_mul_f32_e32 v120, 0xbfb8aa3b, v120
	v_mul_f32_e32 v121, 0xbfb8aa3b, v121
	v_rcp_f32_e32 v117, v117
	v_exp_f32_e32 v120, v120
	v_exp_f32_e32 v121, v121
	v_mul_f32_e32 v122, 0x3d372713, v115
	v_mul_f32_e32 v117, v113, v117
	v_add_f32_e32 v113, 1.0, v120
; __device__ __forceinline__ float gelu_tanh(float y) { const float z = 1.5957691216057308f * (y + 0.044715f * y * y * y); return y * sigmoidf_(z); }
; __device__ __forceinline__ u32x4 pack8(const f32x4 a, const f32x4 b) { u32x4 w; w.x = cvt_pk_bf16(a[0], a[1]); w.y = cvt_pk_bf16(a[2], a[3]); w.z = cvt_pk_bf16(b[0], b[1]); w.w = cvt_pk_bf16(b[2], b[3]); return w; }
; __device__ __forceinline__ void unpack8(const u32x4 w, f32x4& a, f32x4& b) { a[0] = bf_lo(w.x); a[1] = bf_hi(w.x); a[2] = bf_lo(w.y); a[3] = bf_hi(w.y); b[0] = bf_lo(w.z); b[1] = bf_hi(w.z); b[2] = bf_lo(w.w); b[3] = bf_hi(w.w); }
;     template <int KIND> __device__ __forceinline__ void run(f32x4 (&acc)[2][2][4][2], const Unit& u, int tid_in) const {
;     ...
;                 for (int mh = 0; mh < 2; ++mh) { u32x4 yv[2][2], uv[2][2];
; #pragma unroll
;                     for (int ml = 0; ml < 2; ++ml) { int R = rbase + ai * 128 + (mh * 2 + ml) * 16; asm volatile("" : "+v"(R));
; #pragma unroll
;                         for (int bj = 0; bj < 2; ++bj) { const int t = 16 * u.pn + 8 * bj + 2 * wc + (fq >> 1); const size_t tok = (size_t)R * LCH + t;
;                             yv[ml][bj] = *(const u32x4*)(yi + ((size_t)g * T_TOK + tok) * 16 + 8 * (fq & 1)); uv[ml][bj] = *(const u32x4*)((const bf16_t*)x + ((size_t)g * T_TOK + tok) * 16 + 8 * (fq & 1)); } }
; #pragma unroll
;                     for (int ml = 0; ml < 2; ++ml) { const int m = mh * 2 + ml; int R = rbase + ai * 128 + m * 16; asm volatile("" : "+v"(R));
; #pragma unroll
;                         for (int bj = 0; bj < 2; ++bj) { const int t = 16 * u.pn + 8 * bj + 2 * wc + (fq >> 1); const size_t tok = (size_t)R * LCH + t;
;                             f32x4 y0, y1, u0, u1; unpack8(yv[ml][bj], y0, y1); unpack8(uv[ml][bj], u0, u1);
;                             y0 = acc[ai][bj][m][0] + y0 + d0 * u0; y1 = acc[ai][bj][m][1] + y1 + d1 * u1;
; #pragma unroll
;                             for (int j = 0; j < 4; ++j) { y0[j] = gelu_tanh(y0[j]); y1[j] = gelu_tanh(y1[j]); }
;                             *(u32x4*)(yi + ((size_t)g * T_TOK + tok) * 16 + 8 * (fq & 1)) = pack8(y0, y1); } }
	v_add_f32_e32 v120, 1.0, v121
	v_mul_f32_e32 v121, 0x3d372713, v119
	v_mul_f32_e32 v121, v119, v121
	v_fma_f32 v121, v119, v121, v119
	v_mul_f32_e32 v122, v115, v122
	v_mul_f32_e32 v121, 0x3fcc422a, v121
	v_fma_f32 v122, v115, v122, v115
	v_mul_f32_e32 v121, 0xbfb8aa3b, v121
	v_mul_f32_e32 v122, 0x3fcc422a, v122
	v_exp_f32_e32 v121, v121
	v_mul_f32_e32 v122, 0xbfb8aa3b, v122
	v_exp_f32_e32 v122, v122
	v_rcp_f32_e32 v113, v113
	v_add_f32_e32 v121, 1.0, v121
	v_rcp_f32_e32 v120, v120
	v_rcp_f32_e32 v121, v121
	v_add_f32_e32 v122, 1.0, v122
	v_rcp_f32_e32 v122, v122
	v_mul_f32_e32 v113, v118, v113
	v_mul_f32_e32 v118, v114, v120
	v_mul_f32_e32 v114, v119, v121
	v_mul_f32_e32 v115, v115, v122
	v_cvt_pk_bf16_f32 v112, v0, v112
	v_cvt_pk_bf16_f32 v113, v113, v114
	v_cvt_pk_bf16_f32 v114, v116, v117
	v_lshl_add_u64 v[116:117], v[130:131], 0, v[128:129]
	v_or_b32_e32 v132, 32, v185
	v_cvt_pk_bf16_f32 v115, v118, v115
	global_store_dwordx4 v[116:117], v[112:115], off
	v_or_b32_e32 v130, 48, v185
	s_nop 0
	v_mov_b32_e32 v112, v132
	s_nop 0
	v_ashrrev_i32_e32 v113, 31, v112
	v_lshlrev_b64 v[112:113], 9, v[112:113]
	v_lshl_add_u64 v[112:113], v[112:113], 0, s[20:21]
	v_lshl_add_u64 v[114:115], v[112:113], 0, v[172:173]
	v_lshlrev_b64 v[114:115], 1, v[114:115]
	v_lshl_add_u64 v[116:117], v[164:165], 0, v[114:115]
	global_load_dwordx4 v[138:141], v[116:117], off
	v_lshl_add_u64 v[114:115], v[166:167], 0, v[114:115]
	global_load_dwordx4 v[142:145], v[114:115], off
	v_lshl_add_u64 v[112:113], v[112:113], 0, v[174:175]
	v_lshlrev_b64 v[112:113], 1, v[112:113]
	v_lshl_add_u64 v[114:115], v[164:165], 0, v[112:113]
	global_load_dwordx4 v[146:149], v[114:115], off
	v_lshl_add_u64 v[112:113], v[166:167], 0, v[112:113]
	global_load_dwordx4 v[150:153], v[112:113], off
	v_mov_b32_e32 v112, v130
	s_waitcnt vmcnt(0)
	v_lshlrev_b32_e32 v134, 16, v138
	v_ashrrev_i32_e32 v113, 31, v112
	v_lshlrev_b64 v[112:113], 9, v[112:113]
	v_lshl_add_u64 v[112:113], v[112:113], 0, s[20:21]
	v_and_b32_e32 v135, 0xffff0000, v138
	v_lshlrev_b32_e32 v154, 16, v140
	v_and_b32_e32 v155, 0xffff0000, v140
	v_lshl_add_u64 v[114:115], v[112:113], 0, v[172:173]
	v_lshlrev_b32_e32 v156, 16, v142
	v_and_b32_e32 v157, 0xffff0000, v142
	v_lshlrev_b32_e32 v158, 16, v144
	v_and_b32_e32 v159, 0xffff0000, v144
	v_pk_add_f32 v[108:109], v[108:109], v[134:135]
	v_pk_add_f32 v[104:105], v[104:105], v[154:155]
	v_lshlrev_b64 v[114:115], 1, v[114:115]
	v_pk_fma_f32 v[108:109], v[60:61], v[156:157], v[108:109]
	v_pk_fma_f32 v[104:105], v[56:57], v[158:159], v[104:105]
	v_lshl_add_u64 v[116:117], v[164:165], 0, v[114:115]
	v_mul_f32_e32 v0, 0x3d372713, v108
	v_mul_f32_e32 v131, 0x3d372713, v104
	v_mul_f32_e32 v134, 0x3d372713, v109
	global_load_dwordx4 v[124:127], v[116:117], off
	v_lshl_add_u64 v[114:115], v[166:167], 0, v[114:115]
	v_mul_f32_e32 v0, v108, v0
	v_mul_f32_e32 v131, v104, v131
	v_mul_f32_e32 v134, v109, v134
	global_load_dwordx4 v[120:123], v[114:115], off
	v_fma_f32 v0, v108, v0, v108
	v_fma_f32 v131, v104, v131, v104
	v_fma_f32 v134, v109, v134, v109
	v_mul_f32_e32 v0, 0x3fcc422a, v0
	v_mul_f32_e32 v131, 0x3fcc422a, v131
	v_mul_f32_e32 v134, 0x3fcc422a, v134
	v_mul_f32_e32 v0, 0xbfb8aa3b, v0
	v_mul_f32_e32 v131, 0xbfb8aa3b, v131
	v_mul_f32_e32 v134, 0xbfb8aa3b, v134
	v_exp_f32_e32 v0, v0
	v_exp_f32_e32 v131, v131
	v_exp_f32_e32 v134, v134
	v_mul_f32_e32 v135, 0x3d372713, v105
	v_add_f32_e32 v0, 1.0, v0
	v_add_f32_e32 v131, 1.0, v131
	v_add_f32_e32 v134, 1.0, v134
	v_rcp_f32_e32 v0, v0
	v_rcp_f32_e32 v131, v131
	v_rcp_f32_e32 v134, v134
	v_mul_f32_e32 v135, v105, v135
	v_lshlrev_b32_e32 v138, 16, v139
	v_and_b32_e32 v139, 0xffff0000, v139
	v_lshlrev_b32_e32 v140, 16, v141
	v_and_b32_e32 v141, 0xffff0000, v141
	v_fma_f32 v135, v105, v135, v105
	v_lshlrev_b32_e32 v142, 16, v143
	v_and_b32_e32 v143, 0xffff0000, v143
	v_lshlrev_b32_e32 v144, 16, v145
	v_and_b32_e32 v145, 0xffff0000, v145
	v_pk_add_f32 v[110:111], v[110:111], v[138:139]
	v_pk_add_f32 v[106:107], v[106:107], v[140:141]
	v_mul_f32_e32 v135, 0x3fcc422a, v135
	v_pk_fma_f32 v[110:111], v[62:63], v[142:143], v[110:111]
	v_pk_fma_f32 v[106:107], v[58:59], v[144:145], v[106:107]
	v_mul_f32_e32 v135, 0xbfb8aa3b, v135
	v_exp_f32_e32 v135, v135
	v_mul_f32_e32 v0, v108, v0
	v_mul_f32_e32 v108, v104, v131
	v_mul_f32_e32 v104, v109, v134
	v_mul_f32_e32 v131, 0x3d372713, v110
	v_mul_f32_e32 v134, 0x3d372713, v106
	v_mul_f32_e32 v131, v110, v131
	v_mul_f32_e32 v134, v106, v134
	v_fma_f32 v131, v110, v131, v110
	v_fma_f32 v134, v106, v134, v106
	v_mul_f32_e32 v131, 0x3fcc422a, v131
	v_mul_f32_e32 v134, 0x3fcc422a, v134
	v_add_f32_e32 v109, 1.0, v135
	v_mul_f32_e32 v131, 0xbfb8aa3b, v131
	v_mul_f32_e32 v134, 0xbfb8aa3b, v134
	v_rcp_f32_e32 v109, v109
	v_exp_f32_e32 v131, v131
	v_exp_f32_e32 v134, v134
	v_mul_f32_e32 v135, 0x3d372713, v107
	v_mul_f32_e32 v109, v105, v109
	v_add_f32_e32 v105, 1.0, v131
	v_add_f32_e32 v131, 1.0, v134
	v_mul_f32_e32 v134, 0x3d372713, v111
	v_mul_f32_e32 v134, v111, v134
	v_fma_f32 v134, v111, v134, v111
	v_mul_f32_e32 v135, v107, v135
	v_mul_f32_e32 v134, 0x3fcc422a, v134
	v_fma_f32 v135, v107, v135, v107
	v_mul_f32_e32 v134, 0xbfb8aa3b, v134
	v_mul_f32_e32 v135, 0x3fcc422a, v135
	v_exp_f32_e32 v134, v134
	v_mul_f32_e32 v135, 0xbfb8aa3b, v135
	v_exp_f32_e32 v135, v135
	v_lshl_add_u64 v[112:113], v[112:113], 0, v[174:175]
	v_add_f32_e32 v134, 1.0, v134
	v_lshlrev_b64 v[112:113], 1, v[112:113]
	v_rcp_f32_e32 v105, v105
	v_rcp_f32_e32 v131, v131
	v_rcp_f32_e32 v134, v134
	v_add_f32_e32 v135, 1.0, v135
	v_lshl_add_u64 v[114:115], v[164:165], 0, v[112:113]
	v_lshl_add_u64 v[112:113], v[166:167], 0, v[112:113]
; __device__ __forceinline__ float gelu_tanh(float y) { const float z = 1.5957691216057308f * (y + 0.044715f * y * y * y); return y * sigmoidf_(z); }
; __device__ __forceinline__ u32x4 pack8(const f32x4 a, const f32x4 b) { u32x4 w; w.x = cvt_pk_bf16(a[0], a[1]); w.y = cvt_pk_bf16(a[2], a[3]); w.z = cvt_pk_bf16(b[0], b[1]); w.w = cvt_pk_bf16(b[2], b[3]); return w; }
; __device__ __forceinline__ void unpack8(const u32x4 w, f32x4& a, f32x4& b) { a[0] = bf_lo(w.x); a[1] = bf_hi(w.x); a[2] = bf_lo(w.y); a[3] = bf_hi(w.y); b[0] = bf_lo(w.z); b[1] = bf_hi(w.z); b[2] = bf_lo(w.w); b[3] = bf_hi(w.w); }
;     template <int KIND> __device__ __forceinline__ void run(f32x4 (&acc)[2][2][4][2], const Unit& u, int tid_in) const {
;     ...
;                         for (int bj = 0; bj < 2; ++bj) { const int t = 16 * u.pn + 8 * bj + 2 * wc + (fq >> 1); const size_t tok = (size_t)R * LCH + t;
;                             yv[ml][bj] = *(const u32x4*)(yi + ((size_t)g * T_TOK + tok) * 16 + 8 * (fq & 1)); uv[ml][bj] = *(const u32x4*)((const bf16_t*)x + ((size_t)g * T_TOK + tok) * 16 + 8 * (fq & 1)); } }
; #pragma unroll
;                     for (int ml = 0; ml < 2; ++ml) { const int m = mh * 2 + ml; int R = rbase + ai * 128 + m * 16; asm volatile("" : "+v"(R));
; #pragma unroll
;                         for (int bj = 0; bj < 2; ++bj) { const int t = 16 * u.pn + 8 * bj + 2 * wc + (fq >> 1); const size_t tok = (size_t)R * LCH + t;
;                             f32x4 y0, y1, u0, u1; unpack8(yv[ml][bj], y0, y1); unpack8(uv[ml][bj], u0, u1);
;                             y0 = acc[ai][bj][m][0] + y0 + d0 * u0; y1 = acc[ai][bj][m][1] + y1 + d1 * u1;
; #pragma unroll
;                             for (int j = 0; j < 4; ++j) { y0[j] = gelu_tanh(y0[j]); y1[j] = gelu_tanh(y1[j]); }
;                             *(u32x4*)(yi + ((size_t)g * T_TOK + tok) * 16 + 8 * (fq & 1)) = pack8(y0, y1); } }
	v_rcp_f32_e32 v135, v135
	global_load_dwordx4 v[116:119], v[114:115], off
	v_mul_f32_e32 v105, v110, v105
	global_load_dwordx4 v[112:115], v[112:113], off
	v_mul_f32_e32 v110, v106, v131
	v_ashrrev_i32_e32 v133, 31, v132
	v_lshlrev_b64 v[132:133], 10, v[132:133]
	v_lshl_add_u64 v[132:133], v[162:163], 0, v[132:133]
	v_mul_f32_e32 v106, v111, v134
	v_mul_f32_e32 v107, v107, v135
	v_cvt_pk_bf16_f32 v104, v0, v104
	v_cvt_pk_bf16_f32 v105, v105, v106
	v_cvt_pk_bf16_f32 v106, v108, v109
	v_lshl_add_u64 v[108:109], v[132:133], 0, v[136:137]
	v_cvt_pk_bf16_f32 v107, v110, v107
	global_store_dwordx4 v[108:109], v[104:107], off
	v_lshlrev_b32_e32 v108, 16, v148
	v_and_b32_e32 v109, 0xffff0000, v148
	v_lshlrev_b32_e32 v104, 16, v146
	v_and_b32_e32 v105, 0xffff0000, v146
	v_lshlrev_b32_e32 v134, 16, v150
	v_and_b32_e32 v135, 0xffff0000, v150
	v_lshlrev_b32_e32 v140, 16, v152
	v_and_b32_e32 v141, 0xffff0000, v152
	v_pk_add_f32 v[100:101], v[100:101], v[104:105]
	v_pk_add_f32 v[96:97], v[96:97], v[108:109]
	v_pk_fma_f32 v[100:101], v[60:61], v[134:135], v[100:101]
	v_pk_fma_f32 v[96:97], v[56:57], v[140:141], v[96:97]
	v_mul_f32_e32 v0, 0x3d372713, v100
	v_mul_f32_e32 v104, 0x3d372713, v96
	v_mul_f32_e32 v105, 0x3d372713, v101
	v_mul_f32_e32 v0, v100, v0
	v_mul_f32_e32 v104, v96, v104
	v_mul_f32_e32 v105, v101, v105
	v_fma_f32 v0, v100, v0, v100
	v_fma_f32 v104, v96, v104, v96
	v_fma_f32 v105, v101, v105, v101
	v_mul_f32_e32 v0, 0x3fcc422a, v0
	v_mul_f32_e32 v104, 0x3fcc422a, v104
	v_mul_f32_e32 v105, 0x3fcc422a, v105
	v_mul_f32_e32 v0, 0xbfb8aa3b, v0
	v_mul_f32_e32 v104, 0xbfb8aa3b, v104
	v_mul_f32_e32 v105, 0xbfb8aa3b, v105
	v_exp_f32_e32 v0, v0
	v_exp_f32_e32 v104, v104
	v_exp_f32_e32 v105, v105
	v_lshlrev_b32_e32 v106, 16, v147
	v_and_b32_e32 v107, 0xffff0000, v147
	v_pk_add_f32 v[102:103], v[102:103], v[106:107]
	v_add_f32_e32 v0, 1.0, v0
	v_add_f32_e32 v104, 1.0, v104
	v_add_f32_e32 v105, 1.0, v105
	v_mul_f32_e32 v106, 0x3d372713, v97
	v_rcp_f32_e32 v0, v0
	v_rcp_f32_e32 v104, v104
	v_rcp_f32_e32 v105, v105
	v_mul_f32_e32 v106, v97, v106
	v_lshlrev_b32_e32 v110, 16, v149
	v_and_b32_e32 v111, 0xffff0000, v149
	v_fma_f32 v106, v97, v106, v97
	v_lshlrev_b32_e32 v138, 16, v151
	v_and_b32_e32 v139, 0xffff0000, v151
	v_lshlrev_b32_e32 v142, 16, v153
	v_and_b32_e32 v143, 0xffff0000, v153
	v_pk_add_f32 v[98:99], v[98:99], v[110:111]
	v_mul_f32_e32 v106, 0x3fcc422a, v106
	v_pk_fma_f32 v[102:103], v[62:63], v[138:139], v[102:103]
	v_pk_fma_f32 v[98:99], v[58:59], v[142:143], v[98:99]
	v_mul_f32_e32 v106, 0xbfb8aa3b, v106
	v_exp_f32_e32 v106, v106
	v_mul_f32_e32 v0, v100, v0
	v_mul_f32_e32 v100, v96, v104
	v_mul_f32_e32 v96, v101, v105
	v_mul_f32_e32 v104, 0x3d372713, v102
	v_mul_f32_e32 v105, 0x3d372713, v98
	v_mul_f32_e32 v104, v102, v104
	v_mul_f32_e32 v105, v98, v105
	v_fma_f32 v104, v102, v104, v102
	v_fma_f32 v105, v98, v105, v98
	v_mul_f32_e32 v104, 0x3fcc422a, v104
	v_mul_f32_e32 v105, 0x3fcc422a, v105
	v_add_f32_e32 v101, 1.0, v106
	v_mul_f32_e32 v104, 0xbfb8aa3b, v104
	v_mul_f32_e32 v105, 0xbfb8aa3b, v105
	v_rcp_f32_e32 v101, v101
	v_exp_f32_e32 v104, v104
	v_exp_f32_e32 v105, v105
	v_mul_f32_e32 v106, 0x3d372713, v99
	v_mul_f32_e32 v101, v97, v101
	v_add_f32_e32 v97, 1.0, v104
	v_add_f32_e32 v104, 1.0, v105
	v_mul_f32_e32 v105, 0x3d372713, v103
	v_mul_f32_e32 v105, v103, v105
	v_mul_f32_e32 v106, v99, v106
	v_fma_f32 v105, v103, v105, v103
	v_fma_f32 v106, v99, v106, v99
	v_mul_f32_e32 v105, 0x3fcc422a, v105
	v_mul_f32_e32 v106, 0x3fcc422a, v106
	v_mul_f32_e32 v105, 0xbfb8aa3b, v105
	v_mul_f32_e32 v106, 0xbfb8aa3b, v106
	v_exp_f32_e32 v105, v105
	v_exp_f32_e32 v106, v106
	v_rcp_f32_e32 v97, v97
	v_rcp_f32_e32 v104, v104
	v_add_f32_e32 v105, 1.0, v105
	v_add_f32_e32 v106, 1.0, v106
	v_rcp_f32_e32 v105, v105
	v_rcp_f32_e32 v106, v106
	v_mul_f32_e32 v97, v102, v97
	v_mul_f32_e32 v102, v98, v104
	v_mul_f32_e32 v98, v103, v105
	v_mul_f32_e32 v99, v99, v106
	v_cvt_pk_bf16_f32 v96, v0, v96
	v_cvt_pk_bf16_f32 v97, v97, v98
	v_cvt_pk_bf16_f32 v98, v100, v101
	v_cvt_pk_bf16_f32 v99, v102, v99
	v_lshl_add_u64 v[100:101], v[132:133], 0, v[128:129]
	global_store_dwordx4 v[100:101], v[96:99], off
	s_waitcnt vmcnt(0)
	v_lshlrev_b32_e32 v102, 16, v126
	v_and_b32_e32 v103, 0xffff0000, v126
	v_lshlrev_b32_e32 v98, 16, v124
	v_and_b32_e32 v99, 0xffff0000, v124
	v_lshlrev_b32_e32 v106, 16, v120
	v_and_b32_e32 v107, 0xffff0000, v120
	v_lshlrev_b32_e32 v110, 16, v122
	v_and_b32_e32 v111, 0xffff0000, v122
	v_pk_add_f32 v[92:93], v[92:93], v[98:99]
	v_pk_add_f32 v[88:89], v[88:89], v[102:103]
	v_pk_fma_f32 v[92:93], v[60:61], v[106:107], v[92:93]
	v_pk_fma_f32 v[88:89], v[56:57], v[110:111], v[88:89]
	v_mul_f32_e32 v0, 0x3d372713, v92
	v_mul_f32_e32 v98, 0x3d372713, v88
	v_mul_f32_e32 v99, 0x3d372713, v93
	v_mul_f32_e32 v0, v92, v0
	v_mul_f32_e32 v98, v88, v98
	v_mul_f32_e32 v99, v93, v99
	v_fma_f32 v0, v92, v0, v92
	v_fma_f32 v98, v88, v98, v88
	v_fma_f32 v99, v93, v99, v93
	v_mul_f32_e32 v0, 0x3fcc422a, v0
	v_mul_f32_e32 v98, 0x3fcc422a, v98
	v_mul_f32_e32 v99, 0x3fcc422a, v99
	v_mul_f32_e32 v0, 0xbfb8aa3b, v0
	v_mul_f32_e32 v98, 0xbfb8aa3b, v98
	v_mul_f32_e32 v99, 0xbfb8aa3b, v99
	v_exp_f32_e32 v0, v0
	v_exp_f32_e32 v98, v98
	v_exp_f32_e32 v99, v99
	v_lshlrev_b32_e32 v100, 16, v125
	v_and_b32_e32 v101, 0xffff0000, v125
	v_pk_add_f32 v[94:95], v[94:95], v[100:101]
	v_add_f32_e32 v0, 1.0, v0
	v_add_f32_e32 v98, 1.0, v98
	v_add_f32_e32 v99, 1.0, v99
	v_mul_f32_e32 v100, 0x3d372713, v89
	v_rcp_f32_e32 v0, v0
	v_rcp_f32_e32 v98, v98
	v_rcp_f32_e32 v99, v99
	v_mul_f32_e32 v100, v89, v100
	v_lshlrev_b32_e32 v104, 16, v127
	v_and_b32_e32 v105, 0xffff0000, v127
; __device__ __forceinline__ float gelu_tanh(float y) { const float z = 1.5957691216057308f * (y + 0.044715f * y * y * y); return y * sigmoidf_(z); }
; __device__ __forceinline__ u32x4 pack8(const f32x4 a, const f32x4 b) { u32x4 w; w.x = cvt_pk_bf16(a[0], a[1]); w.y = cvt_pk_bf16(a[2], a[3]); w.z = cvt_pk_bf16(b[0], b[1]); w.w = cvt_pk_bf16(b[2], b[3]); return w; }
; __device__ __forceinline__ void unpack8(const u32x4 w, f32x4& a, f32x4& b) { a[0] = bf_lo(w.x); a[1] = bf_hi(w.x); a[2] = bf_lo(w.y); a[3] = bf_hi(w.y); b[0] = bf_lo(w.z); b[1] = bf_hi(w.z); b[2] = bf_lo(w.w); b[3] = bf_hi(w.w); }
;     template <int KIND> __device__ __forceinline__ void run(f32x4 (&acc)[2][2][4][2], const Unit& u, int tid_in) const {
;     ...
;                 for (int mh = 0; mh < 2; ++mh) { u32x4 yv[2][2], uv[2][2];
; #pragma unroll
;                     for (int ml = 0; ml < 2; ++ml) { int R = rbase + ai * 128 + (mh * 2 + ml) * 16; asm volatile("" : "+v"(R));
; #pragma unroll
;                         for (int bj = 0; bj < 2; ++bj) { const int t = 16 * u.pn + 8 * bj + 2 * wc + (fq >> 1); const size_t tok = (size_t)R * LCH + t;
;                             yv[ml][bj] = *(const u32x4*)(yi + ((size_t)g * T_TOK + tok) * 16 + 8 * (fq & 1)); uv[ml][bj] = *(const u32x4*)((const bf16_t*)x + ((size_t)g * T_TOK + tok) * 16 + 8 * (fq & 1)); } }
; #pragma unroll
;                     for (int ml = 0; ml < 2; ++ml) { const int m = mh * 2 + ml; int R = rbase + ai * 128 + m * 16; asm volatile("" : "+v"(R));
; #pragma unroll
;                         for (int bj = 0; bj < 2; ++bj) { const int t = 16 * u.pn + 8 * bj + 2 * wc + (fq >> 1); const size_t tok = (size_t)R * LCH + t;
;                             f32x4 y0, y1, u0, u1; unpack8(yv[ml][bj], y0, y1); unpack8(uv[ml][bj], u0, u1);
;                             y0 = acc[ai][bj][m][0] + y0 + d0 * u0; y1 = acc[ai][bj][m][1] + y1 + d1 * u1;
; #pragma unroll
;                             for (int j = 0; j < 4; ++j) { y0[j] = gelu_tanh(y0[j]); y1[j] = gelu_tanh(y1[j]); }
;                             *(u32x4*)(yi + ((size_t)g * T_TOK + tok) * 16 + 8 * (fq & 1)) = pack8(y0, y1); } }
	v_fma_f32 v100, v89, v100, v89
	v_lshlrev_b32_e32 v108, 16, v121
	v_and_b32_e32 v109, 0xffff0000, v121
	v_lshlrev_b32_e32 v120, 16, v123
	v_and_b32_e32 v121, 0xffff0000, v123
	v_pk_add_f32 v[90:91], v[90:91], v[104:105]
	v_mul_f32_e32 v100, 0x3fcc422a, v100
	v_pk_fma_f32 v[94:95], v[62:63], v[108:109], v[94:95]
	v_pk_fma_f32 v[90:91], v[58:59], v[120:121], v[90:91]
	v_mul_f32_e32 v100, 0xbfb8aa3b, v100
	v_exp_f32_e32 v100, v100
	v_mul_f32_e32 v0, v92, v0
	v_mul_f32_e32 v92, v88, v98
	v_mul_f32_e32 v88, v93, v99
	v_mul_f32_e32 v98, 0x3d372713, v94
	v_mul_f32_e32 v99, 0x3d372713, v90
	v_mul_f32_e32 v98, v94, v98
	v_mul_f32_e32 v99, v90, v99
	v_fma_f32 v98, v94, v98, v94
	v_fma_f32 v99, v90, v99, v90
	v_mul_f32_e32 v98, 0x3fcc422a, v98
	v_mul_f32_e32 v99, 0x3fcc422a, v99
	v_add_f32_e32 v93, 1.0, v100
	v_mul_f32_e32 v98, 0xbfb8aa3b, v98
	v_mul_f32_e32 v99, 0xbfb8aa3b, v99
	v_rcp_f32_e32 v93, v93
	v_exp_f32_e32 v98, v98
	v_exp_f32_e32 v99, v99
	v_mul_f32_e32 v100, 0x3d372713, v91
	v_mul_f32_e32 v93, v89, v93
	v_add_f32_e32 v89, 1.0, v98
	v_add_f32_e32 v98, 1.0, v99
	v_mul_f32_e32 v99, 0x3d372713, v95
	v_mul_f32_e32 v99, v95, v99
	v_fma_f32 v99, v95, v99, v95
	v_mul_f32_e32 v100, v91, v100
	v_mul_f32_e32 v99, 0x3fcc422a, v99
	v_fma_f32 v100, v91, v100, v91
	v_mul_f32_e32 v99, 0xbfb8aa3b, v99
	v_mul_f32_e32 v100, 0x3fcc422a, v100
	v_exp_f32_e32 v99, v99
	v_mul_f32_e32 v100, 0xbfb8aa3b, v100
	v_exp_f32_e32 v100, v100
	v_rcp_f32_e32 v89, v89
	v_add_f32_e32 v99, 1.0, v99
	v_rcp_f32_e32 v98, v98
	v_rcp_f32_e32 v99, v99
	v_add_f32_e32 v100, 1.0, v100
	v_rcp_f32_e32 v100, v100
	v_mul_f32_e32 v89, v94, v89
	v_ashrrev_i32_e32 v131, 31, v130
	v_lshlrev_b64 v[96:97], 10, v[130:131]
	v_lshl_add_u64 v[96:97], v[162:163], 0, v[96:97]
	v_mul_f32_e32 v94, v90, v98
	v_mul_f32_e32 v90, v95, v99
	v_mul_f32_e32 v91, v91, v100
	v_cvt_pk_bf16_f32 v88, v0, v88
	v_cvt_pk_bf16_f32 v89, v89, v90
	v_cvt_pk_bf16_f32 v90, v92, v93
	v_lshl_add_u64 v[92:93], v[96:97], 0, v[136:137]
	v_cvt_pk_bf16_f32 v91, v94, v91
	global_store_dwordx4 v[92:93], v[88:91], off
	v_lshlrev_b32_e32 v92, 16, v118
	v_and_b32_e32 v93, 0xffff0000, v118
	v_lshlrev_b32_e32 v88, 16, v116
	v_and_b32_e32 v89, 0xffff0000, v116
	v_lshlrev_b32_e32 v98, 16, v112
	v_and_b32_e32 v99, 0xffff0000, v112
	v_lshlrev_b32_e32 v102, 16, v114
	v_and_b32_e32 v103, 0xffff0000, v114
	v_pk_add_f32 v[84:85], v[84:85], v[88:89]
	v_pk_add_f32 v[80:81], v[80:81], v[92:93]
	v_pk_fma_f32 v[84:85], v[60:61], v[98:99], v[84:85]
	v_pk_fma_f32 v[80:81], v[56:57], v[102:103], v[80:81]
	v_mul_f32_e32 v0, 0x3d372713, v84
	v_mul_f32_e32 v88, 0x3d372713, v80
	v_mul_f32_e32 v89, 0x3d372713, v85
	v_mul_f32_e32 v0, v84, v0
	v_mul_f32_e32 v88, v80, v88
	v_mul_f32_e32 v89, v85, v89
	v_fma_f32 v0, v84, v0, v84
	v_fma_f32 v88, v80, v88, v80
	v_fma_f32 v89, v85, v89, v85
	v_mul_f32_e32 v0, 0x3fcc422a, v0
	v_mul_f32_e32 v88, 0x3fcc422a, v88
	v_mul_f32_e32 v89, 0x3fcc422a, v89
	v_mul_f32_e32 v0, 0xbfb8aa3b, v0
	v_mul_f32_e32 v88, 0xbfb8aa3b, v88
	v_mul_f32_e32 v89, 0xbfb8aa3b, v89
	v_exp_f32_e32 v0, v0
	v_exp_f32_e32 v88, v88
	v_exp_f32_e32 v89, v89
	v_lshlrev_b32_e32 v90, 16, v117
	v_and_b32_e32 v91, 0xffff0000, v117
	v_pk_add_f32 v[86:87], v[86:87], v[90:91]
	v_add_f32_e32 v0, 1.0, v0
	v_add_f32_e32 v88, 1.0, v88
	v_add_f32_e32 v89, 1.0, v89
	v_mul_f32_e32 v90, 0x3d372713, v81
	v_rcp_f32_e32 v0, v0
	v_rcp_f32_e32 v88, v88
	v_rcp_f32_e32 v89, v89
	v_mul_f32_e32 v90, v81, v90
	v_lshlrev_b32_e32 v94, 16, v119
	v_and_b32_e32 v95, 0xffff0000, v119
	v_fma_f32 v90, v81, v90, v81
	v_lshlrev_b32_e32 v100, 16, v113
	v_and_b32_e32 v101, 0xffff0000, v113
	v_lshlrev_b32_e32 v104, 16, v115
	v_and_b32_e32 v105, 0xffff0000, v115
	v_pk_add_f32 v[82:83], v[82:83], v[94:95]
	v_mul_f32_e32 v90, 0x3fcc422a, v90
	v_pk_fma_f32 v[86:87], v[62:63], v[100:101], v[86:87]
	v_pk_fma_f32 v[82:83], v[58:59], v[104:105], v[82:83]
	v_mul_f32_e32 v90, 0xbfb8aa3b, v90
	v_exp_f32_e32 v90, v90
	v_mul_f32_e32 v0, v84, v0
	v_mul_f32_e32 v84, v80, v88
	v_mul_f32_e32 v80, v85, v89
	v_mul_f32_e32 v88, 0x3d372713, v86
	v_mul_f32_e32 v89, 0x3d372713, v82
	v_mul_f32_e32 v88, v86, v88
	v_mul_f32_e32 v89, v82, v89
	v_fma_f32 v88, v86, v88, v86
	v_fma_f32 v89, v82, v89, v82
	v_mul_f32_e32 v88, 0x3fcc422a, v88
	v_mul_f32_e32 v89, 0x3fcc422a, v89
	v_add_f32_e32 v85, 1.0, v90
	v_mul_f32_e32 v88, 0xbfb8aa3b, v88
	v_mul_f32_e32 v89, 0xbfb8aa3b, v89
	v_rcp_f32_e32 v85, v85
	v_exp_f32_e32 v88, v88
	v_exp_f32_e32 v89, v89
	v_mul_f32_e32 v90, 0x3d372713, v83
	v_mul_f32_e32 v85, v81, v85
	v_add_f32_e32 v81, 1.0, v88
	v_add_f32_e32 v88, 1.0, v89
	v_mul_f32_e32 v89, 0x3d372713, v87
	v_mul_f32_e32 v89, v87, v89
	v_fma_f32 v89, v87, v89, v87
	v_mul_f32_e32 v90, v83, v90
	v_mul_f32_e32 v89, 0x3fcc422a, v89
	v_fma_f32 v90, v83, v90, v83
	v_mul_f32_e32 v89, 0xbfb8aa3b, v89
	v_mul_f32_e32 v90, 0x3fcc422a, v90
	v_exp_f32_e32 v89, v89
	v_mul_f32_e32 v90, 0xbfb8aa3b, v90
	v_exp_f32_e32 v90, v90
	v_rcp_f32_e32 v81, v81
	v_add_f32_e32 v89, 1.0, v89
	v_rcp_f32_e32 v88, v88
	v_rcp_f32_e32 v89, v89
	v_add_f32_e32 v90, 1.0, v90
	v_rcp_f32_e32 v90, v90
	v_mul_f32_e32 v81, v86, v81
	v_mul_f32_e32 v86, v82, v88
	v_mul_f32_e32 v82, v87, v89
	v_mul_f32_e32 v83, v83, v90
	v_cvt_pk_bf16_f32 v80, v0, v80
	v_cvt_pk_bf16_f32 v81, v81, v82
	v_cvt_pk_bf16_f32 v82, v84, v85
	v_lshl_add_u64 v[84:85], v[96:97], 0, v[128:129]
	v_add_u32_e32 v98, 0x80, v185
	v_cvt_pk_bf16_f32 v83, v86, v83
	global_store_dwordx4 v[84:85], v[80:83], off
	v_add_u32_e32 v96, 0x90, v185
	s_nop 0
	v_mov_b32_e32 v80, v98
	s_nop 0
	v_ashrrev_i32_e32 v81, 31, v80
	v_lshlrev_b64 v[80:81], 9, v[80:81]
	v_lshl_add_u64 v[80:81], v[80:81], 0, s[20:21]
	v_lshl_add_u64 v[82:83], v[80:81], 0, v[172:173]
	v_lshlrev_b64 v[82:83], 1, v[82:83]
	v_lshl_add_u64 v[84:85], v[164:165], 0, v[82:83]
	global_load_dwordx4 v[100:103], v[84:85], off
	v_lshl_add_u64 v[82:83], v[166:167], 0, v[82:83]
	global_load_dwordx4 v[104:107], v[82:83], off
	v_lshl_add_u64 v[80:81], v[80:81], 0, v[174:175]
	v_lshlrev_b64 v[80:81], 1, v[80:81]
	v_lshl_add_u64 v[82:83], v[164:165], 0, v[80:81]
	global_load_dwordx4 v[108:111], v[82:83], off
	v_lshl_add_u64 v[80:81], v[166:167], 0, v[80:81]
	global_load_dwordx4 v[112:115], v[80:81], off
	v_mov_b32_e32 v80, v96
	s_waitcnt vmcnt(0)
; __device__ __forceinline__ float gelu_tanh(float y) { const float z = 1.5957691216057308f * (y + 0.044715f * y * y * y); return y * sigmoidf_(z); }
; __device__ __forceinline__ u32x4 pack8(const f32x4 a, const f32x4 b) { u32x4 w; w.x = cvt_pk_bf16(a[0], a[1]); w.y = cvt_pk_bf16(a[2], a[3]); w.z = cvt_pk_bf16(b[0], b[1]); w.w = cvt_pk_bf16(b[2], b[3]); return w; }
; __device__ __forceinline__ void unpack8(const u32x4 w, f32x4& a, f32x4& b) { a[0] = bf_lo(w.x); a[1] = bf_hi(w.x); a[2] = bf_lo(w.y); a[3] = bf_hi(w.y); b[0] = bf_lo(w.z); b[1] = bf_hi(w.z); b[2] = bf_lo(w.w); b[3] = bf_hi(w.w); }
;     template <int KIND> __device__ __forceinline__ void run(f32x4 (&acc)[2][2][4][2], const Unit& u, int tid_in) const {
;     ...
;                         for (int bj = 0; bj < 2; ++bj) { const int t = 16 * u.pn + 8 * bj + 2 * wc + (fq >> 1); const size_t tok = (size_t)R * LCH + t;
;                             yv[ml][bj] = *(const u32x4*)(yi + ((size_t)g * T_TOK + tok) * 16 + 8 * (fq & 1)); uv[ml][bj] = *(const u32x4*)((const bf16_t*)x + ((size_t)g * T_TOK + tok) * 16 + 8 * (fq & 1)); } }
; #pragma unroll
;                     for (int ml = 0; ml < 2; ++ml) { const int m = mh * 2 + ml; int R = rbase + ai * 128 + m * 16; asm volatile("" : "+v"(R));
; #pragma unroll
;                         for (int bj = 0; bj < 2; ++bj) { const int t = 16 * u.pn + 8 * bj + 2 * wc + (fq >> 1); const size_t tok = (size_t)R * LCH + t;
;                             f32x4 y0, y1, u0, u1; unpack8(yv[ml][bj], y0, y1); unpack8(uv[ml][bj], u0, u1);
;                             y0 = acc[ai][bj][m][0] + y0 + d0 * u0; y1 = acc[ai][bj][m][1] + y1 + d1 * u1;
; #pragma unroll
;                             for (int j = 0; j < 4; ++j) { y0[j] = gelu_tanh(y0[j]); y1[j] = gelu_tanh(y1[j]); }
;                             *(u32x4*)(yi + ((size_t)g * T_TOK + tok) * 16 + 8 * (fq & 1)) = pack8(y0, y1); } }
	v_lshlrev_b32_e32 v116, 16, v100
	v_ashrrev_i32_e32 v81, 31, v80
	v_lshlrev_b64 v[80:81], 9, v[80:81]
	v_lshl_add_u64 v[80:81], v[80:81], 0, s[20:21]
	v_and_b32_e32 v117, 0xffff0000, v100
	v_lshlrev_b32_e32 v118, 16, v102
	v_and_b32_e32 v119, 0xffff0000, v102
	v_lshl_add_u64 v[82:83], v[80:81], 0, v[172:173]
	v_lshlrev_b32_e32 v120, 16, v104
	v_and_b32_e32 v121, 0xffff0000, v104
	v_lshlrev_b32_e32 v122, 16, v106
	v_and_b32_e32 v123, 0xffff0000, v106
	v_pk_add_f32 v[76:77], v[76:77], v[116:117]
	v_pk_add_f32 v[72:73], v[72:73], v[118:119]
	v_lshlrev_b64 v[82:83], 1, v[82:83]
	v_lshlrev_b32_e32 v100, 16, v101
	v_and_b32_e32 v101, 0xffff0000, v101
	v_pk_fma_f32 v[76:77], v[60:61], v[120:121], v[76:77]
	v_pk_fma_f32 v[72:73], v[56:57], v[122:123], v[72:73]
	v_lshl_add_u64 v[84:85], v[164:165], 0, v[82:83]
	v_pk_add_f32 v[78:79], v[78:79], v[100:101]
	v_mul_f32_e32 v0, 0x3d372713, v76
	v_mul_f32_e32 v97, 0x3d372713, v72
	v_mul_f32_e32 v100, 0x3d372713, v77
	global_load_dwordx4 v[92:95], v[84:85], off
	v_lshl_add_u64 v[82:83], v[166:167], 0, v[82:83]
	v_mul_f32_e32 v0, v76, v0
	v_mul_f32_e32 v97, v72, v97
	v_mul_f32_e32 v100, v77, v100
	global_load_dwordx4 v[88:91], v[82:83], off
	v_fma_f32 v0, v76, v0, v76
	v_fma_f32 v97, v72, v97, v72
	v_fma_f32 v100, v77, v100, v77
	v_mul_f32_e32 v0, 0x3fcc422a, v0
	v_mul_f32_e32 v97, 0x3fcc422a, v97
	v_mul_f32_e32 v100, 0x3fcc422a, v100
	v_mul_f32_e32 v0, 0xbfb8aa3b, v0
	v_mul_f32_e32 v97, 0xbfb8aa3b, v97
	v_mul_f32_e32 v100, 0xbfb8aa3b, v100
	v_exp_f32_e32 v0, v0
	v_exp_f32_e32 v97, v97
	v_exp_f32_e32 v100, v100
	v_mul_f32_e32 v101, 0x3d372713, v73
	v_add_f32_e32 v0, 1.0, v0
	v_add_f32_e32 v97, 1.0, v97
	v_add_f32_e32 v100, 1.0, v100
	v_rcp_f32_e32 v0, v0
	v_rcp_f32_e32 v97, v97
	v_rcp_f32_e32 v100, v100
	v_mul_f32_e32 v101, v73, v101
	v_lshlrev_b32_e32 v102, 16, v103
	v_and_b32_e32 v103, 0xffff0000, v103
	v_fma_f32 v101, v73, v101, v73
	v_lshlrev_b32_e32 v104, 16, v105
	v_and_b32_e32 v105, 0xffff0000, v105
	v_lshlrev_b32_e32 v106, 16, v107
	v_and_b32_e32 v107, 0xffff0000, v107
	v_pk_add_f32 v[74:75], v[74:75], v[102:103]
	v_mul_f32_e32 v101, 0x3fcc422a, v101
	v_pk_fma_f32 v[78:79], v[62:63], v[104:105], v[78:79]
	v_pk_fma_f32 v[74:75], v[58:59], v[106:107], v[74:75]
	v_mul_f32_e32 v101, 0xbfb8aa3b, v101
	v_exp_f32_e32 v101, v101
	v_mul_f32_e32 v0, v76, v0
	v_mul_f32_e32 v76, v72, v97
	v_mul_f32_e32 v72, v77, v100
	v_mul_f32_e32 v97, 0x3d372713, v78
	v_mul_f32_e32 v100, 0x3d372713, v74
	v_mul_f32_e32 v97, v78, v97
	v_mul_f32_e32 v100, v74, v100
	v_fma_f32 v97, v78, v97, v78
	v_fma_f32 v100, v74, v100, v74
	v_mul_f32_e32 v97, 0x3fcc422a, v97
	v_mul_f32_e32 v100, 0x3fcc422a, v100
	v_add_f32_e32 v77, 1.0, v101
	v_mul_f32_e32 v97, 0xbfb8aa3b, v97
	v_mul_f32_e32 v100, 0xbfb8aa3b, v100
	v_rcp_f32_e32 v77, v77
	v_exp_f32_e32 v97, v97
	v_exp_f32_e32 v100, v100
	v_mul_f32_e32 v101, 0x3d372713, v75
	v_mul_f32_e32 v77, v73, v77
	v_add_f32_e32 v73, 1.0, v97
	v_add_f32_e32 v97, 1.0, v100
	v_mul_f32_e32 v100, 0x3d372713, v79
	v_mul_f32_e32 v100, v79, v100
	v_fma_f32 v100, v79, v100, v79
	v_mul_f32_e32 v101, v75, v101
	v_mul_f32_e32 v100, 0x3fcc422a, v100
	v_fma_f32 v101, v75, v101, v75
	v_mul_f32_e32 v100, 0xbfb8aa3b, v100
	v_mul_f32_e32 v101, 0x3fcc422a, v101
	v_exp_f32_e32 v100, v100
	v_mul_f32_e32 v101, 0xbfb8aa3b, v101
	v_exp_f32_e32 v101, v101
	v_lshl_add_u64 v[80:81], v[80:81], 0, v[174:175]
	v_add_f32_e32 v100, 1.0, v100
	v_lshlrev_b64 v[80:81], 1, v[80:81]
	v_rcp_f32_e32 v73, v73
	v_rcp_f32_e32 v97, v97
	v_rcp_f32_e32 v100, v100
	v_add_f32_e32 v101, 1.0, v101
	v_lshl_add_u64 v[82:83], v[164:165], 0, v[80:81]
	v_lshl_add_u64 v[80:81], v[166:167], 0, v[80:81]
	v_rcp_f32_e32 v101, v101
	global_load_dwordx4 v[84:87], v[82:83], off
	v_mul_f32_e32 v73, v78, v73
	global_load_dwordx4 v[80:83], v[80:81], off
	v_mul_f32_e32 v78, v74, v97
	v_ashrrev_i32_e32 v99, 31, v98
	v_lshlrev_b64 v[98:99], 10, v[98:99]
	v_lshl_add_u64 v[98:99], v[162:163], 0, v[98:99]
	v_mul_f32_e32 v74, v79, v100
	v_mul_f32_e32 v75, v75, v101
	v_cvt_pk_bf16_f32 v72, v0, v72
	v_cvt_pk_bf16_f32 v73, v73, v74
	v_cvt_pk_bf16_f32 v74, v76, v77
	v_lshl_add_u64 v[76:77], v[98:99], 0, v[136:137]
	v_cvt_pk_bf16_f32 v75, v78, v75
	global_store_dwordx4 v[76:77], v[72:75], off
	v_lshlrev_b32_e32 v76, 16, v110
	v_and_b32_e32 v77, 0xffff0000, v110
	v_lshlrev_b32_e32 v72, 16, v108
	v_and_b32_e32 v73, 0xffff0000, v108
	v_lshlrev_b32_e32 v100, 16, v112
	v_and_b32_e32 v101, 0xffff0000, v112
	v_lshlrev_b32_e32 v104, 16, v114
	v_and_b32_e32 v105, 0xffff0000, v114
	v_pk_add_f32 v[68:69], v[68:69], v[72:73]
	v_pk_add_f32 v[64:65], v[64:65], v[76:77]
	v_pk_fma_f32 v[68:69], v[60:61], v[100:101], v[68:69]
	v_pk_fma_f32 v[64:65], v[56:57], v[104:105], v[64:65]
	v_mul_f32_e32 v0, 0x3d372713, v68
	v_mul_f32_e32 v72, 0x3d372713, v64
	v_mul_f32_e32 v73, 0x3d372713, v69
	v_mul_f32_e32 v0, v68, v0
	v_mul_f32_e32 v72, v64, v72
	v_mul_f32_e32 v73, v69, v73
	v_fma_f32 v0, v68, v0, v68
	v_fma_f32 v72, v64, v72, v64
	v_fma_f32 v73, v69, v73, v69
	v_mul_f32_e32 v0, 0x3fcc422a, v0
	v_mul_f32_e32 v72, 0x3fcc422a, v72
	v_mul_f32_e32 v73, 0x3fcc422a, v73
	v_mul_f32_e32 v0, 0xbfb8aa3b, v0
	v_mul_f32_e32 v72, 0xbfb8aa3b, v72
	v_mul_f32_e32 v73, 0xbfb8aa3b, v73
	v_exp_f32_e32 v0, v0
	v_exp_f32_e32 v72, v72
	v_exp_f32_e32 v73, v73
	v_lshlrev_b32_e32 v74, 16, v109
	v_and_b32_e32 v75, 0xffff0000, v109
	v_pk_add_f32 v[70:71], v[70:71], v[74:75]
	v_add_f32_e32 v0, 1.0, v0
	v_add_f32_e32 v72, 1.0, v72
	v_add_f32_e32 v73, 1.0, v73
	v_mul_f32_e32 v74, 0x3d372713, v65
	v_rcp_f32_e32 v0, v0
	v_rcp_f32_e32 v72, v72
	v_rcp_f32_e32 v73, v73
	v_mul_f32_e32 v74, v65, v74
	v_lshlrev_b32_e32 v78, 16, v111
; __device__ __forceinline__ float gelu_tanh(float y) { const float z = 1.5957691216057308f * (y + 0.044715f * y * y * y); return y * sigmoidf_(z); }
; __device__ __forceinline__ u32x4 pack8(const f32x4 a, const f32x4 b) { u32x4 w; w.x = cvt_pk_bf16(a[0], a[1]); w.y = cvt_pk_bf16(a[2], a[3]); w.z = cvt_pk_bf16(b[0], b[1]); w.w = cvt_pk_bf16(b[2], b[3]); return w; }
; __device__ __forceinline__ void unpack8(const u32x4 w, f32x4& a, f32x4& b) { a[0] = bf_lo(w.x); a[1] = bf_hi(w.x); a[2] = bf_lo(w.y); a[3] = bf_hi(w.y); b[0] = bf_lo(w.z); b[1] = bf_hi(w.z); b[2] = bf_lo(w.w); b[3] = bf_hi(w.w); }
;     template <int KIND> __device__ __forceinline__ void run(f32x4 (&acc)[2][2][4][2], const Unit& u, int tid_in) const {
;     ...
;                         for (int bj = 0; bj < 2; ++bj) { const int t = 16 * u.pn + 8 * bj + 2 * wc + (fq >> 1); const size_t tok = (size_t)R * LCH + t;
;                             yv[ml][bj] = *(const u32x4*)(yi + ((size_t)g * T_TOK + tok) * 16 + 8 * (fq & 1)); uv[ml][bj] = *(const u32x4*)((const bf16_t*)x + ((size_t)g * T_TOK + tok) * 16 + 8 * (fq & 1)); } }
; #pragma unroll
;                     for (int ml = 0; ml < 2; ++ml) { const int m = mh * 2 + ml; int R = rbase + ai * 128 + m * 16; asm volatile("" : "+v"(R));
; #pragma unroll
;                         for (int bj = 0; bj < 2; ++bj) { const int t = 16 * u.pn + 8 * bj + 2 * wc + (fq >> 1); const size_t tok = (size_t)R * LCH + t;
;                             f32x4 y0, y1, u0, u1; unpack8(yv[ml][bj], y0, y1); unpack8(uv[ml][bj], u0, u1);
;                             y0 = acc[ai][bj][m][0] + y0 + d0 * u0; y1 = acc[ai][bj][m][1] + y1 + d1 * u1;
; #pragma unroll
;                             for (int j = 0; j < 4; ++j) { y0[j] = gelu_tanh(y0[j]); y1[j] = gelu_tanh(y1[j]); }
;                             *(u32x4*)(yi + ((size_t)g * T_TOK + tok) * 16 + 8 * (fq & 1)) = pack8(y0, y1); } }
	v_and_b32_e32 v79, 0xffff0000, v111
	v_fma_f32 v74, v65, v74, v65
	v_lshlrev_b32_e32 v102, 16, v113
	v_and_b32_e32 v103, 0xffff0000, v113
	v_lshlrev_b32_e32 v106, 16, v115
	v_and_b32_e32 v107, 0xffff0000, v115
	v_pk_add_f32 v[66:67], v[66:67], v[78:79]
	v_mul_f32_e32 v74, 0x3fcc422a, v74
	v_pk_fma_f32 v[70:71], v[62:63], v[102:103], v[70:71]
	v_pk_fma_f32 v[66:67], v[58:59], v[106:107], v[66:67]
	v_mul_f32_e32 v74, 0xbfb8aa3b, v74
	v_exp_f32_e32 v74, v74
	v_mul_f32_e32 v0, v68, v0
	v_mul_f32_e32 v68, v64, v72
	v_mul_f32_e32 v64, v69, v73
	v_mul_f32_e32 v72, 0x3d372713, v70
	v_mul_f32_e32 v73, 0x3d372713, v66
	v_mul_f32_e32 v72, v70, v72
	v_mul_f32_e32 v73, v66, v73
	v_fma_f32 v72, v70, v72, v70
	v_fma_f32 v73, v66, v73, v66
	v_mul_f32_e32 v72, 0x3fcc422a, v72
	v_mul_f32_e32 v73, 0x3fcc422a, v73
	v_add_f32_e32 v69, 1.0, v74
	v_mul_f32_e32 v72, 0xbfb8aa3b, v72
	v_mul_f32_e32 v73, 0xbfb8aa3b, v73
	v_rcp_f32_e32 v69, v69
	v_exp_f32_e32 v72, v72
	v_exp_f32_e32 v73, v73
	v_mul_f32_e32 v74, 0x3d372713, v67
	v_mul_f32_e32 v69, v65, v69
	v_add_f32_e32 v65, 1.0, v72
	v_add_f32_e32 v72, 1.0, v73
	v_mul_f32_e32 v73, 0x3d372713, v71
	v_mul_f32_e32 v73, v71, v73
	v_mul_f32_e32 v74, v67, v74
	v_fma_f32 v73, v71, v73, v71
	v_fma_f32 v74, v67, v74, v67
	v_mul_f32_e32 v73, 0x3fcc422a, v73
	v_mul_f32_e32 v74, 0x3fcc422a, v74
	v_mul_f32_e32 v73, 0xbfb8aa3b, v73
	v_mul_f32_e32 v74, 0xbfb8aa3b, v74
	v_exp_f32_e32 v73, v73
	v_exp_f32_e32 v74, v74
	v_rcp_f32_e32 v65, v65
	v_rcp_f32_e32 v72, v72
	v_add_f32_e32 v73, 1.0, v73
	v_add_f32_e32 v74, 1.0, v74
	v_rcp_f32_e32 v73, v73
	v_rcp_f32_e32 v74, v74
	v_mul_f32_e32 v65, v70, v65
	v_mul_f32_e32 v70, v66, v72
	v_mul_f32_e32 v66, v71, v73
	v_mul_f32_e32 v67, v67, v74
	v_cvt_pk_bf16_f32 v64, v0, v64
	v_cvt_pk_bf16_f32 v65, v65, v66
	v_cvt_pk_bf16_f32 v66, v68, v69
	v_cvt_pk_bf16_f32 v67, v70, v67
	v_lshl_add_u64 v[68:69], v[98:99], 0, v[128:129]
	global_store_dwordx4 v[68:69], v[64:67], off
	s_waitcnt vmcnt(0)
	v_lshlrev_b32_e32 v70, 16, v94
	v_and_b32_e32 v71, 0xffff0000, v94
	v_lshlrev_b32_e32 v66, 16, v92
	v_and_b32_e32 v67, 0xffff0000, v92
	v_lshlrev_b32_e32 v74, 16, v88
	v_and_b32_e32 v75, 0xffff0000, v88
	v_lshlrev_b32_e32 v78, 16, v90
	v_and_b32_e32 v79, 0xffff0000, v90
	v_pk_add_f32 v[52:53], v[52:53], v[66:67]
	v_pk_add_f32 v[48:49], v[48:49], v[70:71]
	v_pk_fma_f32 v[52:53], v[60:61], v[74:75], v[52:53]
	v_pk_fma_f32 v[48:49], v[56:57], v[78:79], v[48:49]
	v_mul_f32_e32 v0, 0x3d372713, v52
	v_mul_f32_e32 v66, 0x3d372713, v48
	v_mul_f32_e32 v67, 0x3d372713, v53
	v_mul_f32_e32 v0, v52, v0
	v_mul_f32_e32 v66, v48, v66
	v_mul_f32_e32 v67, v53, v67
	v_fma_f32 v0, v52, v0, v52
	v_fma_f32 v66, v48, v66, v48
	v_fma_f32 v67, v53, v67, v53
	v_mul_f32_e32 v0, 0x3fcc422a, v0
	v_mul_f32_e32 v66, 0x3fcc422a, v66
	v_mul_f32_e32 v67, 0x3fcc422a, v67
	v_mul_f32_e32 v0, 0xbfb8aa3b, v0
	v_mul_f32_e32 v66, 0xbfb8aa3b, v66
	v_mul_f32_e32 v67, 0xbfb8aa3b, v67
	v_exp_f32_e32 v0, v0
	v_exp_f32_e32 v66, v66
	v_exp_f32_e32 v67, v67
	v_lshlrev_b32_e32 v68, 16, v93
	v_and_b32_e32 v69, 0xffff0000, v93
	v_pk_add_f32 v[54:55], v[54:55], v[68:69]
	v_add_f32_e32 v0, 1.0, v0
	v_add_f32_e32 v66, 1.0, v66
	v_add_f32_e32 v67, 1.0, v67
	v_mul_f32_e32 v68, 0x3d372713, v49
	v_rcp_f32_e32 v0, v0
	v_rcp_f32_e32 v66, v66
	v_rcp_f32_e32 v67, v67
	v_mul_f32_e32 v68, v49, v68
	v_lshlrev_b32_e32 v72, 16, v95
	v_and_b32_e32 v73, 0xffff0000, v95
	v_fma_f32 v68, v49, v68, v49
	v_lshlrev_b32_e32 v76, 16, v89
	v_and_b32_e32 v77, 0xffff0000, v89
	v_lshlrev_b32_e32 v88, 16, v91
	v_and_b32_e32 v89, 0xffff0000, v91
	v_pk_add_f32 v[50:51], v[50:51], v[72:73]
	v_mul_f32_e32 v68, 0x3fcc422a, v68
	v_pk_fma_f32 v[54:55], v[62:63], v[76:77], v[54:55]
	v_pk_fma_f32 v[50:51], v[58:59], v[88:89], v[50:51]
	v_mul_f32_e32 v68, 0xbfb8aa3b, v68
	v_exp_f32_e32 v68, v68
	v_mul_f32_e32 v0, v52, v0
	v_mul_f32_e32 v52, v48, v66
	v_mul_f32_e32 v48, v53, v67
	v_mul_f32_e32 v66, 0x3d372713, v54
	v_mul_f32_e32 v67, 0x3d372713, v50
	v_mul_f32_e32 v66, v54, v66
	v_mul_f32_e32 v67, v50, v67
	v_fma_f32 v66, v54, v66, v54
	v_fma_f32 v67, v50, v67, v50
	v_mul_f32_e32 v66, 0x3fcc422a, v66
	v_mul_f32_e32 v67, 0x3fcc422a, v67
	v_add_f32_e32 v53, 1.0, v68
	v_mul_f32_e32 v66, 0xbfb8aa3b, v66
	v_mul_f32_e32 v67, 0xbfb8aa3b, v67
	v_rcp_f32_e32 v53, v53
	v_exp_f32_e32 v66, v66
	v_exp_f32_e32 v67, v67
	v_mul_f32_e32 v68, 0x3d372713, v51
	v_mul_f32_e32 v53, v49, v53
	v_add_f32_e32 v49, 1.0, v66
	v_add_f32_e32 v66, 1.0, v67
	v_mul_f32_e32 v67, 0x3d372713, v55
	v_mul_f32_e32 v67, v55, v67
	v_fma_f32 v67, v55, v67, v55
	v_mul_f32_e32 v68, v51, v68
	v_mul_f32_e32 v67, 0x3fcc422a, v67
	v_fma_f32 v68, v51, v68, v51
	v_mul_f32_e32 v67, 0xbfb8aa3b, v67
	v_mul_f32_e32 v68, 0x3fcc422a, v68
	v_exp_f32_e32 v67, v67
	v_mul_f32_e32 v68, 0xbfb8aa3b, v68
	v_exp_f32_e32 v68, v68
	v_rcp_f32_e32 v49, v49
	v_add_f32_e32 v67, 1.0, v67
	v_rcp_f32_e32 v66, v66
	v_rcp_f32_e32 v67, v67
	v_add_f32_e32 v68, 1.0, v68
	v_rcp_f32_e32 v68, v68
	v_mul_f32_e32 v49, v54, v49
	v_ashrrev_i32_e32 v97, 31, v96
	v_lshlrev_b64 v[64:65], 10, v[96:97]
	v_lshl_add_u64 v[64:65], v[162:163], 0, v[64:65]
	v_mul_f32_e32 v54, v50, v66
	v_mul_f32_e32 v50, v55, v67
	v_mul_f32_e32 v51, v51, v68
	v_cvt_pk_bf16_f32 v48, v0, v48
	v_cvt_pk_bf16_f32 v49, v49, v50
	v_cvt_pk_bf16_f32 v50, v52, v53
	v_lshl_add_u64 v[52:53], v[64:65], 0, v[136:137]
	v_cvt_pk_bf16_f32 v51, v54, v51
	global_store_dwordx4 v[52:53], v[48:51], off
	v_lshlrev_b32_e32 v52, 16, v86
	v_and_b32_e32 v53, 0xffff0000, v86
	v_lshlrev_b32_e32 v48, 16, v84
	v_and_b32_e32 v49, 0xffff0000, v84
	v_lshlrev_b32_e32 v66, 16, v80
	v_and_b32_e32 v67, 0xffff0000, v80
	v_lshlrev_b32_e32 v70, 16, v82
; __device__ __forceinline__ float gelu_tanh(float y) { const float z = 1.5957691216057308f * (y + 0.044715f * y * y * y); return y * sigmoidf_(z); }
; __device__ __forceinline__ u32x4 pack8(const f32x4 a, const f32x4 b) { u32x4 w; w.x = cvt_pk_bf16(a[0], a[1]); w.y = cvt_pk_bf16(a[2], a[3]); w.z = cvt_pk_bf16(b[0], b[1]); w.w = cvt_pk_bf16(b[2], b[3]); return w; }
; __device__ __forceinline__ void unpack8(const u32x4 w, f32x4& a, f32x4& b) { a[0] = bf_lo(w.x); a[1] = bf_hi(w.x); a[2] = bf_lo(w.y); a[3] = bf_hi(w.y); b[0] = bf_lo(w.z); b[1] = bf_hi(w.z); b[2] = bf_lo(w.w); b[3] = bf_hi(w.w); }
;     template <int KIND> __device__ __forceinline__ void run(f32x4 (&acc)[2][2][4][2], const Unit& u, int tid_in) const {
;     ...
;                 for (int mh = 0; mh < 2; ++mh) { u32x4 yv[2][2], uv[2][2];
; #pragma unroll
;                     for (int ml = 0; ml < 2; ++ml) { int R = rbase + ai * 128 + (mh * 2 + ml) * 16; asm volatile("" : "+v"(R));
; #pragma unroll
;                         for (int bj = 0; bj < 2; ++bj) { const int t = 16 * u.pn + 8 * bj + 2 * wc + (fq >> 1); const size_t tok = (size_t)R * LCH + t;
;                             yv[ml][bj] = *(const u32x4*)(yi + ((size_t)g * T_TOK + tok) * 16 + 8 * (fq & 1)); uv[ml][bj] = *(const u32x4*)((const bf16_t*)x + ((size_t)g * T_TOK + tok) * 16 + 8 * (fq & 1)); } }
; #pragma unroll
;                     for (int ml = 0; ml < 2; ++ml) { const int m = mh * 2 + ml; int R = rbase + ai * 128 + m * 16; asm volatile("" : "+v"(R));
; #pragma unroll
;                         for (int bj = 0; bj < 2; ++bj) { const int t = 16 * u.pn + 8 * bj + 2 * wc + (fq >> 1); const size_t tok = (size_t)R * LCH + t;
;                             f32x4 y0, y1, u0, u1; unpack8(yv[ml][bj], y0, y1); unpack8(uv[ml][bj], u0, u1);
;                             y0 = acc[ai][bj][m][0] + y0 + d0 * u0; y1 = acc[ai][bj][m][1] + y1 + d1 * u1;
; #pragma unroll
;                             for (int j = 0; j < 4; ++j) { y0[j] = gelu_tanh(y0[j]); y1[j] = gelu_tanh(y1[j]); }
;                             *(u32x4*)(yi + ((size_t)g * T_TOK + tok) * 16 + 8 * (fq & 1)) = pack8(y0, y1); } }
	v_and_b32_e32 v71, 0xffff0000, v82
	v_pk_add_f32 v[44:45], v[44:45], v[48:49]
	v_pk_add_f32 v[40:41], v[40:41], v[52:53]
	v_pk_fma_f32 v[44:45], v[60:61], v[66:67], v[44:45]
	v_pk_fma_f32 v[40:41], v[56:57], v[70:71], v[40:41]
	v_mul_f32_e32 v0, 0x3d372713, v44
	v_mul_f32_e32 v48, 0x3d372713, v40
	v_mul_f32_e32 v49, 0x3d372713, v45
	v_mul_f32_e32 v0, v44, v0
	v_mul_f32_e32 v48, v40, v48
	v_mul_f32_e32 v49, v45, v49
	v_fma_f32 v0, v44, v0, v44
	v_fma_f32 v48, v40, v48, v40
	v_fma_f32 v49, v45, v49, v45
	v_mul_f32_e32 v0, 0x3fcc422a, v0
	v_mul_f32_e32 v48, 0x3fcc422a, v48
	v_mul_f32_e32 v49, 0x3fcc422a, v49
	v_mul_f32_e32 v0, 0xbfb8aa3b, v0
	v_mul_f32_e32 v48, 0xbfb8aa3b, v48
	v_mul_f32_e32 v49, 0xbfb8aa3b, v49
	v_exp_f32_e32 v0, v0
	v_exp_f32_e32 v48, v48
	v_exp_f32_e32 v49, v49
	v_lshlrev_b32_e32 v50, 16, v85
	v_and_b32_e32 v51, 0xffff0000, v85
	v_pk_add_f32 v[46:47], v[46:47], v[50:51]
	v_add_f32_e32 v0, 1.0, v0
	v_add_f32_e32 v48, 1.0, v48
	v_add_f32_e32 v49, 1.0, v49
	v_mul_f32_e32 v50, 0x3d372713, v41
	v_rcp_f32_e32 v0, v0
	v_rcp_f32_e32 v48, v48
	v_rcp_f32_e32 v49, v49
	v_mul_f32_e32 v50, v41, v50
	v_lshlrev_b32_e32 v54, 16, v87
	v_and_b32_e32 v55, 0xffff0000, v87
	v_fma_f32 v50, v41, v50, v41
	v_lshlrev_b32_e32 v68, 16, v81
	v_and_b32_e32 v69, 0xffff0000, v81
	v_lshlrev_b32_e32 v72, 16, v83
	v_and_b32_e32 v73, 0xffff0000, v83
	v_pk_add_f32 v[42:43], v[42:43], v[54:55]
	v_mul_f32_e32 v50, 0x3fcc422a, v50
	v_pk_fma_f32 v[46:47], v[62:63], v[68:69], v[46:47]
	v_pk_fma_f32 v[42:43], v[58:59], v[72:73], v[42:43]
	v_mul_f32_e32 v50, 0xbfb8aa3b, v50
	v_exp_f32_e32 v50, v50
	v_mul_f32_e32 v0, v44, v0
	v_mul_f32_e32 v44, v40, v48
	v_mul_f32_e32 v40, v45, v49
	v_mul_f32_e32 v48, 0x3d372713, v46
	v_mul_f32_e32 v49, 0x3d372713, v42
	v_mul_f32_e32 v48, v46, v48
	v_mul_f32_e32 v49, v42, v49
	v_fma_f32 v48, v46, v48, v46
	v_fma_f32 v49, v42, v49, v42
	v_mul_f32_e32 v48, 0x3fcc422a, v48
	v_mul_f32_e32 v49, 0x3fcc422a, v49
	v_add_f32_e32 v45, 1.0, v50
	v_mul_f32_e32 v48, 0xbfb8aa3b, v48
	v_mul_f32_e32 v49, 0xbfb8aa3b, v49
	v_rcp_f32_e32 v45, v45
	v_exp_f32_e32 v48, v48
	v_exp_f32_e32 v49, v49
	v_mul_f32_e32 v50, 0x3d372713, v43
	v_mul_f32_e32 v45, v41, v45
	v_add_f32_e32 v41, 1.0, v48
	v_add_f32_e32 v48, 1.0, v49
	v_mul_f32_e32 v49, 0x3d372713, v47
	v_mul_f32_e32 v49, v47, v49
	v_fma_f32 v49, v47, v49, v47
	v_mul_f32_e32 v50, v43, v50
	v_mul_f32_e32 v49, 0x3fcc422a, v49
	v_fma_f32 v50, v43, v50, v43
	v_mul_f32_e32 v49, 0xbfb8aa3b, v49
	v_mul_f32_e32 v50, 0x3fcc422a, v50
	v_exp_f32_e32 v49, v49
	v_mul_f32_e32 v50, 0xbfb8aa3b, v50
	v_exp_f32_e32 v50, v50
	v_rcp_f32_e32 v41, v41
	v_add_f32_e32 v49, 1.0, v49
	v_rcp_f32_e32 v48, v48
	v_rcp_f32_e32 v49, v49
	v_add_f32_e32 v50, 1.0, v50
	v_rcp_f32_e32 v50, v50
	v_mul_f32_e32 v41, v46, v41
	v_mul_f32_e32 v46, v42, v48
	v_mul_f32_e32 v42, v47, v49
	v_mul_f32_e32 v43, v43, v50
	v_cvt_pk_bf16_f32 v40, v0, v40
	v_cvt_pk_bf16_f32 v41, v41, v42
	v_cvt_pk_bf16_f32 v42, v44, v45
	v_lshl_add_u64 v[44:45], v[64:65], 0, v[128:129]
	v_add_u32_e32 v66, 0xa0, v185
	v_cvt_pk_bf16_f32 v43, v46, v43
	global_store_dwordx4 v[44:45], v[40:43], off
	v_add_u32_e32 v64, 0xb0, v185
	s_nop 0
	v_mov_b32_e32 v40, v66
	s_nop 0
	v_ashrrev_i32_e32 v41, 31, v40
	v_lshlrev_b64 v[40:41], 9, v[40:41]
	v_lshl_add_u64 v[40:41], v[40:41], 0, s[20:21]
	v_lshl_add_u64 v[42:43], v[40:41], 0, v[172:173]
	v_lshlrev_b64 v[42:43], 1, v[42:43]
	v_lshl_add_u64 v[44:45], v[164:165], 0, v[42:43]
	global_load_dwordx4 v[68:71], v[44:45], off
	v_lshl_add_u64 v[42:43], v[166:167], 0, v[42:43]
	global_load_dwordx4 v[72:75], v[42:43], off
	v_lshl_add_u64 v[40:41], v[40:41], 0, v[174:175]
	v_lshlrev_b64 v[40:41], 1, v[40:41]
	v_lshl_add_u64 v[42:43], v[164:165], 0, v[40:41]
	global_load_dwordx4 v[76:79], v[42:43], off
	v_lshl_add_u64 v[40:41], v[166:167], 0, v[40:41]
	global_load_dwordx4 v[80:83], v[40:41], off
	v_mov_b32_e32 v40, v64
	s_waitcnt vmcnt(0)
	v_lshlrev_b32_e32 v84, 16, v68
	v_ashrrev_i32_e32 v41, 31, v40
	v_lshlrev_b64 v[40:41], 9, v[40:41]
	v_lshl_add_u64 v[40:41], v[40:41], 0, s[20:21]
	v_and_b32_e32 v85, 0xffff0000, v68
	v_lshlrev_b32_e32 v86, 16, v70
	v_and_b32_e32 v87, 0xffff0000, v70
	v_lshl_add_u64 v[42:43], v[40:41], 0, v[172:173]
	v_lshlrev_b32_e32 v88, 16, v72
	v_and_b32_e32 v89, 0xffff0000, v72
	v_lshlrev_b32_e32 v90, 16, v74
	v_and_b32_e32 v91, 0xffff0000, v74
	v_pk_add_f32 v[36:37], v[36:37], v[84:85]
	v_pk_add_f32 v[32:33], v[32:33], v[86:87]
	v_lshlrev_b64 v[42:43], 1, v[42:43]
	v_lshlrev_b32_e32 v68, 16, v69
	v_and_b32_e32 v69, 0xffff0000, v69
	v_pk_fma_f32 v[36:37], v[60:61], v[88:89], v[36:37]
	v_pk_fma_f32 v[32:33], v[56:57], v[90:91], v[32:33]
	v_lshl_add_u64 v[44:45], v[164:165], 0, v[42:43]
	v_pk_add_f32 v[38:39], v[38:39], v[68:69]
	v_mul_f32_e32 v0, 0x3d372713, v36
	v_mul_f32_e32 v65, 0x3d372713, v32
	v_mul_f32_e32 v68, 0x3d372713, v37
	global_load_dwordx4 v[52:55], v[44:45], off
	v_lshl_add_u64 v[42:43], v[166:167], 0, v[42:43]
	v_mul_f32_e32 v0, v36, v0
	v_mul_f32_e32 v65, v32, v65
	v_mul_f32_e32 v68, v37, v68
	global_load_dwordx4 v[48:51], v[42:43], off
	v_fma_f32 v0, v36, v0, v36
	v_fma_f32 v65, v32, v65, v32
	v_fma_f32 v68, v37, v68, v37
	v_mul_f32_e32 v0, 0x3fcc422a, v0
	v_mul_f32_e32 v65, 0x3fcc422a, v65
	v_mul_f32_e32 v68, 0x3fcc422a, v68
	v_mul_f32_e32 v0, 0xbfb8aa3b, v0
	v_mul_f32_e32 v65, 0xbfb8aa3b, v65
	v_mul_f32_e32 v68, 0xbfb8aa3b, v68
	v_exp_f32_e32 v0, v0
	v_exp_f32_e32 v65, v65
	v_exp_f32_e32 v68, v68
	v_mul_f32_e32 v69, 0x3d372713, v33
	v_add_f32_e32 v0, 1.0, v0
	v_add_f32_e32 v65, 1.0, v65
	v_add_f32_e32 v68, 1.0, v68
	v_rcp_f32_e32 v0, v0
	v_rcp_f32_e32 v65, v65
	v_rcp_f32_e32 v68, v68
; __device__ __forceinline__ float gelu_tanh(float y) { const float z = 1.5957691216057308f * (y + 0.044715f * y * y * y); return y * sigmoidf_(z); }
; __device__ __forceinline__ u32x4 pack8(const f32x4 a, const f32x4 b) { u32x4 w; w.x = cvt_pk_bf16(a[0], a[1]); w.y = cvt_pk_bf16(a[2], a[3]); w.z = cvt_pk_bf16(b[0], b[1]); w.w = cvt_pk_bf16(b[2], b[3]); return w; }
; __device__ __forceinline__ void unpack8(const u32x4 w, f32x4& a, f32x4& b) { a[0] = bf_lo(w.x); a[1] = bf_hi(w.x); a[2] = bf_lo(w.y); a[3] = bf_hi(w.y); b[0] = bf_lo(w.z); b[1] = bf_hi(w.z); b[2] = bf_lo(w.w); b[3] = bf_hi(w.w); }
;     template <int KIND> __device__ __forceinline__ void run(f32x4 (&acc)[2][2][4][2], const Unit& u, int tid_in) const {
;     ...
;                         for (int bj = 0; bj < 2; ++bj) { const int t = 16 * u.pn + 8 * bj + 2 * wc + (fq >> 1); const size_t tok = (size_t)R * LCH + t;
;                             yv[ml][bj] = *(const u32x4*)(yi + ((size_t)g * T_TOK + tok) * 16 + 8 * (fq & 1)); uv[ml][bj] = *(const u32x4*)((const bf16_t*)x + ((size_t)g * T_TOK + tok) * 16 + 8 * (fq & 1)); } }
; #pragma unroll
;                     for (int ml = 0; ml < 2; ++ml) { const int m = mh * 2 + ml; int R = rbase + ai * 128 + m * 16; asm volatile("" : "+v"(R));
; #pragma unroll
;                         for (int bj = 0; bj < 2; ++bj) { const int t = 16 * u.pn + 8 * bj + 2 * wc + (fq >> 1); const size_t tok = (size_t)R * LCH + t;
;                             f32x4 y0, y1, u0, u1; unpack8(yv[ml][bj], y0, y1); unpack8(uv[ml][bj], u0, u1);
;                             y0 = acc[ai][bj][m][0] + y0 + d0 * u0; y1 = acc[ai][bj][m][1] + y1 + d1 * u1;
; #pragma unroll
;                             for (int j = 0; j < 4; ++j) { y0[j] = gelu_tanh(y0[j]); y1[j] = gelu_tanh(y1[j]); }
;                             *(u32x4*)(yi + ((size_t)g * T_TOK + tok) * 16 + 8 * (fq & 1)) = pack8(y0, y1); } }
	v_mul_f32_e32 v69, v33, v69
	v_lshlrev_b32_e32 v70, 16, v71
	v_and_b32_e32 v71, 0xffff0000, v71
	v_fma_f32 v69, v33, v69, v33
	v_lshlrev_b32_e32 v72, 16, v73
	v_and_b32_e32 v73, 0xffff0000, v73
	v_lshlrev_b32_e32 v74, 16, v75
	v_and_b32_e32 v75, 0xffff0000, v75
	v_pk_add_f32 v[34:35], v[34:35], v[70:71]
	v_mul_f32_e32 v69, 0x3fcc422a, v69
	v_pk_fma_f32 v[38:39], v[62:63], v[72:73], v[38:39]
	v_pk_fma_f32 v[34:35], v[58:59], v[74:75], v[34:35]
	v_mul_f32_e32 v69, 0xbfb8aa3b, v69
	v_exp_f32_e32 v69, v69
	v_mul_f32_e32 v0, v36, v0
	v_mul_f32_e32 v36, v32, v65
	v_mul_f32_e32 v32, v37, v68
	v_mul_f32_e32 v65, 0x3d372713, v38
	v_mul_f32_e32 v68, 0x3d372713, v34
	v_mul_f32_e32 v65, v38, v65
	v_mul_f32_e32 v68, v34, v68
	v_fma_f32 v65, v38, v65, v38
	v_fma_f32 v68, v34, v68, v34
	v_mul_f32_e32 v65, 0x3fcc422a, v65
	v_mul_f32_e32 v68, 0x3fcc422a, v68
	v_add_f32_e32 v37, 1.0, v69
	v_mul_f32_e32 v65, 0xbfb8aa3b, v65
	v_mul_f32_e32 v68, 0xbfb8aa3b, v68
	v_rcp_f32_e32 v37, v37
	v_exp_f32_e32 v65, v65
	v_exp_f32_e32 v68, v68
	v_mul_f32_e32 v69, 0x3d372713, v35
	v_mul_f32_e32 v37, v33, v37
	v_add_f32_e32 v33, 1.0, v65
	v_add_f32_e32 v65, 1.0, v68
	v_mul_f32_e32 v68, 0x3d372713, v39
	v_mul_f32_e32 v68, v39, v68
	v_fma_f32 v68, v39, v68, v39
	v_mul_f32_e32 v69, v35, v69
	v_mul_f32_e32 v68, 0x3fcc422a, v68
	v_fma_f32 v69, v35, v69, v35
	v_mul_f32_e32 v68, 0xbfb8aa3b, v68
	v_mul_f32_e32 v69, 0x3fcc422a, v69
	v_exp_f32_e32 v68, v68
	v_mul_f32_e32 v69, 0xbfb8aa3b, v69
	v_exp_f32_e32 v69, v69
	v_lshl_add_u64 v[40:41], v[40:41], 0, v[174:175]
	v_add_f32_e32 v68, 1.0, v68
	v_lshlrev_b64 v[40:41], 1, v[40:41]
	v_rcp_f32_e32 v33, v33
	v_rcp_f32_e32 v65, v65
	v_rcp_f32_e32 v68, v68
	v_add_f32_e32 v69, 1.0, v69
	v_lshl_add_u64 v[42:43], v[164:165], 0, v[40:41]
	v_lshl_add_u64 v[40:41], v[166:167], 0, v[40:41]
	v_rcp_f32_e32 v69, v69
	global_load_dwordx4 v[44:47], v[42:43], off
	v_mul_f32_e32 v33, v38, v33
	global_load_dwordx4 v[40:43], v[40:41], off
	v_mul_f32_e32 v38, v34, v65
	v_ashrrev_i32_e32 v67, 31, v66
	v_lshlrev_b64 v[66:67], 10, v[66:67]
	v_lshl_add_u64 v[66:67], v[162:163], 0, v[66:67]
	v_mul_f32_e32 v34, v39, v68
	v_mul_f32_e32 v35, v35, v69
	v_cvt_pk_bf16_f32 v32, v0, v32
	v_cvt_pk_bf16_f32 v33, v33, v34
	v_cvt_pk_bf16_f32 v34, v36, v37
	v_lshl_add_u64 v[36:37], v[66:67], 0, v[136:137]
	v_cvt_pk_bf16_f32 v35, v38, v35
	global_store_dwordx4 v[36:37], v[32:35], off
	v_lshlrev_b32_e32 v36, 16, v78
	v_and_b32_e32 v37, 0xffff0000, v78
	v_lshlrev_b32_e32 v32, 16, v76
	v_and_b32_e32 v33, 0xffff0000, v76
	v_lshlrev_b32_e32 v68, 16, v80
	v_and_b32_e32 v69, 0xffff0000, v80
	v_lshlrev_b32_e32 v72, 16, v82
	v_and_b32_e32 v73, 0xffff0000, v82
	v_pk_add_f32 v[28:29], v[28:29], v[32:33]
	v_pk_add_f32 v[24:25], v[24:25], v[36:37]
	v_pk_fma_f32 v[28:29], v[60:61], v[68:69], v[28:29]
	v_pk_fma_f32 v[24:25], v[56:57], v[72:73], v[24:25]
	v_mul_f32_e32 v0, 0x3d372713, v28
	v_mul_f32_e32 v32, 0x3d372713, v24
	v_mul_f32_e32 v33, 0x3d372713, v29
	v_mul_f32_e32 v0, v28, v0
	v_mul_f32_e32 v32, v24, v32
	v_mul_f32_e32 v33, v29, v33
	v_fma_f32 v0, v28, v0, v28
	v_fma_f32 v32, v24, v32, v24
	v_fma_f32 v33, v29, v33, v29
	v_mul_f32_e32 v0, 0x3fcc422a, v0
	v_mul_f32_e32 v32, 0x3fcc422a, v32
	v_mul_f32_e32 v33, 0x3fcc422a, v33
	v_mul_f32_e32 v0, 0xbfb8aa3b, v0
	v_mul_f32_e32 v32, 0xbfb8aa3b, v32
	v_mul_f32_e32 v33, 0xbfb8aa3b, v33
	v_exp_f32_e32 v0, v0
	v_exp_f32_e32 v32, v32
	v_exp_f32_e32 v33, v33
	v_lshlrev_b32_e32 v34, 16, v77
	v_and_b32_e32 v35, 0xffff0000, v77
	v_pk_add_f32 v[30:31], v[30:31], v[34:35]
	v_add_f32_e32 v0, 1.0, v0
	v_add_f32_e32 v32, 1.0, v32
	v_add_f32_e32 v33, 1.0, v33
	v_mul_f32_e32 v34, 0x3d372713, v25
	v_rcp_f32_e32 v0, v0
	v_rcp_f32_e32 v32, v32
	v_rcp_f32_e32 v33, v33
	v_mul_f32_e32 v34, v25, v34
	v_lshlrev_b32_e32 v38, 16, v79
	v_and_b32_e32 v39, 0xffff0000, v79
	v_fma_f32 v34, v25, v34, v25
	v_lshlrev_b32_e32 v70, 16, v81
	v_and_b32_e32 v71, 0xffff0000, v81
	v_lshlrev_b32_e32 v74, 16, v83
	v_and_b32_e32 v75, 0xffff0000, v83
	v_pk_add_f32 v[26:27], v[26:27], v[38:39]
	v_mul_f32_e32 v34, 0x3fcc422a, v34
	v_pk_fma_f32 v[30:31], v[62:63], v[70:71], v[30:31]
	v_pk_fma_f32 v[26:27], v[58:59], v[74:75], v[26:27]
	v_mul_f32_e32 v34, 0xbfb8aa3b, v34
	v_exp_f32_e32 v34, v34
	v_mul_f32_e32 v0, v28, v0
	v_mul_f32_e32 v28, v24, v32
	v_mul_f32_e32 v24, v29, v33
	v_mul_f32_e32 v32, 0x3d372713, v30
	v_mul_f32_e32 v33, 0x3d372713, v26
	v_mul_f32_e32 v32, v30, v32
	v_mul_f32_e32 v33, v26, v33
	v_fma_f32 v32, v30, v32, v30
	v_fma_f32 v33, v26, v33, v26
	v_mul_f32_e32 v32, 0x3fcc422a, v32
	v_mul_f32_e32 v33, 0x3fcc422a, v33
	v_add_f32_e32 v29, 1.0, v34
	v_mul_f32_e32 v32, 0xbfb8aa3b, v32
	v_mul_f32_e32 v33, 0xbfb8aa3b, v33
	v_rcp_f32_e32 v29, v29
	v_exp_f32_e32 v32, v32
	v_exp_f32_e32 v33, v33
	v_mul_f32_e32 v34, 0x3d372713, v27
	v_mul_f32_e32 v29, v25, v29
	v_add_f32_e32 v25, 1.0, v32
	v_add_f32_e32 v32, 1.0, v33
	v_mul_f32_e32 v33, 0x3d372713, v31
	v_mul_f32_e32 v33, v31, v33
	v_mul_f32_e32 v34, v27, v34
	v_fma_f32 v33, v31, v33, v31
	v_fma_f32 v34, v27, v34, v27
	v_mul_f32_e32 v33, 0x3fcc422a, v33
	v_mul_f32_e32 v34, 0x3fcc422a, v34
	v_mul_f32_e32 v33, 0xbfb8aa3b, v33
	v_mul_f32_e32 v34, 0xbfb8aa3b, v34
	v_exp_f32_e32 v33, v33
	v_exp_f32_e32 v34, v34
	v_rcp_f32_e32 v25, v25
	v_rcp_f32_e32 v32, v32
	v_add_f32_e32 v33, 1.0, v33
	v_add_f32_e32 v34, 1.0, v34
	v_rcp_f32_e32 v33, v33
	v_rcp_f32_e32 v34, v34
	v_mul_f32_e32 v25, v30, v25
	v_mul_f32_e32 v30, v26, v32
	v_mul_f32_e32 v26, v31, v33
	v_mul_f32_e32 v27, v27, v34
	v_cvt_pk_bf16_f32 v24, v0, v24
	v_cvt_pk_bf16_f32 v25, v25, v26
	v_cvt_pk_bf16_f32 v26, v28, v29
	v_cvt_pk_bf16_f32 v27, v30, v27
	v_lshl_add_u64 v[28:29], v[66:67], 0, v[128:129]
	global_store_dwordx4 v[28:29], v[24:27], off
	s_waitcnt vmcnt(0)
; __device__ __forceinline__ float gelu_tanh(float y) { const float z = 1.5957691216057308f * (y + 0.044715f * y * y * y); return y * sigmoidf_(z); }
; __device__ __forceinline__ u32x4 pack8(const f32x4 a, const f32x4 b) { u32x4 w; w.x = cvt_pk_bf16(a[0], a[1]); w.y = cvt_pk_bf16(a[2], a[3]); w.z = cvt_pk_bf16(b[0], b[1]); w.w = cvt_pk_bf16(b[2], b[3]); return w; }
; __device__ __forceinline__ void unpack8(const u32x4 w, f32x4& a, f32x4& b) { a[0] = bf_lo(w.x); a[1] = bf_hi(w.x); a[2] = bf_lo(w.y); a[3] = bf_hi(w.y); b[0] = bf_lo(w.z); b[1] = bf_hi(w.z); b[2] = bf_lo(w.w); b[3] = bf_hi(w.w); }
; #define G_WAIT_V(n) asm volatile("s_waitcnt vmcnt(" #n ")" ::: "memory")
; #define G_BAR __builtin_amdgcn_s_barrier()
;     template <int KIND> __device__ __forceinline__ void run(f32x4 (&acc)[2][2][4][2], const Unit& u, int tid_in) const {
;     ...
;                         for (int bj = 0; bj < 2; ++bj) { const int t = 16 * u.pn + 8 * bj + 2 * wc + (fq >> 1); const size_t tok = (size_t)R * LCH + t;
;                             yv[ml][bj] = *(const u32x4*)(yi + ((size_t)g * T_TOK + tok) * 16 + 8 * (fq & 1)); uv[ml][bj] = *(const u32x4*)((const bf16_t*)x + ((size_t)g * T_TOK + tok) * 16 + 8 * (fq & 1)); } }
; #pragma unroll
;                     for (int ml = 0; ml < 2; ++ml) { const int m = mh * 2 + ml; int R = rbase + ai * 128 + m * 16; asm volatile("" : "+v"(R));
; #pragma unroll
;                         for (int bj = 0; bj < 2; ++bj) { const int t = 16 * u.pn + 8 * bj + 2 * wc + (fq >> 1); const size_t tok = (size_t)R * LCH + t;
;                             f32x4 y0, y1, u0, u1; unpack8(yv[ml][bj], y0, y1); unpack8(uv[ml][bj], u0, u1);
;                             y0 = acc[ai][bj][m][0] + y0 + d0 * u0; y1 = acc[ai][bj][m][1] + y1 + d1 * u1;
; #pragma unroll
;                             for (int j = 0; j < 4; ++j) { y0[j] = gelu_tanh(y0[j]); y1[j] = gelu_tanh(y1[j]); }
;                             *(u32x4*)(yi + ((size_t)g * T_TOK + tok) * 16 + 8 * (fq & 1)) = pack8(y0, y1); } }
;     ...
;     G_WAIT_V(0);
;     if (wr == 0) G_BAR;
;     G_BAR;
	v_lshlrev_b32_e32 v30, 16, v54
	v_and_b32_e32 v31, 0xffff0000, v54
	v_lshlrev_b32_e32 v26, 16, v52
	v_and_b32_e32 v27, 0xffff0000, v52
	v_lshlrev_b32_e32 v34, 16, v48
	v_and_b32_e32 v35, 0xffff0000, v48
	v_lshlrev_b32_e32 v38, 16, v50
	v_and_b32_e32 v39, 0xffff0000, v50
	v_pk_add_f32 v[20:21], v[20:21], v[26:27]
	v_pk_add_f32 v[16:17], v[16:17], v[30:31]
	v_pk_fma_f32 v[20:21], v[60:61], v[34:35], v[20:21]
	v_pk_fma_f32 v[16:17], v[56:57], v[38:39], v[16:17]
	v_mul_f32_e32 v0, 0x3d372713, v20
	v_mul_f32_e32 v26, 0x3d372713, v16
	v_mul_f32_e32 v27, 0x3d372713, v21
	v_mul_f32_e32 v0, v20, v0
	v_mul_f32_e32 v26, v16, v26
	v_mul_f32_e32 v27, v21, v27
	v_fma_f32 v0, v20, v0, v20
	v_fma_f32 v26, v16, v26, v16
	v_fma_f32 v27, v21, v27, v21
	v_mul_f32_e32 v0, 0x3fcc422a, v0
	v_mul_f32_e32 v26, 0x3fcc422a, v26
	v_mul_f32_e32 v27, 0x3fcc422a, v27
	v_mul_f32_e32 v0, 0xbfb8aa3b, v0
	v_mul_f32_e32 v26, 0xbfb8aa3b, v26
	v_mul_f32_e32 v27, 0xbfb8aa3b, v27
	v_exp_f32_e32 v0, v0
	v_exp_f32_e32 v26, v26
	v_exp_f32_e32 v27, v27
	v_lshlrev_b32_e32 v28, 16, v53
	v_and_b32_e32 v29, 0xffff0000, v53
	v_pk_add_f32 v[22:23], v[22:23], v[28:29]
	v_add_f32_e32 v0, 1.0, v0
	v_add_f32_e32 v26, 1.0, v26
	v_add_f32_e32 v27, 1.0, v27
	v_mul_f32_e32 v28, 0x3d372713, v17
	v_rcp_f32_e32 v0, v0
	v_rcp_f32_e32 v26, v26
	v_rcp_f32_e32 v27, v27
	v_mul_f32_e32 v28, v17, v28
	v_lshlrev_b32_e32 v32, 16, v55
	v_and_b32_e32 v33, 0xffff0000, v55
	v_fma_f32 v28, v17, v28, v17
	v_lshlrev_b32_e32 v36, 16, v49
	v_and_b32_e32 v37, 0xffff0000, v49
	v_lshlrev_b32_e32 v48, 16, v51
	v_and_b32_e32 v49, 0xffff0000, v51
	v_pk_add_f32 v[18:19], v[18:19], v[32:33]
	v_mul_f32_e32 v28, 0x3fcc422a, v28
	v_pk_fma_f32 v[22:23], v[62:63], v[36:37], v[22:23]
	v_pk_fma_f32 v[18:19], v[58:59], v[48:49], v[18:19]
	v_mul_f32_e32 v28, 0xbfb8aa3b, v28
	v_exp_f32_e32 v28, v28
	v_mul_f32_e32 v0, v20, v0
	v_mul_f32_e32 v20, v16, v26
	v_mul_f32_e32 v16, v21, v27
	v_mul_f32_e32 v26, 0x3d372713, v22
	v_mul_f32_e32 v27, 0x3d372713, v18
	v_mul_f32_e32 v26, v22, v26
	v_mul_f32_e32 v27, v18, v27
	v_fma_f32 v26, v22, v26, v22
	v_fma_f32 v27, v18, v27, v18
	v_mul_f32_e32 v26, 0x3fcc422a, v26
	v_mul_f32_e32 v27, 0x3fcc422a, v27
	v_add_f32_e32 v21, 1.0, v28
	v_mul_f32_e32 v26, 0xbfb8aa3b, v26
	v_mul_f32_e32 v27, 0xbfb8aa3b, v27
	v_rcp_f32_e32 v21, v21
	v_exp_f32_e32 v26, v26
	v_exp_f32_e32 v27, v27
	v_mul_f32_e32 v28, 0x3d372713, v19
	v_mul_f32_e32 v21, v17, v21
	v_add_f32_e32 v17, 1.0, v26
	v_add_f32_e32 v26, 1.0, v27
	v_mul_f32_e32 v27, 0x3d372713, v23
	v_mul_f32_e32 v27, v23, v27
	v_fma_f32 v27, v23, v27, v23
	v_mul_f32_e32 v28, v19, v28
	v_mul_f32_e32 v27, 0x3fcc422a, v27
	v_fma_f32 v28, v19, v28, v19
	v_mul_f32_e32 v27, 0xbfb8aa3b, v27
	v_mul_f32_e32 v28, 0x3fcc422a, v28
	v_exp_f32_e32 v27, v27
	v_mul_f32_e32 v28, 0xbfb8aa3b, v28
	v_exp_f32_e32 v28, v28
	v_rcp_f32_e32 v17, v17
	v_add_f32_e32 v27, 1.0, v27
	v_rcp_f32_e32 v26, v26
	v_rcp_f32_e32 v27, v27
	v_add_f32_e32 v28, 1.0, v28
	v_rcp_f32_e32 v28, v28
	v_mul_f32_e32 v17, v22, v17
	v_ashrrev_i32_e32 v65, 31, v64
	v_lshlrev_b64 v[24:25], 10, v[64:65]
	v_lshl_add_u64 v[24:25], v[162:163], 0, v[24:25]
	v_mul_f32_e32 v22, v18, v26
	v_mul_f32_e32 v18, v23, v27
	v_mul_f32_e32 v19, v19, v28
	v_cvt_pk_bf16_f32 v16, v0, v16
	v_cvt_pk_bf16_f32 v17, v17, v18
	v_cvt_pk_bf16_f32 v18, v20, v21
	v_lshl_add_u64 v[20:21], v[24:25], 0, v[136:137]
	v_cvt_pk_bf16_f32 v19, v22, v19
	global_store_dwordx4 v[20:21], v[16:19], off
	v_lshlrev_b32_e32 v20, 16, v46
	v_and_b32_e32 v21, 0xffff0000, v46
	v_lshlrev_b32_e32 v16, 16, v44
	v_and_b32_e32 v17, 0xffff0000, v44
	v_lshlrev_b32_e32 v26, 16, v40
	v_and_b32_e32 v27, 0xffff0000, v40
	v_lshlrev_b32_e32 v30, 16, v42
	v_and_b32_e32 v31, 0xffff0000, v42
	v_pk_add_f32 v[12:13], v[12:13], v[16:17]
	v_pk_add_f32 v[8:9], v[8:9], v[20:21]
	v_pk_fma_f32 v[12:13], v[60:61], v[26:27], v[12:13]
	v_pk_fma_f32 v[8:9], v[56:57], v[30:31], v[8:9]
	v_mul_f32_e32 v0, 0x3d372713, v12
	v_mul_f32_e32 v16, 0x3d372713, v8
	v_mul_f32_e32 v17, 0x3d372713, v13
	v_mul_f32_e32 v0, v12, v0
	v_mul_f32_e32 v16, v8, v16
	v_mul_f32_e32 v17, v13, v17
	v_fma_f32 v0, v12, v0, v12
	v_fma_f32 v16, v8, v16, v8
	v_fma_f32 v17, v13, v17, v13
	v_mul_f32_e32 v0, 0x3fcc422a, v0
	v_mul_f32_e32 v16, 0x3fcc422a, v16
	v_mul_f32_e32 v17, 0x3fcc422a, v17
	v_mul_f32_e32 v0, 0xbfb8aa3b, v0
	v_mul_f32_e32 v16, 0xbfb8aa3b, v16
	v_mul_f32_e32 v17, 0xbfb8aa3b, v17
	v_exp_f32_e32 v0, v0
	v_exp_f32_e32 v16, v16
	v_exp_f32_e32 v17, v17
	v_lshlrev_b32_e32 v18, 16, v45
	v_and_b32_e32 v19, 0xffff0000, v45
	v_pk_add_f32 v[14:15], v[14:15], v[18:19]
	v_add_f32_e32 v0, 1.0, v0
	v_add_f32_e32 v16, 1.0, v16
	v_add_f32_e32 v17, 1.0, v17
	v_mul_f32_e32 v18, 0x3d372713, v9
	v_rcp_f32_e32 v0, v0
	v_rcp_f32_e32 v16, v16
	v_rcp_f32_e32 v17, v17
	v_mul_f32_e32 v18, v9, v18
	v_lshlrev_b32_e32 v22, 16, v47
	v_and_b32_e32 v23, 0xffff0000, v47
	v_fma_f32 v18, v9, v18, v9
	v_lshlrev_b32_e32 v28, 16, v41
	v_and_b32_e32 v29, 0xffff0000, v41
	v_lshlrev_b32_e32 v32, 16, v43
	v_and_b32_e32 v33, 0xffff0000, v43
	v_pk_add_f32 v[10:11], v[10:11], v[22:23]
	v_mul_f32_e32 v18, 0x3fcc422a, v18
	v_pk_fma_f32 v[14:15], v[62:63], v[28:29], v[14:15]
	v_pk_fma_f32 v[10:11], v[58:59], v[32:33], v[10:11]
	v_mul_f32_e32 v18, 0xbfb8aa3b, v18
	v_exp_f32_e32 v18, v18
	v_mul_f32_e32 v0, v12, v0
	v_mul_f32_e32 v12, v8, v16
	v_mul_f32_e32 v8, v13, v17
	v_mul_f32_e32 v16, 0x3d372713, v14
	v_mul_f32_e32 v17, 0x3d372713, v10
	v_mul_f32_e32 v16, v14, v16
	v_mul_f32_e32 v17, v10, v17
	v_fma_f32 v16, v14, v16, v14
	v_fma_f32 v17, v10, v17, v10
	v_mul_f32_e32 v16, 0x3fcc422a, v16
	v_mul_f32_e32 v17, 0x3fcc422a, v17
	v_add_f32_e32 v13, 1.0, v18
	v_mul_f32_e32 v16, 0xbfb8aa3b, v16
	v_mul_f32_e32 v17, 0xbfb8aa3b, v17
	v_rcp_f32_e32 v13, v13
	v_exp_f32_e32 v16, v16
	v_exp_f32_e32 v17, v17
	v_mul_f32_e32 v18, 0x3d372713, v11
	v_mul_f32_e32 v13, v9, v13
	v_add_f32_e32 v9, 1.0, v16
	v_add_f32_e32 v16, 1.0, v17
	v_mul_f32_e32 v17, 0x3d372713, v15
	v_mul_f32_e32 v17, v15, v17
	v_fma_f32 v17, v15, v17, v15
	v_mul_f32_e32 v18, v11, v18
	v_mul_f32_e32 v17, 0x3fcc422a, v17
	v_fma_f32 v18, v11, v18, v11
	v_mul_f32_e32 v17, 0xbfb8aa3b, v17
	v_mul_f32_e32 v18, 0x3fcc422a, v18
	v_exp_f32_e32 v17, v17
	v_mul_f32_e32 v18, 0xbfb8aa3b, v18
	v_exp_f32_e32 v18, v18
	v_rcp_f32_e32 v9, v9
	v_add_f32_e32 v17, 1.0, v17
	v_rcp_f32_e32 v16, v16
	v_rcp_f32_e32 v17, v17
	v_add_f32_e32 v18, 1.0, v18
	v_rcp_f32_e32 v18, v18
	v_mul_f32_e32 v9, v14, v9
	v_mul_f32_e32 v14, v10, v16
	v_mul_f32_e32 v10, v15, v17
	v_mul_f32_e32 v11, v11, v18
	v_cvt_pk_bf16_f32 v8, v0, v8
	v_cvt_pk_bf16_f32 v9, v9, v10
	v_cvt_pk_bf16_f32 v10, v12, v13
	v_lshl_add_u64 v[12:13], v[24:25], 0, v[128:129]
	v_cvt_pk_bf16_f32 v11, v14, v11
	global_store_dwordx4 v[12:13], v[8:11], off
	s_mov_b64 s[20:21], s[16:17]
	s_cbranch_vccz .LBB0_737
	s_cmp_eq_u32 s101, 2
	s_cbranch_scc0 .Ldbj_SSM2_pe
	s_barrier
.Ldbj_SSM2_pe:
	s_mov_b32 s101, 0
	s_waitcnt vmcnt(0)
	s_cmpk_gt_u32 s61, 0xff
	s_cbranch_scc1 .LBB0_746
	s_barrier

; #define G_STAGE(bufoff, gbase, o0, h64) do { \
;         __builtin_amdgcn_global_load_lds((const unsigned*)((const char*)(gbase) + (o0)), (LAS unsigned*)(lds + (bufoff) + ldsw), 16, 0, 0); \
;         __builtin_amdgcn_global_load_lds((const unsigned*)((const char*)(gbase) + (h64) + (o0)), (LAS unsigned*)(lds + (bufoff) + ldsw + 8192), 16, 0, 0); } while (0)
; #define G_LDA(dst, b, h) do { _Pragma("unroll") for (int m = 0; m < 4; ++m) _Pragma("unroll") for (int k = 0; k < 2; ++k) dst[m][k] = *(const LAS bf16x8*)(lds + G_SA(b, h) + aoff + m * 2048 + k * 1024); } while (0)
; #define G_LDB(dst, b, h) do { _Pragma("unroll") for (int n = 0; n < 2; ++n) _Pragma("unroll") for (int k = 0; k < 2; ++k) dst[n][k] = *(const LAS bf16x8*)(lds + G_SB(b, h) + boff + n * 2048 + k * 1024); } while (0)
; #define G_WAIT_L(n) asm volatile("s_waitcnt lgkmcnt(" #n ")" ::: "memory")
; #define G_BAR __builtin_amdgcn_s_barrier()
; #define G_SCHED __builtin_amdgcn_sched_barrier(0)
;     ...
;         for (int t = 0; t < nt; t += 2) {
;             const bool last = (t == nt - 2);
;             const char* a1 = cA + (size_t)(t + 1) * ckA;
;             const char* a2 = last ? nA : cA + (size_t)(t + 2) * ckA; const char* b2 = last ? nB : cB + (size_t)(t + 2) * kB;
;             const char* a3 = a2 + ckA; const char* b3 = b2 + kB;
;             G_LDB(B0, 0, 0); G_SCHED; G_LDA(At, 0, 0); G_STAGE(G_SA(1, 1), a1 + chA, cA0, qA);
;             G_WAIT_L(8); G_BAR; G_WAIT_L(0); G_MMA(0, 0, At, B0); G_BAR; G_SCHED;
;             G_LDB(B1, 0, 1); G_STAGE(G_SB(0, 0), b2, cB0, qB);
;             G_BAR; G_WAIT_L(0); G_MMA(0, 1, At, B1); G_BAR;
;             G_LDA(At, 0, 1); G_STAGE(G_SA(0, 0), a2, cA0, qA);
;             G_BAR; G_WAIT_L(0); G_MMA(1, 0, At, B0); G_BAR; G_SCHED;
;     ...
;         for (int a = 0; a < 2; ++a)
; #pragma unroll
;             for (int b = 0; b < 2; ++b)
; #pragma unroll
;                 for (int m = 0; m < 4; ++m)
; #pragma unroll
;                     for (int n = 0; n < 2; ++n) acc[a][b][m][n] = (f32x4){0.f, 0.f, 0.f, 0.f};
.LBB0_803:
	s_add_u32 s13, s18, 0x100
	s_addc_u32 s18, s19, 0
	s_add_u32 s2, s2, 0x800000
	v_mov_b64_e32 v[8:9], 0
	s_addc_u32 s3, s3, 0
	s_mov_b32 s19, -2
	v_mov_b64_e32 v[10:11], 0
	v_mov_b64_e32 v[12:13], 0
	v_mov_b64_e32 v[14:15], 0
	v_mov_b64_e32 v[24:25], 0
	v_mov_b64_e32 v[26:27], 0
	v_mov_b64_e32 v[28:29], 0
	v_mov_b64_e32 v[30:31], 0
	v_mov_b64_e32 v[40:41], 0
	v_mov_b64_e32 v[42:43], 0
	v_mov_b64_e32 v[44:45], 0
	v_mov_b64_e32 v[46:47], 0
	v_mov_b64_e32 v[56:57], 0
	v_mov_b64_e32 v[58:59], 0
	v_mov_b64_e32 v[60:61], 0
	v_mov_b64_e32 v[62:63], 0
	v_mov_b64_e32 v[16:17], 0
	v_mov_b64_e32 v[18:19], 0
	v_mov_b64_e32 v[20:21], 0
	v_mov_b64_e32 v[22:23], 0
	v_mov_b64_e32 v[32:33], 0
	v_mov_b64_e32 v[34:35], 0
	v_mov_b64_e32 v[36:37], 0
	v_mov_b64_e32 v[38:39], 0
	v_mov_b64_e32 v[48:49], 0
	v_mov_b64_e32 v[50:51], 0
	v_mov_b64_e32 v[52:53], 0
	v_mov_b64_e32 v[54:55], 0
	v_mov_b64_e32 v[64:65], 0
	v_mov_b64_e32 v[66:67], 0
	v_mov_b64_e32 v[68:69], 0
	v_mov_b64_e32 v[70:71], 0
	v_mov_b64_e32 v[72:73], 0
	v_mov_b64_e32 v[74:75], 0
	v_mov_b64_e32 v[76:77], 0
	v_mov_b64_e32 v[78:79], 0
	v_mov_b64_e32 v[88:89], 0
	v_mov_b64_e32 v[90:91], 0
	v_mov_b64_e32 v[92:93], 0
	v_mov_b64_e32 v[94:95], 0
	v_mov_b64_e32 v[104:105], 0
	v_mov_b64_e32 v[106:107], 0
	v_mov_b64_e32 v[108:109], 0
	v_mov_b64_e32 v[110:111], 0
	v_mov_b64_e32 v[128:129], 0
	v_mov_b64_e32 v[130:131], 0
	v_mov_b64_e32 v[132:133], 0
	v_mov_b64_e32 v[134:135], 0
	v_mov_b64_e32 v[80:81], 0
	v_mov_b64_e32 v[82:83], 0
	v_mov_b64_e32 v[84:85], 0
	v_mov_b64_e32 v[86:87], 0
	v_mov_b64_e32 v[96:97], 0
	v_mov_b64_e32 v[98:99], 0
	v_mov_b64_e32 v[100:101], 0
	v_mov_b64_e32 v[102:103], 0
	v_mov_b64_e32 v[116:117], 0
	v_mov_b64_e32 v[118:119], 0
	v_mov_b64_e32 v[120:121], 0
	v_mov_b64_e32 v[122:123], 0
	v_mov_b64_e32 v[140:141], 0
	v_mov_b64_e32 v[142:143], 0
	v_mov_b64_e32 v[144:145], 0
	v_mov_b64_e32 v[146:147], 0
	s_mov_b64 s[42:43], 0x20080
	s_mov_b64 s[50:51], 0x10000
	s_mov_b64 s[52:53], 0x30000
	s_mov_b64 s[54:55], 0x10080
	s_mov_b64 s[58:59], 0x30080
	s_mov_b64 s[62:63], 0x400000
	s_cmp_eq_u32 s101, 2
	s_cselect_b32 s101, 0, s101
.LBB0_804:
	s_add_i32 s40, 0, 0x10000
	v_add_u32_e32 v0, s40, v196
	ds_read_b128 v[112:115], v0
	ds_read_b128 v[124:127], v0 offset:1024
	ds_read_b128 v[136:139], v0 offset:2048
	ds_read_b128 v[148:151], v0 offset:3072
	s_cmp_eq_u32 s19, 4
	s_cselect_b32 s5, s15, s3
	s_cselect_b32 s4, s14, s2
	s_cselect_b32 s37, s17, s18
	s_cselect_b32 s36, s16, s13
	s_mov_b32 s38, 0xffc01000
	v_lshl_add_u64 v[184:185], s[2:3], 0, v[166:167]
	s_mov_b32 s39, -1
	v_lshl_add_u64 v[206:207], v[184:185], 0, s[38:39]
	s_mov_b32 s38, 0xffc01800
	s_add_i32 m0, s24, 0xc000
	s_mov_b32 s39, -1
	ds_read_b128 v[152:155], v197
	ds_read_b128 v[156:159], v197 offset:1024
	ds_read_b128 v[160:163], v197 offset:2048
	ds_read_b128 v[172:175], v197 offset:3072
	ds_read_b128 v[176:179], v197 offset:4096
	ds_read_b128 v[180:183], v197 offset:5120
	ds_read_b128 v[198:201], v197 offset:6144
	ds_read_b128 v[202:205], v197 offset:7168
	global_load_lds_dwordx4 v[206:207], off
	v_lshl_add_u64 v[184:185], v[184:185], 0, s[38:39]
	s_add_i32 m0, s24, 0xe000
	s_nop 0
	global_load_lds_dwordx4 v[184:185], off
	s_waitcnt lgkmcnt(8)
	s_cmp_eq_u32 s101, 1
	s_cbranch_scc1 .Ldb_GLU_sk
	s_barrier
.Ldb_GLU_sk:
	s_mov_b32 s101, 0
	s_waitcnt lgkmcnt(0)
	v_mfma_f32_16x16x32_bf16 v[144:147], v[112:115], v[152:155], v[144:147]
	v_mfma_f32_16x16x32_bf16 v[140:143], v[136:139], v[152:155], v[140:143]
	v_mfma_f32_16x16x32_bf16 v[120:123], v[112:115], v[160:163], v[120:123]
	v_mfma_f32_16x16x32_bf16 v[116:119], v[136:139], v[160:163], v[116:119]
	v_mfma_f32_16x16x32_bf16 v[100:103], v[112:115], v[176:179], v[100:103]
	v_mfma_f32_16x16x32_bf16 v[96:99], v[136:139], v[176:179], v[96:99]
	v_mfma_f32_16x16x32_bf16 v[84:87], v[112:115], v[198:201], v[84:87]
	v_mfma_f32_16x16x32_bf16 v[80:83], v[136:139], v[198:201], v[80:83]
	v_mfma_f32_16x16x32_bf16 v[144:147], v[124:127], v[156:159], v[144:147]
	v_mfma_f32_16x16x32_bf16 v[140:143], v[148:151], v[156:159], v[140:143]
	v_mfma_f32_16x16x32_bf16 v[120:123], v[124:127], v[172:175], v[120:123]
	v_mfma_f32_16x16x32_bf16 v[116:119], v[148:151], v[172:175], v[116:119]
	v_mfma_f32_16x16x32_bf16 v[100:103], v[124:127], v[180:183], v[100:103]
	v_mfma_f32_16x16x32_bf16 v[96:99], v[148:151], v[180:183], v[96:99]
	v_mfma_f32_16x16x32_bf16 v[84:87], v[124:127], v[202:205], v[84:87]
	v_mfma_f32_16x16x32_bf16 v[80:83], v[148:151], v[202:205], v[80:83]
	s_barrier
	s_add_i32 s38, 0, 0x14000
	v_lshl_add_u64 v[184:185], s[36:37], 0, v[2:3]
	s_add_i32 s36, s40, s21
	v_add_u32_e32 v0, s38, v196
	s_mov_b32 m0, s36
	ds_read_b128 v[206:209], v0
	ds_read_b128 v[210:213], v0 offset:1024
	ds_read_b128 v[214:217], v0 offset:2048
	ds_read_b128 v[218:221], v0 offset:3072
	global_load_lds_dwordx4 v[184:185], off
	v_lshl_add_u64 v[222:223], v[184:185], 0, s[50:51]
	s_add_i32 m0, s36, 0x2000
	s_nop 0
	global_load_lds_dwordx4 v[222:223], off
	s_barrier
	s_waitcnt lgkmcnt(0)
	v_mfma_f32_16x16x32_bf16 v[132:135], v[206:209], v[152:155], v[132:135]
	v_mfma_f32_16x16x32_bf16 v[128:131], v[214:217], v[152:155], v[128:131]
	v_mfma_f32_16x16x32_bf16 v[108:111], v[206:209], v[160:163], v[108:111]
	v_mfma_f32_16x16x32_bf16 v[104:107], v[214:217], v[160:163], v[104:107]
	v_mfma_f32_16x16x32_bf16 v[92:95], v[206:209], v[176:179], v[92:95]
	v_mfma_f32_16x16x32_bf16 v[88:91], v[214:217], v[176:179], v[88:91]
	v_mfma_f32_16x16x32_bf16 v[76:79], v[206:209], v[198:201], v[76:79]
	v_mfma_f32_16x16x32_bf16 v[72:75], v[214:217], v[198:201], v[72:75]
	v_mfma_f32_16x16x32_bf16 v[132:135], v[210:213], v[156:159], v[132:135]
	v_mfma_f32_16x16x32_bf16 v[128:131], v[218:221], v[156:159], v[128:131]
	v_mfma_f32_16x16x32_bf16 v[108:111], v[210:213], v[172:175], v[108:111]
	v_mfma_f32_16x16x32_bf16 v[104:107], v[218:221], v[172:175], v[104:107]
	v_mfma_f32_16x16x32_bf16 v[92:95], v[210:213], v[180:183], v[92:95]
	v_mfma_f32_16x16x32_bf16 v[88:91], v[218:221], v[180:183], v[88:91]
	v_mfma_f32_16x16x32_bf16 v[76:79], v[210:213], v[202:205], v[76:79]
	v_mfma_f32_16x16x32_bf16 v[72:75], v[218:221], v[202:205], v[72:75]
	s_barrier
; #define G_STAGE(bufoff, gbase, o0, h64) do { \
;         __builtin_amdgcn_global_load_lds((const unsigned*)((const char*)(gbase) + (o0)), (LAS unsigned*)(lds + (bufoff) + ldsw), 16, 0, 0); \
;         __builtin_amdgcn_global_load_lds((const unsigned*)((const char*)(gbase) + (h64) + (o0)), (LAS unsigned*)(lds + (bufoff) + ldsw + 8192), 16, 0, 0); } while (0)
; #define G_LDA(dst, b, h) do { _Pragma("unroll") for (int m = 0; m < 4; ++m) _Pragma("unroll") for (int k = 0; k < 2; ++k) dst[m][k] = *(const LAS bf16x8*)(lds + G_SA(b, h) + aoff + m * 2048 + k * 1024); } while (0)
; #define G_LDB(dst, b, h) do { _Pragma("unroll") for (int n = 0; n < 2; ++n) _Pragma("unroll") for (int k = 0; k < 2; ++k) dst[n][k] = *(const LAS bf16x8*)(lds + G_SB(b, h) + boff + n * 2048 + k * 1024); } while (0)
; #define G_WAIT_V(n) asm volatile("s_waitcnt vmcnt(" #n ")" ::: "memory")
; #define G_WAIT_L(n) asm volatile("s_waitcnt lgkmcnt(" #n ")" ::: "memory")
; #define G_BAR __builtin_amdgcn_s_barrier()
; #define G_SCHED __builtin_amdgcn_sched_barrier(0)
;     ...
;             G_STAGE(G_SB(0, 1), b2 + chB, cB0, qB);
;             G_WAIT_V(6); G_BAR; G_MMA(1, 1, At, B1); G_BAR;
;             G_LDB(B0, 1, 0); G_SCHED; G_LDA(At, 1, 0); G_STAGE(G_SA(0, 1), a2 + chA, cA0, qA);
;             G_WAIT_L(8); G_BAR; G_WAIT_L(0); G_MMA(0, 0, At, B0); G_BAR; G_SCHED;
;             G_LDB(B1, 1, 1); G_STAGE(G_SB(1, 0), b3, cB0, qB);
;             G_BAR; G_WAIT_L(0); G_MMA(0, 1, At, B1); G_BAR;
;             G_LDA(At, 1, 1); G_STAGE(G_SA(1, 0), a3, cA0, qA);
;             G_BAR; G_WAIT_L(0); G_MMA(1, 0, At, B0); G_BAR; G_SCHED;
	s_mov_b32 m0, s24
	v_lshl_add_u64 v[222:223], s[4:5], 0, v[164:165]
	ds_read_b128 v[152:155], v197 offset:16384
	ds_read_b128 v[156:159], v197 offset:17408
	ds_read_b128 v[160:163], v197 offset:18432
	ds_read_b128 v[172:175], v197 offset:19456
	ds_read_b128 v[176:179], v197 offset:20480
	ds_read_b128 v[180:183], v197 offset:21504
	ds_read_b128 v[198:201], v197 offset:22528
	ds_read_b128 v[202:205], v197 offset:23552
	global_load_lds_dwordx4 v[222:223], off
	v_lshl_add_u64 v[224:225], v[222:223], 0, s[70:71]
	s_mov_b32 m0, s25
	s_nop 0
	global_load_lds_dwordx4 v[224:225], off
	s_barrier
	s_waitcnt lgkmcnt(0)
	v_mfma_f32_16x16x32_bf16 v[68:71], v[112:115], v[152:155], v[68:71]
	v_mfma_f32_16x16x32_bf16 v[64:67], v[136:139], v[152:155], v[64:67]
	v_mfma_f32_16x16x32_bf16 v[52:55], v[112:115], v[160:163], v[52:55]
	v_mfma_f32_16x16x32_bf16 v[48:51], v[136:139], v[160:163], v[48:51]
	v_mfma_f32_16x16x32_bf16 v[36:39], v[112:115], v[176:179], v[36:39]
	v_mfma_f32_16x16x32_bf16 v[32:35], v[136:139], v[176:179], v[32:35]
	v_mfma_f32_16x16x32_bf16 v[20:23], v[112:115], v[198:201], v[20:23]
	v_mfma_f32_16x16x32_bf16 v[16:19], v[136:139], v[198:201], v[16:19]
	v_mfma_f32_16x16x32_bf16 v[68:71], v[124:127], v[156:159], v[68:71]
	v_mfma_f32_16x16x32_bf16 v[64:67], v[148:151], v[156:159], v[64:67]
	v_mfma_f32_16x16x32_bf16 v[52:55], v[124:127], v[172:175], v[52:55]
	v_mfma_f32_16x16x32_bf16 v[48:51], v[148:151], v[172:175], v[48:51]
	v_mfma_f32_16x16x32_bf16 v[36:39], v[124:127], v[180:183], v[36:39]
	v_mfma_f32_16x16x32_bf16 v[32:35], v[148:151], v[180:183], v[32:35]
	v_mfma_f32_16x16x32_bf16 v[20:23], v[124:127], v[202:205], v[20:23]
	v_mfma_f32_16x16x32_bf16 v[16:19], v[148:151], v[202:205], v[16:19]
	s_barrier
	s_add_i32 s4, s38, s21
	v_lshl_add_u64 v[112:113], v[184:185], 0, s[0:1]
	s_mov_b32 m0, s4
	s_nop 0
	global_load_lds_dwordx4 v[112:113], off
	v_lshl_add_u64 v[112:113], v[184:185], 0, s[52:53]
	s_add_i32 m0, s4, 0x2000
	s_nop 0
	global_load_lds_dwordx4 v[112:113], off
	s_waitcnt vmcnt(6)
	s_barrier
	v_mfma_f32_16x16x32_bf16 v[60:63], v[206:209], v[152:155], v[60:63]
	v_mfma_f32_16x16x32_bf16 v[56:59], v[214:217], v[152:155], v[56:59]
	v_mfma_f32_16x16x32_bf16 v[44:47], v[206:209], v[160:163], v[44:47]
	v_mfma_f32_16x16x32_bf16 v[40:43], v[214:217], v[160:163], v[40:43]
	v_mfma_f32_16x16x32_bf16 v[28:31], v[206:209], v[176:179], v[28:31]
	v_mfma_f32_16x16x32_bf16 v[24:27], v[214:217], v[176:179], v[24:27]
	v_mfma_f32_16x16x32_bf16 v[12:15], v[206:209], v[198:201], v[12:15]
	v_mfma_f32_16x16x32_bf16 v[8:11], v[214:217], v[198:201], v[8:11]
	v_mfma_f32_16x16x32_bf16 v[60:63], v[210:213], v[156:159], v[60:63]
	v_mfma_f32_16x16x32_bf16 v[56:59], v[218:221], v[156:159], v[56:59]
	v_mfma_f32_16x16x32_bf16 v[44:47], v[210:213], v[172:175], v[44:47]
	v_mfma_f32_16x16x32_bf16 v[40:43], v[218:221], v[172:175], v[40:43]
	v_mfma_f32_16x16x32_bf16 v[28:31], v[210:213], v[180:183], v[28:31]
	v_mfma_f32_16x16x32_bf16 v[24:27], v[218:221], v[180:183], v[24:27]
	v_mfma_f32_16x16x32_bf16 v[12:15], v[210:213], v[202:205], v[12:15]
	v_mfma_f32_16x16x32_bf16 v[8:11], v[218:221], v[202:205], v[8:11]
	s_barrier
	s_add_i32 s4, 0, 0x18000
	v_add_u32_e32 v0, s4, v196
	ds_read_b128 v[112:115], v0
	ds_read_b128 v[124:127], v0 offset:1024
	ds_read_b128 v[136:139], v0 offset:2048
	ds_read_b128 v[148:151], v0 offset:3072
	s_mov_b32 m0, s26
	v_lshl_add_u64 v[206:207], v[222:223], 0, s[80:81]
	ds_read_b128 v[152:155], v197 offset:32768
	ds_read_b128 v[156:159], v197 offset:33792
	ds_read_b128 v[160:163], v197 offset:34816
	ds_read_b128 v[172:175], v197 offset:35840
	ds_read_b128 v[176:179], v197 offset:36864
	ds_read_b128 v[180:183], v197 offset:37888
	ds_read_b128 v[198:201], v197 offset:38912
	ds_read_b128 v[202:205], v197 offset:39936
	global_load_lds_dwordx4 v[206:207], off
	v_lshl_add_u64 v[206:207], v[222:223], 0, s[82:83]
	s_mov_b32 m0, s27
	s_nop 0
	global_load_lds_dwordx4 v[206:207], off
	s_waitcnt lgkmcnt(8)
	s_barrier
	s_waitcnt lgkmcnt(0)
	v_mfma_f32_16x16x32_bf16 v[144:147], v[112:115], v[152:155], v[144:147]
	v_mfma_f32_16x16x32_bf16 v[140:143], v[136:139], v[152:155], v[140:143]
	v_mfma_f32_16x16x32_bf16 v[120:123], v[112:115], v[160:163], v[120:123]
	v_mfma_f32_16x16x32_bf16 v[116:119], v[136:139], v[160:163], v[116:119]
	v_mfma_f32_16x16x32_bf16 v[100:103], v[112:115], v[176:179], v[100:103]
	v_mfma_f32_16x16x32_bf16 v[96:99], v[136:139], v[176:179], v[96:99]
	v_mfma_f32_16x16x32_bf16 v[84:87], v[112:115], v[198:201], v[84:87]
	v_mfma_f32_16x16x32_bf16 v[80:83], v[136:139], v[198:201], v[80:83]
	v_mfma_f32_16x16x32_bf16 v[144:147], v[124:127], v[156:159], v[144:147]
	v_mfma_f32_16x16x32_bf16 v[140:143], v[148:151], v[156:159], v[140:143]
	v_mfma_f32_16x16x32_bf16 v[120:123], v[124:127], v[172:175], v[120:123]
	v_mfma_f32_16x16x32_bf16 v[116:119], v[148:151], v[172:175], v[116:119]
	v_mfma_f32_16x16x32_bf16 v[100:103], v[124:127], v[180:183], v[100:103]
	v_mfma_f32_16x16x32_bf16 v[96:99], v[148:151], v[180:183], v[96:99]
	v_mfma_f32_16x16x32_bf16 v[84:87], v[124:127], v[202:205], v[84:87]
	v_mfma_f32_16x16x32_bf16 v[80:83], v[148:151], v[202:205], v[80:83]
	s_barrier
; #define G_STAGE(bufoff, gbase, o0, h64) do { \
;         __builtin_amdgcn_global_load_lds((const unsigned*)((const char*)(gbase) + (o0)), (LAS unsigned*)(lds + (bufoff) + ldsw), 16, 0, 0); \
;         __builtin_amdgcn_global_load_lds((const unsigned*)((const char*)(gbase) + (h64) + (o0)), (LAS unsigned*)(lds + (bufoff) + ldsw + 8192), 16, 0, 0); } while (0)
; #define G_LDA(dst, b, h) do { _Pragma("unroll") for (int m = 0; m < 4; ++m) _Pragma("unroll") for (int k = 0; k < 2; ++k) dst[m][k] = *(const LAS bf16x8*)(lds + G_SA(b, h) + aoff + m * 2048 + k * 1024); } while (0)
; #define G_LDB(dst, b, h) do { _Pragma("unroll") for (int n = 0; n < 2; ++n) _Pragma("unroll") for (int k = 0; k < 2; ++k) dst[n][k] = *(const LAS bf16x8*)(lds + G_SB(b, h) + boff + n * 2048 + k * 1024); } while (0)
; #define G_WAIT_V(n) asm volatile("s_waitcnt vmcnt(" #n ")" ::: "memory")
; #define G_WAIT_L(n) asm volatile("s_waitcnt lgkmcnt(" #n ")" ::: "memory")
; #define G_BAR __builtin_amdgcn_s_barrier()
; #define G_SCHED __builtin_amdgcn_sched_barrier(0)
;     ...
;             G_LDB(B0, 1, 0); G_SCHED; G_LDA(At, 1, 0); G_STAGE(G_SA(0, 1), a2 + chA, cA0, qA);
;             G_WAIT_L(8); G_BAR; G_WAIT_L(0); G_MMA(0, 0, At, B0); G_BAR; G_SCHED;
;             G_LDB(B1, 1, 1); G_STAGE(G_SB(1, 0), b3, cB0, qB);
;             G_BAR; G_WAIT_L(0); G_MMA(0, 1, At, B1); G_BAR;
;             G_LDA(At, 1, 1); G_STAGE(G_SA(1, 0), a3, cA0, qA);
;             G_BAR; G_WAIT_L(0); G_MMA(1, 0, At, B0); G_BAR; G_SCHED;
;             G_STAGE(G_SB(1, 1), b3 + chB, cB0, qB);
;             G_WAIT_V(6); G_BAR; G_MMA(1, 1, At, B1); G_BAR;
;         }
	s_add_i32 s5, 0, 0x1c000
	s_add_i32 s4, s4, s21
	v_add_u32_e32 v0, s5, v196
	v_lshl_add_u64 v[224:225], v[184:185], 0, s[46:47]
	s_mov_b32 m0, s4
	ds_read_b128 v[206:209], v0
	ds_read_b128 v[210:213], v0 offset:1024
	ds_read_b128 v[214:217], v0 offset:2048
	ds_read_b128 v[218:221], v0 offset:3072
	global_load_lds_dwordx4 v[224:225], off
	v_lshl_add_u64 v[224:225], v[184:185], 0, s[54:55]
	s_add_i32 m0, s4, 0x2000
	s_nop 0
	global_load_lds_dwordx4 v[224:225], off
	s_barrier
	s_waitcnt lgkmcnt(0)
	v_mfma_f32_16x16x32_bf16 v[132:135], v[206:209], v[152:155], v[132:135]
	v_mfma_f32_16x16x32_bf16 v[128:131], v[214:217], v[152:155], v[128:131]
	v_mfma_f32_16x16x32_bf16 v[108:111], v[206:209], v[160:163], v[108:111]
	v_mfma_f32_16x16x32_bf16 v[104:107], v[214:217], v[160:163], v[104:107]
	v_mfma_f32_16x16x32_bf16 v[92:95], v[206:209], v[176:179], v[92:95]
	v_mfma_f32_16x16x32_bf16 v[88:91], v[214:217], v[176:179], v[88:91]
	v_mfma_f32_16x16x32_bf16 v[76:79], v[206:209], v[198:201], v[76:79]
	v_mfma_f32_16x16x32_bf16 v[72:75], v[214:217], v[198:201], v[72:75]
	v_mfma_f32_16x16x32_bf16 v[132:135], v[210:213], v[156:159], v[132:135]
	v_mfma_f32_16x16x32_bf16 v[128:131], v[218:221], v[156:159], v[128:131]
	v_mfma_f32_16x16x32_bf16 v[108:111], v[210:213], v[172:175], v[108:111]
	v_mfma_f32_16x16x32_bf16 v[104:107], v[218:221], v[172:175], v[104:107]
	v_mfma_f32_16x16x32_bf16 v[92:95], v[210:213], v[180:183], v[92:95]
	v_mfma_f32_16x16x32_bf16 v[88:91], v[218:221], v[180:183], v[88:91]
	v_mfma_f32_16x16x32_bf16 v[76:79], v[210:213], v[202:205], v[76:79]
	v_mfma_f32_16x16x32_bf16 v[72:75], v[218:221], v[202:205], v[72:75]
	s_barrier
	s_mov_b32 m0, s29
	v_lshl_add_u64 v[224:225], v[222:223], 0, s[62:63]
	ds_read_b128 v[152:155], v197 offset:49152
	ds_read_b128 v[156:159], v197 offset:50176
	ds_read_b128 v[160:163], v197 offset:51200
	ds_read_b128 v[172:175], v197 offset:52224
	ds_read_b128 v[176:179], v197 offset:53248
	ds_read_b128 v[180:183], v197 offset:54272
	ds_read_b128 v[198:201], v197 offset:55296
	ds_read_b128 v[202:205], v197 offset:56320
	global_load_lds_dwordx4 v[224:225], off
	v_lshl_add_u64 v[222:223], v[222:223], 0, s[84:85]
	s_mov_b32 m0, s30
	s_nop 0
	global_load_lds_dwordx4 v[222:223], off
	s_barrier
	s_waitcnt lgkmcnt(0)
	v_mfma_f32_16x16x32_bf16 v[68:71], v[112:115], v[152:155], v[68:71]
	v_mfma_f32_16x16x32_bf16 v[64:67], v[136:139], v[152:155], v[64:67]
	v_mfma_f32_16x16x32_bf16 v[52:55], v[112:115], v[160:163], v[52:55]
	v_mfma_f32_16x16x32_bf16 v[48:51], v[136:139], v[160:163], v[48:51]
	v_mfma_f32_16x16x32_bf16 v[36:39], v[112:115], v[176:179], v[36:39]
	v_mfma_f32_16x16x32_bf16 v[32:35], v[136:139], v[176:179], v[32:35]
	v_mfma_f32_16x16x32_bf16 v[20:23], v[112:115], v[198:201], v[20:23]
	v_mfma_f32_16x16x32_bf16 v[16:19], v[136:139], v[198:201], v[16:19]
	v_mfma_f32_16x16x32_bf16 v[68:71], v[124:127], v[156:159], v[68:71]
	v_mfma_f32_16x16x32_bf16 v[64:67], v[148:151], v[156:159], v[64:67]
	v_mfma_f32_16x16x32_bf16 v[52:55], v[124:127], v[172:175], v[52:55]
	v_mfma_f32_16x16x32_bf16 v[48:51], v[148:151], v[172:175], v[48:51]
	v_mfma_f32_16x16x32_bf16 v[36:39], v[124:127], v[180:183], v[36:39]
	v_mfma_f32_16x16x32_bf16 v[32:35], v[148:151], v[180:183], v[32:35]
	v_mfma_f32_16x16x32_bf16 v[20:23], v[124:127], v[202:205], v[20:23]
	v_mfma_f32_16x16x32_bf16 v[16:19], v[148:151], v[202:205], v[16:19]
	s_barrier
	s_add_i32 s4, s5, s21
	v_lshl_add_u64 v[112:113], v[184:185], 0, s[42:43]
	s_mov_b32 m0, s4
	s_nop 0
	global_load_lds_dwordx4 v[112:113], off
	v_lshl_add_u64 v[112:113], v[184:185], 0, s[58:59]
	s_add_i32 m0, s4, 0x2000
	s_nop 0
	global_load_lds_dwordx4 v[112:113], off
	s_add_i32 s19, s19, 2
	s_add_u32 s13, s13, 0x100
	s_addc_u32 s18, s18, 0
	s_add_u32 s2, s2, 0x800000
	s_addc_u32 s3, s3, 0
	s_cmp_gt_u32 s19, 5
	s_waitcnt vmcnt(6)
	s_barrier
	v_mfma_f32_16x16x32_bf16 v[60:63], v[206:209], v[152:155], v[60:63]
	v_mfma_f32_16x16x32_bf16 v[56:59], v[214:217], v[152:155], v[56:59]
	v_mfma_f32_16x16x32_bf16 v[44:47], v[206:209], v[160:163], v[44:47]
	v_mfma_f32_16x16x32_bf16 v[40:43], v[214:217], v[160:163], v[40:43]
	v_mfma_f32_16x16x32_bf16 v[28:31], v[206:209], v[176:179], v[28:31]
	v_mfma_f32_16x16x32_bf16 v[24:27], v[214:217], v[176:179], v[24:27]
	v_mfma_f32_16x16x32_bf16 v[12:15], v[206:209], v[198:201], v[12:15]
	v_mfma_f32_16x16x32_bf16 v[8:11], v[214:217], v[198:201], v[8:11]
	v_mfma_f32_16x16x32_bf16 v[60:63], v[210:213], v[156:159], v[60:63]
	v_mfma_f32_16x16x32_bf16 v[56:59], v[218:221], v[156:159], v[56:59]
	v_mfma_f32_16x16x32_bf16 v[44:47], v[210:213], v[172:175], v[44:47]
	v_mfma_f32_16x16x32_bf16 v[40:43], v[218:221], v[172:175], v[40:43]
	v_mfma_f32_16x16x32_bf16 v[28:31], v[210:213], v[180:183], v[28:31]
	v_mfma_f32_16x16x32_bf16 v[24:27], v[218:221], v[180:183], v[24:27]
	v_mfma_f32_16x16x32_bf16 v[12:15], v[210:213], v[202:205], v[12:15]
	v_mfma_f32_16x16x32_bf16 v[8:11], v[218:221], v[202:205], v[8:11]
	s_cbranch_scc0 .Ldb_GLU_cont
	v_readfirstlane_b32 s101, v186
	s_cmpk_gt_u32 s101, 0xff
	s_cbranch_scc1 .Ldb_GLU_young
	s_barrier
	s_mov_b32 s101, 1
	s_branch .Ldb_GLU_exit

; __device__ __forceinline__ float sigmoidf_(float v) { return __builtin_amdgcn_rcpf(1.0f + __expf(-v)); }
; __device__ __forceinline__ u32x4 pack8(const f32x4 a, const f32x4 b) { u32x4 w; w.x = cvt_pk_bf16(a[0], a[1]); w.y = cvt_pk_bf16(a[2], a[3]); w.z = cvt_pk_bf16(b[0], b[1]); w.w = cvt_pk_bf16(b[2], b[3]); return w; }
; __device__ __forceinline__ void unpack8(const u32x4 w, f32x4& a, f32x4& b) { a[0] = bf_lo(w.x); a[1] = bf_hi(w.x); a[2] = bf_lo(w.y); a[3] = bf_hi(w.y); b[0] = bf_lo(w.z); b[1] = bf_hi(w.z); b[2] = bf_lo(w.w); b[3] = bf_hi(w.w); }
; #define MEMFENCE asm volatile("" ::: "memory")
;     template <int KIND> __device__ __forceinline__ void run(f32x4 (&acc)[2][2][4][2], const Unit& u, int tid_in) const {
;     ...
;         if constexpr (KIND == K_GLU) {
; #pragma unroll
;             for (int ai = 0; ai < 2; ++ai) { u32x4 yv[4][2];
; #pragma unroll
;                 for (int m = 0; m < 4; ++m) { int row = rbase + ai * 128 + m * 16; asm volatile("" : "+v"(row));
; #pragma unroll
;                     for (int bj = 0; bj < 2; ++bj) { const int col = u.pn * 256 + bj * 128 + cl; yv[m][bj] = *(const u32x4*)(yi + ((size_t)(col >> 4) * T_TOK + row) * 16 + (col & 15)); } }
; #pragma unroll
;                 for (int m = 0; m < 4; ++m) { int row = rbase + ai * 128 + m * 16; asm volatile("" : "+v"(row));
; #pragma unroll
;                     for (int bj = 0; bj < 2; ++bj) { const int col = u.pn * 256 + bj * 128 + cl; f32x4 y0, y1; unpack8(yv[m][bj], y0, y1);
; #pragma unroll
;                         for (int j = 0; j < 4; ++j) { y0[j] *= sigmoidf_(acc[ai][bj][m][0][j]); y1[j] *= sigmoidf_(acc[ai][bj][m][1][j]); }
;                         *(u32x4*)(zb + (size_t)row * ZW + 1024 + col) = pack8(y0, y1); } }
;                 MEMFENCE; }
;         }
.Ldb_GLU_exit:
	v_mov_b32_e32 v0, v195
	s_lshl_b32 s3, s35, 8
	v_readfirstlane_b32 s2, v0
	s_ashr_i32 s4, s2, 2
	s_lshr_b32 s2, s2, 1
	s_and_b32 s2, s2, 0x60
	v_lshrrev_b32_e32 v112, 1, v0
	v_and_or_b32 v112, v112, 24, s2
	s_andn2_b32 s4, s4, 63
	v_lshl_or_b32 v182, s33, 8, v112
	s_add_i32 s4, s4, s3
	v_ashrrev_i32_e32 v112, 4, v182
	v_and_or_b32 v198, v0, 15, s4
	v_ashrrev_i32_e32 v113, 31, v112
	v_lshlrev_b64 v[176:177], 20, v[112:113]
	v_mov_b32_e32 v112, v198
	v_and_b32_e32 v0, 16, v0
	v_lshl_add_u64 v[174:175], s[8:9], 0, v[0:1]
	v_ashrrev_i32_e32 v113, 31, v112
	v_lshlrev_b64 v[112:113], 5, v[112:113]
	v_lshl_add_u64 v[112:113], v[174:175], 0, v[112:113]
	v_lshl_add_u64 v[114:115], v[112:113], 0, v[176:177]
	global_load_dwordx4 v[202:205], v[114:115], off
	v_or_b32_e32 v180, 0x80, v182
	v_ashrrev_i32_e32 v114, 4, v180
	v_ashrrev_i32_e32 v115, 31, v114
	v_lshlrev_b64 v[178:179], 20, v[114:115]
	v_lshl_add_u64 v[112:113], v[112:113], 0, v[178:179]
	global_load_dwordx4 v[160:163], v[112:113], off
	v_or_b32_e32 v200, 16, v198
	v_mov_b32_e32 v112, v200
	v_or_b32_e32 v199, 32, v198
	v_ashrrev_i32_e32 v113, 31, v112
	v_lshlrev_b64 v[112:113], 5, v[112:113]
	v_lshl_add_u64 v[112:113], v[174:175], 0, v[112:113]
	v_lshl_add_u64 v[114:115], v[112:113], 0, v[176:177]
	global_load_dwordx4 v[156:159], v[114:115], off
	v_lshl_add_u64 v[112:113], v[112:113], 0, v[178:179]
	global_load_dwordx4 v[152:155], v[112:113], off
	v_mov_b32_e32 v112, v199
	v_mul_f32_e32 v144, 0xbfb8aa3b, v144
	v_ashrrev_i32_e32 v113, 31, v112
	v_lshlrev_b64 v[112:113], 5, v[112:113]
	v_mul_f32_e32 v142, 0xbfb8aa3b, v142
	v_lshl_add_u64 v[112:113], v[174:175], 0, v[112:113]
	v_exp_f32_e32 v144, v144
	v_exp_f32_e32 v142, v142
	v_lshl_add_u64 v[114:115], v[112:113], 0, v[176:177]
	v_lshl_add_u64 v[112:113], v[112:113], 0, v[178:179]
	v_or_b32_e32 v0, 48, v198
	global_load_dwordx4 v[148:151], v[114:115], off
	global_load_dwordx4 v[136:139], v[112:113], off
	v_mov_b32_e32 v112, v0
	v_add_f32_e32 v144, 1.0, v144
	v_ashrrev_i32_e32 v113, 31, v112
	v_lshlrev_b64 v[112:113], 5, v[112:113]
	v_add_f32_e32 v142, 1.0, v142
	v_lshl_add_u64 v[112:113], v[174:175], 0, v[112:113]
	v_rcp_f32_e32 v144, v144
	v_rcp_f32_e32 v142, v142
	v_lshl_add_u64 v[114:115], v[112:113], 0, v[176:177]
	v_lshl_add_u64 v[112:113], v[112:113], 0, v[178:179]
	v_mov_b32_e32 v181, v198
	global_load_dwordx4 v[124:127], v[114:115], off
	v_mov_b64_e32 v[172:173], s[6:7]
	global_load_dwordx4 v[112:115], v[112:113], off
	v_mul_f32_e32 v145, 0xbfb8aa3b, v145
	v_mad_i64_i32 v[184:185], s[2:3], v181, s76, v[172:173]
	v_mul_f32_e32 v140, 0xbfb8aa3b, v140
	v_exp_f32_e32 v145, v145
	v_mul_f32_e32 v141, 0xbfb8aa3b, v141
	v_mul_f32_e32 v146, 0xbfb8aa3b, v146
	v_exp_f32_e32 v140, v140
	v_exp_f32_e32 v141, v141
	v_exp_f32_e32 v146, v146
	v_add_f32_e32 v145, 1.0, v145
	v_mul_f32_e32 v132, 0xbfb8aa3b, v132
	v_mul_f32_e32 v130, 0xbfb8aa3b, v130
	v_add_f32_e32 v140, 1.0, v140
	v_rcp_f32_e32 v145, v145
	v_add_f32_e32 v141, 1.0, v141
	v_add_f32_e32 v146, 1.0, v146
	v_exp_f32_e32 v132, v132
	v_exp_f32_e32 v130, v130
	v_rcp_f32_e32 v140, v140
	v_rcp_f32_e32 v141, v141
	v_rcp_f32_e32 v146, v146
	v_add_f32_e32 v132, 1.0, v132
	v_add_f32_e32 v130, 1.0, v130
	s_mov_b64 s[4:5], 0xae00800
	v_rcp_f32_e32 v132, v132
	v_rcp_f32_e32 v130, v130
	v_lshl_add_u64 v[184:185], v[184:185], 0, s[4:5]
	v_mul_f32_e32 v128, 0xbfb8aa3b, v128
	v_mul_f32_e32 v129, 0xbfb8aa3b, v129
	v_exp_f32_e32 v128, v128
	v_mul_f32_e32 v133, 0xbfb8aa3b, v133
	s_waitcnt vmcnt(0)
	v_lshlrev_b32_e32 v181, 16, v202
	v_lshlrev_b32_e32 v206, 16, v205
	v_mul_f32_e32 v144, v144, v181
	v_mul_f32_e32 v181, v142, v206
	v_mul_f32_e32 v142, 0xbfb8aa3b, v147
	v_exp_f32_e32 v142, v142
	v_and_b32_e32 v183, 0xffff0000, v202
	v_and_b32_e32 v202, 0xffff0000, v203
	v_and_b32_e32 v205, 0xffff0000, v205
	v_add_f32_e32 v142, 1.0, v142
	v_rcp_f32_e32 v142, v142
	v_lshlrev_b32_e32 v201, 16, v203
	v_lshlrev_b32_e32 v203, 16, v204
	v_and_b32_e32 v204, 0xffff0000, v204
	v_mul_f32_e32 v147, v142, v202
	v_mul_f32_e32 v142, 0xbfb8aa3b, v143
	v_exp_f32_e32 v142, v142
	v_mul_f32_e32 v145, v145, v183
	v_mul_f32_e32 v140, v140, v203
	v_mul_f32_e32 v141, v141, v204
	v_add_f32_e32 v142, 1.0, v142
	v_rcp_f32_e32 v142, v142
	v_mul_f32_e32 v146, v146, v201
	v_exp_f32_e32 v129, v129
	v_mul_f32_e32 v134, 0xbfb8aa3b, v134
	v_mul_f32_e32 v183, v142, v205
	v_cvt_pk_bf16_f32 v142, v144, v145
	v_cvt_pk_bf16_f32 v143, v146, v147
	v_cvt_pk_bf16_f32 v144, v140, v141
	v_cvt_pk_bf16_f32 v145, v181, v183
	v_ashrrev_i32_e32 v183, 31, v182
	v_lshlrev_b64 v[140:141], 1, v[182:183]
	v_lshl_add_u64 v[146:147], v[184:185], 0, v[140:141]
	global_store_dwordx4 v[146:147], v[142:145], off
	v_exp_f32_e32 v133, v133
	v_exp_f32_e32 v134, v134
	v_lshlrev_b32_e32 v142, 16, v160
	v_and_b32_e32 v143, 0xffff0000, v160
	v_lshlrev_b32_e32 v160, 16, v163
	v_mul_f32_e32 v132, v132, v142
	v_mul_f32_e32 v142, v130, v160
	v_mul_f32_e32 v130, 0xbfb8aa3b, v135
	v_exp_f32_e32 v130, v130
	v_and_b32_e32 v145, 0xffff0000, v161
	v_mul_f32_e32 v120, 0xbfb8aa3b, v120
	v_mul_f32_e32 v116, 0xbfb8aa3b, v116
	v_add_f32_e32 v130, 1.0, v130
	v_rcp_f32_e32 v130, v130
	v_mul_f32_e32 v117, 0xbfb8aa3b, v117
	v_mul_f32_e32 v118, 0xbfb8aa3b, v118
	v_add_f32_e32 v128, 1.0, v128
	v_mul_f32_e32 v135, v130, v145
	v_mul_f32_e32 v130, 0xbfb8aa3b, v131
	v_exp_f32_e32 v130, v130
	v_add_f32_e32 v129, 1.0, v129
	v_exp_f32_e32 v120, v120
	v_exp_f32_e32 v116, v116
	v_exp_f32_e32 v117, v117
	v_exp_f32_e32 v118, v118
	v_rcp_f32_e32 v128, v128
	v_add_f32_e32 v133, 1.0, v133
	v_rcp_f32_e32 v129, v129
	v_add_f32_e32 v134, 1.0, v134
	v_add_f32_e32 v130, 1.0, v130
	v_rcp_f32_e32 v133, v133
; __device__ __forceinline__ float sigmoidf_(float v) { return __builtin_amdgcn_rcpf(1.0f + __expf(-v)); }
; __device__ __forceinline__ u32x4 pack8(const f32x4 a, const f32x4 b) { u32x4 w; w.x = cvt_pk_bf16(a[0], a[1]); w.y = cvt_pk_bf16(a[2], a[3]); w.z = cvt_pk_bf16(b[0], b[1]); w.w = cvt_pk_bf16(b[2], b[3]); return w; }
; __device__ __forceinline__ void unpack8(const u32x4 w, f32x4& a, f32x4& b) { a[0] = bf_lo(w.x); a[1] = bf_hi(w.x); a[2] = bf_lo(w.y); a[3] = bf_hi(w.y); b[0] = bf_lo(w.z); b[1] = bf_hi(w.z); b[2] = bf_lo(w.w); b[3] = bf_hi(w.w); }
;     template <int KIND> __device__ __forceinline__ void run(f32x4 (&acc)[2][2][4][2], const Unit& u, int tid_in) const {
;     ...
;                 for (int m = 0; m < 4; ++m) { int row = rbase + ai * 128 + m * 16; asm volatile("" : "+v"(row));
; #pragma unroll
;                     for (int bj = 0; bj < 2; ++bj) { const int col = u.pn * 256 + bj * 128 + cl; f32x4 y0, y1; unpack8(yv[m][bj], y0, y1);
; #pragma unroll
;                         for (int j = 0; j < 4; ++j) { y0[j] *= sigmoidf_(acc[ai][bj][m][0][j]); y1[j] *= sigmoidf_(acc[ai][bj][m][1][j]); }
;                         *(u32x4*)(zb + (size_t)row * ZW + 1024 + col) = pack8(y0, y1); } }
	v_rcp_f32_e32 v134, v134
	v_rcp_f32_e32 v130, v130
	v_lshlrev_b32_e32 v146, 16, v162
	v_and_b32_e32 v147, 0xffff0000, v162
	v_add_f32_e32 v120, 1.0, v120
	v_add_f32_e32 v116, 1.0, v116
	v_add_f32_e32 v117, 1.0, v117
	v_add_f32_e32 v118, 1.0, v118
	v_lshlrev_b32_e32 v144, 16, v161
	v_and_b32_e32 v161, 0xffff0000, v163
	v_mul_f32_e32 v128, v128, v146
	v_mul_f32_e32 v129, v129, v147
	v_ashrrev_i32_e32 v181, 31, v180
	v_rcp_f32_e32 v120, v120
	v_rcp_f32_e32 v116, v116
	v_rcp_f32_e32 v117, v117
	v_rcp_f32_e32 v118, v118
	v_mul_f32_e32 v133, v133, v143
	v_mul_f32_e32 v134, v134, v144
	v_mul_f32_e32 v143, v130, v161
	v_cvt_pk_bf16_f32 v130, v132, v133
	v_cvt_pk_bf16_f32 v131, v134, v135
	v_cvt_pk_bf16_f32 v132, v128, v129
	v_lshlrev_b64 v[128:129], 1, v[180:181]
	v_lshl_add_u64 v[134:135], v[184:185], 0, v[128:129]
	v_cvt_pk_bf16_f32 v133, v142, v143
	global_store_dwordx4 v[134:135], v[130:133], off
	v_lshlrev_b32_e32 v142, 16, v158
	v_and_b32_e32 v143, 0xffff0000, v158
	v_lshlrev_b32_e32 v132, 16, v156
	v_lshlrev_b32_e32 v144, 16, v159
	v_mul_f32_e32 v120, v120, v132
	v_mul_f32_e32 v132, v116, v142
	v_mul_f32_e32 v116, 0xbfb8aa3b, v121
	v_mul_f32_e32 v121, v117, v143
	v_mul_f32_e32 v117, 0xbfb8aa3b, v122
	v_mul_f32_e32 v122, v118, v144
	v_mul_f32_e32 v118, 0xbfb8aa3b, v123
	v_exp_f32_e32 v116, v116
	v_exp_f32_e32 v117, v117
	v_exp_f32_e32 v118, v118
	v_mul_f32_e32 v119, 0xbfb8aa3b, v119
	v_exp_f32_e32 v119, v119
	v_mul_f32_e32 v108, 0xbfb8aa3b, v108
	v_mul_f32_e32 v104, 0xbfb8aa3b, v104
	v_mul_f32_e32 v105, 0xbfb8aa3b, v105
	v_mul_f32_e32 v106, 0xbfb8aa3b, v106
	v_exp_f32_e32 v108, v108
	v_exp_f32_e32 v104, v104
	v_exp_f32_e32 v105, v105
	v_exp_f32_e32 v106, v106
	v_add_f32_e32 v116, 1.0, v116
	v_add_f32_e32 v117, 1.0, v117
	v_add_f32_e32 v118, 1.0, v118
	v_rcp_f32_e32 v116, v116
	v_rcp_f32_e32 v117, v117
	v_rcp_f32_e32 v118, v118
	v_add_f32_e32 v119, 1.0, v119
	v_rcp_f32_e32 v119, v119
	v_add_f32_e32 v108, 1.0, v108
	v_add_f32_e32 v104, 1.0, v104
	v_add_f32_e32 v105, 1.0, v105
	v_add_f32_e32 v106, 1.0, v106
	v_and_b32_e32 v133, 0xffff0000, v156
	v_mad_i64_i32 v[130:131], s[2:3], v200, s76, v[172:173]
	v_lshlrev_b32_e32 v134, 16, v157
	v_and_b32_e32 v135, 0xffff0000, v157
	v_rcp_f32_e32 v108, v108
	v_rcp_f32_e32 v104, v104
	v_rcp_f32_e32 v105, v105
	v_rcp_f32_e32 v106, v106
	v_lshl_add_u64 v[130:131], v[130:131], 0, s[4:5]
	v_and_b32_e32 v145, 0xffff0000, v159
	v_mul_f32_e32 v116, v116, v133
	v_mul_f32_e32 v117, v117, v134
	v_mul_f32_e32 v118, v118, v135
	v_mul_f32_e32 v119, v119, v145
	v_cvt_pk_bf16_f32 v116, v120, v116
	v_cvt_pk_bf16_f32 v117, v117, v118
	v_cvt_pk_bf16_f32 v118, v132, v121
	v_lshl_add_u64 v[120:121], v[130:131], 0, v[140:141]
	v_cvt_pk_bf16_f32 v119, v122, v119
	global_store_dwordx4 v[120:121], v[116:119], off
	v_lshlrev_b32_e32 v120, 16, v154
	v_and_b32_e32 v121, 0xffff0000, v154
	v_lshlrev_b32_e32 v116, 16, v152
	v_lshlrev_b32_e32 v122, 16, v155
	v_mul_f32_e32 v108, v108, v116
	v_mul_f32_e32 v116, v104, v120
	v_mul_f32_e32 v104, 0xbfb8aa3b, v109
	v_mul_f32_e32 v109, v105, v121
	v_mul_f32_e32 v105, 0xbfb8aa3b, v110
	v_mul_f32_e32 v110, v106, v122
	v_mul_f32_e32 v106, 0xbfb8aa3b, v111
	v_exp_f32_e32 v104, v104
	v_exp_f32_e32 v105, v105
	v_exp_f32_e32 v106, v106
	v_mul_f32_e32 v107, 0xbfb8aa3b, v107
	v_exp_f32_e32 v107, v107
	v_mul_f32_e32 v100, 0xbfb8aa3b, v100
	v_mul_f32_e32 v96, 0xbfb8aa3b, v96
	v_mul_f32_e32 v97, 0xbfb8aa3b, v97
	v_mul_f32_e32 v98, 0xbfb8aa3b, v98
	v_exp_f32_e32 v100, v100
	v_exp_f32_e32 v96, v96
	v_exp_f32_e32 v97, v97
	v_exp_f32_e32 v98, v98
	v_add_f32_e32 v104, 1.0, v104
	v_add_f32_e32 v105, 1.0, v105
	v_add_f32_e32 v106, 1.0, v106
	v_rcp_f32_e32 v104, v104
	v_rcp_f32_e32 v105, v105
	v_rcp_f32_e32 v106, v106
	v_add_f32_e32 v107, 1.0, v107
	v_rcp_f32_e32 v107, v107
	v_add_f32_e32 v100, 1.0, v100
	v_add_f32_e32 v96, 1.0, v96
	v_add_f32_e32 v97, 1.0, v97
	v_add_f32_e32 v98, 1.0, v98
	v_and_b32_e32 v117, 0xffff0000, v152
	v_lshlrev_b32_e32 v118, 16, v153
	v_and_b32_e32 v119, 0xffff0000, v153
	v_rcp_f32_e32 v100, v100
	v_rcp_f32_e32 v96, v96
	v_rcp_f32_e32 v97, v97
	v_rcp_f32_e32 v98, v98
	v_and_b32_e32 v123, 0xffff0000, v155
	v_mul_f32_e32 v104, v104, v117
	v_mul_f32_e32 v105, v105, v118
	v_mul_f32_e32 v106, v106, v119
	v_mul_f32_e32 v107, v107, v123
	v_cvt_pk_bf16_f32 v104, v108, v104
	v_cvt_pk_bf16_f32 v105, v105, v106
	v_cvt_pk_bf16_f32 v106, v116, v109
	v_lshl_add_u64 v[108:109], v[130:131], 0, v[128:129]
	v_cvt_pk_bf16_f32 v107, v110, v107
	global_store_dwordx4 v[108:109], v[104:107], off
	v_lshlrev_b32_e32 v110, 16, v150
	v_and_b32_e32 v111, 0xffff0000, v150
	v_lshlrev_b32_e32 v106, 16, v148
	v_lshlrev_b32_e32 v116, 16, v151
	v_mul_f32_e32 v100, v100, v106
	v_mul_f32_e32 v106, v96, v110
	v_mul_f32_e32 v96, 0xbfb8aa3b, v101
	v_mul_f32_e32 v101, v97, v111
	v_mul_f32_e32 v97, 0xbfb8aa3b, v102
	v_mul_f32_e32 v102, v98, v116
	v_mul_f32_e32 v98, 0xbfb8aa3b, v103
	v_exp_f32_e32 v96, v96
	v_exp_f32_e32 v97, v97
	v_exp_f32_e32 v98, v98
	v_mul_f32_e32 v99, 0xbfb8aa3b, v99
	v_exp_f32_e32 v99, v99
	v_mul_f32_e32 v92, 0xbfb8aa3b, v92
	v_mul_f32_e32 v88, 0xbfb8aa3b, v88
	v_mul_f32_e32 v89, 0xbfb8aa3b, v89
	v_mul_f32_e32 v90, 0xbfb8aa3b, v90
	v_exp_f32_e32 v92, v92
	v_exp_f32_e32 v88, v88
	v_exp_f32_e32 v89, v89
	v_exp_f32_e32 v90, v90
	v_add_f32_e32 v96, 1.0, v96
	v_add_f32_e32 v97, 1.0, v97
	v_add_f32_e32 v98, 1.0, v98
	v_rcp_f32_e32 v96, v96
	v_rcp_f32_e32 v97, v97
	v_rcp_f32_e32 v98, v98
	v_add_f32_e32 v99, 1.0, v99
	v_rcp_f32_e32 v99, v99
	v_add_f32_e32 v92, 1.0, v92
	v_add_f32_e32 v88, 1.0, v88
	v_add_f32_e32 v89, 1.0, v89
	v_add_f32_e32 v90, 1.0, v90
	v_and_b32_e32 v107, 0xffff0000, v148
; __device__ __forceinline__ float sigmoidf_(float v) { return __builtin_amdgcn_rcpf(1.0f + __expf(-v)); }
; __device__ __forceinline__ u32x4 pack8(const f32x4 a, const f32x4 b) { u32x4 w; w.x = cvt_pk_bf16(a[0], a[1]); w.y = cvt_pk_bf16(a[2], a[3]); w.z = cvt_pk_bf16(b[0], b[1]); w.w = cvt_pk_bf16(b[2], b[3]); return w; }
; __device__ __forceinline__ void unpack8(const u32x4 w, f32x4& a, f32x4& b) { a[0] = bf_lo(w.x); a[1] = bf_hi(w.x); a[2] = bf_lo(w.y); a[3] = bf_hi(w.y); b[0] = bf_lo(w.z); b[1] = bf_hi(w.z); b[2] = bf_lo(w.w); b[3] = bf_hi(w.w); }
;     template <int KIND> __device__ __forceinline__ void run(f32x4 (&acc)[2][2][4][2], const Unit& u, int tid_in) const {
;     ...
;             for (int ai = 0; ai < 2; ++ai) { u32x4 yv[4][2];
; #pragma unroll
;                 for (int m = 0; m < 4; ++m) { int row = rbase + ai * 128 + m * 16; asm volatile("" : "+v"(row));
; #pragma unroll
;                     for (int bj = 0; bj < 2; ++bj) { const int col = u.pn * 256 + bj * 128 + cl; yv[m][bj] = *(const u32x4*)(yi + ((size_t)(col >> 4) * T_TOK + row) * 16 + (col & 15)); } }
; #pragma unroll
;                 for (int m = 0; m < 4; ++m) { int row = rbase + ai * 128 + m * 16; asm volatile("" : "+v"(row));
; #pragma unroll
;                     for (int bj = 0; bj < 2; ++bj) { const int col = u.pn * 256 + bj * 128 + cl; f32x4 y0, y1; unpack8(yv[m][bj], y0, y1);
; #pragma unroll
;                         for (int j = 0; j < 4; ++j) { y0[j] *= sigmoidf_(acc[ai][bj][m][0][j]); y1[j] *= sigmoidf_(acc[ai][bj][m][1][j]); }
;                         *(u32x4*)(zb + (size_t)row * ZW + 1024 + col) = pack8(y0, y1); } }
	v_mad_i64_i32 v[104:105], s[2:3], v199, s76, v[172:173]
	v_lshlrev_b32_e32 v108, 16, v149
	v_and_b32_e32 v109, 0xffff0000, v149
	v_rcp_f32_e32 v92, v92
	v_rcp_f32_e32 v88, v88
	v_rcp_f32_e32 v89, v89
	v_rcp_f32_e32 v90, v90
	v_lshl_add_u64 v[104:105], v[104:105], 0, s[4:5]
	v_and_b32_e32 v117, 0xffff0000, v151
	v_mul_f32_e32 v96, v96, v107
	v_mul_f32_e32 v97, v97, v108
	v_mul_f32_e32 v98, v98, v109
	v_mul_f32_e32 v99, v99, v117
	v_cvt_pk_bf16_f32 v96, v100, v96
	v_cvt_pk_bf16_f32 v97, v97, v98
	v_cvt_pk_bf16_f32 v98, v106, v101
	v_lshl_add_u64 v[100:101], v[104:105], 0, v[140:141]
	v_cvt_pk_bf16_f32 v99, v102, v99
	global_store_dwordx4 v[100:101], v[96:99], off
	v_lshlrev_b32_e32 v100, 16, v138
	v_and_b32_e32 v101, 0xffff0000, v138
	v_lshlrev_b32_e32 v96, 16, v136
	v_lshlrev_b32_e32 v102, 16, v139
	v_mul_f32_e32 v92, v92, v96
	v_mul_f32_e32 v96, v88, v100
	v_mul_f32_e32 v88, 0xbfb8aa3b, v93
	v_mul_f32_e32 v93, v89, v101
	v_mul_f32_e32 v89, 0xbfb8aa3b, v94
	v_mul_f32_e32 v94, v90, v102
	v_mul_f32_e32 v90, 0xbfb8aa3b, v95
	v_exp_f32_e32 v88, v88
	v_exp_f32_e32 v89, v89
	v_exp_f32_e32 v90, v90
	v_mul_f32_e32 v91, 0xbfb8aa3b, v91
	v_exp_f32_e32 v91, v91
	v_mul_f32_e32 v84, 0xbfb8aa3b, v84
	v_mul_f32_e32 v80, 0xbfb8aa3b, v80
	v_mul_f32_e32 v81, 0xbfb8aa3b, v81
	v_mul_f32_e32 v82, 0xbfb8aa3b, v82
	v_add_f32_e32 v88, 1.0, v88
	v_add_f32_e32 v89, 1.0, v89
	v_add_f32_e32 v90, 1.0, v90
	v_exp_f32_e32 v84, v84
	v_exp_f32_e32 v80, v80
	v_exp_f32_e32 v81, v81
	v_exp_f32_e32 v82, v82
	v_rcp_f32_e32 v88, v88
	v_rcp_f32_e32 v89, v89
	v_rcp_f32_e32 v90, v90
	v_add_f32_e32 v91, 1.0, v91
	v_rcp_f32_e32 v91, v91
	v_and_b32_e32 v97, 0xffff0000, v136
	v_lshlrev_b32_e32 v98, 16, v137
	v_and_b32_e32 v99, 0xffff0000, v137
	v_add_f32_e32 v84, 1.0, v84
	v_add_f32_e32 v80, 1.0, v80
	v_add_f32_e32 v81, 1.0, v81
	v_add_f32_e32 v82, 1.0, v82
	v_and_b32_e32 v103, 0xffff0000, v139
	v_mul_f32_e32 v88, v88, v97
	v_mul_f32_e32 v89, v89, v98
	v_mul_f32_e32 v90, v90, v99
	v_rcp_f32_e32 v84, v84
	v_rcp_f32_e32 v80, v80
	v_rcp_f32_e32 v81, v81
	v_rcp_f32_e32 v82, v82
	v_mul_f32_e32 v91, v91, v103
	v_cvt_pk_bf16_f32 v88, v92, v88
	v_cvt_pk_bf16_f32 v89, v89, v90
	v_cvt_pk_bf16_f32 v90, v96, v93
	v_lshl_add_u64 v[92:93], v[104:105], 0, v[128:129]
	v_cvt_pk_bf16_f32 v91, v94, v91
	global_store_dwordx4 v[92:93], v[88:91], off
	v_lshlrev_b32_e32 v93, 16, v126
	v_and_b32_e32 v94, 0xffff0000, v126
	v_mad_i64_i32 v[88:89], s[2:3], v0, s76, v[172:173]
	v_lshlrev_b32_e32 v0, 16, v124
	v_lshlrev_b32_e32 v95, 16, v127
	v_mul_f32_e32 v0, v84, v0
	v_mul_f32_e32 v84, v80, v93
	v_mul_f32_e32 v80, 0xbfb8aa3b, v85
	v_mul_f32_e32 v85, v81, v94
	v_mul_f32_e32 v81, 0xbfb8aa3b, v86
	v_mul_f32_e32 v86, v82, v95
	v_mul_f32_e32 v82, 0xbfb8aa3b, v87
	v_mul_f32_e32 v83, 0xbfb8aa3b, v83
	v_exp_f32_e32 v80, v80
	v_exp_f32_e32 v81, v81
	v_exp_f32_e32 v82, v82
	v_exp_f32_e32 v83, v83
	v_mul_f32_e32 v76, 0xbfb8aa3b, v76
	v_mul_f32_e32 v72, 0xbfb8aa3b, v72
	v_mul_f32_e32 v73, 0xbfb8aa3b, v73
	v_mul_f32_e32 v74, 0xbfb8aa3b, v74
	v_exp_f32_e32 v76, v76
	v_exp_f32_e32 v72, v72
	v_exp_f32_e32 v73, v73
	v_exp_f32_e32 v74, v74
	v_add_f32_e32 v80, 1.0, v80
	v_add_f32_e32 v81, 1.0, v81
	v_add_f32_e32 v82, 1.0, v82
	v_add_f32_e32 v83, 1.0, v83
	v_rcp_f32_e32 v80, v80
	v_rcp_f32_e32 v81, v81
	v_rcp_f32_e32 v82, v82
	v_rcp_f32_e32 v83, v83
	v_add_f32_e32 v76, 1.0, v76
	v_add_f32_e32 v72, 1.0, v72
	v_add_f32_e32 v73, 1.0, v73
	v_add_f32_e32 v74, 1.0, v74
	v_and_b32_e32 v90, 0xffff0000, v124
	v_lshlrev_b32_e32 v91, 16, v125
	v_and_b32_e32 v92, 0xffff0000, v125
	v_and_b32_e32 v96, 0xffff0000, v127
	v_rcp_f32_e32 v76, v76
	v_rcp_f32_e32 v72, v72
	v_rcp_f32_e32 v73, v73
	v_rcp_f32_e32 v74, v74
	v_lshl_add_u64 v[88:89], v[88:89], 0, s[4:5]
	v_mul_f32_e32 v80, v80, v90
	v_mul_f32_e32 v81, v81, v91
	v_mul_f32_e32 v82, v82, v92
	v_mul_f32_e32 v83, v83, v96
	v_cvt_pk_bf16_f32 v80, v0, v80
	v_cvt_pk_bf16_f32 v81, v81, v82
	v_cvt_pk_bf16_f32 v82, v84, v85
	v_cvt_pk_bf16_f32 v83, v86, v83
	v_lshl_add_u64 v[84:85], v[88:89], 0, v[140:141]
	global_store_dwordx4 v[84:85], v[80:83], off
	v_lshlrev_b32_e32 v0, 16, v112
	v_and_b32_e32 v84, 0xffff0000, v114
	v_lshlrev_b32_e32 v83, 16, v114
	v_lshlrev_b32_e32 v85, 16, v115
	v_mul_f32_e32 v0, v76, v0
	v_mul_f32_e32 v76, v72, v83
	v_mul_f32_e32 v72, 0xbfb8aa3b, v77
	v_mul_f32_e32 v77, v73, v84
	v_mul_f32_e32 v73, 0xbfb8aa3b, v78
	v_mul_f32_e32 v78, v74, v85
	v_mul_f32_e32 v74, 0xbfb8aa3b, v79
	v_exp_f32_e32 v72, v72
	v_exp_f32_e32 v73, v73
	v_exp_f32_e32 v74, v74
	v_mul_f32_e32 v75, 0xbfb8aa3b, v75
	v_exp_f32_e32 v75, v75
	v_add_f32_e32 v72, 1.0, v72
	v_add_f32_e32 v73, 1.0, v73
	v_add_f32_e32 v74, 1.0, v74
	v_rcp_f32_e32 v72, v72
	v_rcp_f32_e32 v73, v73
	v_rcp_f32_e32 v74, v74
	v_add_f32_e32 v75, 1.0, v75
	v_rcp_f32_e32 v75, v75
	v_and_b32_e32 v80, 0xffff0000, v112
	v_lshlrev_b32_e32 v81, 16, v113
	v_and_b32_e32 v82, 0xffff0000, v113
	v_and_b32_e32 v86, 0xffff0000, v115
	v_mul_f32_e32 v72, v72, v80
	v_mul_f32_e32 v73, v73, v81
	v_mul_f32_e32 v74, v74, v82
	v_mul_f32_e32 v75, v75, v86
	v_cvt_pk_bf16_f32 v72, v0, v72
	v_cvt_pk_bf16_f32 v73, v73, v74
	v_cvt_pk_bf16_f32 v74, v76, v77
	v_lshl_add_u64 v[76:77], v[88:89], 0, v[128:129]
	v_add_u32_e32 v100, 0x80, v198
	v_cvt_pk_bf16_f32 v75, v78, v75
	global_store_dwordx4 v[76:77], v[72:75], off
	v_add_u32_e32 v103, 0x90, v198
	v_add_u32_e32 v102, 0xa0, v198
	v_mov_b32_e32 v72, v100
	v_mul_f32_e32 v68, 0xbfb8aa3b, v68
	v_ashrrev_i32_e32 v73, 31, v72
	v_lshlrev_b64 v[72:73], 5, v[72:73]
	v_lshl_add_u64 v[72:73], v[174:175], 0, v[72:73]
	v_lshl_add_u64 v[74:75], v[72:73], 0, v[176:177]
	global_load_dwordx4 v[104:107], v[74:75], off
; __device__ __forceinline__ float sigmoidf_(float v) { return __builtin_amdgcn_rcpf(1.0f + __expf(-v)); }
; __device__ __forceinline__ u32x4 pack8(const f32x4 a, const f32x4 b) { u32x4 w; w.x = cvt_pk_bf16(a[0], a[1]); w.y = cvt_pk_bf16(a[2], a[3]); w.z = cvt_pk_bf16(b[0], b[1]); w.w = cvt_pk_bf16(b[2], b[3]); return w; }
; __device__ __forceinline__ void unpack8(const u32x4 w, f32x4& a, f32x4& b) { a[0] = bf_lo(w.x); a[1] = bf_hi(w.x); a[2] = bf_lo(w.y); a[3] = bf_hi(w.y); b[0] = bf_lo(w.z); b[1] = bf_hi(w.z); b[2] = bf_lo(w.w); b[3] = bf_hi(w.w); }
;     template <int KIND> __device__ __forceinline__ void run(f32x4 (&acc)[2][2][4][2], const Unit& u, int tid_in) const {
;     ...
;             for (int ai = 0; ai < 2; ++ai) { u32x4 yv[4][2];
; #pragma unroll
;                 for (int m = 0; m < 4; ++m) { int row = rbase + ai * 128 + m * 16; asm volatile("" : "+v"(row));
; #pragma unroll
;                     for (int bj = 0; bj < 2; ++bj) { const int col = u.pn * 256 + bj * 128 + cl; yv[m][bj] = *(const u32x4*)(yi + ((size_t)(col >> 4) * T_TOK + row) * 16 + (col & 15)); } }
; #pragma unroll
;                 for (int m = 0; m < 4; ++m) { int row = rbase + ai * 128 + m * 16; asm volatile("" : "+v"(row));
; #pragma unroll
;                     for (int bj = 0; bj < 2; ++bj) { const int col = u.pn * 256 + bj * 128 + cl; f32x4 y0, y1; unpack8(yv[m][bj], y0, y1);
; #pragma unroll
;                         for (int j = 0; j < 4; ++j) { y0[j] *= sigmoidf_(acc[ai][bj][m][0][j]); y1[j] *= sigmoidf_(acc[ai][bj][m][1][j]); }
;                         *(u32x4*)(zb + (size_t)row * ZW + 1024 + col) = pack8(y0, y1); } }
	v_lshl_add_u64 v[72:73], v[72:73], 0, v[178:179]
	global_load_dwordx4 v[96:99], v[72:73], off
	v_mov_b32_e32 v72, v103
	v_mul_f32_e32 v64, 0xbfb8aa3b, v64
	v_ashrrev_i32_e32 v73, 31, v72
	v_lshlrev_b64 v[72:73], 5, v[72:73]
	v_lshl_add_u64 v[72:73], v[174:175], 0, v[72:73]
	v_lshl_add_u64 v[74:75], v[72:73], 0, v[176:177]
	global_load_dwordx4 v[92:95], v[74:75], off
	v_lshl_add_u64 v[72:73], v[72:73], 0, v[178:179]
	global_load_dwordx4 v[88:91], v[72:73], off
	v_mov_b32_e32 v72, v102
	v_mul_f32_e32 v65, 0xbfb8aa3b, v65
	v_ashrrev_i32_e32 v73, 31, v72
	v_lshlrev_b64 v[72:73], 5, v[72:73]
	v_lshl_add_u64 v[72:73], v[174:175], 0, v[72:73]
	v_lshl_add_u64 v[74:75], v[72:73], 0, v[176:177]
	global_load_dwordx4 v[84:87], v[74:75], off
	v_lshl_add_u64 v[72:73], v[72:73], 0, v[178:179]
	global_load_dwordx4 v[80:83], v[72:73], off
	v_mul_f32_e32 v66, 0xbfb8aa3b, v66
	v_exp_f32_e32 v68, v68
	v_exp_f32_e32 v64, v64
	v_exp_f32_e32 v65, v65
	v_exp_f32_e32 v66, v66
	v_add_u32_e32 v0, 0xb0, v198
	v_mov_b32_e32 v72, v0
	v_add_f32_e32 v68, 1.0, v68
	v_ashrrev_i32_e32 v73, 31, v72
	v_lshlrev_b64 v[72:73], 5, v[72:73]
	v_add_f32_e32 v64, 1.0, v64
	v_add_f32_e32 v65, 1.0, v65
	v_add_f32_e32 v66, 1.0, v66
	v_lshl_add_u64 v[72:73], v[174:175], 0, v[72:73]
	v_rcp_f32_e32 v68, v68
	v_rcp_f32_e32 v64, v64
	v_rcp_f32_e32 v65, v65
	v_rcp_f32_e32 v66, v66
	v_lshl_add_u64 v[74:75], v[72:73], 0, v[176:177]
	global_load_dwordx4 v[76:79], v[74:75], off
	v_mul_f32_e32 v67, 0xbfb8aa3b, v67
	v_exp_f32_e32 v67, v67
	v_mul_f32_e32 v60, 0xbfb8aa3b, v60
	v_mul_f32_e32 v56, 0xbfb8aa3b, v56
	v_mul_f32_e32 v57, 0xbfb8aa3b, v57
	v_mul_f32_e32 v58, 0xbfb8aa3b, v58
	v_exp_f32_e32 v60, v60
	v_exp_f32_e32 v56, v56
	v_exp_f32_e32 v57, v57
	v_exp_f32_e32 v58, v58
	v_add_f32_e32 v67, 1.0, v67
	v_lshl_add_u64 v[72:73], v[72:73], 0, v[178:179]
	v_rcp_f32_e32 v67, v67
	global_load_dwordx4 v[72:75], v[72:73], off
	v_add_f32_e32 v60, 1.0, v60
	v_add_f32_e32 v56, 1.0, v56
	v_add_f32_e32 v57, 1.0, v57
	v_add_f32_e32 v58, 1.0, v58
	v_mad_i64_i32 v[100:101], s[2:3], v100, s76, v[172:173]
	v_rcp_f32_e32 v60, v60
	v_rcp_f32_e32 v56, v56
	v_rcp_f32_e32 v57, v57
	v_rcp_f32_e32 v58, v58
	v_lshl_add_u64 v[100:101], v[100:101], 0, s[4:5]
	v_mul_f32_e32 v59, 0xbfb8aa3b, v59
	v_exp_f32_e32 v59, v59
	v_mul_f32_e32 v52, 0xbfb8aa3b, v52
	v_mul_f32_e32 v48, 0xbfb8aa3b, v48
	v_mul_f32_e32 v49, 0xbfb8aa3b, v49
	v_mul_f32_e32 v50, 0xbfb8aa3b, v50
	v_exp_f32_e32 v52, v52
	v_exp_f32_e32 v48, v48
	v_exp_f32_e32 v49, v49
	v_exp_f32_e32 v50, v50
	s_waitcnt vmcnt(0)
	v_lshlrev_b32_e32 v108, 16, v104
	v_lshlrev_b32_e32 v110, 16, v106
	v_and_b32_e32 v106, 0xffff0000, v106
	v_lshlrev_b32_e32 v111, 16, v107
	v_mul_f32_e32 v68, v68, v108
	v_mul_f32_e32 v108, v64, v110
	v_mul_f32_e32 v64, 0xbfb8aa3b, v69
	v_mul_f32_e32 v69, v65, v106
	v_mul_f32_e32 v65, 0xbfb8aa3b, v70
	v_mul_f32_e32 v70, v66, v111
	v_mul_f32_e32 v66, 0xbfb8aa3b, v71
	v_exp_f32_e32 v64, v64
	v_exp_f32_e32 v65, v65
	v_exp_f32_e32 v66, v66
	v_and_b32_e32 v104, 0xffff0000, v104
	v_add_f32_e32 v64, 1.0, v64
	v_add_f32_e32 v65, 1.0, v65
	v_add_f32_e32 v66, 1.0, v66
	v_rcp_f32_e32 v64, v64
	v_rcp_f32_e32 v65, v65
	v_rcp_f32_e32 v66, v66
	v_lshlrev_b32_e32 v109, 16, v105
	v_and_b32_e32 v105, 0xffff0000, v105
	v_and_b32_e32 v107, 0xffff0000, v107
	v_mul_f32_e32 v64, v64, v104
	v_mul_f32_e32 v65, v65, v109
	v_mul_f32_e32 v66, v66, v105
	v_mul_f32_e32 v67, v67, v107
	v_cvt_pk_bf16_f32 v64, v68, v64
	v_cvt_pk_bf16_f32 v65, v65, v66
	v_cvt_pk_bf16_f32 v66, v108, v69
	v_lshl_add_u64 v[68:69], v[100:101], 0, v[140:141]
	v_cvt_pk_bf16_f32 v67, v70, v67
	global_store_dwordx4 v[68:69], v[64:67], off
	v_lshlrev_b32_e32 v68, 16, v98
	v_and_b32_e32 v69, 0xffff0000, v98
	v_lshlrev_b32_e32 v64, 16, v96
	v_lshlrev_b32_e32 v70, 16, v99
	v_mul_f32_e32 v60, v60, v64
	v_mul_f32_e32 v64, v56, v68
	v_mul_f32_e32 v56, 0xbfb8aa3b, v61
	v_mul_f32_e32 v61, v57, v69
	v_mul_f32_e32 v57, 0xbfb8aa3b, v62
	v_mul_f32_e32 v62, v58, v70
	v_mul_f32_e32 v58, 0xbfb8aa3b, v63
	v_exp_f32_e32 v56, v56
	v_exp_f32_e32 v57, v57
	v_exp_f32_e32 v58, v58
	v_add_f32_e32 v59, 1.0, v59
	v_add_f32_e32 v56, 1.0, v56
	v_add_f32_e32 v57, 1.0, v57
	v_add_f32_e32 v58, 1.0, v58
	v_rcp_f32_e32 v56, v56
	v_rcp_f32_e32 v57, v57
	v_rcp_f32_e32 v58, v58
	v_rcp_f32_e32 v59, v59
	v_add_f32_e32 v52, 1.0, v52
	v_add_f32_e32 v48, 1.0, v48
	v_add_f32_e32 v49, 1.0, v49
	v_add_f32_e32 v50, 1.0, v50
	v_and_b32_e32 v65, 0xffff0000, v96
	v_lshlrev_b32_e32 v66, 16, v97
	v_and_b32_e32 v67, 0xffff0000, v97
	v_rcp_f32_e32 v52, v52
	v_rcp_f32_e32 v48, v48
	v_rcp_f32_e32 v49, v49
	v_rcp_f32_e32 v50, v50
	v_and_b32_e32 v71, 0xffff0000, v99
	v_mul_f32_e32 v56, v56, v65
	v_mul_f32_e32 v57, v57, v66
	v_mul_f32_e32 v58, v58, v67
	v_mul_f32_e32 v59, v59, v71
	v_cvt_pk_bf16_f32 v56, v60, v56
	v_cvt_pk_bf16_f32 v57, v57, v58
	v_cvt_pk_bf16_f32 v58, v64, v61
	v_lshl_add_u64 v[60:61], v[100:101], 0, v[128:129]
	v_cvt_pk_bf16_f32 v59, v62, v59
	global_store_dwordx4 v[60:61], v[56:59], off
	v_lshlrev_b32_e32 v62, 16, v94
	v_and_b32_e32 v63, 0xffff0000, v94
	v_lshlrev_b32_e32 v58, 16, v92
	v_lshlrev_b32_e32 v64, 16, v95
	v_mul_f32_e32 v52, v52, v58
	v_mul_f32_e32 v58, v48, v62
	v_mul_f32_e32 v48, 0xbfb8aa3b, v53
	v_mul_f32_e32 v53, v49, v63
	v_mul_f32_e32 v49, 0xbfb8aa3b, v54
	v_mul_f32_e32 v54, v50, v64
	v_mul_f32_e32 v50, 0xbfb8aa3b, v55
	v_exp_f32_e32 v48, v48
	v_exp_f32_e32 v49, v49
	v_exp_f32_e32 v50, v50
	v_mul_f32_e32 v51, 0xbfb8aa3b, v51
	v_exp_f32_e32 v51, v51
	v_mul_f32_e32 v44, 0xbfb8aa3b, v44
	v_mul_f32_e32 v40, 0xbfb8aa3b, v40
	v_mul_f32_e32 v41, 0xbfb8aa3b, v41
	v_mul_f32_e32 v42, 0xbfb8aa3b, v42
	v_exp_f32_e32 v44, v44
	v_exp_f32_e32 v40, v40
; __device__ __forceinline__ float sigmoidf_(float v) { return __builtin_amdgcn_rcpf(1.0f + __expf(-v)); }
; __device__ __forceinline__ u32x4 pack8(const f32x4 a, const f32x4 b) { u32x4 w; w.x = cvt_pk_bf16(a[0], a[1]); w.y = cvt_pk_bf16(a[2], a[3]); w.z = cvt_pk_bf16(b[0], b[1]); w.w = cvt_pk_bf16(b[2], b[3]); return w; }
; __device__ __forceinline__ void unpack8(const u32x4 w, f32x4& a, f32x4& b) { a[0] = bf_lo(w.x); a[1] = bf_hi(w.x); a[2] = bf_lo(w.y); a[3] = bf_hi(w.y); b[0] = bf_lo(w.z); b[1] = bf_hi(w.z); b[2] = bf_lo(w.w); b[3] = bf_hi(w.w); }
;     template <int KIND> __device__ __forceinline__ void run(f32x4 (&acc)[2][2][4][2], const Unit& u, int tid_in) const {
;     ...
;                 for (int m = 0; m < 4; ++m) { int row = rbase + ai * 128 + m * 16; asm volatile("" : "+v"(row));
; #pragma unroll
;                     for (int bj = 0; bj < 2; ++bj) { const int col = u.pn * 256 + bj * 128 + cl; f32x4 y0, y1; unpack8(yv[m][bj], y0, y1);
; #pragma unroll
;                         for (int j = 0; j < 4; ++j) { y0[j] *= sigmoidf_(acc[ai][bj][m][0][j]); y1[j] *= sigmoidf_(acc[ai][bj][m][1][j]); }
;                         *(u32x4*)(zb + (size_t)row * ZW + 1024 + col) = pack8(y0, y1); } }
	v_exp_f32_e32 v41, v41
	v_exp_f32_e32 v42, v42
	v_add_f32_e32 v48, 1.0, v48
	v_add_f32_e32 v49, 1.0, v49
	v_add_f32_e32 v50, 1.0, v50
	v_rcp_f32_e32 v48, v48
	v_rcp_f32_e32 v49, v49
	v_rcp_f32_e32 v50, v50
	v_add_f32_e32 v51, 1.0, v51
	v_rcp_f32_e32 v51, v51
	v_add_f32_e32 v44, 1.0, v44
	v_add_f32_e32 v40, 1.0, v40
	v_add_f32_e32 v41, 1.0, v41
	v_add_f32_e32 v42, 1.0, v42
	v_and_b32_e32 v59, 0xffff0000, v92
	v_mad_i64_i32 v[56:57], s[2:3], v103, s76, v[172:173]
	v_lshlrev_b32_e32 v60, 16, v93
	v_and_b32_e32 v61, 0xffff0000, v93
	v_rcp_f32_e32 v44, v44
	v_rcp_f32_e32 v40, v40
	v_rcp_f32_e32 v41, v41
	v_rcp_f32_e32 v42, v42
	v_lshl_add_u64 v[56:57], v[56:57], 0, s[4:5]
	v_and_b32_e32 v65, 0xffff0000, v95
	v_mul_f32_e32 v48, v48, v59
	v_mul_f32_e32 v49, v49, v60
	v_mul_f32_e32 v50, v50, v61
	v_mul_f32_e32 v51, v51, v65
	v_cvt_pk_bf16_f32 v48, v52, v48
	v_cvt_pk_bf16_f32 v49, v49, v50
	v_cvt_pk_bf16_f32 v50, v58, v53
	v_lshl_add_u64 v[52:53], v[56:57], 0, v[140:141]
	v_cvt_pk_bf16_f32 v51, v54, v51
	global_store_dwordx4 v[52:53], v[48:51], off
	v_lshlrev_b32_e32 v52, 16, v90
	v_and_b32_e32 v53, 0xffff0000, v90
	v_lshlrev_b32_e32 v48, 16, v88
	v_lshlrev_b32_e32 v54, 16, v91
	v_mul_f32_e32 v44, v44, v48
	v_mul_f32_e32 v48, v40, v52
	v_mul_f32_e32 v40, 0xbfb8aa3b, v45
	v_mul_f32_e32 v45, v41, v53
	v_mul_f32_e32 v41, 0xbfb8aa3b, v46
	v_mul_f32_e32 v46, v42, v54
	v_mul_f32_e32 v42, 0xbfb8aa3b, v47
	v_exp_f32_e32 v40, v40
	v_exp_f32_e32 v41, v41
	v_exp_f32_e32 v42, v42
	v_mul_f32_e32 v43, 0xbfb8aa3b, v43
	v_exp_f32_e32 v43, v43
	v_mul_f32_e32 v36, 0xbfb8aa3b, v36
	v_mul_f32_e32 v32, 0xbfb8aa3b, v32
	v_mul_f32_e32 v33, 0xbfb8aa3b, v33
	v_mul_f32_e32 v34, 0xbfb8aa3b, v34
	v_exp_f32_e32 v36, v36
	v_exp_f32_e32 v32, v32
	v_exp_f32_e32 v33, v33
	v_exp_f32_e32 v34, v34
	v_add_f32_e32 v40, 1.0, v40
	v_add_f32_e32 v41, 1.0, v41
	v_add_f32_e32 v42, 1.0, v42
	v_rcp_f32_e32 v40, v40
	v_rcp_f32_e32 v41, v41
	v_rcp_f32_e32 v42, v42
	v_add_f32_e32 v43, 1.0, v43
	v_rcp_f32_e32 v43, v43
	v_add_f32_e32 v36, 1.0, v36
	v_add_f32_e32 v32, 1.0, v32
	v_add_f32_e32 v33, 1.0, v33
	v_add_f32_e32 v34, 1.0, v34
	v_and_b32_e32 v49, 0xffff0000, v88
	v_lshlrev_b32_e32 v50, 16, v89
	v_and_b32_e32 v51, 0xffff0000, v89
	v_rcp_f32_e32 v36, v36
	v_rcp_f32_e32 v32, v32
	v_rcp_f32_e32 v33, v33
	v_rcp_f32_e32 v34, v34
	v_and_b32_e32 v55, 0xffff0000, v91
	v_mul_f32_e32 v40, v40, v49
	v_mul_f32_e32 v41, v41, v50
	v_mul_f32_e32 v42, v42, v51
	v_mul_f32_e32 v43, v43, v55
	v_cvt_pk_bf16_f32 v40, v44, v40
	v_cvt_pk_bf16_f32 v41, v41, v42
	v_cvt_pk_bf16_f32 v42, v48, v45
	v_lshl_add_u64 v[44:45], v[56:57], 0, v[128:129]
	v_cvt_pk_bf16_f32 v43, v46, v43
	global_store_dwordx4 v[44:45], v[40:43], off
	v_lshlrev_b32_e32 v46, 16, v86
	v_and_b32_e32 v47, 0xffff0000, v86
	v_lshlrev_b32_e32 v42, 16, v84
	v_lshlrev_b32_e32 v48, 16, v87
	v_mul_f32_e32 v36, v36, v42
	v_mul_f32_e32 v42, v32, v46
	v_mul_f32_e32 v32, 0xbfb8aa3b, v37
	v_mul_f32_e32 v37, v33, v47
	v_mul_f32_e32 v33, 0xbfb8aa3b, v38
	v_mul_f32_e32 v38, v34, v48
	v_mul_f32_e32 v34, 0xbfb8aa3b, v39
	v_exp_f32_e32 v32, v32
	v_exp_f32_e32 v33, v33
	v_exp_f32_e32 v34, v34
	v_mul_f32_e32 v35, 0xbfb8aa3b, v35
	v_exp_f32_e32 v35, v35
	v_mul_f32_e32 v28, 0xbfb8aa3b, v28
	v_mul_f32_e32 v24, 0xbfb8aa3b, v24
	v_mul_f32_e32 v25, 0xbfb8aa3b, v25
	v_mul_f32_e32 v26, 0xbfb8aa3b, v26
	v_exp_f32_e32 v28, v28
	v_exp_f32_e32 v24, v24
	v_exp_f32_e32 v25, v25
	v_exp_f32_e32 v26, v26
	v_add_f32_e32 v32, 1.0, v32
	v_add_f32_e32 v33, 1.0, v33
	v_add_f32_e32 v34, 1.0, v34
	v_rcp_f32_e32 v32, v32
	v_rcp_f32_e32 v33, v33
	v_rcp_f32_e32 v34, v34
	v_add_f32_e32 v35, 1.0, v35
	v_rcp_f32_e32 v35, v35
	v_add_f32_e32 v28, 1.0, v28
	v_add_f32_e32 v24, 1.0, v24
	v_add_f32_e32 v25, 1.0, v25
	v_add_f32_e32 v26, 1.0, v26
	v_and_b32_e32 v43, 0xffff0000, v84
	v_mad_i64_i32 v[40:41], s[2:3], v102, s76, v[172:173]
	v_lshlrev_b32_e32 v44, 16, v85
	v_and_b32_e32 v45, 0xffff0000, v85
	v_rcp_f32_e32 v28, v28
	v_rcp_f32_e32 v24, v24
	v_rcp_f32_e32 v25, v25
	v_rcp_f32_e32 v26, v26
	v_lshl_add_u64 v[40:41], v[40:41], 0, s[4:5]
	v_and_b32_e32 v49, 0xffff0000, v87
	v_mul_f32_e32 v32, v32, v43
	v_mul_f32_e32 v33, v33, v44
	v_mul_f32_e32 v34, v34, v45
	v_mul_f32_e32 v35, v35, v49
	v_cvt_pk_bf16_f32 v32, v36, v32
	v_cvt_pk_bf16_f32 v33, v33, v34
	v_cvt_pk_bf16_f32 v34, v42, v37
	v_lshl_add_u64 v[36:37], v[40:41], 0, v[140:141]
	v_cvt_pk_bf16_f32 v35, v38, v35
	global_store_dwordx4 v[36:37], v[32:35], off
	v_lshlrev_b32_e32 v36, 16, v82
	v_and_b32_e32 v37, 0xffff0000, v82
	v_lshlrev_b32_e32 v32, 16, v80
	v_lshlrev_b32_e32 v38, 16, v83
	v_mul_f32_e32 v28, v28, v32
	v_mul_f32_e32 v32, v24, v36
; __device__ __forceinline__ float sigmoidf_(float v) { return __builtin_amdgcn_rcpf(1.0f + __expf(-v)); }
; __device__ __forceinline__ u32x4 pack8(const f32x4 a, const f32x4 b) { u32x4 w; w.x = cvt_pk_bf16(a[0], a[1]); w.y = cvt_pk_bf16(a[2], a[3]); w.z = cvt_pk_bf16(b[0], b[1]); w.w = cvt_pk_bf16(b[2], b[3]); return w; }
; __device__ __forceinline__ void unpack8(const u32x4 w, f32x4& a, f32x4& b) { a[0] = bf_lo(w.x); a[1] = bf_hi(w.x); a[2] = bf_lo(w.y); a[3] = bf_hi(w.y); b[0] = bf_lo(w.z); b[1] = bf_hi(w.z); b[2] = bf_lo(w.w); b[3] = bf_hi(w.w); }
; #define MEMFENCE asm volatile("" ::: "memory")
; #define G_WAIT_V(n) asm volatile("s_waitcnt vmcnt(" #n ")" ::: "memory")
; #define G_BAR __builtin_amdgcn_s_barrier()
;     template <int KIND> __device__ __forceinline__ void run(f32x4 (&acc)[2][2][4][2], const Unit& u, int tid_in) const {
;     ...
;                 for (int m = 0; m < 4; ++m) { int row = rbase + ai * 128 + m * 16; asm volatile("" : "+v"(row));
; #pragma unroll
;                     for (int bj = 0; bj < 2; ++bj) { const int col = u.pn * 256 + bj * 128 + cl; f32x4 y0, y1; unpack8(yv[m][bj], y0, y1);
; #pragma unroll
;                         for (int j = 0; j < 4; ++j) { y0[j] *= sigmoidf_(acc[ai][bj][m][0][j]); y1[j] *= sigmoidf_(acc[ai][bj][m][1][j]); }
;                         *(u32x4*)(zb + (size_t)row * ZW + 1024 + col) = pack8(y0, y1); } }
;                 MEMFENCE; }
;         }
;     ...
;         if (!has_next) break;
;         if (!(cs.kind == K_MG_B && cur.aux < 2))
; #pragma unroll
;         for (int a = 0; a < 2; ++a)
; #pragma unroll
;             for (int b = 0; b < 2; ++b)
; #pragma unroll
;                 for (int m = 0; m < 4; ++m)
; #pragma unroll
;                     for (int n = 0; n < 2; ++n) acc[a][b][m][n] = (f32x4){0.f, 0.f, 0.f, 0.f};
;         cur = nxt; cA = nA; cB = nB; ++ui;
;     }
;     G_WAIT_V(0);
;     if (wr == 0) G_BAR;
;     G_BAR;
	v_mul_f32_e32 v24, 0xbfb8aa3b, v29
	v_mul_f32_e32 v29, v25, v37
	v_mul_f32_e32 v25, 0xbfb8aa3b, v30
	v_mul_f32_e32 v30, v26, v38
	v_mul_f32_e32 v26, 0xbfb8aa3b, v31
	v_exp_f32_e32 v24, v24
	v_exp_f32_e32 v25, v25
	v_exp_f32_e32 v26, v26
	v_mul_f32_e32 v27, 0xbfb8aa3b, v27
	v_exp_f32_e32 v27, v27
	v_mul_f32_e32 v20, 0xbfb8aa3b, v20
	v_mul_f32_e32 v16, 0xbfb8aa3b, v16
	v_mul_f32_e32 v17, 0xbfb8aa3b, v17
	v_mul_f32_e32 v18, 0xbfb8aa3b, v18
	v_add_f32_e32 v24, 1.0, v24
	v_add_f32_e32 v25, 1.0, v25
	v_add_f32_e32 v26, 1.0, v26
	v_exp_f32_e32 v20, v20
	v_exp_f32_e32 v16, v16
	v_exp_f32_e32 v17, v17
	v_exp_f32_e32 v18, v18
	v_rcp_f32_e32 v24, v24
	v_rcp_f32_e32 v25, v25
	v_rcp_f32_e32 v26, v26
	v_add_f32_e32 v27, 1.0, v27
	v_rcp_f32_e32 v27, v27
	v_and_b32_e32 v33, 0xffff0000, v80
	v_lshlrev_b32_e32 v34, 16, v81
	v_and_b32_e32 v35, 0xffff0000, v81
	v_add_f32_e32 v20, 1.0, v20
	v_add_f32_e32 v16, 1.0, v16
	v_add_f32_e32 v17, 1.0, v17
	v_add_f32_e32 v18, 1.0, v18
	v_and_b32_e32 v39, 0xffff0000, v83
	v_mul_f32_e32 v24, v24, v33
	v_mul_f32_e32 v25, v25, v34
	v_mul_f32_e32 v26, v26, v35
	v_rcp_f32_e32 v20, v20
	v_rcp_f32_e32 v16, v16
	v_rcp_f32_e32 v17, v17
	v_rcp_f32_e32 v18, v18
	v_mul_f32_e32 v27, v27, v39
	v_cvt_pk_bf16_f32 v24, v28, v24
	v_cvt_pk_bf16_f32 v25, v25, v26
	v_cvt_pk_bf16_f32 v26, v32, v29
	v_lshl_add_u64 v[28:29], v[40:41], 0, v[128:129]
	v_cvt_pk_bf16_f32 v27, v30, v27
	global_store_dwordx4 v[28:29], v[24:27], off
	v_lshlrev_b32_e32 v29, 16, v78
	v_and_b32_e32 v30, 0xffff0000, v78
	v_mad_i64_i32 v[24:25], s[2:3], v0, s76, v[172:173]
	v_lshlrev_b32_e32 v0, 16, v76
	v_lshlrev_b32_e32 v31, 16, v79
	v_mul_f32_e32 v0, v20, v0
	v_mul_f32_e32 v20, v16, v29
	v_mul_f32_e32 v16, 0xbfb8aa3b, v21
	v_mul_f32_e32 v21, v17, v30
	v_mul_f32_e32 v17, 0xbfb8aa3b, v22
	v_mul_f32_e32 v22, v18, v31
	v_mul_f32_e32 v18, 0xbfb8aa3b, v23
	v_mul_f32_e32 v19, 0xbfb8aa3b, v19
	v_exp_f32_e32 v16, v16
	v_exp_f32_e32 v17, v17
	v_exp_f32_e32 v18, v18
	v_exp_f32_e32 v19, v19
	v_mul_f32_e32 v12, 0xbfb8aa3b, v12
	v_mul_f32_e32 v8, 0xbfb8aa3b, v8
	v_mul_f32_e32 v9, 0xbfb8aa3b, v9
	v_mul_f32_e32 v10, 0xbfb8aa3b, v10
	v_exp_f32_e32 v12, v12
	v_exp_f32_e32 v8, v8
	v_exp_f32_e32 v9, v9
	v_exp_f32_e32 v10, v10
	v_add_f32_e32 v16, 1.0, v16
	v_add_f32_e32 v17, 1.0, v17
	v_add_f32_e32 v18, 1.0, v18
	v_add_f32_e32 v19, 1.0, v19
	v_rcp_f32_e32 v16, v16
	v_rcp_f32_e32 v17, v17
	v_rcp_f32_e32 v18, v18
	v_rcp_f32_e32 v19, v19
	v_add_f32_e32 v12, 1.0, v12
	v_add_f32_e32 v8, 1.0, v8
	v_add_f32_e32 v9, 1.0, v9
	v_add_f32_e32 v10, 1.0, v10
	v_and_b32_e32 v26, 0xffff0000, v76
	v_lshlrev_b32_e32 v27, 16, v77
	v_and_b32_e32 v28, 0xffff0000, v77
	v_and_b32_e32 v32, 0xffff0000, v79
	v_rcp_f32_e32 v12, v12
	v_rcp_f32_e32 v8, v8
	v_rcp_f32_e32 v9, v9
	v_rcp_f32_e32 v10, v10
	v_lshl_add_u64 v[24:25], v[24:25], 0, s[4:5]
	v_mul_f32_e32 v16, v16, v26
	v_mul_f32_e32 v17, v17, v27
	v_mul_f32_e32 v18, v18, v28
	v_mul_f32_e32 v19, v19, v32
	v_cvt_pk_bf16_f32 v16, v0, v16
	v_cvt_pk_bf16_f32 v17, v17, v18
	v_cvt_pk_bf16_f32 v18, v20, v21
	v_cvt_pk_bf16_f32 v19, v22, v19
	v_lshl_add_u64 v[20:21], v[24:25], 0, v[140:141]
	global_store_dwordx4 v[20:21], v[16:19], off
	v_lshlrev_b32_e32 v0, 16, v72
	v_and_b32_e32 v20, 0xffff0000, v74
	v_lshlrev_b32_e32 v19, 16, v74
	v_lshlrev_b32_e32 v21, 16, v75
	v_mul_f32_e32 v0, v12, v0
	v_mul_f32_e32 v12, v8, v19
	v_mul_f32_e32 v8, 0xbfb8aa3b, v13
	v_mul_f32_e32 v13, v9, v20
	v_mul_f32_e32 v9, 0xbfb8aa3b, v14
	v_mul_f32_e32 v14, v10, v21
	v_mul_f32_e32 v10, 0xbfb8aa3b, v15
	v_exp_f32_e32 v8, v8
	v_exp_f32_e32 v9, v9
	v_exp_f32_e32 v10, v10
	v_mul_f32_e32 v11, 0xbfb8aa3b, v11
	v_exp_f32_e32 v11, v11
	v_add_f32_e32 v8, 1.0, v8
	v_add_f32_e32 v9, 1.0, v9
	v_add_f32_e32 v10, 1.0, v10
	v_rcp_f32_e32 v8, v8
	v_rcp_f32_e32 v9, v9
	v_rcp_f32_e32 v10, v10
	v_add_f32_e32 v11, 1.0, v11
	v_rcp_f32_e32 v11, v11
	v_and_b32_e32 v16, 0xffff0000, v72
	v_lshlrev_b32_e32 v17, 16, v73
	v_and_b32_e32 v18, 0xffff0000, v73
	v_and_b32_e32 v22, 0xffff0000, v75
	v_mul_f32_e32 v8, v8, v16
	v_mul_f32_e32 v9, v9, v17
	v_mul_f32_e32 v10, v10, v18
	v_mul_f32_e32 v11, v11, v22
	v_cvt_pk_bf16_f32 v8, v0, v8
	v_cvt_pk_bf16_f32 v9, v9, v10
	v_cvt_pk_bf16_f32 v10, v12, v13
	v_lshl_add_u64 v[12:13], v[24:25], 0, v[128:129]
	v_cvt_pk_bf16_f32 v11, v14, v11
	global_store_dwordx4 v[12:13], v[8:11], off
	s_and_b64 vcc, exec, s[10:11]
	s_mov_b32 s33, s34
	s_mov_b32 s35, s12
	s_mov_b64 s[18:19], s[16:17]
	s_mov_b64 s[2:3], s[14:15]
	s_cbranch_vccz .LBB0_799
	s_cmp_eq_u32 s101, 2
	s_cbranch_scc0 .Ldbj_GLU_pe
	s_barrier
.Ldbj_GLU_pe:
	s_mov_b32 s101, 0
	s_waitcnt vmcnt(0)
	s_cmpk_gt_u32 s20, 0xff
	s_cbranch_scc1 .LBB0_808
	s_barrier

; #define G_STAGE(bufoff, gbase, o0, h64) do { \
;         __builtin_amdgcn_global_load_lds((const unsigned*)((const char*)(gbase) + (o0)), (LAS unsigned*)(lds + (bufoff) + ldsw), 16, 0, 0); \
;         __builtin_amdgcn_global_load_lds((const unsigned*)((const char*)(gbase) + (h64) + (o0)), (LAS unsigned*)(lds + (bufoff) + ldsw + 8192), 16, 0, 0); } while (0)
; #define G_LDA(dst, b, h) do { _Pragma("unroll") for (int m = 0; m < 4; ++m) _Pragma("unroll") for (int k = 0; k < 2; ++k) dst[m][k] = *(const LAS bf16x8*)(lds + G_SA(b, h) + aoff + m * 2048 + k * 1024); } while (0)
; #define G_LDB(dst, b, h) do { _Pragma("unroll") for (int n = 0; n < 2; ++n) _Pragma("unroll") for (int k = 0; k < 2; ++k) dst[n][k] = *(const LAS bf16x8*)(lds + G_SB(b, h) + boff + n * 2048 + k * 1024); } while (0)
; #define G_WAIT_L(n) asm volatile("s_waitcnt lgkmcnt(" #n ")" ::: "memory")
; #define G_BAR __builtin_amdgcn_s_barrier()
; #define G_SCHED __builtin_amdgcn_sched_barrier(0)
;     ...
;             G_LDB(B0, 0, 0); G_SCHED; G_LDA(At, 0, 0); G_STAGE(G_SA(1, 1), a1 + chA, cA0, qA);
;             G_WAIT_L(8); G_BAR; G_WAIT_L(0); G_MMA(0, 0, At, B0); G_BAR; G_SCHED;
;     ...
;         if (!(cs.kind == K_MG_B && cur.aux < 2))
; #pragma unroll
;         for (int a = 0; a < 2; ++a)
; #pragma unroll
;             for (int b = 0; b < 2; ++b)
; #pragma unroll
;                 for (int m = 0; m < 4; ++m)
; #pragma unroll
;                     for (int n = 0; n < 2; ++n) acc[a][b][m][n] = (f32x4){0.f, 0.f, 0.f, 0.f};
.LBB0_871:
	s_add_u32 s2, s2, 0xb0080
	s_addc_u32 s3, s3, 0
	s_add_u32 s37, s12, 0x100
	v_mov_b64_e32 v[8:9], 0
	s_addc_u32 s38, s13, 0
	s_mov_b32 s39, -2
	v_mov_b64_e32 v[10:11], 0
	v_mov_b64_e32 v[12:13], 0
	v_mov_b64_e32 v[14:15], 0
	v_mov_b64_e32 v[24:25], 0
	v_mov_b64_e32 v[26:27], 0
	v_mov_b64_e32 v[28:29], 0
	v_mov_b64_e32 v[30:31], 0
	v_mov_b64_e32 v[40:41], 0
	v_mov_b64_e32 v[42:43], 0
	v_mov_b64_e32 v[44:45], 0
	v_mov_b64_e32 v[46:47], 0
	v_mov_b64_e32 v[56:57], 0
	v_mov_b64_e32 v[58:59], 0
	v_mov_b64_e32 v[60:61], 0
	v_mov_b64_e32 v[62:63], 0
	v_mov_b64_e32 v[16:17], 0
	v_mov_b64_e32 v[18:19], 0
	v_mov_b64_e32 v[20:21], 0
	v_mov_b64_e32 v[22:23], 0
	v_mov_b64_e32 v[36:37], 0
	v_mov_b64_e32 v[38:39], 0
	v_mov_b64_e32 v[32:33], 0
	v_mov_b64_e32 v[34:35], 0
	v_mov_b64_e32 v[52:53], 0
	v_mov_b64_e32 v[54:55], 0
	v_mov_b64_e32 v[48:49], 0
	v_mov_b64_e32 v[50:51], 0
	v_mov_b64_e32 v[68:69], 0
	v_mov_b64_e32 v[70:71], 0
	v_mov_b64_e32 v[64:65], 0
	v_mov_b64_e32 v[66:67], 0
	v_mov_b64_e32 v[72:73], 0
	v_mov_b64_e32 v[74:75], 0
	v_mov_b64_e32 v[76:77], 0
	v_mov_b64_e32 v[78:79], 0
	v_mov_b64_e32 v[88:89], 0
	v_mov_b64_e32 v[90:91], 0
	v_mov_b64_e32 v[92:93], 0
	v_mov_b64_e32 v[94:95], 0
	v_mov_b64_e32 v[104:105], 0
	v_mov_b64_e32 v[106:107], 0
	v_mov_b64_e32 v[108:109], 0
	v_mov_b64_e32 v[110:111], 0
	v_mov_b64_e32 v[120:121], 0
	v_mov_b64_e32 v[122:123], 0
	v_mov_b64_e32 v[124:125], 0
	v_mov_b64_e32 v[126:127], 0
	v_mov_b64_e32 v[84:85], 0
	v_mov_b64_e32 v[86:87], 0
	v_mov_b64_e32 v[80:81], 0
	v_mov_b64_e32 v[82:83], 0
	v_mov_b64_e32 v[100:101], 0
	v_mov_b64_e32 v[102:103], 0
	v_mov_b64_e32 v[96:97], 0
	v_mov_b64_e32 v[98:99], 0
	v_mov_b64_e32 v[116:117], 0
	v_mov_b64_e32 v[118:119], 0
	v_mov_b64_e32 v[112:113], 0
	v_mov_b64_e32 v[114:115], 0
	v_mov_b64_e32 v[132:133], 0
	v_mov_b64_e32 v[134:135], 0
	v_mov_b64_e32 v[128:129], 0
	v_mov_b64_e32 v[130:131], 0
	s_mov_b64 s[42:43], 0x20080
	s_mov_b64 s[50:51], 0x10000
	s_mov_b64 s[52:53], 0x30000
	s_mov_b64 s[54:55], 0x10080
	s_mov_b64 s[58:59], 0x30080
	s_cmp_eq_u32 s101, 2
	s_cselect_b32 s101, 0, s101
.LBB0_872:
	s_add_u32 s4, s2, 0xfff50080
	s_addc_u32 s5, s3, -1
	s_add_i32 s40, 0, 0x10000
	v_add_u32_e32 v140, s40, v159
	ds_read_b128 v[144:147], v140
	ds_read_b128 v[148:151], v140 offset:1024
	ds_read_b128 v[136:139], v140 offset:2048
	ds_read_b128 v[140:143], v140 offset:3072
	s_cmp_eq_u32 s39, 4
	s_cselect_b32 s13, s9, s5
	s_cselect_b32 s12, s8, s4
	s_cselect_b32 s15, s11, s38
	s_cselect_b32 s14, s10, s37
	v_lshl_add_u64 v[154:155], s[2:3], 0, v[152:153]
	s_add_i32 m0, s22, 0xc000
	ds_read_b128 v[160:163], v236
	ds_read_b128 v[164:167], v236 offset:1024
	ds_read_b128 v[176:179], v236 offset:2048
	ds_read_b128 v[180:183], v236 offset:3072
	ds_read_b128 v[196:199], v236 offset:4096
	ds_read_b128 v[200:203], v236 offset:5120
	ds_read_b128 v[204:207], v236 offset:6144
	ds_read_b128 v[208:211], v236 offset:7168
	global_load_lds_dwordx4 v[154:155], off
	v_lshl_add_u64 v[154:155], v[154:155], 0, s[86:87]
	s_add_i32 m0, s22, 0xe000
	s_nop 0
	global_load_lds_dwordx4 v[154:155], off
	s_waitcnt lgkmcnt(8)
	s_cmp_eq_u32 s101, 1
	s_cbranch_scc1 .Ldb_MG0_sk
	s_barrier
.Ldb_MG0_sk:
	s_mov_b32 s101, 0
	s_waitcnt lgkmcnt(0)
	v_mfma_f32_16x16x128_f8f6f4 v[128:131], v[144:151], v[160:167], v[128:131]
	v_mfma_f32_16x16x128_f8f6f4 v[132:135], v[136:143], v[160:167], v[132:135]
	v_mfma_f32_16x16x128_f8f6f4 v[112:115], v[144:151], v[176:183], v[112:115]
	v_mfma_f32_16x16x128_f8f6f4 v[116:119], v[136:143], v[176:183], v[116:119]
	v_mfma_f32_16x16x128_f8f6f4 v[96:99], v[144:151], v[196:203], v[96:99]
	v_mfma_f32_16x16x128_f8f6f4 v[100:103], v[136:143], v[196:203], v[100:103]
	v_mfma_f32_16x16x128_f8f6f4 v[80:83], v[144:151], v[204:211], v[80:83]
	v_mfma_f32_16x16x128_f8f6f4 v[84:87], v[136:143], v[204:211], v[84:87]
	s_barrier
	s_add_i32 s4, 0, 0x14000
	v_add_u32_e32 v154, s4, v159
	s_add_i32 s5, s40, s17
	ds_read_b128 v[212:215], v154
	ds_read_b128 v[216:219], v154 offset:1024
	ds_read_b128 v[220:223], v154 offset:2048
	ds_read_b128 v[224:227], v154 offset:3072
	v_lshl_add_u64 v[154:155], s[14:15], 0, v[0:1]
	s_mov_b32 m0, s5
	v_lshl_add_u64 v[156:157], v[154:155], 0, s[50:51]
	global_load_lds_dwordx4 v[154:155], off
	s_add_i32 m0, s5, 0x2000
	s_nop 0
	global_load_lds_dwordx4 v[156:157], off
	s_barrier
	s_waitcnt lgkmcnt(0)
	v_mfma_f32_16x16x128_f8f6f4 v[124:127], v[212:219], v[160:167], v[124:127]
	v_mfma_f32_16x16x128_f8f6f4 v[120:123], v[220:227], v[160:167], v[120:123]
	v_mfma_f32_16x16x128_f8f6f4 v[108:111], v[212:219], v[176:183], v[108:111]
	v_mfma_f32_16x16x128_f8f6f4 v[104:107], v[220:227], v[176:183], v[104:107]
	v_mfma_f32_16x16x128_f8f6f4 v[92:95], v[212:219], v[196:203], v[92:95]
	v_mfma_f32_16x16x128_f8f6f4 v[88:91], v[220:227], v[196:203], v[88:91]
	v_mfma_f32_16x16x128_f8f6f4 v[76:79], v[212:219], v[204:211], v[76:79]
	v_mfma_f32_16x16x128_f8f6f4 v[72:75], v[220:227], v[204:211], v[72:75]
	s_barrier
	s_mov_b32 m0, s22
	v_lshl_add_u64 v[156:157], s[12:13], 0, v[2:3]
	ds_read_b128 v[160:163], v236 offset:16384
	ds_read_b128 v[164:167], v236 offset:17408
	ds_read_b128 v[176:179], v236 offset:18432
	ds_read_b128 v[180:183], v236 offset:19456
	ds_read_b128 v[196:199], v236 offset:20480
	ds_read_b128 v[200:203], v236 offset:21504
	ds_read_b128 v[204:207], v236 offset:22528
	ds_read_b128 v[208:211], v236 offset:23552
	global_load_lds_dwordx4 v[156:157], off
	v_lshl_add_u64 v[234:235], v[156:157], 0, s[86:87]
	s_mov_b32 m0, s23
	s_nop 0
	global_load_lds_dwordx4 v[234:235], off
	s_barrier
; #define G_STAGE(bufoff, gbase, o0, h64) do { \
;         __builtin_amdgcn_global_load_lds((const unsigned*)((const char*)(gbase) + (o0)), (LAS unsigned*)(lds + (bufoff) + ldsw), 16, 0, 0); \
;         __builtin_amdgcn_global_load_lds((const unsigned*)((const char*)(gbase) + (h64) + (o0)), (LAS unsigned*)(lds + (bufoff) + ldsw + 8192), 16, 0, 0); } while (0)
; #define G_LDA(dst, b, h) do { _Pragma("unroll") for (int m = 0; m < 4; ++m) _Pragma("unroll") for (int k = 0; k < 2; ++k) dst[m][k] = *(const LAS bf16x8*)(lds + G_SA(b, h) + aoff + m * 2048 + k * 1024); } while (0)
; #define G_LDB(dst, b, h) do { _Pragma("unroll") for (int n = 0; n < 2; ++n) _Pragma("unroll") for (int k = 0; k < 2; ++k) dst[n][k] = *(const LAS bf16x8*)(lds + G_SB(b, h) + boff + n * 2048 + k * 1024); } while (0)
; #define G_WAIT_V(n) asm volatile("s_waitcnt vmcnt(" #n ")" ::: "memory")
; #define G_WAIT_L(n) asm volatile("s_waitcnt lgkmcnt(" #n ")" ::: "memory")
; #define G_BAR __builtin_amdgcn_s_barrier()
; #define G_SCHED __builtin_amdgcn_sched_barrier(0)
;     ...
;             G_BAR; G_WAIT_L(0); G_MMA(0, 1, At, B1); G_BAR;
;             G_LDA(At, 0, 1); G_STAGE(G_SA(0, 0), a2, cA0, qA);
;             G_BAR; G_WAIT_L(0); G_MMA(1, 0, At, B0); G_BAR; G_SCHED;
;             G_STAGE(G_SB(0, 1), b2 + chB, cB0, qB);
;             G_WAIT_V(6); G_BAR; G_MMA(1, 1, At, B1); G_BAR;
;             G_LDB(B0, 1, 0); G_SCHED; G_LDA(At, 1, 0); G_STAGE(G_SA(0, 1), a2 + chA, cA0, qA);
;             G_WAIT_L(8); G_BAR; G_WAIT_L(0); G_MMA(0, 0, At, B0); G_BAR; G_SCHED;
;             G_LDB(B1, 1, 1); G_STAGE(G_SB(1, 0), b3, cB0, qB);
;             G_BAR; G_WAIT_L(0); G_MMA(0, 1, At, B1); G_BAR;
;             G_LDA(At, 1, 1); G_STAGE(G_SA(1, 0), a3, cA0, qA);
;             G_BAR; G_WAIT_L(0); G_MMA(1, 0, At, B0); G_BAR; G_SCHED;
;             G_STAGE(G_SB(1, 1), b3 + chB, cB0, qB);
;             G_WAIT_V(6); G_BAR; G_MMA(1, 1, At, B1); G_BAR;
;         }
	s_waitcnt lgkmcnt(0)
	v_mfma_f32_16x16x128_f8f6f4 v[64:67], v[144:151], v[160:167], v[64:67]
	v_mfma_f32_16x16x128_f8f6f4 v[68:71], v[136:143], v[160:167], v[68:71]
	v_mfma_f32_16x16x128_f8f6f4 v[48:51], v[144:151], v[176:183], v[48:51]
	v_mfma_f32_16x16x128_f8f6f4 v[52:55], v[136:143], v[176:183], v[52:55]
	v_mfma_f32_16x16x128_f8f6f4 v[32:35], v[144:151], v[196:203], v[32:35]
	v_mfma_f32_16x16x128_f8f6f4 v[36:39], v[136:143], v[196:203], v[36:39]
	v_mfma_f32_16x16x128_f8f6f4 v[20:23], v[144:151], v[204:211], v[20:23]
	v_mfma_f32_16x16x128_f8f6f4 v[16:19], v[136:143], v[204:211], v[16:19]
	s_barrier
	s_add_i32 s4, s4, s17
	v_lshl_add_u64 v[140:141], v[154:155], 0, s[0:1]
	s_mov_b32 m0, s4
	s_nop 0
	global_load_lds_dwordx4 v[140:141], off
	v_lshl_add_u64 v[140:141], v[154:155], 0, s[52:53]
	s_add_i32 m0, s4, 0x2000
	s_nop 0
	global_load_lds_dwordx4 v[140:141], off
	s_waitcnt vmcnt(6)
	s_barrier
	v_mfma_f32_16x16x128_f8f6f4 v[60:63], v[212:219], v[160:167], v[60:63]
	v_mfma_f32_16x16x128_f8f6f4 v[56:59], v[220:227], v[160:167], v[56:59]
	v_mfma_f32_16x16x128_f8f6f4 v[44:47], v[212:219], v[176:183], v[44:47]
	v_mfma_f32_16x16x128_f8f6f4 v[40:43], v[220:227], v[176:183], v[40:43]
	v_mfma_f32_16x16x128_f8f6f4 v[28:31], v[212:219], v[196:203], v[28:31]
	v_mfma_f32_16x16x128_f8f6f4 v[24:27], v[220:227], v[196:203], v[24:27]
	v_mfma_f32_16x16x128_f8f6f4 v[12:15], v[212:219], v[204:211], v[12:15]
	v_mfma_f32_16x16x128_f8f6f4 v[8:11], v[220:227], v[204:211], v[8:11]
	s_barrier
	s_add_i32 s4, 0, 0x18000
	v_add_u32_e32 v140, s4, v159
	ds_read_b128 v[144:147], v140
	ds_read_b128 v[148:151], v140 offset:1024
	ds_read_b128 v[136:139], v140 offset:2048
	ds_read_b128 v[140:143], v140 offset:3072
	s_mov_b32 m0, s24
	v_lshl_add_u64 v[234:235], v[156:157], 0, s[88:89]
	ds_read_b128 v[160:163], v236 offset:32768
	ds_read_b128 v[164:167], v236 offset:33792
	ds_read_b128 v[176:179], v236 offset:34816
	ds_read_b128 v[180:183], v236 offset:35840
	ds_read_b128 v[196:199], v236 offset:36864
	ds_read_b128 v[200:203], v236 offset:37888
	ds_read_b128 v[204:207], v236 offset:38912
	ds_read_b128 v[208:211], v236 offset:39936
	global_load_lds_dwordx4 v[234:235], off
	v_lshl_add_u64 v[234:235], v[156:157], 0, s[64:65]
	s_mov_b32 m0, s25
	s_nop 0
	global_load_lds_dwordx4 v[234:235], off
	s_waitcnt lgkmcnt(8)
	s_barrier
	s_waitcnt lgkmcnt(0)
	v_mfma_f32_16x16x128_f8f6f4 v[128:131], v[144:151], v[160:167], v[128:131]
	v_mfma_f32_16x16x128_f8f6f4 v[132:135], v[136:143], v[160:167], v[132:135]
	v_mfma_f32_16x16x128_f8f6f4 v[112:115], v[144:151], v[176:183], v[112:115]
	v_mfma_f32_16x16x128_f8f6f4 v[116:119], v[136:143], v[176:183], v[116:119]
	v_mfma_f32_16x16x128_f8f6f4 v[96:99], v[144:151], v[196:203], v[96:99]
	v_mfma_f32_16x16x128_f8f6f4 v[100:103], v[136:143], v[196:203], v[100:103]
	v_mfma_f32_16x16x128_f8f6f4 v[80:83], v[144:151], v[204:211], v[80:83]
	v_mfma_f32_16x16x128_f8f6f4 v[84:87], v[136:143], v[204:211], v[84:87]
	s_barrier
	s_add_i32 s5, 0, 0x1c000
	s_add_i32 s4, s4, s17
	v_add_u32_e32 v237, s5, v159
	v_lshl_add_u64 v[234:235], v[154:155], 0, s[46:47]
	s_mov_b32 m0, s4
	ds_read_b128 v[212:215], v237
	ds_read_b128 v[216:219], v237 offset:1024
	ds_read_b128 v[220:223], v237 offset:2048
	ds_read_b128 v[224:227], v237 offset:3072
	global_load_lds_dwordx4 v[234:235], off
	v_lshl_add_u64 v[234:235], v[154:155], 0, s[54:55]
	s_add_i32 m0, s4, 0x2000
	s_nop 0
	global_load_lds_dwordx4 v[234:235], off
	s_barrier
	s_waitcnt lgkmcnt(0)
	v_mfma_f32_16x16x128_f8f6f4 v[124:127], v[212:219], v[160:167], v[124:127]
	v_mfma_f32_16x16x128_f8f6f4 v[120:123], v[220:227], v[160:167], v[120:123]
	v_mfma_f32_16x16x128_f8f6f4 v[108:111], v[212:219], v[176:183], v[108:111]
	v_mfma_f32_16x16x128_f8f6f4 v[104:107], v[220:227], v[176:183], v[104:107]
	v_mfma_f32_16x16x128_f8f6f4 v[92:95], v[212:219], v[196:203], v[92:95]
	v_mfma_f32_16x16x128_f8f6f4 v[88:91], v[220:227], v[196:203], v[88:91]
	v_mfma_f32_16x16x128_f8f6f4 v[76:79], v[212:219], v[204:211], v[76:79]
	v_mfma_f32_16x16x128_f8f6f4 v[72:75], v[220:227], v[204:211], v[72:75]
	s_barrier
	s_mov_b32 m0, s26
	v_lshl_add_u64 v[234:235], v[156:157], 0, s[46:47]
	ds_read_b128 v[160:163], v236 offset:49152
	ds_read_b128 v[164:167], v236 offset:50176
	ds_read_b128 v[176:179], v236 offset:51200
	ds_read_b128 v[180:183], v236 offset:52224
	ds_read_b128 v[196:199], v236 offset:53248
	ds_read_b128 v[200:203], v236 offset:54272
	ds_read_b128 v[204:207], v236 offset:55296
	ds_read_b128 v[208:211], v236 offset:56320
	global_load_lds_dwordx4 v[234:235], off
	v_lshl_add_u64 v[156:157], v[156:157], 0, s[66:67]
	s_mov_b32 m0, s27
	s_nop 0
	global_load_lds_dwordx4 v[156:157], off
	s_barrier
	s_waitcnt lgkmcnt(0)
	v_mfma_f32_16x16x128_f8f6f4 v[64:67], v[144:151], v[160:167], v[64:67]
	v_mfma_f32_16x16x128_f8f6f4 v[68:71], v[136:143], v[160:167], v[68:71]
	v_mfma_f32_16x16x128_f8f6f4 v[48:51], v[144:151], v[176:183], v[48:51]
	v_mfma_f32_16x16x128_f8f6f4 v[52:55], v[136:143], v[176:183], v[52:55]
	v_mfma_f32_16x16x128_f8f6f4 v[32:35], v[144:151], v[196:203], v[32:35]
	v_mfma_f32_16x16x128_f8f6f4 v[36:39], v[136:143], v[196:203], v[36:39]
	v_mfma_f32_16x16x128_f8f6f4 v[20:23], v[144:151], v[204:211], v[20:23]
	v_mfma_f32_16x16x128_f8f6f4 v[16:19], v[136:143], v[204:211], v[16:19]
	s_barrier
	s_add_i32 s4, s5, s17
	v_lshl_add_u64 v[140:141], v[154:155], 0, s[42:43]
	s_mov_b32 m0, s4
	s_nop 0
	global_load_lds_dwordx4 v[140:141], off
	v_lshl_add_u64 v[140:141], v[154:155], 0, s[58:59]
	s_add_i32 m0, s4, 0x2000
	s_nop 0
	global_load_lds_dwordx4 v[140:141], off
	s_add_i32 s39, s39, 2
	s_add_u32 s2, s2, 0x100
	s_addc_u32 s3, s3, 0
	s_add_u32 s37, s37, 0x100
	s_addc_u32 s38, s38, 0
	s_cmp_gt_u32 s39, 5
	s_waitcnt vmcnt(6)
	s_barrier
	v_mfma_f32_16x16x128_f8f6f4 v[60:63], v[212:219], v[160:167], v[60:63]
	v_mfma_f32_16x16x128_f8f6f4 v[56:59], v[220:227], v[160:167], v[56:59]
	v_mfma_f32_16x16x128_f8f6f4 v[44:47], v[212:219], v[176:183], v[44:47]
	v_mfma_f32_16x16x128_f8f6f4 v[40:43], v[220:227], v[176:183], v[40:43]
	v_mfma_f32_16x16x128_f8f6f4 v[28:31], v[212:219], v[196:203], v[28:31]
	v_mfma_f32_16x16x128_f8f6f4 v[24:27], v[220:227], v[196:203], v[24:27]
	v_mfma_f32_16x16x128_f8f6f4 v[12:15], v[212:219], v[204:211], v[12:15]
	v_mfma_f32_16x16x128_f8f6f4 v[8:11], v[220:227], v[204:211], v[8:11]
	s_cbranch_scc0 .Ldb_MG0_cont
	v_readfirstlane_b32 s101, v186
	s_cmpk_gt_u32 s101, 0xff
	s_cbranch_scc1 .Ldb_MG0_young
	s_barrier
	s_mov_b32 s101, 1
	s_branch .Ldb_MG0_exit

; __device__ __forceinline__ float sigmoidf_(float v) { return __builtin_amdgcn_rcpf(1.0f + __expf(-v)); }
; #define MEMFENCE asm volatile("" ::: "memory")
;     __device__ __forceinline__ void get_rs(const Unit& u, int wr, int fr, float (&rs)[8]) const {
; #pragma unroll
;         for (int r8 = 0; r8 < 8; ++r8) rs[r8] = rstab[u.ord * 256 + (r8 >> 2) * 128 + wr * 64 + (r8 & 3) * 16 + fr];
;     }
;     template <int KIND> __device__ __forceinline__ void run(f32x4 (&acc)[2][2][4][2], const Unit& u, int tid_in) const {
;     ...
;         if constexpr (KIND == K_MG_G) { float rs[8]; get_rs(u, wr, fr, rs);
;             u32x4* gst = (u32x4*)((unsigned char*)x + 32 * MiB) + ((size_t)(blockIdx.x * 2 + (u.ord & 1)) * 3 + u.aux) * 4096;
; #pragma unroll
;             for (int ai = 0; ai < 2; ++ai)
; #pragma unroll
;                 for (int m = 0; m < 4; ++m) { const float r = rs[ai * 4 + m] * (1.0f / GATE_WSCALE); u32x4 w;
; #pragma unroll
;                     for (int bj = 0; bj < 2; ++bj) { f32x4 a = acc[ai][bj][m][0] * r, b = acc[ai][bj][m][1] * r;
; #pragma unroll
;                         for (int j = 0; j < 4; ++j) { a[j] = sigmoidf_(a[j]); b[j] = sigmoidf_(b[j]); }
;                         if (bj == 0) { w.x = pack4_u8c(a); w.y = pack4_u8c(b); } else { w.z = pack4_u8c(a); w.w = pack4_u8c(b); } }
;                     gst[(ai * 4 + m) * 512 + tid] = w; MEMFENCE; }
.Ldb_MG0_exit:
	v_mov_b32_e32 v142, v158
	s_lshl_b32 s3, s33, 10
	v_readfirstlane_b32 s2, v142
	s_add_i32 s3, s3, 0
	s_and_b32 s2, s2, 0xffffff00
	v_and_b32_e32 v136, 15, v142
	s_add_i32 s3, s3, s2
	v_lshl_add_u32 v136, v136, 2, s3
	v_add_u32_e32 v136, 0x20010, v136
	ds_read2_b32 v[144:145], v136 offset1:16
	ds_read2_b32 v[140:141], v136 offset0:32 offset1:48
	ds_read2_b32 v[138:139], v136 offset0:128 offset1:144
	ds_read2_b32 v[136:137], v136 offset0:160 offset1:176
	s_and_b32 s2, s33, 1
	s_waitcnt lgkmcnt(0)
	v_mul_f32_e32 v144, 0x3c800000, v144
	v_pk_mul_f32 v[128:129], v[128:129], v[144:145] op_sel_hi:[1,0]
	v_pk_mul_f32 v[130:131], v[130:131], v[144:145] op_sel_hi:[1,0]
	v_mul_f32_e32 v128, 0xbfb8aa3b, v128
	v_mul_f32_e32 v129, 0xbfb8aa3b, v129
	v_mul_f32_e32 v131, 0xbfb8aa3b, v131
	v_exp_f32_e32 v128, v128
	v_exp_f32_e32 v129, v129
	v_mul_f32_e32 v130, 0xbfb8aa3b, v130
	v_exp_f32_e32 v131, v131
	v_exp_f32_e32 v130, v130
	v_add_f32_e32 v128, 1.0, v128
	v_add_f32_e32 v129, 1.0, v129
	s_or_b32 s2, s2, s60
	v_pk_mul_f32 v[132:133], v[132:133], v[144:145] op_sel_hi:[1,0]
	v_add_f32_e32 v131, 1.0, v131
	v_rcp_f32_e32 v128, v128
	v_rcp_f32_e32 v129, v129
	v_add_f32_e32 v130, 1.0, v130
	s_mul_hi_u32 s3, s2, 3
	s_mul_i32 s2, s2, 3
	s_ashr_i32 s4, s36, 31
	v_pk_mul_f32 v[134:135], v[134:135], v[144:145] op_sel_hi:[1,0]
	v_mul_f32_e32 v132, 0xbfb8aa3b, v132
	v_mul_f32_e32 v133, 0xbfb8aa3b, v133
	v_rcp_f32_e32 v131, v131
	v_rcp_f32_e32 v130, v130
	s_add_u32 s2, s2, s36
	v_mul_f32_e32 v135, 0xbfb8aa3b, v135
	v_exp_f32_e32 v132, v132
	v_exp_f32_e32 v133, v133
	v_mul_f32_e32 v134, 0xbfb8aa3b, v134
	s_addc_u32 s3, s3, s4
	v_exp_f32_e32 v135, v135
	v_exp_f32_e32 v134, v134
	s_mov_b32 s4, 0x437f0000
	v_fma_f32 v128, v128, s4, 0.5
	v_fma_f32 v129, v129, s4, 0.5
	v_max_f32_e32 v128, 1.0, v128
	v_max_f32_e32 v129, 1.0, v129
	v_fma_f32 v130, v130, s4, 0.5
	v_fma_f32 v131, v131, s4, 0.5
	v_add_f32_e32 v132, 1.0, v132
	v_add_f32_e32 v133, 1.0, v133
	v_cvt_u32_f32_e32 v128, v128
	v_cvt_u32_f32_e32 v129, v129
	v_max_f32_e32 v130, 1.0, v130
	v_max_f32_e32 v131, 1.0, v131
	v_add_f32_e32 v135, 1.0, v135
	v_rcp_f32_e32 v132, v132
	v_rcp_f32_e32 v133, v133
	v_cvt_u32_f32_sdwa v130, v130 dst_sel:WORD_1 dst_unused:UNUSED_PAD src0_sel:DWORD
	v_cvt_u32_f32_sdwa v131, v131 dst_sel:BYTE_3 dst_unused:UNUSED_PAD src0_sel:DWORD
	v_add_f32_e32 v134, 1.0, v134
	v_rcp_f32_e32 v135, v135
	v_rcp_f32_e32 v134, v134
	v_lshl_or_b32 v128, v129, 8, v128
	v_or3_b32 v128, v128, v130, v131
	v_fma_f32 v129, v132, s4, 0.5
	v_fma_f32 v130, v133, s4, 0.5
	v_pk_mul_f32 v[124:125], v[124:125], v[144:145] op_sel_hi:[1,0]
	v_max_f32_e32 v129, 1.0, v129
	v_max_f32_e32 v130, 1.0, v130
	v_fma_f32 v131, v134, s4, 0.5
	v_fma_f32 v132, v135, s4, 0.5
	v_mul_f32_e32 v125, 0xbfb8aa3b, v125
	v_cvt_u32_f32_e32 v129, v129
	v_cvt_u32_f32_e32 v130, v130
	v_max_f32_e32 v131, 1.0, v131
	v_max_f32_e32 v132, 1.0, v132
	v_exp_f32_e32 v125, v125
	v_cvt_u32_f32_sdwa v131, v131 dst_sel:WORD_1 dst_unused:UNUSED_PAD src0_sel:DWORD
	v_cvt_u32_f32_sdwa v132, v132 dst_sel:BYTE_3 dst_unused:UNUSED_PAD src0_sel:DWORD
	v_pk_mul_f32 v[120:121], v[120:121], v[144:145] op_sel_hi:[1,0]
	v_mul_f32_e32 v124, 0xbfb8aa3b, v124
	v_mul_f32_e32 v121, 0xbfb8aa3b, v121
	v_lshl_or_b32 v129, v130, 8, v129
	v_exp_f32_e32 v130, v124
	v_add_f32_e32 v124, 1.0, v125
	v_exp_f32_e32 v121, v121
	v_or3_b32 v129, v129, v131, v132
	v_rcp_f32_e32 v131, v124
	v_mul_f32_e32 v120, 0xbfb8aa3b, v120
	v_pk_mul_f32 v[124:125], v[126:127], v[144:145] op_sel_hi:[1,0]
	v_add_f32_e32 v126, 1.0, v130
	v_exp_f32_e32 v130, v120
	v_add_f32_e32 v120, 1.0, v121
	v_fma_f32 v127, v131, s4, 0.5
	v_rcp_f32_e32 v131, v120
	v_pk_mul_f32 v[120:121], v[122:123], v[144:145] op_sel_hi:[1,0]
	v_add_f32_e32 v122, 1.0, v130
	v_mul_f32_e32 v120, 0xbfb8aa3b, v120
	v_mul_f32_e32 v121, 0xbfb8aa3b, v121
	v_exp_f32_e32 v120, v120
	v_exp_f32_e32 v121, v121
	v_rcp_f32_e32 v122, v122
	v_fma_f32 v123, v131, s4, 0.5
	v_add_f32_e32 v120, 1.0, v120
	v_add_f32_e32 v121, 1.0, v121
	v_rcp_f32_e32 v120, v120
	v_rcp_f32_e32 v121, v121
	v_fma_f32 v122, v122, s4, 0.5
	v_max_f32_e32 v123, 1.0, v123
	v_max_f32_e32 v122, 1.0, v122
	v_fma_f32 v120, v120, s4, 0.5
	v_fma_f32 v121, v121, s4, 0.5
	v_cvt_u32_f32_e32 v123, v123
	v_cvt_u32_f32_e32 v122, v122
	v_max_f32_e32 v120, 1.0, v120
	v_max_f32_e32 v121, 1.0, v121
	v_cvt_u32_f32_sdwa v120, v120 dst_sel:WORD_1 dst_unused:UNUSED_PAD src0_sel:DWORD
	v_cvt_u32_f32_sdwa v121, v121 dst_sel:BYTE_3 dst_unused:UNUSED_PAD src0_sel:DWORD
	v_lshl_or_b32 v122, v123, 8, v122
	v_mul_f32_e32 v124, 0xbfb8aa3b, v124
	v_mul_f32_e32 v125, 0xbfb8aa3b, v125
	v_or3_b32 v131, v122, v120, v121
	v_mul_f32_e32 v122, 0x3c800000, v145
	v_pk_mul_f32 v[112:113], v[112:113], v[122:123] op_sel_hi:[1,0]
	v_pk_mul_f32 v[114:115], v[114:115], v[122:123] op_sel_hi:[1,0]
	v_mul_f32_e32 v112, 0xbfb8aa3b, v112
	v_mul_f32_e32 v113, 0xbfb8aa3b, v113
	v_mul_f32_e32 v115, 0xbfb8aa3b, v115
	v_exp_f32_e32 v112, v112
	v_exp_f32_e32 v113, v113
	v_mul_f32_e32 v114, 0xbfb8aa3b, v114
	v_exp_f32_e32 v115, v115
	v_exp_f32_e32 v114, v114
	v_add_f32_e32 v112, 1.0, v112
	v_add_f32_e32 v113, 1.0, v113
	v_pk_mul_f32 v[116:117], v[116:117], v[122:123] op_sel_hi:[1,0]
	v_add_f32_e32 v115, 1.0, v115
	v_rcp_f32_e32 v112, v112
	v_rcp_f32_e32 v113, v113
	v_add_f32_e32 v114, 1.0, v114
	v_pk_mul_f32 v[118:119], v[118:119], v[122:123] op_sel_hi:[1,0]
	v_mul_f32_e32 v116, 0xbfb8aa3b, v116
	v_mul_f32_e32 v117, 0xbfb8aa3b, v117
	v_rcp_f32_e32 v115, v115
	v_rcp_f32_e32 v114, v114
	v_mul_f32_e32 v119, 0xbfb8aa3b, v119
	v_exp_f32_e32 v116, v116
	v_exp_f32_e32 v117, v117
	v_mul_f32_e32 v118, 0xbfb8aa3b, v118
; __device__ __forceinline__ float sigmoidf_(float v) { return __builtin_amdgcn_rcpf(1.0f + __expf(-v)); }
; #define MEMFENCE asm volatile("" ::: "memory")
;     template <int KIND> __device__ __forceinline__ void run(f32x4 (&acc)[2][2][4][2], const Unit& u, int tid_in) const {
;     ...
;                 for (int m = 0; m < 4; ++m) { const float r = rs[ai * 4 + m] * (1.0f / GATE_WSCALE); u32x4 w;
; #pragma unroll
;                     for (int bj = 0; bj < 2; ++bj) { f32x4 a = acc[ai][bj][m][0] * r, b = acc[ai][bj][m][1] * r;
; #pragma unroll
;                         for (int j = 0; j < 4; ++j) { a[j] = sigmoidf_(a[j]); b[j] = sigmoidf_(b[j]); }
;                         if (bj == 0) { w.x = pack4_u8c(a); w.y = pack4_u8c(b); } else { w.z = pack4_u8c(a); w.w = pack4_u8c(b); } }
;                     gst[(ai * 4 + m) * 512 + tid] = w; MEMFENCE; }
	v_exp_f32_e32 v119, v119
	v_exp_f32_e32 v118, v118
	v_fma_f32 v112, v112, s4, 0.5
	v_fma_f32 v113, v113, s4, 0.5
	v_max_f32_e32 v112, 1.0, v112
	v_max_f32_e32 v113, 1.0, v113
	v_fma_f32 v114, v114, s4, 0.5
	v_fma_f32 v115, v115, s4, 0.5
	v_add_f32_e32 v116, 1.0, v116
	v_add_f32_e32 v117, 1.0, v117
	v_cvt_u32_f32_e32 v112, v112
	v_cvt_u32_f32_e32 v113, v113
	v_max_f32_e32 v114, 1.0, v114
	v_max_f32_e32 v115, 1.0, v115
	v_add_f32_e32 v119, 1.0, v119
	v_rcp_f32_e32 v116, v116
	v_rcp_f32_e32 v117, v117
	v_cvt_u32_f32_sdwa v114, v114 dst_sel:WORD_1 dst_unused:UNUSED_PAD src0_sel:DWORD
	v_cvt_u32_f32_sdwa v115, v115 dst_sel:BYTE_3 dst_unused:UNUSED_PAD src0_sel:DWORD
	v_add_f32_e32 v118, 1.0, v118
	v_rcp_f32_e32 v119, v119
	v_rcp_f32_e32 v118, v118
	v_lshl_or_b32 v112, v113, 8, v112
	v_or3_b32 v112, v112, v114, v115
	v_fma_f32 v113, v116, s4, 0.5
	v_fma_f32 v114, v117, s4, 0.5
	v_pk_mul_f32 v[108:109], v[108:109], v[122:123] op_sel_hi:[1,0]
	v_max_f32_e32 v113, 1.0, v113
	v_max_f32_e32 v114, 1.0, v114
	v_fma_f32 v115, v118, s4, 0.5
	v_fma_f32 v116, v119, s4, 0.5
	v_mul_f32_e32 v109, 0xbfb8aa3b, v109
	v_cvt_u32_f32_e32 v113, v113
	v_cvt_u32_f32_e32 v114, v114
	v_max_f32_e32 v115, 1.0, v115
	v_max_f32_e32 v116, 1.0, v116
	v_exp_f32_e32 v109, v109
	v_cvt_u32_f32_sdwa v115, v115 dst_sel:WORD_1 dst_unused:UNUSED_PAD src0_sel:DWORD
	v_cvt_u32_f32_sdwa v116, v116 dst_sel:BYTE_3 dst_unused:UNUSED_PAD src0_sel:DWORD
	v_pk_mul_f32 v[104:105], v[104:105], v[122:123] op_sel_hi:[1,0]
	v_mul_f32_e32 v108, 0xbfb8aa3b, v108
	v_mul_f32_e32 v105, 0xbfb8aa3b, v105
	v_lshl_or_b32 v113, v114, 8, v113
	v_exp_f32_e32 v114, v108
	v_add_f32_e32 v108, 1.0, v109
	v_exp_f32_e32 v105, v105
	v_or3_b32 v113, v113, v115, v116
	v_rcp_f32_e32 v115, v108
	v_mul_f32_e32 v104, 0xbfb8aa3b, v104
	v_pk_mul_f32 v[108:109], v[110:111], v[122:123] op_sel_hi:[1,0]
	v_add_f32_e32 v110, 1.0, v114
	v_exp_f32_e32 v114, v104
	v_add_f32_e32 v104, 1.0, v105
	v_fma_f32 v111, v115, s4, 0.5
	v_rcp_f32_e32 v115, v104
	v_pk_mul_f32 v[104:105], v[106:107], v[122:123] op_sel_hi:[1,0]
	v_add_f32_e32 v106, 1.0, v114
	v_mul_f32_e32 v104, 0xbfb8aa3b, v104
	v_mul_f32_e32 v105, 0xbfb8aa3b, v105
	v_exp_f32_e32 v104, v104
	v_exp_f32_e32 v105, v105
	v_rcp_f32_e32 v106, v106
	v_fma_f32 v107, v115, s4, 0.5
	v_add_f32_e32 v104, 1.0, v104
	v_add_f32_e32 v105, 1.0, v105
	v_rcp_f32_e32 v104, v104
	v_rcp_f32_e32 v105, v105
	v_fma_f32 v106, v106, s4, 0.5
	v_max_f32_e32 v107, 1.0, v107
	v_max_f32_e32 v106, 1.0, v106
	v_fma_f32 v104, v104, s4, 0.5
	v_fma_f32 v105, v105, s4, 0.5
	v_cvt_u32_f32_e32 v107, v107
	v_cvt_u32_f32_e32 v106, v106
	v_max_f32_e32 v104, 1.0, v104
	v_max_f32_e32 v105, 1.0, v105
	v_cvt_u32_f32_sdwa v104, v104 dst_sel:WORD_1 dst_unused:UNUSED_PAD src0_sel:DWORD
	v_cvt_u32_f32_sdwa v105, v105 dst_sel:BYTE_3 dst_unused:UNUSED_PAD src0_sel:DWORD
	v_lshl_or_b32 v106, v107, 8, v106
	v_exp_f32_e32 v124, v124
	v_exp_f32_e32 v125, v125
	v_or3_b32 v115, v106, v104, v105
	v_mul_f32_e32 v106, 0x3c800000, v140
	v_pk_mul_f32 v[96:97], v[96:97], v[106:107] op_sel_hi:[1,0]
	v_pk_mul_f32 v[98:99], v[98:99], v[106:107] op_sel_hi:[1,0]
	v_mul_f32_e32 v96, 0xbfb8aa3b, v96
	v_mul_f32_e32 v97, 0xbfb8aa3b, v97
	v_mul_f32_e32 v99, 0xbfb8aa3b, v99
	v_exp_f32_e32 v96, v96
	v_exp_f32_e32 v97, v97
	v_mul_f32_e32 v98, 0xbfb8aa3b, v98
	v_exp_f32_e32 v99, v99
	v_exp_f32_e32 v98, v98
	v_add_f32_e32 v96, 1.0, v96
	v_add_f32_e32 v97, 1.0, v97
	v_pk_mul_f32 v[100:101], v[100:101], v[106:107] op_sel_hi:[1,0]
	v_add_f32_e32 v99, 1.0, v99
	v_rcp_f32_e32 v96, v96
	v_rcp_f32_e32 v97, v97
	v_add_f32_e32 v98, 1.0, v98
	v_pk_mul_f32 v[102:103], v[102:103], v[106:107] op_sel_hi:[1,0]
	v_mul_f32_e32 v100, 0xbfb8aa3b, v100
	v_mul_f32_e32 v101, 0xbfb8aa3b, v101
	v_rcp_f32_e32 v99, v99
	v_rcp_f32_e32 v98, v98
	v_mul_f32_e32 v103, 0xbfb8aa3b, v103
	v_exp_f32_e32 v100, v100
	v_exp_f32_e32 v101, v101
	v_mul_f32_e32 v102, 0xbfb8aa3b, v102
	v_exp_f32_e32 v103, v103
	v_exp_f32_e32 v102, v102
	v_fma_f32 v96, v96, s4, 0.5
	v_fma_f32 v97, v97, s4, 0.5
	v_max_f32_e32 v96, 1.0, v96
	v_max_f32_e32 v97, 1.0, v97
	v_fma_f32 v98, v98, s4, 0.5
	v_fma_f32 v99, v99, s4, 0.5
	v_add_f32_e32 v100, 1.0, v100
	v_add_f32_e32 v101, 1.0, v101
	v_cvt_u32_f32_e32 v96, v96
	v_cvt_u32_f32_e32 v97, v97
	v_max_f32_e32 v98, 1.0, v98
	v_max_f32_e32 v99, 1.0, v99
	v_add_f32_e32 v103, 1.0, v103
	v_rcp_f32_e32 v100, v100
	v_rcp_f32_e32 v101, v101
	v_cvt_u32_f32_sdwa v98, v98 dst_sel:WORD_1 dst_unused:UNUSED_PAD src0_sel:DWORD
	v_cvt_u32_f32_sdwa v99, v99 dst_sel:BYTE_3 dst_unused:UNUSED_PAD src0_sel:DWORD
	v_add_f32_e32 v102, 1.0, v102
	v_rcp_f32_e32 v103, v103
	v_rcp_f32_e32 v102, v102
	v_lshl_or_b32 v96, v97, 8, v96
	v_or3_b32 v96, v96, v98, v99
	v_fma_f32 v97, v100, s4, 0.5
	v_fma_f32 v98, v101, s4, 0.5
	v_pk_mul_f32 v[92:93], v[92:93], v[106:107] op_sel_hi:[1,0]
	v_max_f32_e32 v97, 1.0, v97
	v_max_f32_e32 v98, 1.0, v98
	v_fma_f32 v99, v102, s4, 0.5
	v_fma_f32 v100, v103, s4, 0.5
	v_mul_f32_e32 v93, 0xbfb8aa3b, v93
	v_cvt_u32_f32_e32 v97, v97
	v_cvt_u32_f32_e32 v98, v98
	v_max_f32_e32 v99, 1.0, v99
	v_max_f32_e32 v100, 1.0, v100
	v_exp_f32_e32 v93, v93
	v_cvt_u32_f32_sdwa v99, v99 dst_sel:WORD_1 dst_unused:UNUSED_PAD src0_sel:DWORD
	v_cvt_u32_f32_sdwa v100, v100 dst_sel:BYTE_3 dst_unused:UNUSED_PAD src0_sel:DWORD
	v_pk_mul_f32 v[88:89], v[88:89], v[106:107] op_sel_hi:[1,0]
	v_mul_f32_e32 v92, 0xbfb8aa3b, v92
	v_mul_f32_e32 v89, 0xbfb8aa3b, v89
	v_lshl_or_b32 v97, v98, 8, v97
	v_exp_f32_e32 v98, v92
	v_add_f32_e32 v92, 1.0, v93
	v_exp_f32_e32 v89, v89
	v_or3_b32 v97, v97, v99, v100
	v_rcp_f32_e32 v99, v92
	v_mul_f32_e32 v88, 0xbfb8aa3b, v88
	v_pk_mul_f32 v[92:93], v[94:95], v[106:107] op_sel_hi:[1,0]
; __device__ __forceinline__ float sigmoidf_(float v) { return __builtin_amdgcn_rcpf(1.0f + __expf(-v)); }
; #define MEMFENCE asm volatile("" ::: "memory")
;     template <int KIND> __device__ __forceinline__ void run(f32x4 (&acc)[2][2][4][2], const Unit& u, int tid_in) const {
;     ...
;                 for (int m = 0; m < 4; ++m) { const float r = rs[ai * 4 + m] * (1.0f / GATE_WSCALE); u32x4 w;
; #pragma unroll
;                     for (int bj = 0; bj < 2; ++bj) { f32x4 a = acc[ai][bj][m][0] * r, b = acc[ai][bj][m][1] * r;
; #pragma unroll
;                         for (int j = 0; j < 4; ++j) { a[j] = sigmoidf_(a[j]); b[j] = sigmoidf_(b[j]); }
;                         if (bj == 0) { w.x = pack4_u8c(a); w.y = pack4_u8c(b); } else { w.z = pack4_u8c(a); w.w = pack4_u8c(b); } }
;                     gst[(ai * 4 + m) * 512 + tid] = w; MEMFENCE; }
	v_add_f32_e32 v94, 1.0, v98
	v_exp_f32_e32 v98, v88
	v_add_f32_e32 v88, 1.0, v89
	v_fma_f32 v95, v99, s4, 0.5
	v_rcp_f32_e32 v99, v88
	v_pk_mul_f32 v[88:89], v[90:91], v[106:107] op_sel_hi:[1,0]
	v_add_f32_e32 v90, 1.0, v98
	v_mul_f32_e32 v88, 0xbfb8aa3b, v88
	v_mul_f32_e32 v89, 0xbfb8aa3b, v89
	v_exp_f32_e32 v88, v88
	v_exp_f32_e32 v89, v89
	v_rcp_f32_e32 v90, v90
	v_fma_f32 v91, v99, s4, 0.5
	v_add_f32_e32 v88, 1.0, v88
	v_add_f32_e32 v89, 1.0, v89
	v_rcp_f32_e32 v88, v88
	v_rcp_f32_e32 v89, v89
	v_fma_f32 v90, v90, s4, 0.5
	v_max_f32_e32 v91, 1.0, v91
	v_max_f32_e32 v90, 1.0, v90
	v_fma_f32 v88, v88, s4, 0.5
	v_fma_f32 v89, v89, s4, 0.5
	v_cvt_u32_f32_e32 v91, v91
	v_cvt_u32_f32_e32 v90, v90
	v_max_f32_e32 v88, 1.0, v88
	v_max_f32_e32 v89, 1.0, v89
	v_cvt_u32_f32_sdwa v88, v88 dst_sel:WORD_1 dst_unused:UNUSED_PAD src0_sel:DWORD
	v_cvt_u32_f32_sdwa v89, v89 dst_sel:BYTE_3 dst_unused:UNUSED_PAD src0_sel:DWORD
	v_lshl_or_b32 v90, v91, 8, v90
	v_mul_f32_e32 v108, 0xbfb8aa3b, v108
	v_mul_f32_e32 v109, 0xbfb8aa3b, v109
	v_or3_b32 v99, v90, v88, v89
	v_mul_f32_e32 v90, 0x3c800000, v141
	v_pk_mul_f32 v[80:81], v[80:81], v[90:91] op_sel_hi:[1,0]
	v_pk_mul_f32 v[82:83], v[82:83], v[90:91] op_sel_hi:[1,0]
	v_mul_f32_e32 v80, 0xbfb8aa3b, v80
	v_mul_f32_e32 v81, 0xbfb8aa3b, v81
	v_mul_f32_e32 v83, 0xbfb8aa3b, v83
	v_exp_f32_e32 v80, v80
	v_exp_f32_e32 v81, v81
	v_mul_f32_e32 v82, 0xbfb8aa3b, v82
	v_exp_f32_e32 v83, v83
	v_exp_f32_e32 v82, v82
	v_add_f32_e32 v80, 1.0, v80
	v_add_f32_e32 v81, 1.0, v81
	v_pk_mul_f32 v[84:85], v[84:85], v[90:91] op_sel_hi:[1,0]
	v_add_f32_e32 v83, 1.0, v83
	v_rcp_f32_e32 v80, v80
	v_rcp_f32_e32 v81, v81
	v_add_f32_e32 v82, 1.0, v82
	v_pk_mul_f32 v[86:87], v[86:87], v[90:91] op_sel_hi:[1,0]
	v_mul_f32_e32 v84, 0xbfb8aa3b, v84
	v_mul_f32_e32 v85, 0xbfb8aa3b, v85
	v_rcp_f32_e32 v83, v83
	v_rcp_f32_e32 v82, v82
	v_mul_f32_e32 v87, 0xbfb8aa3b, v87
	v_exp_f32_e32 v84, v84
	v_exp_f32_e32 v85, v85
	v_mul_f32_e32 v86, 0xbfb8aa3b, v86
	v_exp_f32_e32 v87, v87
	v_exp_f32_e32 v86, v86
	v_fma_f32 v80, v80, s4, 0.5
	v_fma_f32 v81, v81, s4, 0.5
	v_max_f32_e32 v80, 1.0, v80
	v_max_f32_e32 v81, 1.0, v81
	v_fma_f32 v82, v82, s4, 0.5
	v_fma_f32 v83, v83, s4, 0.5
	v_add_f32_e32 v84, 1.0, v84
	v_add_f32_e32 v85, 1.0, v85
	v_cvt_u32_f32_e32 v80, v80
	v_cvt_u32_f32_e32 v81, v81
	v_max_f32_e32 v82, 1.0, v82
	v_max_f32_e32 v83, 1.0, v83
	v_add_f32_e32 v87, 1.0, v87
	v_rcp_f32_e32 v84, v84
	v_rcp_f32_e32 v85, v85
	v_cvt_u32_f32_sdwa v82, v82 dst_sel:WORD_1 dst_unused:UNUSED_PAD src0_sel:DWORD
	v_cvt_u32_f32_sdwa v83, v83 dst_sel:BYTE_3 dst_unused:UNUSED_PAD src0_sel:DWORD
	v_add_f32_e32 v86, 1.0, v86
	v_rcp_f32_e32 v87, v87
	v_rcp_f32_e32 v86, v86
	v_lshl_or_b32 v80, v81, 8, v80
	v_or3_b32 v80, v80, v82, v83
	v_fma_f32 v81, v84, s4, 0.5
	v_fma_f32 v82, v85, s4, 0.5
	v_pk_mul_f32 v[76:77], v[76:77], v[90:91] op_sel_hi:[1,0]
	v_max_f32_e32 v81, 1.0, v81
	v_max_f32_e32 v82, 1.0, v82
	v_fma_f32 v83, v86, s4, 0.5
	v_fma_f32 v84, v87, s4, 0.5
	v_mul_f32_e32 v77, 0xbfb8aa3b, v77
	v_cvt_u32_f32_e32 v81, v81
	v_cvt_u32_f32_e32 v82, v82
	v_max_f32_e32 v83, 1.0, v83
	v_max_f32_e32 v84, 1.0, v84
	v_exp_f32_e32 v77, v77
	v_cvt_u32_f32_sdwa v83, v83 dst_sel:WORD_1 dst_unused:UNUSED_PAD src0_sel:DWORD
	v_cvt_u32_f32_sdwa v84, v84 dst_sel:BYTE_3 dst_unused:UNUSED_PAD src0_sel:DWORD
	v_pk_mul_f32 v[72:73], v[72:73], v[90:91] op_sel_hi:[1,0]
	v_mul_f32_e32 v76, 0xbfb8aa3b, v76
	v_mul_f32_e32 v73, 0xbfb8aa3b, v73
	v_lshl_or_b32 v81, v82, 8, v81
	v_exp_f32_e32 v82, v76
	v_add_f32_e32 v76, 1.0, v77
	v_exp_f32_e32 v73, v73
	v_or3_b32 v81, v81, v83, v84
	v_rcp_f32_e32 v83, v76
	v_mul_f32_e32 v72, 0xbfb8aa3b, v72
	v_pk_mul_f32 v[76:77], v[78:79], v[90:91] op_sel_hi:[1,0]
	v_add_f32_e32 v78, 1.0, v82
	v_exp_f32_e32 v82, v72
	v_add_f32_e32 v72, 1.0, v73
	v_fma_f32 v79, v83, s4, 0.5
	v_rcp_f32_e32 v83, v72
	v_pk_mul_f32 v[72:73], v[74:75], v[90:91] op_sel_hi:[1,0]
	v_add_f32_e32 v74, 1.0, v82
	v_mul_f32_e32 v72, 0xbfb8aa3b, v72
	v_mul_f32_e32 v73, 0xbfb8aa3b, v73
	v_exp_f32_e32 v72, v72
	v_exp_f32_e32 v73, v73
	v_rcp_f32_e32 v74, v74
	v_fma_f32 v75, v83, s4, 0.5
	v_add_f32_e32 v72, 1.0, v72
	v_add_f32_e32 v73, 1.0, v73
	v_rcp_f32_e32 v72, v72
	v_rcp_f32_e32 v73, v73
	v_fma_f32 v74, v74, s4, 0.5
	v_max_f32_e32 v75, 1.0, v75
	v_max_f32_e32 v74, 1.0, v74
	v_fma_f32 v72, v72, s4, 0.5
	v_fma_f32 v73, v73, s4, 0.5
	v_cvt_u32_f32_e32 v75, v75
	v_cvt_u32_f32_e32 v74, v74
	v_max_f32_e32 v72, 1.0, v72
	v_max_f32_e32 v73, 1.0, v73
	v_cvt_u32_f32_sdwa v72, v72 dst_sel:WORD_1 dst_unused:UNUSED_PAD src0_sel:DWORD
	v_cvt_u32_f32_sdwa v73, v73 dst_sel:BYTE_3 dst_unused:UNUSED_PAD src0_sel:DWORD
	v_lshl_or_b32 v74, v75, 8, v74
	v_exp_f32_e32 v108, v108
	v_exp_f32_e32 v109, v109
	v_or3_b32 v83, v74, v72, v73
	v_mul_f32_e32 v74, 0x3c800000, v138
	v_pk_mul_f32 v[64:65], v[64:65], v[74:75] op_sel_hi:[1,0]
	v_pk_mul_f32 v[66:67], v[66:67], v[74:75] op_sel_hi:[1,0]
	v_mul_f32_e32 v64, 0xbfb8aa3b, v64
	v_mul_f32_e32 v65, 0xbfb8aa3b, v65
	v_mul_f32_e32 v67, 0xbfb8aa3b, v67
	v_exp_f32_e32 v64, v64
	v_exp_f32_e32 v65, v65
	v_mul_f32_e32 v66, 0xbfb8aa3b, v66
	v_exp_f32_e32 v67, v67
	v_exp_f32_e32 v66, v66
	v_add_f32_e32 v64, 1.0, v64
	v_add_f32_e32 v65, 1.0, v65
	v_pk_mul_f32 v[68:69], v[68:69], v[74:75] op_sel_hi:[1,0]
	v_add_f32_e32 v67, 1.0, v67
	v_rcp_f32_e32 v64, v64
	v_rcp_f32_e32 v65, v65
	v_add_f32_e32 v66, 1.0, v66
	v_pk_mul_f32 v[70:71], v[70:71], v[74:75] op_sel_hi:[1,0]
	v_mul_f32_e32 v68, 0xbfb8aa3b, v68
	v_mul_f32_e32 v69, 0xbfb8aa3b, v69
	v_rcp_f32_e32 v67, v67
	v_rcp_f32_e32 v66, v66
	v_mul_f32_e32 v71, 0xbfb8aa3b, v71
	v_exp_f32_e32 v68, v68
	v_exp_f32_e32 v69, v69
; __device__ __forceinline__ float sigmoidf_(float v) { return __builtin_amdgcn_rcpf(1.0f + __expf(-v)); }
; #define MEMFENCE asm volatile("" ::: "memory")
;     template <int KIND> __device__ __forceinline__ void run(f32x4 (&acc)[2][2][4][2], const Unit& u, int tid_in) const {
;     ...
;                 for (int m = 0; m < 4; ++m) { const float r = rs[ai * 4 + m] * (1.0f / GATE_WSCALE); u32x4 w;
; #pragma unroll
;                     for (int bj = 0; bj < 2; ++bj) { f32x4 a = acc[ai][bj][m][0] * r, b = acc[ai][bj][m][1] * r;
; #pragma unroll
;                         for (int j = 0; j < 4; ++j) { a[j] = sigmoidf_(a[j]); b[j] = sigmoidf_(b[j]); }
;                         if (bj == 0) { w.x = pack4_u8c(a); w.y = pack4_u8c(b); } else { w.z = pack4_u8c(a); w.w = pack4_u8c(b); } }
;                     gst[(ai * 4 + m) * 512 + tid] = w; MEMFENCE; }
	v_mul_f32_e32 v70, 0xbfb8aa3b, v70
	v_exp_f32_e32 v71, v71
	v_exp_f32_e32 v70, v70
	v_fma_f32 v64, v64, s4, 0.5
	v_fma_f32 v65, v65, s4, 0.5
	v_max_f32_e32 v64, 1.0, v64
	v_max_f32_e32 v65, 1.0, v65
	v_fma_f32 v66, v66, s4, 0.5
	v_fma_f32 v67, v67, s4, 0.5
	v_add_f32_e32 v68, 1.0, v68
	v_add_f32_e32 v69, 1.0, v69
	v_cvt_u32_f32_e32 v64, v64
	v_cvt_u32_f32_e32 v65, v65
	v_max_f32_e32 v66, 1.0, v66
	v_max_f32_e32 v67, 1.0, v67
	v_add_f32_e32 v71, 1.0, v71
	v_rcp_f32_e32 v68, v68
	v_rcp_f32_e32 v69, v69
	v_cvt_u32_f32_sdwa v66, v66 dst_sel:WORD_1 dst_unused:UNUSED_PAD src0_sel:DWORD
	v_cvt_u32_f32_sdwa v67, v67 dst_sel:BYTE_3 dst_unused:UNUSED_PAD src0_sel:DWORD
	v_add_f32_e32 v70, 1.0, v70
	v_rcp_f32_e32 v71, v71
	v_rcp_f32_e32 v70, v70
	v_lshl_or_b32 v64, v65, 8, v64
	v_or3_b32 v64, v64, v66, v67
	v_fma_f32 v65, v68, s4, 0.5
	v_fma_f32 v66, v69, s4, 0.5
	v_pk_mul_f32 v[60:61], v[60:61], v[74:75] op_sel_hi:[1,0]
	v_max_f32_e32 v65, 1.0, v65
	v_max_f32_e32 v66, 1.0, v66
	v_fma_f32 v67, v70, s4, 0.5
	v_fma_f32 v68, v71, s4, 0.5
	v_mul_f32_e32 v61, 0xbfb8aa3b, v61
	v_cvt_u32_f32_e32 v65, v65
	v_cvt_u32_f32_e32 v66, v66
	v_max_f32_e32 v67, 1.0, v67
	v_max_f32_e32 v68, 1.0, v68
	v_exp_f32_e32 v61, v61
	v_cvt_u32_f32_sdwa v67, v67 dst_sel:WORD_1 dst_unused:UNUSED_PAD src0_sel:DWORD
	v_cvt_u32_f32_sdwa v68, v68 dst_sel:BYTE_3 dst_unused:UNUSED_PAD src0_sel:DWORD
	v_pk_mul_f32 v[56:57], v[56:57], v[74:75] op_sel_hi:[1,0]
	v_mul_f32_e32 v60, 0xbfb8aa3b, v60
	v_mul_f32_e32 v57, 0xbfb8aa3b, v57
	v_lshl_or_b32 v65, v66, 8, v65
	v_exp_f32_e32 v66, v60
	v_add_f32_e32 v60, 1.0, v61
	v_exp_f32_e32 v57, v57
	v_or3_b32 v65, v65, v67, v68
	v_rcp_f32_e32 v67, v60
	v_mul_f32_e32 v56, 0xbfb8aa3b, v56
	v_pk_mul_f32 v[60:61], v[62:63], v[74:75] op_sel_hi:[1,0]
	v_add_f32_e32 v62, 1.0, v66
	v_exp_f32_e32 v66, v56
	v_add_f32_e32 v56, 1.0, v57
	v_fma_f32 v63, v67, s4, 0.5
	v_rcp_f32_e32 v67, v56
	v_pk_mul_f32 v[56:57], v[58:59], v[74:75] op_sel_hi:[1,0]
	v_add_f32_e32 v58, 1.0, v66
	v_mul_f32_e32 v56, 0xbfb8aa3b, v56
	v_mul_f32_e32 v57, 0xbfb8aa3b, v57
	v_exp_f32_e32 v56, v56
	v_exp_f32_e32 v57, v57
	v_rcp_f32_e32 v58, v58
	v_fma_f32 v59, v67, s4, 0.5
	v_add_f32_e32 v56, 1.0, v56
	v_add_f32_e32 v57, 1.0, v57
	v_rcp_f32_e32 v56, v56
	v_rcp_f32_e32 v57, v57
	v_fma_f32 v58, v58, s4, 0.5
	v_max_f32_e32 v59, 1.0, v59
	v_max_f32_e32 v58, 1.0, v58
	v_fma_f32 v56, v56, s4, 0.5
	v_fma_f32 v57, v57, s4, 0.5
	v_cvt_u32_f32_e32 v59, v59
	v_cvt_u32_f32_e32 v58, v58
	v_max_f32_e32 v56, 1.0, v56
	v_max_f32_e32 v57, 1.0, v57
	v_cvt_u32_f32_sdwa v56, v56 dst_sel:WORD_1 dst_unused:UNUSED_PAD src0_sel:DWORD
	v_cvt_u32_f32_sdwa v57, v57 dst_sel:BYTE_3 dst_unused:UNUSED_PAD src0_sel:DWORD
	v_lshl_or_b32 v58, v59, 8, v58
	v_mul_f32_e32 v92, 0xbfb8aa3b, v92
	v_mul_f32_e32 v93, 0xbfb8aa3b, v93
	v_or3_b32 v67, v58, v56, v57
	v_mul_f32_e32 v58, 0x3c800000, v139
	v_pk_mul_f32 v[48:49], v[48:49], v[58:59] op_sel_hi:[1,0]
	v_pk_mul_f32 v[50:51], v[50:51], v[58:59] op_sel_hi:[1,0]
	v_mul_f32_e32 v48, 0xbfb8aa3b, v48
	v_mul_f32_e32 v49, 0xbfb8aa3b, v49
	v_mul_f32_e32 v51, 0xbfb8aa3b, v51
	v_exp_f32_e32 v48, v48
	v_exp_f32_e32 v49, v49
	v_mul_f32_e32 v50, 0xbfb8aa3b, v50
	v_exp_f32_e32 v51, v51
	v_exp_f32_e32 v50, v50
	v_add_f32_e32 v48, 1.0, v48
	v_add_f32_e32 v49, 1.0, v49
	v_pk_mul_f32 v[52:53], v[52:53], v[58:59] op_sel_hi:[1,0]
	v_add_f32_e32 v51, 1.0, v51
	v_rcp_f32_e32 v48, v48
	v_rcp_f32_e32 v49, v49
	v_add_f32_e32 v50, 1.0, v50
	v_pk_mul_f32 v[54:55], v[54:55], v[58:59] op_sel_hi:[1,0]
	v_mul_f32_e32 v52, 0xbfb8aa3b, v52
	v_mul_f32_e32 v53, 0xbfb8aa3b, v53
	v_rcp_f32_e32 v51, v51
	v_rcp_f32_e32 v50, v50
	v_mul_f32_e32 v55, 0xbfb8aa3b, v55
	v_exp_f32_e32 v52, v52
	v_exp_f32_e32 v53, v53
	v_mul_f32_e32 v54, 0xbfb8aa3b, v54
	v_exp_f32_e32 v55, v55
	v_exp_f32_e32 v54, v54
	v_fma_f32 v48, v48, s4, 0.5
	v_fma_f32 v49, v49, s4, 0.5
	v_max_f32_e32 v48, 1.0, v48
	v_max_f32_e32 v49, 1.0, v49
	v_fma_f32 v50, v50, s4, 0.5
	v_fma_f32 v51, v51, s4, 0.5
	v_add_f32_e32 v52, 1.0, v52
	v_add_f32_e32 v53, 1.0, v53
	v_cvt_u32_f32_e32 v48, v48
	v_cvt_u32_f32_e32 v49, v49
	v_max_f32_e32 v50, 1.0, v50
	v_max_f32_e32 v51, 1.0, v51
	v_add_f32_e32 v55, 1.0, v55
	v_rcp_f32_e32 v52, v52
	v_rcp_f32_e32 v53, v53
	v_cvt_u32_f32_sdwa v50, v50 dst_sel:WORD_1 dst_unused:UNUSED_PAD src0_sel:DWORD
	v_cvt_u32_f32_sdwa v51, v51 dst_sel:BYTE_3 dst_unused:UNUSED_PAD src0_sel:DWORD
	v_add_f32_e32 v54, 1.0, v54
	v_rcp_f32_e32 v55, v55
	v_rcp_f32_e32 v54, v54
	v_lshl_or_b32 v48, v49, 8, v48
	v_or3_b32 v48, v48, v50, v51
	v_fma_f32 v49, v52, s4, 0.5
	v_fma_f32 v50, v53, s4, 0.5
	v_pk_mul_f32 v[44:45], v[44:45], v[58:59] op_sel_hi:[1,0]
	v_max_f32_e32 v49, 1.0, v49
	v_max_f32_e32 v50, 1.0, v50
	v_fma_f32 v51, v54, s4, 0.5
	v_fma_f32 v52, v55, s4, 0.5
	v_mul_f32_e32 v45, 0xbfb8aa3b, v45
	v_cvt_u32_f32_e32 v49, v49
	v_cvt_u32_f32_e32 v50, v50
	v_max_f32_e32 v51, 1.0, v51
	v_max_f32_e32 v52, 1.0, v52
	v_exp_f32_e32 v45, v45
	v_cvt_u32_f32_sdwa v51, v51 dst_sel:WORD_1 dst_unused:UNUSED_PAD src0_sel:DWORD
	v_cvt_u32_f32_sdwa v52, v52 dst_sel:BYTE_3 dst_unused:UNUSED_PAD src0_sel:DWORD
	v_pk_mul_f32 v[40:41], v[40:41], v[58:59] op_sel_hi:[1,0]
	v_mul_f32_e32 v44, 0xbfb8aa3b, v44
	v_mul_f32_e32 v41, 0xbfb8aa3b, v41
	v_lshl_or_b32 v49, v50, 8, v49
	v_exp_f32_e32 v50, v44
	v_add_f32_e32 v44, 1.0, v45
	v_exp_f32_e32 v41, v41
	v_or3_b32 v49, v49, v51, v52
	v_rcp_f32_e32 v51, v44
	v_mul_f32_e32 v40, 0xbfb8aa3b, v40
	v_pk_mul_f32 v[44:45], v[46:47], v[58:59] op_sel_hi:[1,0]
	v_add_f32_e32 v46, 1.0, v50
	v_exp_f32_e32 v50, v40
	v_add_f32_e32 v40, 1.0, v41
	v_fma_f32 v47, v51, s4, 0.5
	v_rcp_f32_e32 v51, v40
	v_pk_mul_f32 v[40:41], v[42:43], v[58:59] op_sel_hi:[1,0]
; __device__ __forceinline__ float sigmoidf_(float v) { return __builtin_amdgcn_rcpf(1.0f + __expf(-v)); }
; #define MEMFENCE asm volatile("" ::: "memory")
;     template <int KIND> __device__ __forceinline__ void run(f32x4 (&acc)[2][2][4][2], const Unit& u, int tid_in) const {
;     ...
;             u32x4* gst = (u32x4*)((unsigned char*)x + 32 * MiB) + ((size_t)(blockIdx.x * 2 + (u.ord & 1)) * 3 + u.aux) * 4096;
; #pragma unroll
;             for (int ai = 0; ai < 2; ++ai)
; #pragma unroll
;                 for (int m = 0; m < 4; ++m) { const float r = rs[ai * 4 + m] * (1.0f / GATE_WSCALE); u32x4 w;
; #pragma unroll
;                     for (int bj = 0; bj < 2; ++bj) { f32x4 a = acc[ai][bj][m][0] * r, b = acc[ai][bj][m][1] * r;
; #pragma unroll
;                         for (int j = 0; j < 4; ++j) { a[j] = sigmoidf_(a[j]); b[j] = sigmoidf_(b[j]); }
;                         if (bj == 0) { w.x = pack4_u8c(a); w.y = pack4_u8c(b); } else { w.z = pack4_u8c(a); w.w = pack4_u8c(b); } }
;                     gst[(ai * 4 + m) * 512 + tid] = w; MEMFENCE; }
	v_add_f32_e32 v42, 1.0, v50
	v_mul_f32_e32 v40, 0xbfb8aa3b, v40
	v_mul_f32_e32 v41, 0xbfb8aa3b, v41
	v_exp_f32_e32 v40, v40
	v_exp_f32_e32 v41, v41
	v_rcp_f32_e32 v42, v42
	v_fma_f32 v43, v51, s4, 0.5
	v_add_f32_e32 v40, 1.0, v40
	v_add_f32_e32 v41, 1.0, v41
	v_rcp_f32_e32 v40, v40
	v_rcp_f32_e32 v41, v41
	v_fma_f32 v42, v42, s4, 0.5
	v_max_f32_e32 v43, 1.0, v43
	v_max_f32_e32 v42, 1.0, v42
	v_fma_f32 v40, v40, s4, 0.5
	v_fma_f32 v41, v41, s4, 0.5
	v_cvt_u32_f32_e32 v43, v43
	v_cvt_u32_f32_e32 v42, v42
	v_max_f32_e32 v40, 1.0, v40
	v_max_f32_e32 v41, 1.0, v41
	v_cvt_u32_f32_sdwa v40, v40 dst_sel:WORD_1 dst_unused:UNUSED_PAD src0_sel:DWORD
	v_cvt_u32_f32_sdwa v41, v41 dst_sel:BYTE_3 dst_unused:UNUSED_PAD src0_sel:DWORD
	v_lshl_or_b32 v42, v43, 8, v42
	v_exp_f32_e32 v92, v92
	v_exp_f32_e32 v93, v93
	v_or3_b32 v51, v42, v40, v41
	v_mul_f32_e32 v42, 0x3c800000, v136
	v_pk_mul_f32 v[32:33], v[32:33], v[42:43] op_sel_hi:[1,0]
	v_pk_mul_f32 v[34:35], v[34:35], v[42:43] op_sel_hi:[1,0]
	v_mul_f32_e32 v32, 0xbfb8aa3b, v32
	v_mul_f32_e32 v33, 0xbfb8aa3b, v33
	v_mul_f32_e32 v35, 0xbfb8aa3b, v35
	v_exp_f32_e32 v32, v32
	v_exp_f32_e32 v33, v33
	v_mul_f32_e32 v34, 0xbfb8aa3b, v34
	v_exp_f32_e32 v35, v35
	v_exp_f32_e32 v34, v34
	v_add_f32_e32 v32, 1.0, v32
	v_add_f32_e32 v33, 1.0, v33
	v_pk_mul_f32 v[36:37], v[36:37], v[42:43] op_sel_hi:[1,0]
	v_add_f32_e32 v35, 1.0, v35
	v_rcp_f32_e32 v32, v32
	v_rcp_f32_e32 v33, v33
	v_add_f32_e32 v34, 1.0, v34
	v_pk_mul_f32 v[38:39], v[38:39], v[42:43] op_sel_hi:[1,0]
	v_mul_f32_e32 v36, 0xbfb8aa3b, v36
	v_mul_f32_e32 v37, 0xbfb8aa3b, v37
	v_rcp_f32_e32 v35, v35
	v_rcp_f32_e32 v34, v34
	v_mul_f32_e32 v39, 0xbfb8aa3b, v39
	v_exp_f32_e32 v36, v36
	v_exp_f32_e32 v37, v37
	v_mul_f32_e32 v38, 0xbfb8aa3b, v38
	v_exp_f32_e32 v39, v39
	v_exp_f32_e32 v38, v38
	v_fma_f32 v32, v32, s4, 0.5
	v_fma_f32 v33, v33, s4, 0.5
	v_max_f32_e32 v32, 1.0, v32
	v_max_f32_e32 v33, 1.0, v33
	v_fma_f32 v34, v34, s4, 0.5
	v_fma_f32 v35, v35, s4, 0.5
	v_add_f32_e32 v36, 1.0, v36
	v_add_f32_e32 v37, 1.0, v37
	v_cvt_u32_f32_e32 v32, v32
	v_cvt_u32_f32_e32 v33, v33
	v_max_f32_e32 v34, 1.0, v34
	v_max_f32_e32 v35, 1.0, v35
	v_add_f32_e32 v39, 1.0, v39
	v_rcp_f32_e32 v36, v36
	v_rcp_f32_e32 v37, v37
	v_cvt_u32_f32_sdwa v34, v34 dst_sel:WORD_1 dst_unused:UNUSED_PAD src0_sel:DWORD
	v_cvt_u32_f32_sdwa v35, v35 dst_sel:BYTE_3 dst_unused:UNUSED_PAD src0_sel:DWORD
	v_add_f32_e32 v38, 1.0, v38
	v_rcp_f32_e32 v39, v39
	v_rcp_f32_e32 v38, v38
	v_lshl_or_b32 v32, v33, 8, v32
	v_or3_b32 v32, v32, v34, v35
	v_fma_f32 v33, v36, s4, 0.5
	v_fma_f32 v34, v37, s4, 0.5
	v_pk_mul_f32 v[28:29], v[28:29], v[42:43] op_sel_hi:[1,0]
	v_max_f32_e32 v33, 1.0, v33
	v_max_f32_e32 v34, 1.0, v34
	v_fma_f32 v35, v38, s4, 0.5
	v_fma_f32 v36, v39, s4, 0.5
	v_mul_f32_e32 v29, 0xbfb8aa3b, v29
	v_cvt_u32_f32_e32 v33, v33
	v_cvt_u32_f32_e32 v34, v34
	v_max_f32_e32 v35, 1.0, v35
	v_max_f32_e32 v36, 1.0, v36
	v_exp_f32_e32 v29, v29
	v_cvt_u32_f32_sdwa v35, v35 dst_sel:WORD_1 dst_unused:UNUSED_PAD src0_sel:DWORD
	v_cvt_u32_f32_sdwa v36, v36 dst_sel:BYTE_3 dst_unused:UNUSED_PAD src0_sel:DWORD
	v_pk_mul_f32 v[24:25], v[24:25], v[42:43] op_sel_hi:[1,0]
	v_mul_f32_e32 v28, 0xbfb8aa3b, v28
	v_mul_f32_e32 v25, 0xbfb8aa3b, v25
	v_lshl_or_b32 v33, v34, 8, v33
	v_exp_f32_e32 v34, v28
	v_add_f32_e32 v28, 1.0, v29
	v_exp_f32_e32 v25, v25
	v_or3_b32 v33, v33, v35, v36
	v_rcp_f32_e32 v35, v28
	v_mul_f32_e32 v24, 0xbfb8aa3b, v24
	v_mul_f32_e32 v76, 0xbfb8aa3b, v76
	v_mul_f32_e32 v77, 0xbfb8aa3b, v77
	v_pk_mul_f32 v[28:29], v[30:31], v[42:43] op_sel_hi:[1,0]
	v_add_f32_e32 v30, 1.0, v34
	v_exp_f32_e32 v34, v24
	v_add_f32_e32 v24, 1.0, v25
	v_exp_f32_e32 v76, v76
	v_exp_f32_e32 v77, v77
	v_mul_f32_e32 v60, 0xbfb8aa3b, v60
	v_mul_f32_e32 v61, 0xbfb8aa3b, v61
	v_fma_f32 v31, v35, s4, 0.5
	v_rcp_f32_e32 v35, v24
	v_pk_mul_f32 v[24:25], v[26:27], v[42:43] op_sel_hi:[1,0]
	v_rcp_f32_e32 v126, v126
	v_add_f32_e32 v124, 1.0, v124
	v_add_f32_e32 v125, 1.0, v125
	v_exp_f32_e32 v60, v60
	v_exp_f32_e32 v61, v61
	v_mul_f32_e32 v44, 0xbfb8aa3b, v44
	v_mul_f32_e32 v45, 0xbfb8aa3b, v45
	v_mul_f32_e32 v24, 0xbfb8aa3b, v24
	v_mul_f32_e32 v25, 0xbfb8aa3b, v25
	v_rcp_f32_e32 v124, v124
	v_rcp_f32_e32 v125, v125
	v_rcp_f32_e32 v110, v110
	v_add_f32_e32 v108, 1.0, v108
	v_add_f32_e32 v109, 1.0, v109
	v_exp_f32_e32 v44, v44
	v_exp_f32_e32 v45, v45
	v_mul_f32_e32 v28, 0xbfb8aa3b, v28
	v_mul_f32_e32 v29, 0xbfb8aa3b, v29
	v_exp_f32_e32 v24, v24
	v_exp_f32_e32 v25, v25
	s_lshl_b64 s[2:3], s[2:3], 16
	v_rcp_f32_e32 v108, v108
	v_rcp_f32_e32 v109, v109
	v_rcp_f32_e32 v94, v94
	v_add_f32_e32 v92, 1.0, v92
	v_add_f32_e32 v93, 1.0, v93
	v_exp_f32_e32 v28, v28
	v_exp_f32_e32 v29, v29
	s_add_u32 s2, s29, s2
	v_rcp_f32_e32 v92, v92
	v_rcp_f32_e32 v93, v93
	v_rcp_f32_e32 v78, v78
	v_add_f32_e32 v76, 1.0, v76
	v_add_f32_e32 v77, 1.0, v77
	s_addc_u32 s3, s30, s3
	v_fma_f32 v126, v126, s4, 0.5
	v_ashrrev_i32_e32 v143, 31, v142
	v_rcp_f32_e32 v76, v76
	v_rcp_f32_e32 v77, v77
	v_rcp_f32_e32 v62, v62
	v_add_f32_e32 v60, 1.0, v60
	v_add_f32_e32 v61, 1.0, v61
	v_add_f32_e32 v26, 1.0, v34
	v_max_f32_e32 v127, 1.0, v127
	v_max_f32_e32 v126, 1.0, v126
	v_fma_f32 v124, v124, s4, 0.5
	v_fma_f32 v125, v125, s4, 0.5
	v_lshl_add_u64 v[120:121], v[142:143], 4, s[2:3]
	v_fma_f32 v110, v110, s4, 0.5
	s_movk_i32 s2, 0x2000
	v_rcp_f32_e32 v60, v60
	v_rcp_f32_e32 v61, v61
	v_rcp_f32_e32 v46, v46
	v_add_f32_e32 v44, 1.0, v44
	v_add_f32_e32 v45, 1.0, v45
	v_rcp_f32_e32 v26, v26
	v_add_f32_e32 v24, 1.0, v24
	v_add_f32_e32 v25, 1.0, v25
	v_cvt_u32_f32_e32 v127, v127
	v_cvt_u32_f32_e32 v126, v126
	v_max_f32_e32 v124, 1.0, v124
	v_max_f32_e32 v125, 1.0, v125
; #define MEMFENCE asm volatile("" ::: "memory")
;     template <int KIND> __device__ __forceinline__ void run(f32x4 (&acc)[2][2][4][2], const Unit& u, int tid_in) const {
;     ...
;                         if (bj == 0) { w.x = pack4_u8c(a); w.y = pack4_u8c(b); } else { w.z = pack4_u8c(a); w.w = pack4_u8c(b); } }
;                     gst[(ai * 4 + m) * 512 + tid] = w; MEMFENCE; }
	v_max_f32_e32 v111, 1.0, v111
	v_max_f32_e32 v110, 1.0, v110
	v_fma_f32 v108, v108, s4, 0.5
	v_fma_f32 v109, v109, s4, 0.5
	v_add_co_u32_e32 v104, vcc, s2, v120
	v_fma_f32 v94, v94, s4, 0.5
	v_rcp_f32_e32 v44, v44
	v_rcp_f32_e32 v45, v45
	v_rcp_f32_e32 v30, v30
	v_add_f32_e32 v28, 1.0, v28
	v_add_f32_e32 v29, 1.0, v29
	v_rcp_f32_e32 v24, v24
	v_rcp_f32_e32 v25, v25
	v_cvt_u32_f32_sdwa v124, v124 dst_sel:WORD_1 dst_unused:UNUSED_PAD src0_sel:DWORD
	v_cvt_u32_f32_sdwa v125, v125 dst_sel:BYTE_3 dst_unused:UNUSED_PAD src0_sel:DWORD
	v_cvt_u32_f32_e32 v111, v111
	v_cvt_u32_f32_e32 v110, v110
	v_max_f32_e32 v108, 1.0, v108
	v_max_f32_e32 v109, 1.0, v109
	v_addc_co_u32_e32 v105, vcc, 0, v121, vcc
	v_max_f32_e32 v95, 1.0, v95
	v_max_f32_e32 v94, 1.0, v94
	v_fma_f32 v92, v92, s4, 0.5
	v_fma_f32 v93, v93, s4, 0.5
	v_fma_f32 v78, v78, s4, 0.5
	v_rcp_f32_e32 v28, v28
	v_rcp_f32_e32 v29, v29
	v_cvt_u32_f32_sdwa v108, v108 dst_sel:WORD_1 dst_unused:UNUSED_PAD src0_sel:DWORD
	v_cvt_u32_f32_sdwa v109, v109 dst_sel:BYTE_3 dst_unused:UNUSED_PAD src0_sel:DWORD
	v_cvt_u32_f32_e32 v95, v95
	v_cvt_u32_f32_e32 v94, v94
	v_max_f32_e32 v92, 1.0, v92
	v_max_f32_e32 v93, 1.0, v93
	v_add_co_u32_e32 v88, vcc, s49, v120
	v_max_f32_e32 v79, 1.0, v79
	v_max_f32_e32 v78, 1.0, v78
	v_fma_f32 v76, v76, s4, 0.5
	v_fma_f32 v77, v77, s4, 0.5
	v_fma_f32 v62, v62, s4, 0.5
	v_cvt_u32_f32_sdwa v92, v92 dst_sel:WORD_1 dst_unused:UNUSED_PAD src0_sel:DWORD
	v_cvt_u32_f32_sdwa v93, v93 dst_sel:BYTE_3 dst_unused:UNUSED_PAD src0_sel:DWORD
	v_addc_co_u32_e32 v89, vcc, 0, v121, vcc
	v_cvt_u32_f32_e32 v79, v79
	v_cvt_u32_f32_e32 v78, v78
	v_max_f32_e32 v76, 1.0, v76
	v_max_f32_e32 v77, 1.0, v77
	s_movk_i32 s2, 0x6000
	v_max_f32_e32 v63, 1.0, v63
	v_max_f32_e32 v62, 1.0, v62
	v_fma_f32 v60, v60, s4, 0.5
	v_fma_f32 v61, v61, s4, 0.5
	v_fma_f32 v46, v46, s4, 0.5
	v_fma_f32 v27, v35, s4, 0.5
	v_fma_f32 v26, v26, s4, 0.5
	v_lshl_or_b32 v126, v127, 8, v126
	v_cvt_u32_f32_sdwa v76, v76 dst_sel:WORD_1 dst_unused:UNUSED_PAD src0_sel:DWORD
	v_cvt_u32_f32_sdwa v77, v77 dst_sel:BYTE_3 dst_unused:UNUSED_PAD src0_sel:DWORD
	v_add_co_u32_e32 v72, vcc, s2, v120
	v_cvt_u32_f32_e32 v63, v63
	v_cvt_u32_f32_e32 v62, v62
	v_max_f32_e32 v60, 1.0, v60
	v_max_f32_e32 v61, 1.0, v61
	v_max_f32_e32 v47, 1.0, v47
	v_max_f32_e32 v46, 1.0, v46
	v_fma_f32 v44, v44, s4, 0.5
	v_fma_f32 v45, v45, s4, 0.5
	v_fma_f32 v30, v30, s4, 0.5
	v_max_f32_e32 v27, 1.0, v27
	v_max_f32_e32 v26, 1.0, v26
	v_fma_f32 v24, v24, s4, 0.5
	v_fma_f32 v25, v25, s4, 0.5
	v_or3_b32 v130, v126, v124, v125
	v_lshl_or_b32 v110, v111, 8, v110
	v_addc_co_u32_e32 v73, vcc, 0, v121, vcc
	v_cvt_u32_f32_sdwa v60, v60 dst_sel:WORD_1 dst_unused:UNUSED_PAD src0_sel:DWORD
	v_cvt_u32_f32_sdwa v61, v61 dst_sel:BYTE_3 dst_unused:UNUSED_PAD src0_sel:DWORD
	v_cvt_u32_f32_e32 v47, v47
	v_cvt_u32_f32_e32 v46, v46
	v_max_f32_e32 v44, 1.0, v44
	v_max_f32_e32 v45, 1.0, v45
	v_max_f32_e32 v31, 1.0, v31
	v_max_f32_e32 v30, 1.0, v30
	v_fma_f32 v28, v28, s4, 0.5
	v_fma_f32 v29, v29, s4, 0.5
	v_cvt_u32_f32_e32 v27, v27
	v_cvt_u32_f32_e32 v26, v26
	v_max_f32_e32 v24, 1.0, v24
	v_max_f32_e32 v25, 1.0, v25
	global_store_dwordx4 v[120:121], v[128:131], off
	v_or3_b32 v114, v110, v108, v109
	v_lshl_or_b32 v94, v95, 8, v94
	v_add_co_u32_e32 v56, vcc, s77, v120
	v_cvt_u32_f32_sdwa v44, v44 dst_sel:WORD_1 dst_unused:UNUSED_PAD src0_sel:DWORD
	v_cvt_u32_f32_sdwa v45, v45 dst_sel:BYTE_3 dst_unused:UNUSED_PAD src0_sel:DWORD
	v_cvt_u32_f32_e32 v31, v31
	v_cvt_u32_f32_e32 v30, v30
	v_max_f32_e32 v28, 1.0, v28
	v_max_f32_e32 v29, 1.0, v29
	v_cvt_u32_f32_sdwa v24, v24 dst_sel:WORD_1 dst_unused:UNUSED_PAD src0_sel:DWORD
	v_cvt_u32_f32_sdwa v25, v25 dst_sel:BYTE_3 dst_unused:UNUSED_PAD src0_sel:DWORD
	global_store_dwordx4 v[104:105], v[112:115], off
	v_or3_b32 v98, v94, v92, v93
	v_lshl_or_b32 v78, v79, 8, v78
	v_addc_co_u32_e32 v57, vcc, 0, v121, vcc
	s_mov_b32 s2, 0xa000
	v_cvt_u32_f32_sdwa v28, v28 dst_sel:WORD_1 dst_unused:UNUSED_PAD src0_sel:DWORD
	v_cvt_u32_f32_sdwa v29, v29 dst_sel:BYTE_3 dst_unused:UNUSED_PAD src0_sel:DWORD
	global_store_dwordx4 v[88:89], v[96:99], off
	v_or3_b32 v82, v78, v76, v77
	v_lshl_or_b32 v62, v63, 8, v62
	v_add_co_u32_e32 v40, vcc, s2, v120
	global_store_dwordx4 v[72:73], v[80:83], off
	v_or3_b32 v66, v62, v60, v61
	v_lshl_or_b32 v46, v47, 8, v46
	v_addc_co_u32_e32 v41, vcc, 0, v121, vcc
	v_lshl_or_b32 v26, v27, 8, v26
	s_mov_b32 s2, 0xc000
	global_store_dwordx4 v[56:57], v[64:67], off
	v_or3_b32 v50, v46, v44, v45
	v_lshl_or_b32 v30, v31, 8, v30
	v_or3_b32 v35, v26, v24, v25
	v_add_co_u32_e32 v24, vcc, s2, v120
	global_store_dwordx4 v[40:41], v[48:51], off
	v_or3_b32 v34, v30, v28, v29
	v_addc_co_u32_e32 v25, vcc, 0, v121, vcc
	global_store_dwordx4 v[24:25], v[32:35], off
; __device__ __forceinline__ float sigmoidf_(float v) { return __builtin_amdgcn_rcpf(1.0f + __expf(-v)); }
; #define MEMFENCE asm volatile("" ::: "memory")
; #define G_WAIT_V(n) asm volatile("s_waitcnt vmcnt(" #n ")" ::: "memory")
; #define G_BAR __builtin_amdgcn_s_barrier()
;     template <int KIND> __device__ __forceinline__ void run(f32x4 (&acc)[2][2][4][2], const Unit& u, int tid_in) const {
;     ...
;                 for (int m = 0; m < 4; ++m) { const float r = rs[ai * 4 + m] * (1.0f / GATE_WSCALE); u32x4 w;
; #pragma unroll
;                     for (int bj = 0; bj < 2; ++bj) { f32x4 a = acc[ai][bj][m][0] * r, b = acc[ai][bj][m][1] * r;
; #pragma unroll
;                         for (int j = 0; j < 4; ++j) { a[j] = sigmoidf_(a[j]); b[j] = sigmoidf_(b[j]); }
;                         if (bj == 0) { w.x = pack4_u8c(a); w.y = pack4_u8c(b); } else { w.z = pack4_u8c(a); w.w = pack4_u8c(b); } }
;                     gst[(ai * 4 + m) * 512 + tid] = w; MEMFENCE; }
;     ...
;         if (!has_next) break;
;         if (!(cs.kind == K_MG_B && cur.aux < 2))
; #pragma unroll
;         for (int a = 0; a < 2; ++a)
; #pragma unroll
;             for (int b = 0; b < 2; ++b)
; #pragma unroll
;                 for (int m = 0; m < 4; ++m)
; #pragma unroll
;                     for (int n = 0; n < 2; ++n) acc[a][b][m][n] = (f32x4){0.f, 0.f, 0.f, 0.f};
;         cur = nxt; cA = nA; cB = nB; ++ui;
;     }
;     G_WAIT_V(0);
;     if (wr == 0) G_BAR;
;     G_BAR;
	v_mul_f32_e32 v24, 0x3c800000, v137
	v_pk_mul_f32 v[20:21], v[20:21], v[24:25] op_sel_hi:[1,0]
	s_mov_b32 s33, s35
	v_mul_f32_e32 v21, 0xbfb8aa3b, v21
	v_exp_f32_e32 v21, v21
	v_mul_f32_e32 v20, 0xbfb8aa3b, v20
	v_exp_f32_e32 v25, v20
	s_mov_b32 s36, s34
	v_add_f32_e32 v20, 1.0, v21
	v_rcp_f32_e32 v26, v20
	v_pk_mul_f32 v[20:21], v[22:23], v[24:25] op_sel_hi:[1,0]
	v_add_f32_e32 v22, 1.0, v25
	v_mul_f32_e32 v20, 0xbfb8aa3b, v20
	v_exp_f32_e32 v20, v20
	v_rcp_f32_e32 v22, v22
	v_mul_f32_e32 v21, 0xbfb8aa3b, v21
	v_exp_f32_e32 v21, v21
	v_add_f32_e32 v20, 1.0, v20
	v_fma_f32 v23, v26, s4, 0.5
	v_fma_f32 v22, v22, s4, 0.5
	v_rcp_f32_e32 v20, v20
	v_max_f32_e32 v23, 1.0, v23
	v_max_f32_e32 v22, 1.0, v22
	v_add_f32_e32 v21, 1.0, v21
	v_cvt_u32_f32_e32 v23, v23
	v_cvt_u32_f32_e32 v22, v22
	v_rcp_f32_e32 v21, v21
	v_fma_f32 v20, v20, s4, 0.5
	v_max_f32_e32 v20, 1.0, v20
	v_lshl_or_b32 v22, v23, 8, v22
	v_cvt_u32_f32_sdwa v23, v20 dst_sel:WORD_1 dst_unused:UNUSED_PAD src0_sel:DWORD
	v_fma_f32 v20, v21, s4, 0.5
	v_max_f32_e32 v20, 1.0, v20
	v_cvt_u32_f32_sdwa v25, v20 dst_sel:BYTE_3 dst_unused:UNUSED_PAD src0_sel:DWORD
	s_mov_b64 s[12:13], s[10:11]
	s_mov_b64 s[2:3], s[8:9]
	v_pk_mul_f32 v[20:21], v[16:17], v[24:25] op_sel_hi:[1,0]
	s_nop 0
	v_mul_f32_e32 v16, 0xbfb8aa3b, v21
	v_mul_f32_e32 v20, 0xbfb8aa3b, v20
	v_pk_mul_f32 v[18:19], v[18:19], v[24:25] op_sel_hi:[1,0]
	v_exp_f32_e32 v17, v16
	v_exp_f32_e32 v20, v20
	v_mul_f32_e32 v18, 0xbfb8aa3b, v18
	v_mul_f32_e32 v19, 0xbfb8aa3b, v19
	v_exp_f32_e32 v18, v18
	v_exp_f32_e32 v19, v19
	v_add_f32_e32 v17, 1.0, v17
	v_add_f32_e32 v20, 1.0, v20
	v_rcp_f32_e32 v17, v17
	v_rcp_f32_e32 v20, v20
	v_add_f32_e32 v18, 1.0, v18
	v_add_f32_e32 v19, 1.0, v19
	v_rcp_f32_e32 v18, v18
	v_rcp_f32_e32 v19, v19
	v_fma_f32 v17, v17, s4, 0.5
	v_fma_f32 v20, v20, s4, 0.5
	v_max_f32_e32 v17, 1.0, v17
	v_max_f32_e32 v20, 1.0, v20
	v_fma_f32 v18, v18, s4, 0.5
	v_fma_f32 v19, v19, s4, 0.5
	v_pk_mul_f32 v[12:13], v[12:13], v[24:25] op_sel_hi:[1,0]
	v_cvt_u32_f32_e32 v17, v17
	v_cvt_u32_f32_e32 v20, v20
	v_max_f32_e32 v18, 1.0, v18
	v_max_f32_e32 v19, 1.0, v19
	v_mul_f32_e32 v13, 0xbfb8aa3b, v13
	v_cvt_u32_f32_sdwa v18, v18 dst_sel:WORD_1 dst_unused:UNUSED_PAD src0_sel:DWORD
	v_cvt_u32_f32_sdwa v19, v19 dst_sel:BYTE_3 dst_unused:UNUSED_PAD src0_sel:DWORD
	v_exp_f32_e32 v13, v13
	v_pk_mul_f32 v[8:9], v[8:9], v[24:25] op_sel_hi:[1,0]
	v_lshl_or_b32 v17, v17, 8, v20
	v_mul_f32_e32 v12, 0xbfb8aa3b, v12
	v_mul_f32_e32 v9, 0xbfb8aa3b, v9
	v_or3_b32 v17, v17, v18, v19
	v_exp_f32_e32 v18, v12
	v_add_f32_e32 v12, 1.0, v13
	v_exp_f32_e32 v9, v9
	v_rcp_f32_e32 v19, v12
	v_mul_f32_e32 v8, 0xbfb8aa3b, v8
	v_pk_mul_f32 v[12:13], v[14:15], v[24:25] op_sel_hi:[1,0]
	v_add_f32_e32 v14, 1.0, v18
	v_exp_f32_e32 v18, v8
	v_add_f32_e32 v8, 1.0, v9
	v_fma_f32 v15, v19, s4, 0.5
	v_rcp_f32_e32 v19, v8
	v_pk_mul_f32 v[8:9], v[10:11], v[24:25] op_sel_hi:[1,0]
	v_mul_f32_e32 v12, 0xbfb8aa3b, v12
	v_mul_f32_e32 v8, 0xbfb8aa3b, v8
	v_mul_f32_e32 v9, 0xbfb8aa3b, v9
	v_mul_f32_e32 v13, 0xbfb8aa3b, v13
	v_exp_f32_e32 v8, v8
	v_exp_f32_e32 v9, v9
	v_exp_f32_e32 v12, v12
	v_exp_f32_e32 v13, v13
	v_add_f32_e32 v10, 1.0, v18
	v_rcp_f32_e32 v10, v10
	v_add_f32_e32 v8, 1.0, v8
	v_add_f32_e32 v9, 1.0, v9
	v_rcp_f32_e32 v14, v14
	v_add_f32_e32 v12, 1.0, v12
	v_add_f32_e32 v13, 1.0, v13
	v_rcp_f32_e32 v8, v8
	v_rcp_f32_e32 v9, v9
	v_rcp_f32_e32 v12, v12
	v_rcp_f32_e32 v13, v13
	v_fma_f32 v11, v19, s4, 0.5
	v_fma_f32 v10, v10, s4, 0.5
	v_fma_f32 v14, v14, s4, 0.5
	v_max_f32_e32 v11, 1.0, v11
	v_max_f32_e32 v10, 1.0, v10
	v_fma_f32 v8, v8, s4, 0.5
	v_fma_f32 v9, v9, s4, 0.5
	v_max_f32_e32 v15, 1.0, v15
	v_max_f32_e32 v14, 1.0, v14
	v_fma_f32 v12, v12, s4, 0.5
	v_fma_f32 v13, v13, s4, 0.5
	v_cvt_u32_f32_e32 v11, v11
	v_cvt_u32_f32_e32 v10, v10
	v_max_f32_e32 v8, 1.0, v8
	v_max_f32_e32 v9, 1.0, v9
	v_cvt_u32_f32_e32 v15, v15
	v_cvt_u32_f32_e32 v14, v14
	v_max_f32_e32 v12, 1.0, v12
	v_max_f32_e32 v13, 1.0, v13
	v_cvt_u32_f32_sdwa v8, v8 dst_sel:WORD_1 dst_unused:UNUSED_PAD src0_sel:DWORD
	v_cvt_u32_f32_sdwa v9, v9 dst_sel:BYTE_3 dst_unused:UNUSED_PAD src0_sel:DWORD
	v_cvt_u32_f32_sdwa v12, v12 dst_sel:WORD_1 dst_unused:UNUSED_PAD src0_sel:DWORD
	v_cvt_u32_f32_sdwa v13, v13 dst_sel:BYTE_3 dst_unused:UNUSED_PAD src0_sel:DWORD
	v_lshl_or_b32 v10, v11, 8, v10
	v_lshl_or_b32 v14, v15, 8, v14
	v_or3_b32 v19, v10, v8, v9
	v_add_co_u32_e32 v8, vcc, 0xe000, v120
	v_or3_b32 v16, v22, v23, v25
	v_or3_b32 v18, v14, v12, v13
	v_addc_co_u32_e32 v9, vcc, 0, v121, vcc
	global_store_dwordx4 v[8:9], v[16:19], off
	s_and_b64 vcc, exec, s[6:7]
	s_cbranch_vccz .LBB0_867
	s_cmp_eq_u32 s101, 2
	s_cbranch_scc0 .Ldbj_MG0_pe
	s_barrier
.Ldbj_MG0_pe:
	s_mov_b32 s101, 0
	s_waitcnt vmcnt(0)
	s_cmpk_gt_u32 s16, 0xff
	s_cbranch_scc1 .LBB0_876
	s_barrier

; #define G_STAGE(bufoff, gbase, o0, h64) do { \
;         __builtin_amdgcn_global_load_lds((const unsigned*)((const char*)(gbase) + (o0)), (LAS unsigned*)(lds + (bufoff) + ldsw), 16, 0, 0); \
;         __builtin_amdgcn_global_load_lds((const unsigned*)((const char*)(gbase) + (h64) + (o0)), (LAS unsigned*)(lds + (bufoff) + ldsw + 8192), 16, 0, 0); } while (0)
; #define G_LDA(dst, b, h) do { _Pragma("unroll") for (int m = 0; m < 4; ++m) _Pragma("unroll") for (int k = 0; k < 2; ++k) dst[m][k] = *(const LAS bf16x8*)(lds + G_SA(b, h) + aoff + m * 2048 + k * 1024); } while (0)
; #define G_LDB(dst, b, h) do { _Pragma("unroll") for (int n = 0; n < 2; ++n) _Pragma("unroll") for (int k = 0; k < 2; ++k) dst[n][k] = *(const LAS bf16x8*)(lds + G_SB(b, h) + boff + n * 2048 + k * 1024); } while (0)
; #define G_WAIT_L(n) asm volatile("s_waitcnt lgkmcnt(" #n ")" ::: "memory")
; #define G_BAR __builtin_amdgcn_s_barrier()
; #define G_SCHED __builtin_amdgcn_sched_barrier(0)
;     ...
;     for (;;) {
;         const bool has_next = sched_next<PH, SUB>(E.ws, E.layer, ui + 1, nxt, E.x);
;         if (!has_next) nxt = cur;
;         const char* nA = nxt.A; const char* nB = nxt.B;
; #pragma unroll 1
;         for (int t = 0; t < nt; t += 2) {
;             const bool last = (t == nt - 2);
;             const char* a1 = cA + (size_t)(t + 1) * ckA;
;             const char* a2 = last ? nA : cA + (size_t)(t + 2) * ckA; const char* b2 = last ? nB : cB + (size_t)(t + 2) * kB;
;             const char* a3 = a2 + ckA; const char* b3 = b2 + kB;
;             G_LDB(B0, 0, 0); G_SCHED; G_LDA(At, 0, 0); G_STAGE(G_SA(1, 1), a1 + chA, cA0, qA);
;             G_WAIT_L(8); G_BAR; G_WAIT_L(0); G_MMA(0, 0, At, B0); G_BAR; G_SCHED;
;             G_LDB(B1, 0, 1); G_STAGE(G_SB(0, 0), b2, cB0, qB);
;             G_BAR; G_WAIT_L(0); G_MMA(0, 1, At, B1); G_BAR;
;             G_LDA(At, 0, 1); G_STAGE(G_SA(0, 0), a2, cA0, qA);
;             G_BAR; G_WAIT_L(0); G_MMA(1, 0, At, B0); G_BAR; G_SCHED;
;     ...
;         if (!(cs.kind == K_MG_B && cur.aux < 2))
.LBB0_889:
	s_add_u32 s6, s6, 0xb0080
	s_addc_u32 s7, s7, 0
	s_add_u32 s8, s18, 0x100
	s_addc_u32 s9, s19, 0
	s_mov_b32 s18, -2
	s_mov_b64 s[50:51], 0x20080
	s_mov_b64 s[52:53], 0x30000
	s_mov_b64 s[54:55], 0x10080
	s_mov_b64 s[58:59], 0x30080
	s_cmp_eq_u32 s101, 2
	s_cselect_b32 s101, 0, s101
.LBB0_890:
	s_add_u32 s4, s6, 0xfff50080
	s_addc_u32 s5, s7, -1
	s_add_i32 s19, 0, 0x10000
	v_add_u32_e32 v0, s19, v175
	ds_read_b128 v[136:139], v0
	ds_read_b128 v[140:143], v0 offset:1024
	ds_read_b128 v[144:147], v0 offset:2048
	ds_read_b128 v[148:151], v0 offset:3072
	s_cmp_eq_u32 s18, 4
	s_cselect_b32 s45, s15, s9
	s_cselect_b32 s44, s14, s8
	s_cselect_b32 s5, s13, s5
	s_cselect_b32 s4, s12, s4
	v_lshl_add_u64 v[2:3], s[6:7], 0, v[156:157]
	s_add_i32 m0, s22, 0xc000
	ds_read_b128 v[158:161], v176
	ds_read_b128 v[162:165], v176 offset:1024
	ds_read_b128 v[178:181], v176 offset:2048
	ds_read_b128 v[182:185], v176 offset:3072
	ds_read_b128 v[196:199], v176 offset:4096
	ds_read_b128 v[200:203], v176 offset:5120
	ds_read_b128 v[204:207], v176 offset:6144
	ds_read_b128 v[208:211], v176 offset:7168
	global_load_lds_dwordx4 v[2:3], off
	v_lshl_add_u64 v[2:3], v[2:3], 0, s[86:87]
	s_add_i32 m0, s22, 0xe000
	s_nop 0
	global_load_lds_dwordx4 v[2:3], off
	s_waitcnt lgkmcnt(8)
	s_cmp_eq_u32 s101, 1
	s_cbranch_scc1 .Ldb_MG1_sk
	s_barrier
.Ldb_MG1_sk:
	s_mov_b32 s101, 0
	s_waitcnt lgkmcnt(0)
	v_mfma_f32_16x16x32_bf16 v[104:107], v[136:139], v[158:161], v[104:107]
	v_mfma_f32_16x16x32_bf16 v[108:111], v[144:147], v[158:161], v[108:111]
	v_mfma_f32_16x16x32_bf16 v[132:135], v[136:139], v[178:181], v[132:135]
	v_mfma_f32_16x16x32_bf16 v[128:131], v[144:147], v[178:181], v[128:131]
	v_mfma_f32_16x16x32_bf16 v[124:127], v[136:139], v[196:199], v[124:127]
	v_mfma_f32_16x16x32_bf16 v[120:123], v[144:147], v[196:199], v[120:123]
	v_mfma_f32_16x16x32_bf16 v[116:119], v[136:139], v[204:207], v[116:119]
	v_mfma_f32_16x16x32_bf16 v[112:115], v[144:147], v[204:207], v[112:115]
	v_mfma_f32_16x16x32_bf16 v[104:107], v[140:143], v[162:165], v[104:107]
	v_mfma_f32_16x16x32_bf16 v[108:111], v[148:151], v[162:165], v[108:111]
	v_mfma_f32_16x16x32_bf16 v[132:135], v[140:143], v[182:185], v[132:135]
	v_mfma_f32_16x16x32_bf16 v[128:131], v[148:151], v[182:185], v[128:131]
	v_mfma_f32_16x16x32_bf16 v[124:127], v[140:143], v[200:203], v[124:127]
	v_mfma_f32_16x16x32_bf16 v[120:123], v[148:151], v[200:203], v[120:123]
	v_mfma_f32_16x16x32_bf16 v[116:119], v[140:143], v[208:211], v[116:119]
	v_mfma_f32_16x16x32_bf16 v[112:115], v[148:151], v[208:211], v[112:115]
	s_barrier
	s_add_i32 s43, 0, 0x14000
	s_add_i32 s19, s19, s21
	v_add_u32_e32 v0, s43, v175
	v_lshl_add_u64 v[2:3], s[44:45], 0, v[154:155]
	s_mov_b64 s[44:45], 0x10000
	s_mov_b32 m0, s19
	ds_read_b128 v[212:215], v0
	ds_read_b128 v[216:219], v0 offset:1024
	ds_read_b128 v[220:223], v0 offset:2048
	ds_read_b128 v[224:227], v0 offset:3072
	global_load_lds_dwordx4 v[2:3], off
	v_lshl_add_u64 v[166:167], v[2:3], 0, s[44:45]
	s_add_i32 m0, s19, 0x2000
	s_nop 0
	global_load_lds_dwordx4 v[166:167], off
	s_barrier
	s_waitcnt lgkmcnt(0)
	v_mfma_f32_16x16x32_bf16 v[100:103], v[212:215], v[158:161], v[100:103]
	v_mfma_f32_16x16x32_bf16 v[96:99], v[220:223], v[158:161], v[96:99]
	v_mfma_f32_16x16x32_bf16 v[92:95], v[212:215], v[178:181], v[92:95]
	v_mfma_f32_16x16x32_bf16 v[88:91], v[220:223], v[178:181], v[88:91]
	v_mfma_f32_16x16x32_bf16 v[84:87], v[212:215], v[196:199], v[84:87]
	v_mfma_f32_16x16x32_bf16 v[80:83], v[220:223], v[196:199], v[80:83]
	v_mfma_f32_16x16x32_bf16 v[76:79], v[212:215], v[204:207], v[76:79]
	v_mfma_f32_16x16x32_bf16 v[72:75], v[220:223], v[204:207], v[72:75]
	v_mfma_f32_16x16x32_bf16 v[100:103], v[216:219], v[162:165], v[100:103]
	v_mfma_f32_16x16x32_bf16 v[96:99], v[224:227], v[162:165], v[96:99]
	v_mfma_f32_16x16x32_bf16 v[92:95], v[216:219], v[182:185], v[92:95]
	v_mfma_f32_16x16x32_bf16 v[88:91], v[224:227], v[182:185], v[88:91]
	v_mfma_f32_16x16x32_bf16 v[84:87], v[216:219], v[200:203], v[84:87]
	v_mfma_f32_16x16x32_bf16 v[80:83], v[224:227], v[200:203], v[80:83]
	v_mfma_f32_16x16x32_bf16 v[76:79], v[216:219], v[208:211], v[76:79]
	v_mfma_f32_16x16x32_bf16 v[72:75], v[224:227], v[208:211], v[72:75]
	s_barrier
	s_mov_b32 m0, s22
	v_lshl_add_u64 v[166:167], s[4:5], 0, v[152:153]
	ds_read_b128 v[158:161], v176 offset:16384
	ds_read_b128 v[162:165], v176 offset:17408
	ds_read_b128 v[178:181], v176 offset:18432
	ds_read_b128 v[182:185], v176 offset:19456
	ds_read_b128 v[196:199], v176 offset:20480
	ds_read_b128 v[200:203], v176 offset:21504
	ds_read_b128 v[204:207], v176 offset:22528
	ds_read_b128 v[208:211], v176 offset:23552
	global_load_lds_dwordx4 v[166:167], off
	v_lshl_add_u64 v[172:173], v[166:167], 0, s[86:87]
	s_mov_b32 m0, s23
	s_nop 0
	global_load_lds_dwordx4 v[172:173], off
	s_barrier
	s_waitcnt lgkmcnt(0)
	v_mfma_f32_16x16x32_bf16 v[68:71], v[136:139], v[158:161], v[68:71]
	v_mfma_f32_16x16x32_bf16 v[64:67], v[144:147], v[158:161], v[64:67]
	v_mfma_f32_16x16x32_bf16 v[60:63], v[136:139], v[178:181], v[60:63]
	v_mfma_f32_16x16x32_bf16 v[56:59], v[144:147], v[178:181], v[56:59]
	v_mfma_f32_16x16x32_bf16 v[52:55], v[136:139], v[196:199], v[52:55]
	v_mfma_f32_16x16x32_bf16 v[48:51], v[144:147], v[196:199], v[48:51]
	v_mfma_f32_16x16x32_bf16 v[44:47], v[136:139], v[204:207], v[44:47]
	v_mfma_f32_16x16x32_bf16 v[40:43], v[144:147], v[204:207], v[40:43]
	v_mfma_f32_16x16x32_bf16 v[68:71], v[140:143], v[162:165], v[68:71]
	v_mfma_f32_16x16x32_bf16 v[64:67], v[148:151], v[162:165], v[64:67]
	v_mfma_f32_16x16x32_bf16 v[60:63], v[140:143], v[182:185], v[60:63]
	v_mfma_f32_16x16x32_bf16 v[56:59], v[148:151], v[182:185], v[56:59]
	v_mfma_f32_16x16x32_bf16 v[52:55], v[140:143], v[200:203], v[52:55]
	v_mfma_f32_16x16x32_bf16 v[48:51], v[148:151], v[200:203], v[48:51]
	v_mfma_f32_16x16x32_bf16 v[44:47], v[140:143], v[208:211], v[44:47]
	v_mfma_f32_16x16x32_bf16 v[40:43], v[148:151], v[208:211], v[40:43]
	s_barrier
; #define G_STAGE(bufoff, gbase, o0, h64) do { \
;         __builtin_amdgcn_global_load_lds((const unsigned*)((const char*)(gbase) + (o0)), (LAS unsigned*)(lds + (bufoff) + ldsw), 16, 0, 0); \
;         __builtin_amdgcn_global_load_lds((const unsigned*)((const char*)(gbase) + (h64) + (o0)), (LAS unsigned*)(lds + (bufoff) + ldsw + 8192), 16, 0, 0); } while (0)
; #define G_LDA(dst, b, h) do { _Pragma("unroll") for (int m = 0; m < 4; ++m) _Pragma("unroll") for (int k = 0; k < 2; ++k) dst[m][k] = *(const LAS bf16x8*)(lds + G_SA(b, h) + aoff + m * 2048 + k * 1024); } while (0)
; #define G_LDB(dst, b, h) do { _Pragma("unroll") for (int n = 0; n < 2; ++n) _Pragma("unroll") for (int k = 0; k < 2; ++k) dst[n][k] = *(const LAS bf16x8*)(lds + G_SB(b, h) + boff + n * 2048 + k * 1024); } while (0)
; #define G_WAIT_V(n) asm volatile("s_waitcnt vmcnt(" #n ")" ::: "memory")
; #define G_WAIT_L(n) asm volatile("s_waitcnt lgkmcnt(" #n ")" ::: "memory")
; #define G_BAR __builtin_amdgcn_s_barrier()
; #define G_SCHED __builtin_amdgcn_sched_barrier(0)
;     ...
;             G_BAR; G_WAIT_L(0); G_MMA(0, 1, At, B1); G_BAR;
;             G_LDA(At, 0, 1); G_STAGE(G_SA(0, 0), a2, cA0, qA);
;             G_BAR; G_WAIT_L(0); G_MMA(1, 0, At, B0); G_BAR; G_SCHED;
;             G_STAGE(G_SB(0, 1), b2 + chB, cB0, qB);
;             G_WAIT_V(6); G_BAR; G_MMA(1, 1, At, B1); G_BAR;
;             G_LDB(B0, 1, 0); G_SCHED; G_LDA(At, 1, 0); G_STAGE(G_SA(0, 1), a2 + chA, cA0, qA);
;             G_WAIT_L(8); G_BAR; G_WAIT_L(0); G_MMA(0, 0, At, B0); G_BAR; G_SCHED;
;             G_LDB(B1, 1, 1); G_STAGE(G_SB(1, 0), b3, cB0, qB);
;             G_BAR; G_WAIT_L(0); G_MMA(0, 1, At, B1); G_BAR;
;             G_LDA(At, 1, 1); G_STAGE(G_SA(1, 0), a3, cA0, qA);
;             G_BAR; G_WAIT_L(0); G_MMA(1, 0, At, B0); G_BAR; G_SCHED;
	s_add_i32 s4, s43, s21
	v_lshl_add_u64 v[136:137], v[2:3], 0, s[0:1]
	s_mov_b32 m0, s4
	s_nop 0
	global_load_lds_dwordx4 v[136:137], off
	v_lshl_add_u64 v[136:137], v[2:3], 0, s[52:53]
	s_add_i32 m0, s4, 0x2000
	s_nop 0
	global_load_lds_dwordx4 v[136:137], off
	s_waitcnt vmcnt(6)
	s_barrier
	v_mfma_f32_16x16x32_bf16 v[36:39], v[212:215], v[158:161], v[36:39]
	v_mfma_f32_16x16x32_bf16 v[32:35], v[220:223], v[158:161], v[32:35]
	v_mfma_f32_16x16x32_bf16 v[28:31], v[212:215], v[178:181], v[28:31]
	v_mfma_f32_16x16x32_bf16 v[24:27], v[220:223], v[178:181], v[24:27]
	v_mfma_f32_16x16x32_bf16 v[20:23], v[212:215], v[196:199], v[20:23]
	v_mfma_f32_16x16x32_bf16 v[16:19], v[220:223], v[196:199], v[16:19]
	v_mfma_f32_16x16x32_bf16 v[12:15], v[212:215], v[204:207], v[12:15]
	v_mfma_f32_16x16x32_bf16 v[8:11], v[220:223], v[204:207], v[8:11]
	v_mfma_f32_16x16x32_bf16 v[36:39], v[216:219], v[162:165], v[36:39]
	v_mfma_f32_16x16x32_bf16 v[32:35], v[224:227], v[162:165], v[32:35]
	v_mfma_f32_16x16x32_bf16 v[28:31], v[216:219], v[182:185], v[28:31]
	v_mfma_f32_16x16x32_bf16 v[24:27], v[224:227], v[182:185], v[24:27]
	v_mfma_f32_16x16x32_bf16 v[20:23], v[216:219], v[200:203], v[20:23]
	v_mfma_f32_16x16x32_bf16 v[16:19], v[224:227], v[200:203], v[16:19]
	v_mfma_f32_16x16x32_bf16 v[12:15], v[216:219], v[208:211], v[12:15]
	v_mfma_f32_16x16x32_bf16 v[8:11], v[224:227], v[208:211], v[8:11]
	s_barrier
	s_add_i32 s4, 0, 0x18000
	v_add_u32_e32 v0, s4, v175
	ds_read_b128 v[136:139], v0
	ds_read_b128 v[140:143], v0 offset:1024
	ds_read_b128 v[144:147], v0 offset:2048
	ds_read_b128 v[148:151], v0 offset:3072
	s_mov_b32 m0, s24
	v_lshl_add_u64 v[172:173], v[166:167], 0, s[88:89]
	ds_read_b128 v[158:161], v176 offset:32768
	ds_read_b128 v[162:165], v176 offset:33792
	ds_read_b128 v[178:181], v176 offset:34816
	ds_read_b128 v[182:185], v176 offset:35840
	ds_read_b128 v[196:199], v176 offset:36864
	ds_read_b128 v[200:203], v176 offset:37888
	ds_read_b128 v[204:207], v176 offset:38912
	ds_read_b128 v[208:211], v176 offset:39936
	global_load_lds_dwordx4 v[172:173], off
	v_lshl_add_u64 v[172:173], v[166:167], 0, s[64:65]
	s_mov_b32 m0, s25
	s_nop 0
	global_load_lds_dwordx4 v[172:173], off
	s_waitcnt lgkmcnt(8)
	s_barrier
	s_waitcnt lgkmcnt(0)
	v_mfma_f32_16x16x32_bf16 v[104:107], v[136:139], v[158:161], v[104:107]
	v_mfma_f32_16x16x32_bf16 v[108:111], v[144:147], v[158:161], v[108:111]
	v_mfma_f32_16x16x32_bf16 v[132:135], v[136:139], v[178:181], v[132:135]
	v_mfma_f32_16x16x32_bf16 v[128:131], v[144:147], v[178:181], v[128:131]
	v_mfma_f32_16x16x32_bf16 v[124:127], v[136:139], v[196:199], v[124:127]
	v_mfma_f32_16x16x32_bf16 v[120:123], v[144:147], v[196:199], v[120:123]
	v_mfma_f32_16x16x32_bf16 v[116:119], v[136:139], v[204:207], v[116:119]
	v_mfma_f32_16x16x32_bf16 v[112:115], v[144:147], v[204:207], v[112:115]
	v_mfma_f32_16x16x32_bf16 v[104:107], v[140:143], v[162:165], v[104:107]
	v_mfma_f32_16x16x32_bf16 v[108:111], v[148:151], v[162:165], v[108:111]
	v_mfma_f32_16x16x32_bf16 v[132:135], v[140:143], v[182:185], v[132:135]
	v_mfma_f32_16x16x32_bf16 v[128:131], v[148:151], v[182:185], v[128:131]
	v_mfma_f32_16x16x32_bf16 v[124:127], v[140:143], v[200:203], v[124:127]
	v_mfma_f32_16x16x32_bf16 v[120:123], v[148:151], v[200:203], v[120:123]
	v_mfma_f32_16x16x32_bf16 v[116:119], v[140:143], v[208:211], v[116:119]
	v_mfma_f32_16x16x32_bf16 v[112:115], v[148:151], v[208:211], v[112:115]
	s_barrier
	s_add_i32 s5, 0, 0x1c000
	s_add_i32 s4, s4, s21
	v_add_u32_e32 v0, s5, v175
	v_lshl_add_u64 v[172:173], v[2:3], 0, s[46:47]
	s_mov_b32 m0, s4
	ds_read_b128 v[212:215], v0
	ds_read_b128 v[216:219], v0 offset:1024
	ds_read_b128 v[220:223], v0 offset:2048
	ds_read_b128 v[224:227], v0 offset:3072
	global_load_lds_dwordx4 v[172:173], off
	v_lshl_add_u64 v[172:173], v[2:3], 0, s[54:55]
	s_add_i32 m0, s4, 0x2000
	s_nop 0
	global_load_lds_dwordx4 v[172:173], off
	s_barrier
; #define G_STAGE(bufoff, gbase, o0, h64) do { \
;         __builtin_amdgcn_global_load_lds((const unsigned*)((const char*)(gbase) + (o0)), (LAS unsigned*)(lds + (bufoff) + ldsw), 16, 0, 0); \
;         __builtin_amdgcn_global_load_lds((const unsigned*)((const char*)(gbase) + (h64) + (o0)), (LAS unsigned*)(lds + (bufoff) + ldsw + 8192), 16, 0, 0); } while (0)
; #define G_WAIT_V(n) asm volatile("s_waitcnt vmcnt(" #n ")" ::: "memory")
; #define G_WAIT_L(n) asm volatile("s_waitcnt lgkmcnt(" #n ")" ::: "memory")
; #define G_BAR __builtin_amdgcn_s_barrier()
; #define G_SCHED __builtin_amdgcn_sched_barrier(0)
;     ...
;             G_BAR; G_WAIT_L(0); G_MMA(1, 0, At, B0); G_BAR; G_SCHED;
;             G_STAGE(G_SB(1, 1), b3 + chB, cB0, qB);
;             G_WAIT_V(6); G_BAR; G_MMA(1, 1, At, B1); G_BAR;
;         }
	s_waitcnt lgkmcnt(0)
	v_mfma_f32_16x16x32_bf16 v[100:103], v[212:215], v[158:161], v[100:103]
	v_mfma_f32_16x16x32_bf16 v[96:99], v[220:223], v[158:161], v[96:99]
	v_mfma_f32_16x16x32_bf16 v[92:95], v[212:215], v[178:181], v[92:95]
	v_mfma_f32_16x16x32_bf16 v[88:91], v[220:223], v[178:181], v[88:91]
	v_mfma_f32_16x16x32_bf16 v[84:87], v[212:215], v[196:199], v[84:87]
	v_mfma_f32_16x16x32_bf16 v[80:83], v[220:223], v[196:199], v[80:83]
	v_mfma_f32_16x16x32_bf16 v[76:79], v[212:215], v[204:207], v[76:79]
	v_mfma_f32_16x16x32_bf16 v[72:75], v[220:223], v[204:207], v[72:75]
	v_mfma_f32_16x16x32_bf16 v[100:103], v[216:219], v[162:165], v[100:103]
	v_mfma_f32_16x16x32_bf16 v[96:99], v[224:227], v[162:165], v[96:99]
	v_mfma_f32_16x16x32_bf16 v[92:95], v[216:219], v[182:185], v[92:95]
	v_mfma_f32_16x16x32_bf16 v[88:91], v[224:227], v[182:185], v[88:91]
	v_mfma_f32_16x16x32_bf16 v[84:87], v[216:219], v[200:203], v[84:87]
	v_mfma_f32_16x16x32_bf16 v[80:83], v[224:227], v[200:203], v[80:83]
	v_mfma_f32_16x16x32_bf16 v[76:79], v[216:219], v[208:211], v[76:79]
	v_mfma_f32_16x16x32_bf16 v[72:75], v[224:227], v[208:211], v[72:75]
	s_barrier
	s_mov_b32 m0, s26
	v_lshl_add_u64 v[172:173], v[166:167], 0, s[46:47]
	ds_read_b128 v[158:161], v176 offset:49152
	ds_read_b128 v[162:165], v176 offset:50176
	ds_read_b128 v[178:181], v176 offset:51200
	ds_read_b128 v[182:185], v176 offset:52224
	ds_read_b128 v[196:199], v176 offset:53248
	ds_read_b128 v[200:203], v176 offset:54272
	ds_read_b128 v[204:207], v176 offset:55296
	ds_read_b128 v[208:211], v176 offset:56320
	global_load_lds_dwordx4 v[172:173], off
	v_lshl_add_u64 v[166:167], v[166:167], 0, s[66:67]
	s_mov_b32 m0, s27
	s_nop 0
	global_load_lds_dwordx4 v[166:167], off
	s_barrier
	s_waitcnt lgkmcnt(0)
	v_mfma_f32_16x16x32_bf16 v[68:71], v[136:139], v[158:161], v[68:71]
	v_mfma_f32_16x16x32_bf16 v[64:67], v[144:147], v[158:161], v[64:67]
	v_mfma_f32_16x16x32_bf16 v[60:63], v[136:139], v[178:181], v[60:63]
	v_mfma_f32_16x16x32_bf16 v[56:59], v[144:147], v[178:181], v[56:59]
	v_mfma_f32_16x16x32_bf16 v[52:55], v[136:139], v[196:199], v[52:55]
	v_mfma_f32_16x16x32_bf16 v[48:51], v[144:147], v[196:199], v[48:51]
	v_mfma_f32_16x16x32_bf16 v[44:47], v[136:139], v[204:207], v[44:47]
	v_mfma_f32_16x16x32_bf16 v[40:43], v[144:147], v[204:207], v[40:43]
	v_mfma_f32_16x16x32_bf16 v[68:71], v[140:143], v[162:165], v[68:71]
	v_mfma_f32_16x16x32_bf16 v[64:67], v[148:151], v[162:165], v[64:67]
	v_mfma_f32_16x16x32_bf16 v[60:63], v[140:143], v[182:185], v[60:63]
	v_mfma_f32_16x16x32_bf16 v[56:59], v[148:151], v[182:185], v[56:59]
	v_mfma_f32_16x16x32_bf16 v[52:55], v[140:143], v[200:203], v[52:55]
	v_mfma_f32_16x16x32_bf16 v[48:51], v[148:151], v[200:203], v[48:51]
	v_mfma_f32_16x16x32_bf16 v[44:47], v[140:143], v[208:211], v[44:47]
	v_mfma_f32_16x16x32_bf16 v[40:43], v[148:151], v[208:211], v[40:43]
	s_barrier
	s_add_i32 s4, s5, s21
	v_lshl_add_u64 v[136:137], v[2:3], 0, s[50:51]
	s_mov_b32 m0, s4
	v_lshl_add_u64 v[2:3], v[2:3], 0, s[58:59]
	global_load_lds_dwordx4 v[136:137], off
	s_add_i32 m0, s4, 0x2000
	s_nop 0
	global_load_lds_dwordx4 v[2:3], off
	s_add_i32 s18, s18, 2
	s_add_u32 s6, s6, 0x100
	s_addc_u32 s7, s7, 0
	s_add_u32 s8, s8, 0x100
	s_addc_u32 s9, s9, 0
	s_cmp_gt_u32 s18, 5
	s_waitcnt vmcnt(6)
	s_barrier
	v_mfma_f32_16x16x32_bf16 v[36:39], v[212:215], v[158:161], v[36:39]
	v_mfma_f32_16x16x32_bf16 v[32:35], v[220:223], v[158:161], v[32:35]
	v_mfma_f32_16x16x32_bf16 v[28:31], v[212:215], v[178:181], v[28:31]
	v_mfma_f32_16x16x32_bf16 v[24:27], v[220:223], v[178:181], v[24:27]
	v_mfma_f32_16x16x32_bf16 v[20:23], v[212:215], v[196:199], v[20:23]
	v_mfma_f32_16x16x32_bf16 v[16:19], v[220:223], v[196:199], v[16:19]
	v_mfma_f32_16x16x32_bf16 v[12:15], v[212:215], v[204:207], v[12:15]
	v_mfma_f32_16x16x32_bf16 v[8:11], v[220:223], v[204:207], v[8:11]
	v_mfma_f32_16x16x32_bf16 v[36:39], v[216:219], v[162:165], v[36:39]
	v_mfma_f32_16x16x32_bf16 v[32:35], v[224:227], v[162:165], v[32:35]
	v_mfma_f32_16x16x32_bf16 v[28:31], v[216:219], v[182:185], v[28:31]
	v_mfma_f32_16x16x32_bf16 v[24:27], v[224:227], v[182:185], v[24:27]
	v_mfma_f32_16x16x32_bf16 v[20:23], v[216:219], v[200:203], v[20:23]
	v_mfma_f32_16x16x32_bf16 v[16:19], v[224:227], v[200:203], v[16:19]
	v_mfma_f32_16x16x32_bf16 v[12:15], v[216:219], v[208:211], v[12:15]
	v_mfma_f32_16x16x32_bf16 v[8:11], v[224:227], v[208:211], v[8:11]
	s_cbranch_scc0 .Ldb_MG1_cont
	v_readfirstlane_b32 s101, v186
	s_cmpk_gt_u32 s101, 0xff
	s_cbranch_scc1 .Ldb_MG1_young
	s_barrier
	s_mov_b32 s101, 1
	s_branch .Ldb_MG1_exit

; #define G_STAGE(bufoff, gbase, o0, h64) do { \
;         __builtin_amdgcn_global_load_lds((const unsigned*)((const char*)(gbase) + (o0)), (LAS unsigned*)(lds + (bufoff) + ldsw), 16, 0, 0); \
;         __builtin_amdgcn_global_load_lds((const unsigned*)((const char*)(gbase) + (h64) + (o0)), (LAS unsigned*)(lds + (bufoff) + ldsw + 8192), 16, 0, 0); } while (0)
; #define G_LDA(dst, b, h) do { _Pragma("unroll") for (int m = 0; m < 4; ++m) _Pragma("unroll") for (int k = 0; k < 2; ++k) dst[m][k] = *(const LAS bf16x8*)(lds + G_SA(b, h) + aoff + m * 2048 + k * 1024); } while (0)
; #define G_LDB(dst, b, h) do { _Pragma("unroll") for (int n = 0; n < 2; ++n) _Pragma("unroll") for (int k = 0; k < 2; ++k) dst[n][k] = *(const LAS bf16x8*)(lds + G_SB(b, h) + boff + n * 2048 + k * 1024); } while (0)
; #define G_WAIT_L(n) asm volatile("s_waitcnt lgkmcnt(" #n ")" ::: "memory")
; #define G_BAR __builtin_amdgcn_s_barrier()
; #define G_SCHED __builtin_amdgcn_sched_barrier(0)
;     ...
;             G_LDB(B0, 0, 0); G_SCHED; G_LDA(At, 0, 0); G_STAGE(G_SA(1, 1), a1 + chA, cA0, qA);
;             G_WAIT_L(8); G_BAR; G_WAIT_L(0); G_MMA(0, 0, At, B0); G_BAR; G_SCHED;
;             G_LDB(B1, 0, 1); G_STAGE(G_SB(0, 0), b2, cB0, qB);
;             G_BAR; G_WAIT_L(0); G_MMA(0, 1, At, B1); G_BAR;
;     ...
;         if (!(cs.kind == K_MG_B && cur.aux < 2))
; #pragma unroll
;         for (int a = 0; a < 2; ++a)
; #pragma unroll
;             for (int b = 0; b < 2; ++b)
; #pragma unroll
;                 for (int m = 0; m < 4; ++m)
; #pragma unroll
;                     for (int n = 0; n < 2; ++n) acc[a][b][m][n] = (f32x4){0.f, 0.f, 0.f, 0.f};
.LBB0_1036:
	s_add_u32 s2, s2, 0x40080
	s_addc_u32 s3, s3, 0
	s_add_u32 s6, s6, 0x100
	s_waitcnt lgkmcnt(0)
	v_mov_b64_e32 v[8:9], 0
	s_addc_u32 s7, s7, 0
	s_mov_b32 s15, -2
	v_mov_b64_e32 v[10:11], 0
	v_mov_b64_e32 v[12:13], 0
	v_mov_b64_e32 v[14:15], 0
	v_mov_b64_e32 v[24:25], 0
	v_mov_b64_e32 v[26:27], 0
	v_mov_b64_e32 v[28:29], 0
	v_mov_b64_e32 v[30:31], 0
	v_mov_b64_e32 v[40:41], 0
	v_mov_b64_e32 v[42:43], 0
	v_mov_b64_e32 v[44:45], 0
	v_mov_b64_e32 v[46:47], 0
	v_mov_b64_e32 v[56:57], 0
	v_mov_b64_e32 v[58:59], 0
	v_mov_b64_e32 v[60:61], 0
	v_mov_b64_e32 v[62:63], 0
	v_mov_b64_e32 v[16:17], 0
	v_mov_b64_e32 v[18:19], 0
	v_mov_b64_e32 v[20:21], 0
	v_mov_b64_e32 v[22:23], 0
	v_mov_b64_e32 v[32:33], 0
	v_mov_b64_e32 v[34:35], 0
	v_mov_b64_e32 v[36:37], 0
	v_mov_b64_e32 v[38:39], 0
	v_mov_b64_e32 v[48:49], 0
	v_mov_b64_e32 v[50:51], 0
	v_mov_b64_e32 v[52:53], 0
	v_mov_b64_e32 v[54:55], 0
	v_mov_b64_e32 v[64:65], 0
	v_mov_b64_e32 v[66:67], 0
	v_mov_b64_e32 v[68:69], 0
	v_mov_b64_e32 v[70:71], 0
	v_mov_b64_e32 v[72:73], 0
	v_mov_b64_e32 v[74:75], 0
	v_mov_b64_e32 v[76:77], 0
	v_mov_b64_e32 v[78:79], 0
	v_mov_b64_e32 v[88:89], 0
	v_mov_b64_e32 v[90:91], 0
	v_mov_b64_e32 v[92:93], 0
	v_mov_b64_e32 v[94:95], 0
	v_mov_b64_e32 v[104:105], 0
	v_mov_b64_e32 v[106:107], 0
	v_mov_b64_e32 v[108:109], 0
	v_mov_b64_e32 v[110:111], 0
	v_mov_b64_e32 v[120:121], 0
	v_mov_b64_e32 v[122:123], 0
	v_mov_b64_e32 v[124:125], 0
	v_mov_b64_e32 v[126:127], 0
	v_mov_b64_e32 v[80:81], 0
	v_mov_b64_e32 v[82:83], 0
	v_mov_b64_e32 v[84:85], 0
	v_mov_b64_e32 v[86:87], 0
	v_mov_b64_e32 v[96:97], 0
	v_mov_b64_e32 v[98:99], 0
	v_mov_b64_e32 v[100:101], 0
	v_mov_b64_e32 v[102:103], 0
	v_mov_b64_e32 v[112:113], 0
	v_mov_b64_e32 v[114:115], 0
	v_mov_b64_e32 v[116:117], 0
	v_mov_b64_e32 v[118:119], 0
	v_mov_b64_e32 v[128:129], 0
	v_mov_b64_e32 v[130:131], 0
	v_mov_b64_e32 v[132:133], 0
	v_mov_b64_e32 v[134:135], 0
	s_mov_b64 s[42:43], 0x40000
	s_mov_b64 s[50:51], 0x60000
	s_mov_b64 s[52:53], 0x20080
	s_mov_b64 s[54:55], 0x40080
	s_mov_b64 s[58:59], 0x60080
	s_cmp_eq_u32 s101, 2
	s_cselect_b32 s101, 0, s101
.LBB0_1037:
	s_add_u32 s4, s2, 0xfffc0080
	s_addc_u32 s5, s3, -1
	s_add_i32 s33, 0, 0x10000
	v_add_u32_e32 v0, s33, v181
	ds_read_b128 v[136:139], v0
	ds_read_b128 v[140:143], v0 offset:1024
	ds_read_b128 v[144:147], v0 offset:2048
	ds_read_b128 v[148:151], v0 offset:3072
	s_cmp_eq_u32 s15, 12
	s_cselect_b32 s5, s17, s5
	s_cselect_b32 s4, s16, s4
	s_cselect_b32 s21, s19, s7
	s_cselect_b32 s20, s18, s6
	v_lshl_add_u64 v[184:185], s[2:3], 0, v[166:167]
	s_add_i32 m0, s24, 0xc000
	ds_read_b128 v[152:155], v182
	ds_read_b128 v[156:159], v182 offset:1024
	ds_read_b128 v[160:163], v182 offset:2048
	ds_read_b128 v[172:175], v182 offset:3072
	ds_read_b128 v[176:179], v182 offset:4096
	ds_read_b128 v[196:199], v182 offset:5120
	ds_read_b128 v[200:203], v182 offset:6144
	ds_read_b128 v[204:207], v182 offset:7168
	global_load_lds_dwordx4 v[184:185], off
	v_lshl_add_u64 v[184:185], v[184:185], 0, s[0:1]
	s_add_i32 m0, s24, 0xe000
	s_nop 0
	global_load_lds_dwordx4 v[184:185], off
	s_waitcnt lgkmcnt(8)
	s_cmp_eq_u32 s101, 1
	s_cbranch_scc1 .Ldb_WOUT_sk
	s_barrier
.Ldb_WOUT_sk:
	s_mov_b32 s101, 0
	s_waitcnt lgkmcnt(0)
	v_mfma_f32_16x16x32_bf16 v[132:135], v[136:139], v[152:155], v[132:135]
	v_mfma_f32_16x16x32_bf16 v[128:131], v[144:147], v[152:155], v[128:131]
	v_mfma_f32_16x16x32_bf16 v[116:119], v[136:139], v[160:163], v[116:119]
	v_mfma_f32_16x16x32_bf16 v[112:115], v[144:147], v[160:163], v[112:115]
	v_mfma_f32_16x16x32_bf16 v[100:103], v[136:139], v[176:179], v[100:103]
	v_mfma_f32_16x16x32_bf16 v[96:99], v[144:147], v[176:179], v[96:99]
	v_mfma_f32_16x16x32_bf16 v[84:87], v[136:139], v[200:203], v[84:87]
	v_mfma_f32_16x16x32_bf16 v[80:83], v[144:147], v[200:203], v[80:83]
	v_mfma_f32_16x16x32_bf16 v[132:135], v[140:143], v[156:159], v[132:135]
	v_mfma_f32_16x16x32_bf16 v[128:131], v[148:151], v[156:159], v[128:131]
	v_mfma_f32_16x16x32_bf16 v[116:119], v[140:143], v[172:175], v[116:119]
	v_mfma_f32_16x16x32_bf16 v[112:115], v[148:151], v[172:175], v[112:115]
	v_mfma_f32_16x16x32_bf16 v[100:103], v[140:143], v[196:199], v[100:103]
	v_mfma_f32_16x16x32_bf16 v[96:99], v[148:151], v[196:199], v[96:99]
	v_mfma_f32_16x16x32_bf16 v[84:87], v[140:143], v[204:207], v[84:87]
	v_mfma_f32_16x16x32_bf16 v[80:83], v[148:151], v[204:207], v[80:83]
	s_barrier
	s_add_i32 s41, 0, 0x14000
	v_lshl_add_u64 v[184:185], s[20:21], 0, v[164:165]
	s_add_i32 s20, s33, s23
	v_add_u32_e32 v0, s41, v181
	s_mov_b32 m0, s20
	ds_read_b128 v[208:211], v0
	ds_read_b128 v[212:215], v0 offset:1024
	ds_read_b128 v[216:219], v0 offset:2048
	ds_read_b128 v[220:223], v0 offset:3072
	global_load_lds_dwordx4 v[184:185], off
	v_lshl_add_u64 v[224:225], v[184:185], 0, s[0:1]
	s_add_i32 m0, s20, 0x2000
	s_nop 0
	global_load_lds_dwordx4 v[224:225], off
	s_barrier
	s_waitcnt lgkmcnt(0)
	v_mfma_f32_16x16x32_bf16 v[124:127], v[208:211], v[152:155], v[124:127]
	v_mfma_f32_16x16x32_bf16 v[120:123], v[216:219], v[152:155], v[120:123]
	v_mfma_f32_16x16x32_bf16 v[108:111], v[208:211], v[160:163], v[108:111]
	v_mfma_f32_16x16x32_bf16 v[104:107], v[216:219], v[160:163], v[104:107]
	v_mfma_f32_16x16x32_bf16 v[92:95], v[208:211], v[176:179], v[92:95]
	v_mfma_f32_16x16x32_bf16 v[88:91], v[216:219], v[176:179], v[88:91]
	v_mfma_f32_16x16x32_bf16 v[76:79], v[208:211], v[200:203], v[76:79]
	v_mfma_f32_16x16x32_bf16 v[72:75], v[216:219], v[200:203], v[72:75]
	v_mfma_f32_16x16x32_bf16 v[124:127], v[212:215], v[156:159], v[124:127]
	v_mfma_f32_16x16x32_bf16 v[120:123], v[220:223], v[156:159], v[120:123]
	v_mfma_f32_16x16x32_bf16 v[108:111], v[212:215], v[172:175], v[108:111]
	v_mfma_f32_16x16x32_bf16 v[104:107], v[220:223], v[172:175], v[104:107]
	v_mfma_f32_16x16x32_bf16 v[92:95], v[212:215], v[196:199], v[92:95]
	v_mfma_f32_16x16x32_bf16 v[88:91], v[220:223], v[196:199], v[88:91]
	v_mfma_f32_16x16x32_bf16 v[76:79], v[212:215], v[204:207], v[76:79]
	v_mfma_f32_16x16x32_bf16 v[72:75], v[220:223], v[204:207], v[72:75]
	s_barrier
; #define G_STAGE(bufoff, gbase, o0, h64) do { \
;         __builtin_amdgcn_global_load_lds((const unsigned*)((const char*)(gbase) + (o0)), (LAS unsigned*)(lds + (bufoff) + ldsw), 16, 0, 0); \
;         __builtin_amdgcn_global_load_lds((const unsigned*)((const char*)(gbase) + (h64) + (o0)), (LAS unsigned*)(lds + (bufoff) + ldsw + 8192), 16, 0, 0); } while (0)
; #define G_LDA(dst, b, h) do { _Pragma("unroll") for (int m = 0; m < 4; ++m) _Pragma("unroll") for (int k = 0; k < 2; ++k) dst[m][k] = *(const LAS bf16x8*)(lds + G_SA(b, h) + aoff + m * 2048 + k * 1024); } while (0)
; #define G_LDB(dst, b, h) do { _Pragma("unroll") for (int n = 0; n < 2; ++n) _Pragma("unroll") for (int k = 0; k < 2; ++k) dst[n][k] = *(const LAS bf16x8*)(lds + G_SB(b, h) + boff + n * 2048 + k * 1024); } while (0)
; #define G_WAIT_V(n) asm volatile("s_waitcnt vmcnt(" #n ")" ::: "memory")
; #define G_WAIT_L(n) asm volatile("s_waitcnt lgkmcnt(" #n ")" ::: "memory")
; #define G_BAR __builtin_amdgcn_s_barrier()
; #define G_SCHED __builtin_amdgcn_sched_barrier(0)
;     ...
;             G_LDA(At, 0, 1); G_STAGE(G_SA(0, 0), a2, cA0, qA);
;             G_BAR; G_WAIT_L(0); G_MMA(1, 0, At, B0); G_BAR; G_SCHED;
;             G_STAGE(G_SB(0, 1), b2 + chB, cB0, qB);
;             G_WAIT_V(6); G_BAR; G_MMA(1, 1, At, B1); G_BAR;
;             G_LDB(B0, 1, 0); G_SCHED; G_LDA(At, 1, 0); G_STAGE(G_SA(0, 1), a2 + chA, cA0, qA);
;             G_WAIT_L(8); G_BAR; G_WAIT_L(0); G_MMA(0, 0, At, B0); G_BAR; G_SCHED;
;             G_LDB(B1, 1, 1); G_STAGE(G_SB(1, 0), b3, cB0, qB);
;             G_BAR; G_WAIT_L(0); G_MMA(0, 1, At, B1); G_BAR;
;             G_LDA(At, 1, 1); G_STAGE(G_SA(1, 0), a3, cA0, qA);
;             G_BAR; G_WAIT_L(0); G_MMA(1, 0, At, B0); G_BAR; G_SCHED;
	s_mov_b32 m0, s24
	v_lshl_add_u64 v[224:225], s[4:5], 0, v[2:3]
	ds_read_b128 v[152:155], v182 offset:16384
	ds_read_b128 v[156:159], v182 offset:17408
	ds_read_b128 v[160:163], v182 offset:18432
	ds_read_b128 v[172:175], v182 offset:19456
	ds_read_b128 v[176:179], v182 offset:20480
	ds_read_b128 v[196:199], v182 offset:21504
	ds_read_b128 v[200:203], v182 offset:22528
	ds_read_b128 v[204:207], v182 offset:23552
	global_load_lds_dwordx4 v[224:225], off
	v_lshl_add_u64 v[226:227], v[224:225], 0, s[0:1]
	s_mov_b32 m0, s25
	s_nop 0
	global_load_lds_dwordx4 v[226:227], off
	s_barrier
	s_waitcnt lgkmcnt(0)
	v_mfma_f32_16x16x32_bf16 v[68:71], v[136:139], v[152:155], v[68:71]
	v_mfma_f32_16x16x32_bf16 v[64:67], v[144:147], v[152:155], v[64:67]
	v_mfma_f32_16x16x32_bf16 v[52:55], v[136:139], v[160:163], v[52:55]
	v_mfma_f32_16x16x32_bf16 v[48:51], v[144:147], v[160:163], v[48:51]
	v_mfma_f32_16x16x32_bf16 v[36:39], v[136:139], v[176:179], v[36:39]
	v_mfma_f32_16x16x32_bf16 v[32:35], v[144:147], v[176:179], v[32:35]
	v_mfma_f32_16x16x32_bf16 v[20:23], v[136:139], v[200:203], v[20:23]
	v_mfma_f32_16x16x32_bf16 v[16:19], v[144:147], v[200:203], v[16:19]
	v_mfma_f32_16x16x32_bf16 v[68:71], v[140:143], v[156:159], v[68:71]
	v_mfma_f32_16x16x32_bf16 v[64:67], v[148:151], v[156:159], v[64:67]
	v_mfma_f32_16x16x32_bf16 v[52:55], v[140:143], v[172:175], v[52:55]
	v_mfma_f32_16x16x32_bf16 v[48:51], v[148:151], v[172:175], v[48:51]
	v_mfma_f32_16x16x32_bf16 v[36:39], v[140:143], v[196:199], v[36:39]
	v_mfma_f32_16x16x32_bf16 v[32:35], v[148:151], v[196:199], v[32:35]
	v_mfma_f32_16x16x32_bf16 v[20:23], v[140:143], v[204:207], v[20:23]
	v_mfma_f32_16x16x32_bf16 v[16:19], v[148:151], v[204:207], v[16:19]
	s_barrier
	s_add_i32 s4, s41, s23
	v_lshl_add_u64 v[136:137], v[184:185], 0, s[42:43]
	s_mov_b32 m0, s4
	s_nop 0
	global_load_lds_dwordx4 v[136:137], off
	v_lshl_add_u64 v[136:137], v[184:185], 0, s[50:51]
	s_add_i32 m0, s4, 0x2000
	s_nop 0
	global_load_lds_dwordx4 v[136:137], off
	s_waitcnt vmcnt(6)
	s_barrier
	v_mfma_f32_16x16x32_bf16 v[60:63], v[208:211], v[152:155], v[60:63]
	v_mfma_f32_16x16x32_bf16 v[56:59], v[216:219], v[152:155], v[56:59]
	v_mfma_f32_16x16x32_bf16 v[44:47], v[208:211], v[160:163], v[44:47]
	v_mfma_f32_16x16x32_bf16 v[40:43], v[216:219], v[160:163], v[40:43]
	v_mfma_f32_16x16x32_bf16 v[28:31], v[208:211], v[176:179], v[28:31]
	v_mfma_f32_16x16x32_bf16 v[24:27], v[216:219], v[176:179], v[24:27]
	v_mfma_f32_16x16x32_bf16 v[12:15], v[208:211], v[200:203], v[12:15]
	v_mfma_f32_16x16x32_bf16 v[8:11], v[216:219], v[200:203], v[8:11]
	v_mfma_f32_16x16x32_bf16 v[60:63], v[212:215], v[156:159], v[60:63]
	v_mfma_f32_16x16x32_bf16 v[56:59], v[220:223], v[156:159], v[56:59]
	v_mfma_f32_16x16x32_bf16 v[44:47], v[212:215], v[172:175], v[44:47]
	v_mfma_f32_16x16x32_bf16 v[40:43], v[220:223], v[172:175], v[40:43]
	v_mfma_f32_16x16x32_bf16 v[28:31], v[212:215], v[196:199], v[28:31]
	v_mfma_f32_16x16x32_bf16 v[24:27], v[220:223], v[196:199], v[24:27]
	v_mfma_f32_16x16x32_bf16 v[12:15], v[212:215], v[204:207], v[12:15]
	v_mfma_f32_16x16x32_bf16 v[8:11], v[220:223], v[204:207], v[8:11]
	s_barrier
	s_add_i32 s4, 0, 0x18000
	v_add_u32_e32 v0, s4, v181
	ds_read_b128 v[136:139], v0
	ds_read_b128 v[140:143], v0 offset:1024
	ds_read_b128 v[144:147], v0 offset:2048
	ds_read_b128 v[148:151], v0 offset:3072
	s_mov_b32 m0, s26
	v_lshl_add_u64 v[208:209], v[224:225], 0, s[42:43]
	ds_read_b128 v[152:155], v182 offset:32768
	ds_read_b128 v[156:159], v182 offset:33792
	ds_read_b128 v[160:163], v182 offset:34816
	ds_read_b128 v[172:175], v182 offset:35840
	ds_read_b128 v[176:179], v182 offset:36864
	ds_read_b128 v[196:199], v182 offset:37888
	ds_read_b128 v[200:203], v182 offset:38912
	ds_read_b128 v[204:207], v182 offset:39936
	global_load_lds_dwordx4 v[208:209], off
	v_lshl_add_u64 v[208:209], v[224:225], 0, s[50:51]
	s_mov_b32 m0, s27
	s_nop 0
	global_load_lds_dwordx4 v[208:209], off
	s_waitcnt lgkmcnt(8)
	s_barrier
	s_waitcnt lgkmcnt(0)
	v_mfma_f32_16x16x32_bf16 v[132:135], v[136:139], v[152:155], v[132:135]
	v_mfma_f32_16x16x32_bf16 v[128:131], v[144:147], v[152:155], v[128:131]
	v_mfma_f32_16x16x32_bf16 v[116:119], v[136:139], v[160:163], v[116:119]
	v_mfma_f32_16x16x32_bf16 v[112:115], v[144:147], v[160:163], v[112:115]
	v_mfma_f32_16x16x32_bf16 v[100:103], v[136:139], v[176:179], v[100:103]
	v_mfma_f32_16x16x32_bf16 v[96:99], v[144:147], v[176:179], v[96:99]
	v_mfma_f32_16x16x32_bf16 v[84:87], v[136:139], v[200:203], v[84:87]
	v_mfma_f32_16x16x32_bf16 v[80:83], v[144:147], v[200:203], v[80:83]
	v_mfma_f32_16x16x32_bf16 v[132:135], v[140:143], v[156:159], v[132:135]
	v_mfma_f32_16x16x32_bf16 v[128:131], v[148:151], v[156:159], v[128:131]
	v_mfma_f32_16x16x32_bf16 v[116:119], v[140:143], v[172:175], v[116:119]
	v_mfma_f32_16x16x32_bf16 v[112:115], v[148:151], v[172:175], v[112:115]
	v_mfma_f32_16x16x32_bf16 v[100:103], v[140:143], v[196:199], v[100:103]
	v_mfma_f32_16x16x32_bf16 v[96:99], v[148:151], v[196:199], v[96:99]
	v_mfma_f32_16x16x32_bf16 v[84:87], v[140:143], v[204:207], v[84:87]
	v_mfma_f32_16x16x32_bf16 v[80:83], v[148:151], v[204:207], v[80:83]
	s_barrier
; #define G_STAGE(bufoff, gbase, o0, h64) do { \
;         __builtin_amdgcn_global_load_lds((const unsigned*)((const char*)(gbase) + (o0)), (LAS unsigned*)(lds + (bufoff) + ldsw), 16, 0, 0); \
;         __builtin_amdgcn_global_load_lds((const unsigned*)((const char*)(gbase) + (h64) + (o0)), (LAS unsigned*)(lds + (bufoff) + ldsw + 8192), 16, 0, 0); } while (0)
; #define G_LDA(dst, b, h) do { _Pragma("unroll") for (int m = 0; m < 4; ++m) _Pragma("unroll") for (int k = 0; k < 2; ++k) dst[m][k] = *(const LAS bf16x8*)(lds + G_SA(b, h) + aoff + m * 2048 + k * 1024); } while (0)
; #define G_LDB(dst, b, h) do { _Pragma("unroll") for (int n = 0; n < 2; ++n) _Pragma("unroll") for (int k = 0; k < 2; ++k) dst[n][k] = *(const LAS bf16x8*)(lds + G_SB(b, h) + boff + n * 2048 + k * 1024); } while (0)
; #define G_WAIT_V(n) asm volatile("s_waitcnt vmcnt(" #n ")" ::: "memory")
; #define G_WAIT_L(n) asm volatile("s_waitcnt lgkmcnt(" #n ")" ::: "memory")
; #define G_BAR __builtin_amdgcn_s_barrier()
; #define G_SCHED __builtin_amdgcn_sched_barrier(0)
;     ...
;             G_WAIT_L(8); G_BAR; G_WAIT_L(0); G_MMA(0, 0, At, B0); G_BAR; G_SCHED;
;             G_LDB(B1, 1, 1); G_STAGE(G_SB(1, 0), b3, cB0, qB);
;             G_BAR; G_WAIT_L(0); G_MMA(0, 1, At, B1); G_BAR;
;             G_LDA(At, 1, 1); G_STAGE(G_SA(1, 0), a3, cA0, qA);
;             G_BAR; G_WAIT_L(0); G_MMA(1, 0, At, B0); G_BAR; G_SCHED;
;             G_STAGE(G_SB(1, 1), b3 + chB, cB0, qB);
;             G_WAIT_V(6); G_BAR; G_MMA(1, 1, At, B1); G_BAR;
;         }
	s_add_i32 s5, 0, 0x1c000
	s_add_i32 s4, s4, s23
	v_add_u32_e32 v0, s5, v181
	v_lshl_add_u64 v[226:227], v[184:185], 0, s[46:47]
	s_mov_b32 m0, s4
	ds_read_b128 v[208:211], v0
	ds_read_b128 v[212:215], v0 offset:1024
	ds_read_b128 v[216:219], v0 offset:2048
	ds_read_b128 v[220:223], v0 offset:3072
	global_load_lds_dwordx4 v[226:227], off
	v_lshl_add_u64 v[226:227], v[184:185], 0, s[52:53]
	s_add_i32 m0, s4, 0x2000
	s_nop 0
	global_load_lds_dwordx4 v[226:227], off
	s_barrier
	s_waitcnt lgkmcnt(0)
	v_mfma_f32_16x16x32_bf16 v[124:127], v[208:211], v[152:155], v[124:127]
	v_mfma_f32_16x16x32_bf16 v[120:123], v[216:219], v[152:155], v[120:123]
	v_mfma_f32_16x16x32_bf16 v[108:111], v[208:211], v[160:163], v[108:111]
	v_mfma_f32_16x16x32_bf16 v[104:107], v[216:219], v[160:163], v[104:107]
	v_mfma_f32_16x16x32_bf16 v[92:95], v[208:211], v[176:179], v[92:95]
	v_mfma_f32_16x16x32_bf16 v[88:91], v[216:219], v[176:179], v[88:91]
	v_mfma_f32_16x16x32_bf16 v[76:79], v[208:211], v[200:203], v[76:79]
	v_mfma_f32_16x16x32_bf16 v[72:75], v[216:219], v[200:203], v[72:75]
	v_mfma_f32_16x16x32_bf16 v[124:127], v[212:215], v[156:159], v[124:127]
	v_mfma_f32_16x16x32_bf16 v[120:123], v[220:223], v[156:159], v[120:123]
	v_mfma_f32_16x16x32_bf16 v[108:111], v[212:215], v[172:175], v[108:111]
	v_mfma_f32_16x16x32_bf16 v[104:107], v[220:223], v[172:175], v[104:107]
	v_mfma_f32_16x16x32_bf16 v[92:95], v[212:215], v[196:199], v[92:95]
	v_mfma_f32_16x16x32_bf16 v[88:91], v[220:223], v[196:199], v[88:91]
	v_mfma_f32_16x16x32_bf16 v[76:79], v[212:215], v[204:207], v[76:79]
	v_mfma_f32_16x16x32_bf16 v[72:75], v[220:223], v[204:207], v[72:75]
	s_barrier
	s_mov_b32 m0, s29
	v_lshl_add_u64 v[226:227], v[224:225], 0, s[46:47]
	ds_read_b128 v[152:155], v182 offset:49152
	ds_read_b128 v[156:159], v182 offset:50176
	ds_read_b128 v[160:163], v182 offset:51200
	ds_read_b128 v[172:175], v182 offset:52224
	ds_read_b128 v[176:179], v182 offset:53248
	ds_read_b128 v[196:199], v182 offset:54272
	ds_read_b128 v[200:203], v182 offset:55296
	ds_read_b128 v[204:207], v182 offset:56320
	global_load_lds_dwordx4 v[226:227], off
	v_lshl_add_u64 v[224:225], v[224:225], 0, s[52:53]
	s_mov_b32 m0, s30
	s_nop 0
	global_load_lds_dwordx4 v[224:225], off
	s_barrier
	s_waitcnt lgkmcnt(0)
	v_mfma_f32_16x16x32_bf16 v[68:71], v[136:139], v[152:155], v[68:71]
	v_mfma_f32_16x16x32_bf16 v[64:67], v[144:147], v[152:155], v[64:67]
	v_mfma_f32_16x16x32_bf16 v[52:55], v[136:139], v[160:163], v[52:55]
	v_mfma_f32_16x16x32_bf16 v[48:51], v[144:147], v[160:163], v[48:51]
	v_mfma_f32_16x16x32_bf16 v[36:39], v[136:139], v[176:179], v[36:39]
	v_mfma_f32_16x16x32_bf16 v[32:35], v[144:147], v[176:179], v[32:35]
	v_mfma_f32_16x16x32_bf16 v[20:23], v[136:139], v[200:203], v[20:23]
	v_mfma_f32_16x16x32_bf16 v[16:19], v[144:147], v[200:203], v[16:19]
	v_mfma_f32_16x16x32_bf16 v[68:71], v[140:143], v[156:159], v[68:71]
	v_mfma_f32_16x16x32_bf16 v[64:67], v[148:151], v[156:159], v[64:67]
	v_mfma_f32_16x16x32_bf16 v[52:55], v[140:143], v[172:175], v[52:55]
	v_mfma_f32_16x16x32_bf16 v[48:51], v[148:151], v[172:175], v[48:51]
	v_mfma_f32_16x16x32_bf16 v[36:39], v[140:143], v[196:199], v[36:39]
	v_mfma_f32_16x16x32_bf16 v[32:35], v[148:151], v[196:199], v[32:35]
	v_mfma_f32_16x16x32_bf16 v[20:23], v[140:143], v[204:207], v[20:23]
	v_mfma_f32_16x16x32_bf16 v[16:19], v[148:151], v[204:207], v[16:19]
	s_barrier
	s_add_i32 s4, s5, s23
	v_lshl_add_u64 v[136:137], v[184:185], 0, s[54:55]
	s_mov_b32 m0, s4
	s_nop 0
	global_load_lds_dwordx4 v[136:137], off
	v_lshl_add_u64 v[136:137], v[184:185], 0, s[58:59]
	s_add_i32 m0, s4, 0x2000
	s_nop 0
	global_load_lds_dwordx4 v[136:137], off
	s_add_i32 s15, s15, 2
	s_add_u32 s2, s2, 0x100
	s_addc_u32 s3, s3, 0
	s_add_u32 s6, s6, 0x100
	s_addc_u32 s7, s7, 0
	s_cmp_gt_u32 s15, 13
	s_waitcnt vmcnt(6)
	s_barrier
	v_mfma_f32_16x16x32_bf16 v[60:63], v[208:211], v[152:155], v[60:63]
	v_mfma_f32_16x16x32_bf16 v[56:59], v[216:219], v[152:155], v[56:59]
	v_mfma_f32_16x16x32_bf16 v[44:47], v[208:211], v[160:163], v[44:47]
	v_mfma_f32_16x16x32_bf16 v[40:43], v[216:219], v[160:163], v[40:43]
	v_mfma_f32_16x16x32_bf16 v[28:31], v[208:211], v[176:179], v[28:31]
	v_mfma_f32_16x16x32_bf16 v[24:27], v[216:219], v[176:179], v[24:27]
	v_mfma_f32_16x16x32_bf16 v[12:15], v[208:211], v[200:203], v[12:15]
	v_mfma_f32_16x16x32_bf16 v[8:11], v[216:219], v[200:203], v[8:11]
	v_mfma_f32_16x16x32_bf16 v[60:63], v[212:215], v[156:159], v[60:63]
	v_mfma_f32_16x16x32_bf16 v[56:59], v[220:223], v[156:159], v[56:59]
	v_mfma_f32_16x16x32_bf16 v[44:47], v[212:215], v[172:175], v[44:47]
	v_mfma_f32_16x16x32_bf16 v[40:43], v[220:223], v[172:175], v[40:43]
	v_mfma_f32_16x16x32_bf16 v[28:31], v[212:215], v[196:199], v[28:31]
	v_mfma_f32_16x16x32_bf16 v[24:27], v[220:223], v[196:199], v[24:27]
	v_mfma_f32_16x16x32_bf16 v[12:15], v[212:215], v[204:207], v[12:15]
	v_mfma_f32_16x16x32_bf16 v[8:11], v[220:223], v[204:207], v[8:11]
	s_cbranch_scc0 .Ldb_WOUT_cont
	v_readfirstlane_b32 s101, v186
	s_cmpk_gt_u32 s101, 0xff
	s_cbranch_scc1 .Ldb_WOUT_young
	s_barrier
	s_mov_b32 s101, 1
	s_branch .Ldb_WOUT_exit

; #define G_WAIT_V(n) asm volatile("s_waitcnt vmcnt(" #n ")" ::: "memory")
; #define G_BAR __builtin_amdgcn_s_barrier()
;     ...
;         if (!has_next) break;
;     ...
;     G_WAIT_V(0);
;     if (wr == 0) G_BAR;
;     G_BAR;
.Ldbj_WOUT_pe:
	s_mov_b32 s101, 0
	s_waitcnt vmcnt(0)
	s_cmpk_gt_u32 s22, 0xff
	s_cbranch_scc1 .LBB0_1056
	s_barrier

; #define G_STAGE(bufoff, gbase, o0, h64) do { \
;         __builtin_amdgcn_global_load_lds((const unsigned*)((const char*)(gbase) + (o0)), (LAS unsigned*)(lds + (bufoff) + ldsw), 16, 0, 0); \
;         __builtin_amdgcn_global_load_lds((const unsigned*)((const char*)(gbase) + (h64) + (o0)), (LAS unsigned*)(lds + (bufoff) + ldsw + 8192), 16, 0, 0); } while (0)
; #define G_LDA(dst, b, h) do { _Pragma("unroll") for (int m = 0; m < 4; ++m) _Pragma("unroll") for (int k = 0; k < 2; ++k) dst[m][k] = *(const LAS bf16x8*)(lds + G_SA(b, h) + aoff + m * 2048 + k * 1024); } while (0)
; #define G_LDB(dst, b, h) do { _Pragma("unroll") for (int n = 0; n < 2; ++n) _Pragma("unroll") for (int k = 0; k < 2; ++k) dst[n][k] = *(const LAS bf16x8*)(lds + G_SB(b, h) + boff + n * 2048 + k * 1024); } while (0)
; #define G_WAIT_L(n) asm volatile("s_waitcnt lgkmcnt(" #n ")" ::: "memory")
; #define G_BAR __builtin_amdgcn_s_barrier()
; #define G_SCHED __builtin_amdgcn_sched_barrier(0)
;     ...
;         for (int t = 0; t < nt; t += 2) {
;             const bool last = (t == nt - 2);
;             const char* a1 = cA + (size_t)(t + 1) * ckA;
;             const char* a2 = last ? nA : cA + (size_t)(t + 2) * ckA; const char* b2 = last ? nB : cB + (size_t)(t + 2) * kB;
;             const char* a3 = a2 + ckA; const char* b3 = b2 + kB;
;             G_LDB(B0, 0, 0); G_SCHED; G_LDA(At, 0, 0); G_STAGE(G_SA(1, 1), a1 + chA, cA0, qA);
;             G_WAIT_L(8); G_BAR; G_WAIT_L(0); G_MMA(0, 0, At, B0); G_BAR; G_SCHED;
;             G_LDB(B1, 0, 1); G_STAGE(G_SB(0, 0), b2, cB0, qB);
;             G_BAR; G_WAIT_L(0); G_MMA(0, 1, At, B1); G_BAR;
;     ...
;         if (!(cs.kind == K_MG_B && cur.aux < 2))
; #pragma unroll
;         for (int a = 0; a < 2; ++a)
; #pragma unroll
;             for (int b = 0; b < 2; ++b)
; #pragma unroll
;                 for (int m = 0; m < 4; ++m)
; #pragma unroll
;                     for (int n = 0; n < 2; ++n) acc[a][b][m][n] = (f32x4){0.f, 0.f, 0.f, 0.f};
.LBB0_1119:
	s_add_u32 s2, s16, 0x40080
	s_addc_u32 s3, s17, 0
	s_add_u32 s16, s18, 0x100
	v_mov_b64_e32 v[8:9], 0
	s_addc_u32 s17, s19, 0
	s_mov_b32 s18, -2
	v_mov_b64_e32 v[10:11], 0
	v_mov_b64_e32 v[16:17], 0
	v_mov_b64_e32 v[18:19], 0
	v_mov_b64_e32 v[24:25], 0
	v_mov_b64_e32 v[26:27], 0
	v_mov_b64_e32 v[32:33], 0
	v_mov_b64_e32 v[34:35], 0
	v_mov_b64_e32 v[40:41], 0
	v_mov_b64_e32 v[42:43], 0
	v_mov_b64_e32 v[48:49], 0
	v_mov_b64_e32 v[50:51], 0
	v_mov_b64_e32 v[56:57], 0
	v_mov_b64_e32 v[58:59], 0
	v_mov_b64_e32 v[64:65], 0
	v_mov_b64_e32 v[66:67], 0
	v_mov_b64_e32 v[12:13], 0
	v_mov_b64_e32 v[14:15], 0
	v_mov_b64_e32 v[20:21], 0
	v_mov_b64_e32 v[22:23], 0
	v_mov_b64_e32 v[28:29], 0
	v_mov_b64_e32 v[30:31], 0
	v_mov_b64_e32 v[36:37], 0
	v_mov_b64_e32 v[38:39], 0
	v_mov_b64_e32 v[44:45], 0
	v_mov_b64_e32 v[46:47], 0
	v_mov_b64_e32 v[52:53], 0
	v_mov_b64_e32 v[54:55], 0
	v_mov_b64_e32 v[60:61], 0
	v_mov_b64_e32 v[62:63], 0
	v_mov_b64_e32 v[68:69], 0
	v_mov_b64_e32 v[70:71], 0
	v_mov_b64_e32 v[72:73], 0
	v_mov_b64_e32 v[74:75], 0
	v_mov_b64_e32 v[80:81], 0
	v_mov_b64_e32 v[82:83], 0
	v_mov_b64_e32 v[88:89], 0
	v_mov_b64_e32 v[90:91], 0
	v_mov_b64_e32 v[96:97], 0
	v_mov_b64_e32 v[98:99], 0
	v_mov_b64_e32 v[104:105], 0
	v_mov_b64_e32 v[106:107], 0
	v_mov_b64_e32 v[112:113], 0
	v_mov_b64_e32 v[114:115], 0
	v_mov_b64_e32 v[120:121], 0
	v_mov_b64_e32 v[122:123], 0
	v_mov_b64_e32 v[128:129], 0
	v_mov_b64_e32 v[130:131], 0
	v_mov_b64_e32 v[76:77], 0
	v_mov_b64_e32 v[78:79], 0
	v_mov_b64_e32 v[84:85], 0
	v_mov_b64_e32 v[86:87], 0
	v_mov_b64_e32 v[92:93], 0
	v_mov_b64_e32 v[94:95], 0
	v_mov_b64_e32 v[100:101], 0
	v_mov_b64_e32 v[102:103], 0
	v_mov_b64_e32 v[108:109], 0
	v_mov_b64_e32 v[110:111], 0
	v_mov_b64_e32 v[116:117], 0
	v_mov_b64_e32 v[118:119], 0
	v_mov_b64_e32 v[124:125], 0
	v_mov_b64_e32 v[126:127], 0
	v_mov_b64_e32 v[132:133], 0
	v_mov_b64_e32 v[134:135], 0
	s_mov_b64 s[42:43], 0x40000
	s_mov_b64 s[50:51], 0x60000
	s_mov_b64 s[52:53], 0x20080
	s_mov_b64 s[54:55], 0x40080
	s_mov_b64 s[58:59], 0x60080
	s_cmp_eq_u32 s101, 2
	s_cselect_b32 s101, 0, s101
.LBB0_1120:
	s_add_u32 s4, s2, 0xfffc0080
	s_addc_u32 s5, s3, -1
	s_add_i32 s19, 0, 0x10000
	v_add_u32_e32 v0, s19, v149
	ds_read_b128 v[140:143], v0
	ds_read_b128 v[144:147], v0 offset:1024
	ds_read_b128 v[152:155], v0 offset:2048
	ds_read_b128 v[156:159], v0 offset:3072
	s_cmp_eq_u32 s18, 12
	s_cselect_b32 s5, s13, s5
	s_cselect_b32 s4, s12, s4
	s_cselect_b32 s41, s15, s17
	s_cselect_b32 s40, s14, s16
	v_lshl_add_u64 v[184:185], s[2:3], 0, v[138:139]
	s_add_i32 m0, s26, 0xc000
	ds_read_b128 v[160:163], v150
	ds_read_b128 v[164:167], v150 offset:1024
	ds_read_b128 v[172:175], v150 offset:2048
	ds_read_b128 v[176:179], v150 offset:3072
	ds_read_b128 v[180:183], v150 offset:4096
	ds_read_b128 v[196:199], v150 offset:5120
	ds_read_b128 v[200:203], v150 offset:6144
	ds_read_b128 v[204:207], v150 offset:7168
	global_load_lds_dwordx4 v[184:185], off
	v_lshl_add_u64 v[184:185], v[184:185], 0, s[0:1]
	s_add_i32 m0, s26, 0xe000
	s_nop 0
	global_load_lds_dwordx4 v[184:185], off
	s_waitcnt lgkmcnt(8)
	s_cmp_eq_u32 s101, 1
	s_cbranch_scc1 .Ldb_FFI_sk
	s_barrier
.Ldb_FFI_sk:
	s_mov_b32 s101, 0
	s_waitcnt lgkmcnt(0)
	v_mfma_f32_16x16x32_bf16 v[132:135], v[140:143], v[160:163], v[132:135]
	v_mfma_f32_16x16x32_bf16 v[124:127], v[152:155], v[160:163], v[124:127]
	v_mfma_f32_16x16x32_bf16 v[116:119], v[140:143], v[172:175], v[116:119]
	v_mfma_f32_16x16x32_bf16 v[108:111], v[152:155], v[172:175], v[108:111]
	v_mfma_f32_16x16x32_bf16 v[100:103], v[140:143], v[180:183], v[100:103]
	v_mfma_f32_16x16x32_bf16 v[92:95], v[152:155], v[180:183], v[92:95]
	v_mfma_f32_16x16x32_bf16 v[84:87], v[140:143], v[200:203], v[84:87]
	v_mfma_f32_16x16x32_bf16 v[76:79], v[152:155], v[200:203], v[76:79]
	v_mfma_f32_16x16x32_bf16 v[132:135], v[144:147], v[164:167], v[132:135]
	v_mfma_f32_16x16x32_bf16 v[124:127], v[156:159], v[164:167], v[124:127]
	v_mfma_f32_16x16x32_bf16 v[116:119], v[144:147], v[176:179], v[116:119]
	v_mfma_f32_16x16x32_bf16 v[108:111], v[156:159], v[176:179], v[108:111]
	v_mfma_f32_16x16x32_bf16 v[100:103], v[144:147], v[196:199], v[100:103]
	v_mfma_f32_16x16x32_bf16 v[92:95], v[156:159], v[196:199], v[92:95]
	v_mfma_f32_16x16x32_bf16 v[84:87], v[144:147], v[204:207], v[84:87]
	v_mfma_f32_16x16x32_bf16 v[76:79], v[156:159], v[204:207], v[76:79]
	s_barrier
	s_add_i32 s39, 0, 0x14000
	s_add_i32 s19, s19, s21
	v_add_u32_e32 v0, s39, v149
	v_lshl_add_u64 v[184:185], s[40:41], 0, v[2:3]
	s_mov_b32 m0, s19
	ds_read_b128 v[208:211], v0
	ds_read_b128 v[212:215], v0 offset:1024
	ds_read_b128 v[216:219], v0 offset:2048
	ds_read_b128 v[220:223], v0 offset:3072
	global_load_lds_dwordx4 v[184:185], off
	v_lshl_add_u64 v[224:225], v[184:185], 0, s[0:1]
	s_add_i32 m0, s19, 0x2000
	s_nop 0
	global_load_lds_dwordx4 v[224:225], off
	s_barrier
	s_waitcnt lgkmcnt(0)
	v_mfma_f32_16x16x32_bf16 v[128:131], v[208:211], v[160:163], v[128:131]
	v_mfma_f32_16x16x32_bf16 v[120:123], v[216:219], v[160:163], v[120:123]
	v_mfma_f32_16x16x32_bf16 v[112:115], v[208:211], v[172:175], v[112:115]
	v_mfma_f32_16x16x32_bf16 v[104:107], v[216:219], v[172:175], v[104:107]
	v_mfma_f32_16x16x32_bf16 v[96:99], v[208:211], v[180:183], v[96:99]
	v_mfma_f32_16x16x32_bf16 v[88:91], v[216:219], v[180:183], v[88:91]
	v_mfma_f32_16x16x32_bf16 v[80:83], v[208:211], v[200:203], v[80:83]
	v_mfma_f32_16x16x32_bf16 v[72:75], v[216:219], v[200:203], v[72:75]
	v_mfma_f32_16x16x32_bf16 v[128:131], v[212:215], v[164:167], v[128:131]
	v_mfma_f32_16x16x32_bf16 v[120:123], v[220:223], v[164:167], v[120:123]
	v_mfma_f32_16x16x32_bf16 v[112:115], v[212:215], v[176:179], v[112:115]
	v_mfma_f32_16x16x32_bf16 v[104:107], v[220:223], v[176:179], v[104:107]
	v_mfma_f32_16x16x32_bf16 v[96:99], v[212:215], v[196:199], v[96:99]
	v_mfma_f32_16x16x32_bf16 v[88:91], v[220:223], v[196:199], v[88:91]
	v_mfma_f32_16x16x32_bf16 v[80:83], v[212:215], v[204:207], v[80:83]
	v_mfma_f32_16x16x32_bf16 v[72:75], v[220:223], v[204:207], v[72:75]
	s_barrier
; #define G_STAGE(bufoff, gbase, o0, h64) do { \
;         __builtin_amdgcn_global_load_lds((const unsigned*)((const char*)(gbase) + (o0)), (LAS unsigned*)(lds + (bufoff) + ldsw), 16, 0, 0); \
;         __builtin_amdgcn_global_load_lds((const unsigned*)((const char*)(gbase) + (h64) + (o0)), (LAS unsigned*)(lds + (bufoff) + ldsw + 8192), 16, 0, 0); } while (0)
; #define G_LDA(dst, b, h) do { _Pragma("unroll") for (int m = 0; m < 4; ++m) _Pragma("unroll") for (int k = 0; k < 2; ++k) dst[m][k] = *(const LAS bf16x8*)(lds + G_SA(b, h) + aoff + m * 2048 + k * 1024); } while (0)
; #define G_LDB(dst, b, h) do { _Pragma("unroll") for (int n = 0; n < 2; ++n) _Pragma("unroll") for (int k = 0; k < 2; ++k) dst[n][k] = *(const LAS bf16x8*)(lds + G_SB(b, h) + boff + n * 2048 + k * 1024); } while (0)
; #define G_WAIT_V(n) asm volatile("s_waitcnt vmcnt(" #n ")" ::: "memory")
; #define G_WAIT_L(n) asm volatile("s_waitcnt lgkmcnt(" #n ")" ::: "memory")
; #define G_BAR __builtin_amdgcn_s_barrier()
; #define G_SCHED __builtin_amdgcn_sched_barrier(0)
;     ...
;             G_BAR; G_WAIT_L(0); G_MMA(0, 1, At, B1); G_BAR;
;             G_LDA(At, 0, 1); G_STAGE(G_SA(0, 0), a2, cA0, qA);
;             G_BAR; G_WAIT_L(0); G_MMA(1, 0, At, B0); G_BAR; G_SCHED;
;             G_STAGE(G_SB(0, 1), b2 + chB, cB0, qB);
;             G_WAIT_V(6); G_BAR; G_MMA(1, 1, At, B1); G_BAR;
;             G_LDB(B0, 1, 0); G_SCHED; G_LDA(At, 1, 0); G_STAGE(G_SA(0, 1), a2 + chA, cA0, qA);
;             G_WAIT_L(8); G_BAR; G_WAIT_L(0); G_MMA(0, 0, At, B0); G_BAR; G_SCHED;
	s_mov_b32 m0, s26
	v_lshl_add_u64 v[224:225], s[4:5], 0, v[136:137]
	ds_read_b128 v[160:163], v150 offset:16384
	ds_read_b128 v[164:167], v150 offset:17408
	ds_read_b128 v[172:175], v150 offset:18432
	ds_read_b128 v[176:179], v150 offset:19456
	ds_read_b128 v[180:183], v150 offset:20480
	ds_read_b128 v[196:199], v150 offset:21504
	ds_read_b128 v[200:203], v150 offset:22528
	ds_read_b128 v[204:207], v150 offset:23552
	global_load_lds_dwordx4 v[224:225], off
	v_lshl_add_u64 v[226:227], v[224:225], 0, s[0:1]
	s_mov_b32 m0, s27
	s_nop 0
	global_load_lds_dwordx4 v[226:227], off
	s_barrier
	s_waitcnt lgkmcnt(0)
	v_mfma_f32_16x16x32_bf16 v[68:71], v[140:143], v[160:163], v[68:71]
	v_mfma_f32_16x16x32_bf16 v[60:63], v[152:155], v[160:163], v[60:63]
	v_mfma_f32_16x16x32_bf16 v[52:55], v[140:143], v[172:175], v[52:55]
	v_mfma_f32_16x16x32_bf16 v[44:47], v[152:155], v[172:175], v[44:47]
	v_mfma_f32_16x16x32_bf16 v[36:39], v[140:143], v[180:183], v[36:39]
	v_mfma_f32_16x16x32_bf16 v[28:31], v[152:155], v[180:183], v[28:31]
	v_mfma_f32_16x16x32_bf16 v[20:23], v[140:143], v[200:203], v[20:23]
	v_mfma_f32_16x16x32_bf16 v[12:15], v[152:155], v[200:203], v[12:15]
	v_mfma_f32_16x16x32_bf16 v[68:71], v[144:147], v[164:167], v[68:71]
	v_mfma_f32_16x16x32_bf16 v[60:63], v[156:159], v[164:167], v[60:63]
	v_mfma_f32_16x16x32_bf16 v[52:55], v[144:147], v[176:179], v[52:55]
	v_mfma_f32_16x16x32_bf16 v[44:47], v[156:159], v[176:179], v[44:47]
	v_mfma_f32_16x16x32_bf16 v[36:39], v[144:147], v[196:199], v[36:39]
	v_mfma_f32_16x16x32_bf16 v[28:31], v[156:159], v[196:199], v[28:31]
	v_mfma_f32_16x16x32_bf16 v[20:23], v[144:147], v[204:207], v[20:23]
	v_mfma_f32_16x16x32_bf16 v[12:15], v[156:159], v[204:207], v[12:15]
	s_barrier
	s_add_i32 s4, s39, s21
	v_lshl_add_u64 v[140:141], v[184:185], 0, s[42:43]
	s_mov_b32 m0, s4
	s_nop 0
	global_load_lds_dwordx4 v[140:141], off
	v_lshl_add_u64 v[140:141], v[184:185], 0, s[50:51]
	s_add_i32 m0, s4, 0x2000
	s_nop 0
	global_load_lds_dwordx4 v[140:141], off
	s_waitcnt vmcnt(6)
	s_barrier
	v_mfma_f32_16x16x32_bf16 v[64:67], v[208:211], v[160:163], v[64:67]
	v_mfma_f32_16x16x32_bf16 v[56:59], v[216:219], v[160:163], v[56:59]
	v_mfma_f32_16x16x32_bf16 v[48:51], v[208:211], v[172:175], v[48:51]
	v_mfma_f32_16x16x32_bf16 v[40:43], v[216:219], v[172:175], v[40:43]
	v_mfma_f32_16x16x32_bf16 v[32:35], v[208:211], v[180:183], v[32:35]
	v_mfma_f32_16x16x32_bf16 v[24:27], v[216:219], v[180:183], v[24:27]
	v_mfma_f32_16x16x32_bf16 v[16:19], v[208:211], v[200:203], v[16:19]
	v_mfma_f32_16x16x32_bf16 v[8:11], v[216:219], v[200:203], v[8:11]
	v_mfma_f32_16x16x32_bf16 v[64:67], v[212:215], v[164:167], v[64:67]
	v_mfma_f32_16x16x32_bf16 v[56:59], v[220:223], v[164:167], v[56:59]
	v_mfma_f32_16x16x32_bf16 v[48:51], v[212:215], v[176:179], v[48:51]
	v_mfma_f32_16x16x32_bf16 v[40:43], v[220:223], v[176:179], v[40:43]
	v_mfma_f32_16x16x32_bf16 v[32:35], v[212:215], v[196:199], v[32:35]
	v_mfma_f32_16x16x32_bf16 v[24:27], v[220:223], v[196:199], v[24:27]
	v_mfma_f32_16x16x32_bf16 v[16:19], v[212:215], v[204:207], v[16:19]
	v_mfma_f32_16x16x32_bf16 v[8:11], v[220:223], v[204:207], v[8:11]
	s_barrier
	s_add_i32 s4, 0, 0x18000
	v_add_u32_e32 v0, s4, v149
	ds_read_b128 v[140:143], v0
	ds_read_b128 v[144:147], v0 offset:1024
	ds_read_b128 v[152:155], v0 offset:2048
	ds_read_b128 v[156:159], v0 offset:3072
	s_mov_b32 m0, s29
	v_lshl_add_u64 v[208:209], v[224:225], 0, s[42:43]
	ds_read_b128 v[160:163], v150 offset:32768
	ds_read_b128 v[164:167], v150 offset:33792
	ds_read_b128 v[172:175], v150 offset:34816
	ds_read_b128 v[176:179], v150 offset:35840
	ds_read_b128 v[180:183], v150 offset:36864
	ds_read_b128 v[196:199], v150 offset:37888
	ds_read_b128 v[200:203], v150 offset:38912
	ds_read_b128 v[204:207], v150 offset:39936
	global_load_lds_dwordx4 v[208:209], off
	v_lshl_add_u64 v[208:209], v[224:225], 0, s[50:51]
	s_mov_b32 m0, s30
	s_nop 0
	global_load_lds_dwordx4 v[208:209], off
	s_waitcnt lgkmcnt(8)
	s_barrier
	s_waitcnt lgkmcnt(0)
	v_mfma_f32_16x16x32_bf16 v[132:135], v[140:143], v[160:163], v[132:135]
	v_mfma_f32_16x16x32_bf16 v[124:127], v[152:155], v[160:163], v[124:127]
	v_mfma_f32_16x16x32_bf16 v[116:119], v[140:143], v[172:175], v[116:119]
	v_mfma_f32_16x16x32_bf16 v[108:111], v[152:155], v[172:175], v[108:111]
	v_mfma_f32_16x16x32_bf16 v[100:103], v[140:143], v[180:183], v[100:103]
	v_mfma_f32_16x16x32_bf16 v[92:95], v[152:155], v[180:183], v[92:95]
	v_mfma_f32_16x16x32_bf16 v[84:87], v[140:143], v[200:203], v[84:87]
	v_mfma_f32_16x16x32_bf16 v[76:79], v[152:155], v[200:203], v[76:79]
	v_mfma_f32_16x16x32_bf16 v[132:135], v[144:147], v[164:167], v[132:135]
	v_mfma_f32_16x16x32_bf16 v[124:127], v[156:159], v[164:167], v[124:127]
	v_mfma_f32_16x16x32_bf16 v[116:119], v[144:147], v[176:179], v[116:119]
	v_mfma_f32_16x16x32_bf16 v[108:111], v[156:159], v[176:179], v[108:111]
	v_mfma_f32_16x16x32_bf16 v[100:103], v[144:147], v[196:199], v[100:103]
	v_mfma_f32_16x16x32_bf16 v[92:95], v[156:159], v[196:199], v[92:95]
	v_mfma_f32_16x16x32_bf16 v[84:87], v[144:147], v[204:207], v[84:87]
	v_mfma_f32_16x16x32_bf16 v[76:79], v[156:159], v[204:207], v[76:79]
	s_barrier
; #define G_STAGE(bufoff, gbase, o0, h64) do { \
;         __builtin_amdgcn_global_load_lds((const unsigned*)((const char*)(gbase) + (o0)), (LAS unsigned*)(lds + (bufoff) + ldsw), 16, 0, 0); \
;         __builtin_amdgcn_global_load_lds((const unsigned*)((const char*)(gbase) + (h64) + (o0)), (LAS unsigned*)(lds + (bufoff) + ldsw + 8192), 16, 0, 0); } while (0)
; #define G_LDA(dst, b, h) do { _Pragma("unroll") for (int m = 0; m < 4; ++m) _Pragma("unroll") for (int k = 0; k < 2; ++k) dst[m][k] = *(const LAS bf16x8*)(lds + G_SA(b, h) + aoff + m * 2048 + k * 1024); } while (0)
; #define G_LDB(dst, b, h) do { _Pragma("unroll") for (int n = 0; n < 2; ++n) _Pragma("unroll") for (int k = 0; k < 2; ++k) dst[n][k] = *(const LAS bf16x8*)(lds + G_SB(b, h) + boff + n * 2048 + k * 1024); } while (0)
; #define G_WAIT_V(n) asm volatile("s_waitcnt vmcnt(" #n ")" ::: "memory")
; #define G_WAIT_L(n) asm volatile("s_waitcnt lgkmcnt(" #n ")" ::: "memory")
; #define G_BAR __builtin_amdgcn_s_barrier()
; #define G_SCHED __builtin_amdgcn_sched_barrier(0)
;     ...
;             G_WAIT_L(8); G_BAR; G_WAIT_L(0); G_MMA(0, 0, At, B0); G_BAR; G_SCHED;
;             G_LDB(B1, 1, 1); G_STAGE(G_SB(1, 0), b3, cB0, qB);
;             G_BAR; G_WAIT_L(0); G_MMA(0, 1, At, B1); G_BAR;
;             G_LDA(At, 1, 1); G_STAGE(G_SA(1, 0), a3, cA0, qA);
;             G_BAR; G_WAIT_L(0); G_MMA(1, 0, At, B0); G_BAR; G_SCHED;
;             G_STAGE(G_SB(1, 1), b3 + chB, cB0, qB);
;             G_WAIT_V(6); G_BAR; G_MMA(1, 1, At, B1); G_BAR;
;         }
	s_add_i32 s5, 0, 0x1c000
	s_add_i32 s4, s4, s21
	v_add_u32_e32 v0, s5, v149
	v_lshl_add_u64 v[226:227], v[184:185], 0, s[46:47]
	s_mov_b32 m0, s4
	ds_read_b128 v[208:211], v0
	ds_read_b128 v[212:215], v0 offset:1024
	ds_read_b128 v[216:219], v0 offset:2048
	ds_read_b128 v[220:223], v0 offset:3072
	global_load_lds_dwordx4 v[226:227], off
	v_lshl_add_u64 v[226:227], v[184:185], 0, s[52:53]
	s_add_i32 m0, s4, 0x2000
	s_nop 0
	global_load_lds_dwordx4 v[226:227], off
	s_barrier
	s_waitcnt lgkmcnt(0)
	v_mfma_f32_16x16x32_bf16 v[128:131], v[208:211], v[160:163], v[128:131]
	v_mfma_f32_16x16x32_bf16 v[120:123], v[216:219], v[160:163], v[120:123]
	v_mfma_f32_16x16x32_bf16 v[112:115], v[208:211], v[172:175], v[112:115]
	v_mfma_f32_16x16x32_bf16 v[104:107], v[216:219], v[172:175], v[104:107]
	v_mfma_f32_16x16x32_bf16 v[96:99], v[208:211], v[180:183], v[96:99]
	v_mfma_f32_16x16x32_bf16 v[88:91], v[216:219], v[180:183], v[88:91]
	v_mfma_f32_16x16x32_bf16 v[80:83], v[208:211], v[200:203], v[80:83]
	v_mfma_f32_16x16x32_bf16 v[72:75], v[216:219], v[200:203], v[72:75]
	v_mfma_f32_16x16x32_bf16 v[128:131], v[212:215], v[164:167], v[128:131]
	v_mfma_f32_16x16x32_bf16 v[120:123], v[220:223], v[164:167], v[120:123]
	v_mfma_f32_16x16x32_bf16 v[112:115], v[212:215], v[176:179], v[112:115]
	v_mfma_f32_16x16x32_bf16 v[104:107], v[220:223], v[176:179], v[104:107]
	v_mfma_f32_16x16x32_bf16 v[96:99], v[212:215], v[196:199], v[96:99]
	v_mfma_f32_16x16x32_bf16 v[88:91], v[220:223], v[196:199], v[88:91]
	v_mfma_f32_16x16x32_bf16 v[80:83], v[212:215], v[204:207], v[80:83]
	v_mfma_f32_16x16x32_bf16 v[72:75], v[220:223], v[204:207], v[72:75]
	s_barrier
	s_mov_b32 m0, s31
	v_lshl_add_u64 v[226:227], v[224:225], 0, s[46:47]
	ds_read_b128 v[160:163], v150 offset:49152
	ds_read_b128 v[164:167], v150 offset:50176
	ds_read_b128 v[172:175], v150 offset:51200
	ds_read_b128 v[176:179], v150 offset:52224
	ds_read_b128 v[180:183], v150 offset:53248
	ds_read_b128 v[196:199], v150 offset:54272
	ds_read_b128 v[200:203], v150 offset:55296
	ds_read_b128 v[204:207], v150 offset:56320
	global_load_lds_dwordx4 v[226:227], off
	v_lshl_add_u64 v[224:225], v[224:225], 0, s[52:53]
	s_mov_b32 m0, s34
	s_nop 0
	global_load_lds_dwordx4 v[224:225], off
	s_barrier
	s_waitcnt lgkmcnt(0)
	v_mfma_f32_16x16x32_bf16 v[68:71], v[140:143], v[160:163], v[68:71]
	v_mfma_f32_16x16x32_bf16 v[60:63], v[152:155], v[160:163], v[60:63]
	v_mfma_f32_16x16x32_bf16 v[52:55], v[140:143], v[172:175], v[52:55]
	v_mfma_f32_16x16x32_bf16 v[44:47], v[152:155], v[172:175], v[44:47]
	v_mfma_f32_16x16x32_bf16 v[36:39], v[140:143], v[180:183], v[36:39]
	v_mfma_f32_16x16x32_bf16 v[28:31], v[152:155], v[180:183], v[28:31]
	v_mfma_f32_16x16x32_bf16 v[20:23], v[140:143], v[200:203], v[20:23]
	v_mfma_f32_16x16x32_bf16 v[12:15], v[152:155], v[200:203], v[12:15]
	v_mfma_f32_16x16x32_bf16 v[68:71], v[144:147], v[164:167], v[68:71]
	v_mfma_f32_16x16x32_bf16 v[60:63], v[156:159], v[164:167], v[60:63]
	v_mfma_f32_16x16x32_bf16 v[52:55], v[144:147], v[176:179], v[52:55]
	v_mfma_f32_16x16x32_bf16 v[44:47], v[156:159], v[176:179], v[44:47]
	v_mfma_f32_16x16x32_bf16 v[36:39], v[144:147], v[196:199], v[36:39]
	v_mfma_f32_16x16x32_bf16 v[28:31], v[156:159], v[196:199], v[28:31]
	v_mfma_f32_16x16x32_bf16 v[20:23], v[144:147], v[204:207], v[20:23]
	v_mfma_f32_16x16x32_bf16 v[12:15], v[156:159], v[204:207], v[12:15]
	s_barrier
	s_add_i32 s4, s5, s21
	v_lshl_add_u64 v[140:141], v[184:185], 0, s[54:55]
	s_mov_b32 m0, s4
	s_nop 0
	global_load_lds_dwordx4 v[140:141], off
	v_lshl_add_u64 v[140:141], v[184:185], 0, s[58:59]
	s_add_i32 m0, s4, 0x2000
	s_nop 0
	global_load_lds_dwordx4 v[140:141], off
	s_add_i32 s18, s18, 2
	s_add_u32 s2, s2, 0x100
	s_addc_u32 s3, s3, 0
	s_add_u32 s16, s16, 0x100
	s_addc_u32 s17, s17, 0
	s_cmp_gt_u32 s18, 13
	s_waitcnt vmcnt(6)
	s_barrier
	v_mfma_f32_16x16x32_bf16 v[64:67], v[208:211], v[160:163], v[64:67]
	v_mfma_f32_16x16x32_bf16 v[56:59], v[216:219], v[160:163], v[56:59]
	v_mfma_f32_16x16x32_bf16 v[48:51], v[208:211], v[172:175], v[48:51]
	v_mfma_f32_16x16x32_bf16 v[40:43], v[216:219], v[172:175], v[40:43]
	v_mfma_f32_16x16x32_bf16 v[32:35], v[208:211], v[180:183], v[32:35]
	v_mfma_f32_16x16x32_bf16 v[24:27], v[216:219], v[180:183], v[24:27]
	v_mfma_f32_16x16x32_bf16 v[16:19], v[208:211], v[200:203], v[16:19]
	v_mfma_f32_16x16x32_bf16 v[8:11], v[216:219], v[200:203], v[8:11]
	v_mfma_f32_16x16x32_bf16 v[64:67], v[212:215], v[164:167], v[64:67]
	v_mfma_f32_16x16x32_bf16 v[56:59], v[220:223], v[164:167], v[56:59]
	v_mfma_f32_16x16x32_bf16 v[48:51], v[212:215], v[176:179], v[48:51]
	v_mfma_f32_16x16x32_bf16 v[40:43], v[220:223], v[176:179], v[40:43]
	v_mfma_f32_16x16x32_bf16 v[32:35], v[212:215], v[196:199], v[32:35]
	v_mfma_f32_16x16x32_bf16 v[24:27], v[220:223], v[196:199], v[24:27]
	v_mfma_f32_16x16x32_bf16 v[16:19], v[212:215], v[204:207], v[16:19]
	v_mfma_f32_16x16x32_bf16 v[8:11], v[220:223], v[204:207], v[8:11]
	s_cbranch_scc0 .Ldb_FFI_cont
	v_readfirstlane_b32 s101, v186
	s_cmpk_gt_u32 s101, 0xff
	s_cbranch_scc1 .Ldb_FFI_young
	s_barrier
	s_mov_b32 s101, 1
	s_branch .Ldb_FFI_exit

; __device__ __forceinline__ float sigmoidf_(float v) { return __builtin_amdgcn_rcpf(1.0f + __expf(-v)); }
; __device__ __forceinline__ u32x4 pack8(const f32x4 a, const f32x4 b) { u32x4 w; w.x = cvt_pk_bf16(a[0], a[1]); w.y = cvt_pk_bf16(a[2], a[3]); w.z = cvt_pk_bf16(b[0], b[1]); w.w = cvt_pk_bf16(b[2], b[3]); return w; }
; #define MEMFENCE asm volatile("" ::: "memory")
;     __device__ __forceinline__ void get_rs(const Unit& u, int wr, int fr, float (&rs)[8]) const {
; #pragma unroll
;         for (int r8 = 0; r8 < 8; ++r8) rs[r8] = rstab[u.ord * 256 + (r8 >> 2) * 128 + wr * 64 + (r8 & 3) * 16 + fr];
;     }
;     template <int KIND> __device__ __forceinline__ void run(f32x4 (&acc)[2][2][4][2], const Unit& u, int tid_in) const {
;     ...
;         if constexpr (KIND == K_FFI) { bf16_t* act = zb; float rs[8]; get_rs(u, wr, fr, rs);
; #pragma unroll
;             for (int ai = 0; ai < 2; ++ai)
; #pragma unroll
;                 for (int m = 0; m < 4; ++m) { int row = rbase + ai * 128 + m * 16; asm volatile("" : "+v"(row)); const float r = rs[ai * 4 + m]; f32x4 o[2];
; #pragma unroll
;                     for (int n = 0; n < 2; ++n) { const f32x4 g = acc[ai][0][m][n] * r, v = acc[ai][1][m][n] * r;
; #pragma unroll
;                         for (int j = 0; j < 4; ++j) o[n][j] = g[j] * sigmoidf_(g[j]) * v[j]; }
;                     *(u32x4*)(act + (size_t)row * ZW + u.pn * 128 + cl) = pack8(o[0], o[1]); MEMFENCE; }
.Ldb_FFI_exit:
	v_readfirstlane_b32 s2, v148
	s_lshr_b32 s4, s2, 1
	s_and_b32 s4, s4, 0x60
	v_lshrrev_b32_e32 v0, 1, v148
	v_and_or_b32 v0, v0, 24, s4
	v_and_b32_e32 v140, 15, v148
	s_lshl_b32 s4, s38, 10
	s_and_b32 s3, s2, 0xffffff00
	s_add_i32 s4, s4, s3
	v_lshl_add_u32 v141, v140, 2, s4
	v_add_u32_e32 v141, 0x20010, v141
	ds_read_b32 v240, v141
	ds_read_b32 v242, v141 offset:64
	ds_read_b32 v244, v141 offset:128
	ds_read_b32 v246, v141 offset:192
	ds_read_b32 v248, v141 offset:512
	ds_read_b32 v250, v141 offset:576
	ds_read_b32 v252, v141 offset:640
	ds_read_b32 v254, v141 offset:704
	s_ashr_i32 s3, s2, 2
	s_andn2_b32 s3, s3, 63
	v_or_b32_e32 v140, s3, v140
	v_lshl_add_u32 v140, s37, 8, v140
	v_mul_lo_u32 v140, v140, s76
	s_lshl_b32 s3, s33, 8
	v_lshlrev_b32_e32 v0, 1, v0
	v_add3_u32 v140, v140, v0, s3
	s_mov_b64 s[4:5], s[6:7]
	s_mov_b32 s2, 0xbfb8aa3b
	s_mov_b32 s100, 1.0
	s_waitcnt lgkmcnt(0)
	v_pk_mul_f32 v[132:133], v[132:133], v[240:241] op_sel_hi:[1,0]
	v_pk_mul_f32 v[128:129], v[128:129], v[240:241] op_sel_hi:[1,0]
	v_pk_mul_f32 v[216:217], v[132:133], s[2:3] op_sel_hi:[1,0]
	v_pk_mul_f32 v[134:135], v[134:135], v[240:241] op_sel_hi:[1,0]
	v_pk_mul_f32 v[130:131], v[130:131], v[240:241] op_sel_hi:[1,0]
	v_pk_mul_f32 v[218:219], v[134:135], s[2:3] op_sel_hi:[1,0]
	v_pk_mul_f32 v[124:125], v[124:125], v[240:241] op_sel_hi:[1,0]
	v_pk_mul_f32 v[120:121], v[120:121], v[240:241] op_sel_hi:[1,0]
	v_pk_mul_f32 v[220:221], v[124:125], s[2:3] op_sel_hi:[1,0]
	v_pk_mul_f32 v[126:127], v[126:127], v[240:241] op_sel_hi:[1,0]
	v_pk_mul_f32 v[122:123], v[122:123], v[240:241] op_sel_hi:[1,0]
	v_pk_mul_f32 v[222:223], v[126:127], s[2:3] op_sel_hi:[1,0]
	v_exp_f32_e32 v216, v216
	v_exp_f32_e32 v217, v217
	v_exp_f32_e32 v218, v218
	v_exp_f32_e32 v219, v219
	v_exp_f32_e32 v220, v220
	v_exp_f32_e32 v221, v221
	v_exp_f32_e32 v222, v222
	v_exp_f32_e32 v223, v223
	v_pk_add_f32 v[216:217], v[216:217], s[100:101] op_sel_hi:[1,0]
	v_pk_add_f32 v[218:219], v[218:219], s[100:101] op_sel_hi:[1,0]
	v_pk_add_f32 v[220:221], v[220:221], s[100:101] op_sel_hi:[1,0]
	v_pk_add_f32 v[222:223], v[222:223], s[100:101] op_sel_hi:[1,0]
	v_rcp_f32_e32 v216, v216
	v_rcp_f32_e32 v217, v217
	v_rcp_f32_e32 v218, v218
	v_rcp_f32_e32 v219, v219
	v_rcp_f32_e32 v220, v220
	v_rcp_f32_e32 v221, v221
	v_rcp_f32_e32 v222, v222
	v_rcp_f32_e32 v223, v223
	v_pk_mul_f32 v[132:133], v[132:133], v[216:217]
	v_pk_mul_f32 v[134:135], v[134:135], v[218:219]
	v_pk_mul_f32 v[124:125], v[124:125], v[220:221]
	v_pk_mul_f32 v[126:127], v[126:127], v[222:223]
	v_pk_mul_f32 v[132:133], v[132:133], v[128:129]
	v_pk_mul_f32 v[134:135], v[134:135], v[130:131]
	v_pk_mul_f32 v[124:125], v[124:125], v[120:121]
	v_pk_mul_f32 v[126:127], v[126:127], v[122:123]
	v_cvt_pk_bf16_f32 v236, v132, v133
	v_cvt_pk_bf16_f32 v237, v134, v135
	v_cvt_pk_bf16_f32 v238, v124, v125
	v_cvt_pk_bf16_f32 v239, v126, v127
	global_store_dwordx4 v140, v[236:239], s[4:5]
	s_add_u32 s4, s4, 0x16000
	s_addc_u32 s5, s5, 0
	v_pk_mul_f32 v[116:117], v[116:117], v[242:243] op_sel_hi:[1,0]
	v_pk_mul_f32 v[112:113], v[112:113], v[242:243] op_sel_hi:[1,0]
	v_pk_mul_f32 v[216:217], v[116:117], s[2:3] op_sel_hi:[1,0]
	v_pk_mul_f32 v[118:119], v[118:119], v[242:243] op_sel_hi:[1,0]
	v_pk_mul_f32 v[114:115], v[114:115], v[242:243] op_sel_hi:[1,0]
	v_pk_mul_f32 v[218:219], v[118:119], s[2:3] op_sel_hi:[1,0]
	v_pk_mul_f32 v[108:109], v[108:109], v[242:243] op_sel_hi:[1,0]
	v_pk_mul_f32 v[104:105], v[104:105], v[242:243] op_sel_hi:[1,0]
	v_pk_mul_f32 v[220:221], v[108:109], s[2:3] op_sel_hi:[1,0]
	v_pk_mul_f32 v[110:111], v[110:111], v[242:243] op_sel_hi:[1,0]
	v_pk_mul_f32 v[106:107], v[106:107], v[242:243] op_sel_hi:[1,0]
	v_pk_mul_f32 v[222:223], v[110:111], s[2:3] op_sel_hi:[1,0]
	v_exp_f32_e32 v216, v216
	v_exp_f32_e32 v217, v217
	v_exp_f32_e32 v218, v218
	v_exp_f32_e32 v219, v219
	v_exp_f32_e32 v220, v220
	v_exp_f32_e32 v221, v221
	v_exp_f32_e32 v222, v222
	v_exp_f32_e32 v223, v223
	v_pk_add_f32 v[216:217], v[216:217], s[100:101] op_sel_hi:[1,0]
	v_pk_add_f32 v[218:219], v[218:219], s[100:101] op_sel_hi:[1,0]
	v_pk_add_f32 v[220:221], v[220:221], s[100:101] op_sel_hi:[1,0]
	v_pk_add_f32 v[222:223], v[222:223], s[100:101] op_sel_hi:[1,0]
	v_rcp_f32_e32 v216, v216
	v_rcp_f32_e32 v217, v217
	v_rcp_f32_e32 v218, v218
	v_rcp_f32_e32 v219, v219
	v_rcp_f32_e32 v220, v220
	v_rcp_f32_e32 v221, v221
	v_rcp_f32_e32 v222, v222
	v_rcp_f32_e32 v223, v223
	v_pk_mul_f32 v[116:117], v[116:117], v[216:217]
	v_pk_mul_f32 v[118:119], v[118:119], v[218:219]
	v_pk_mul_f32 v[108:109], v[108:109], v[220:221]
	v_pk_mul_f32 v[110:111], v[110:111], v[222:223]
	v_pk_mul_f32 v[116:117], v[116:117], v[112:113]
	v_pk_mul_f32 v[118:119], v[118:119], v[114:115]
	v_pk_mul_f32 v[108:109], v[108:109], v[104:105]
	v_pk_mul_f32 v[110:111], v[110:111], v[106:107]
	v_cvt_pk_bf16_f32 v236, v116, v117
	v_cvt_pk_bf16_f32 v237, v118, v119
	v_cvt_pk_bf16_f32 v238, v108, v109
	v_cvt_pk_bf16_f32 v239, v110, v111
	global_store_dwordx4 v140, v[236:239], s[4:5]
	s_add_u32 s4, s4, 0x16000
	s_addc_u32 s5, s5, 0
	v_pk_mul_f32 v[100:101], v[100:101], v[244:245] op_sel_hi:[1,0]
	v_pk_mul_f32 v[96:97], v[96:97], v[244:245] op_sel_hi:[1,0]
	v_pk_mul_f32 v[216:217], v[100:101], s[2:3] op_sel_hi:[1,0]
	v_pk_mul_f32 v[102:103], v[102:103], v[244:245] op_sel_hi:[1,0]
	v_pk_mul_f32 v[98:99], v[98:99], v[244:245] op_sel_hi:[1,0]
	v_pk_mul_f32 v[218:219], v[102:103], s[2:3] op_sel_hi:[1,0]
	v_pk_mul_f32 v[92:93], v[92:93], v[244:245] op_sel_hi:[1,0]
	v_pk_mul_f32 v[88:89], v[88:89], v[244:245] op_sel_hi:[1,0]
	v_pk_mul_f32 v[220:221], v[92:93], s[2:3] op_sel_hi:[1,0]
; __device__ __forceinline__ float sigmoidf_(float v) { return __builtin_amdgcn_rcpf(1.0f + __expf(-v)); }
; __device__ __forceinline__ u32x4 pack8(const f32x4 a, const f32x4 b) { u32x4 w; w.x = cvt_pk_bf16(a[0], a[1]); w.y = cvt_pk_bf16(a[2], a[3]); w.z = cvt_pk_bf16(b[0], b[1]); w.w = cvt_pk_bf16(b[2], b[3]); return w; }
; #define MEMFENCE asm volatile("" ::: "memory")
;     template <int KIND> __device__ __forceinline__ void run(f32x4 (&acc)[2][2][4][2], const Unit& u, int tid_in) const {
;     ...
;         if constexpr (KIND == K_FFI) { bf16_t* act = zb; float rs[8]; get_rs(u, wr, fr, rs);
; #pragma unroll
;             for (int ai = 0; ai < 2; ++ai)
; #pragma unroll
;                 for (int m = 0; m < 4; ++m) { int row = rbase + ai * 128 + m * 16; asm volatile("" : "+v"(row)); const float r = rs[ai * 4 + m]; f32x4 o[2];
; #pragma unroll
;                     for (int n = 0; n < 2; ++n) { const f32x4 g = acc[ai][0][m][n] * r, v = acc[ai][1][m][n] * r;
; #pragma unroll
;                         for (int j = 0; j < 4; ++j) o[n][j] = g[j] * sigmoidf_(g[j]) * v[j]; }
;                     *(u32x4*)(act + (size_t)row * ZW + u.pn * 128 + cl) = pack8(o[0], o[1]); MEMFENCE; }
	v_pk_mul_f32 v[94:95], v[94:95], v[244:245] op_sel_hi:[1,0]
	v_pk_mul_f32 v[90:91], v[90:91], v[244:245] op_sel_hi:[1,0]
	v_pk_mul_f32 v[222:223], v[94:95], s[2:3] op_sel_hi:[1,0]
	v_exp_f32_e32 v216, v216
	v_exp_f32_e32 v217, v217
	v_exp_f32_e32 v218, v218
	v_exp_f32_e32 v219, v219
	v_exp_f32_e32 v220, v220
	v_exp_f32_e32 v221, v221
	v_exp_f32_e32 v222, v222
	v_exp_f32_e32 v223, v223
	v_pk_add_f32 v[216:217], v[216:217], s[100:101] op_sel_hi:[1,0]
	v_pk_add_f32 v[218:219], v[218:219], s[100:101] op_sel_hi:[1,0]
	v_pk_add_f32 v[220:221], v[220:221], s[100:101] op_sel_hi:[1,0]
	v_pk_add_f32 v[222:223], v[222:223], s[100:101] op_sel_hi:[1,0]
	v_rcp_f32_e32 v216, v216
	v_rcp_f32_e32 v217, v217
	v_rcp_f32_e32 v218, v218
	v_rcp_f32_e32 v219, v219
	v_rcp_f32_e32 v220, v220
	v_rcp_f32_e32 v221, v221
	v_rcp_f32_e32 v222, v222
	v_rcp_f32_e32 v223, v223
	v_pk_mul_f32 v[100:101], v[100:101], v[216:217]
	v_pk_mul_f32 v[102:103], v[102:103], v[218:219]
	v_pk_mul_f32 v[92:93], v[92:93], v[220:221]
	v_pk_mul_f32 v[94:95], v[94:95], v[222:223]
	v_pk_mul_f32 v[100:101], v[100:101], v[96:97]
	v_pk_mul_f32 v[102:103], v[102:103], v[98:99]
	v_pk_mul_f32 v[92:93], v[92:93], v[88:89]
	v_pk_mul_f32 v[94:95], v[94:95], v[90:91]
	v_cvt_pk_bf16_f32 v236, v100, v101
	v_cvt_pk_bf16_f32 v237, v102, v103
	v_cvt_pk_bf16_f32 v238, v92, v93
	v_cvt_pk_bf16_f32 v239, v94, v95
	global_store_dwordx4 v140, v[236:239], s[4:5]
	s_add_u32 s4, s4, 0x16000
	s_addc_u32 s5, s5, 0
	v_pk_mul_f32 v[84:85], v[84:85], v[246:247] op_sel_hi:[1,0]
	v_pk_mul_f32 v[80:81], v[80:81], v[246:247] op_sel_hi:[1,0]
	v_pk_mul_f32 v[216:217], v[84:85], s[2:3] op_sel_hi:[1,0]
	v_pk_mul_f32 v[86:87], v[86:87], v[246:247] op_sel_hi:[1,0]
	v_pk_mul_f32 v[82:83], v[82:83], v[246:247] op_sel_hi:[1,0]
	v_pk_mul_f32 v[218:219], v[86:87], s[2:3] op_sel_hi:[1,0]
	v_pk_mul_f32 v[76:77], v[76:77], v[246:247] op_sel_hi:[1,0]
	v_pk_mul_f32 v[72:73], v[72:73], v[246:247] op_sel_hi:[1,0]
	v_pk_mul_f32 v[220:221], v[76:77], s[2:3] op_sel_hi:[1,0]
	v_pk_mul_f32 v[78:79], v[78:79], v[246:247] op_sel_hi:[1,0]
	v_pk_mul_f32 v[74:75], v[74:75], v[246:247] op_sel_hi:[1,0]
	v_pk_mul_f32 v[222:223], v[78:79], s[2:3] op_sel_hi:[1,0]
	v_exp_f32_e32 v216, v216
	v_exp_f32_e32 v217, v217
	v_exp_f32_e32 v218, v218
	v_exp_f32_e32 v219, v219
	v_exp_f32_e32 v220, v220
	v_exp_f32_e32 v221, v221
	v_exp_f32_e32 v222, v222
	v_exp_f32_e32 v223, v223
	v_pk_add_f32 v[216:217], v[216:217], s[100:101] op_sel_hi:[1,0]
	v_pk_add_f32 v[218:219], v[218:219], s[100:101] op_sel_hi:[1,0]
	v_pk_add_f32 v[220:221], v[220:221], s[100:101] op_sel_hi:[1,0]
	v_pk_add_f32 v[222:223], v[222:223], s[100:101] op_sel_hi:[1,0]
	v_rcp_f32_e32 v216, v216
	v_rcp_f32_e32 v217, v217
	v_rcp_f32_e32 v218, v218
	v_rcp_f32_e32 v219, v219
	v_rcp_f32_e32 v220, v220
	v_rcp_f32_e32 v221, v221
	v_rcp_f32_e32 v222, v222
	v_rcp_f32_e32 v223, v223
	v_pk_mul_f32 v[84:85], v[84:85], v[216:217]
	v_pk_mul_f32 v[86:87], v[86:87], v[218:219]
	v_pk_mul_f32 v[76:77], v[76:77], v[220:221]
	v_pk_mul_f32 v[78:79], v[78:79], v[222:223]
	v_pk_mul_f32 v[84:85], v[84:85], v[80:81]
	v_pk_mul_f32 v[86:87], v[86:87], v[82:83]
	v_pk_mul_f32 v[76:77], v[76:77], v[72:73]
	v_pk_mul_f32 v[78:79], v[78:79], v[74:75]
	v_cvt_pk_bf16_f32 v236, v84, v85
	v_cvt_pk_bf16_f32 v237, v86, v87
	v_cvt_pk_bf16_f32 v238, v76, v77
	v_cvt_pk_bf16_f32 v239, v78, v79
	global_store_dwordx4 v140, v[236:239], s[4:5]
	s_add_u32 s4, s4, 0x6e000
	s_addc_u32 s5, s5, 0
	v_pk_mul_f32 v[68:69], v[68:69], v[248:249] op_sel_hi:[1,0]
	v_pk_mul_f32 v[64:65], v[64:65], v[248:249] op_sel_hi:[1,0]
	v_pk_mul_f32 v[216:217], v[68:69], s[2:3] op_sel_hi:[1,0]
	v_pk_mul_f32 v[70:71], v[70:71], v[248:249] op_sel_hi:[1,0]
	v_pk_mul_f32 v[66:67], v[66:67], v[248:249] op_sel_hi:[1,0]
	v_pk_mul_f32 v[218:219], v[70:71], s[2:3] op_sel_hi:[1,0]
	v_pk_mul_f32 v[60:61], v[60:61], v[248:249] op_sel_hi:[1,0]
	v_pk_mul_f32 v[56:57], v[56:57], v[248:249] op_sel_hi:[1,0]
	v_pk_mul_f32 v[220:221], v[60:61], s[2:3] op_sel_hi:[1,0]
	v_pk_mul_f32 v[62:63], v[62:63], v[248:249] op_sel_hi:[1,0]
	v_pk_mul_f32 v[58:59], v[58:59], v[248:249] op_sel_hi:[1,0]
	v_pk_mul_f32 v[222:223], v[62:63], s[2:3] op_sel_hi:[1,0]
	v_exp_f32_e32 v216, v216
	v_exp_f32_e32 v217, v217
	v_exp_f32_e32 v218, v218
	v_exp_f32_e32 v219, v219
	v_exp_f32_e32 v220, v220
	v_exp_f32_e32 v221, v221
	v_exp_f32_e32 v222, v222
	v_exp_f32_e32 v223, v223
	v_pk_add_f32 v[216:217], v[216:217], s[100:101] op_sel_hi:[1,0]
	v_pk_add_f32 v[218:219], v[218:219], s[100:101] op_sel_hi:[1,0]
	v_pk_add_f32 v[220:221], v[220:221], s[100:101] op_sel_hi:[1,0]
	v_pk_add_f32 v[222:223], v[222:223], s[100:101] op_sel_hi:[1,0]
	v_rcp_f32_e32 v216, v216
	v_rcp_f32_e32 v217, v217
	v_rcp_f32_e32 v218, v218
	v_rcp_f32_e32 v219, v219
	v_rcp_f32_e32 v220, v220
	v_rcp_f32_e32 v221, v221
	v_rcp_f32_e32 v222, v222
	v_rcp_f32_e32 v223, v223
	v_pk_mul_f32 v[68:69], v[68:69], v[216:217]
	v_pk_mul_f32 v[70:71], v[70:71], v[218:219]
	v_pk_mul_f32 v[60:61], v[60:61], v[220:221]
	v_pk_mul_f32 v[62:63], v[62:63], v[222:223]
	v_pk_mul_f32 v[68:69], v[68:69], v[64:65]
	v_pk_mul_f32 v[70:71], v[70:71], v[66:67]
	v_pk_mul_f32 v[60:61], v[60:61], v[56:57]
	v_pk_mul_f32 v[62:63], v[62:63], v[58:59]
	v_cvt_pk_bf16_f32 v236, v68, v69
	v_cvt_pk_bf16_f32 v237, v70, v71
	v_cvt_pk_bf16_f32 v238, v60, v61
	v_cvt_pk_bf16_f32 v239, v62, v63
	global_store_dwordx4 v140, v[236:239], s[4:5]
	s_add_u32 s4, s4, 0x16000
	s_addc_u32 s5, s5, 0
	v_pk_mul_f32 v[52:53], v[52:53], v[250:251] op_sel_hi:[1,0]
	v_pk_mul_f32 v[48:49], v[48:49], v[250:251] op_sel_hi:[1,0]
	v_pk_mul_f32 v[216:217], v[52:53], s[2:3] op_sel_hi:[1,0]
; __device__ __forceinline__ float sigmoidf_(float v) { return __builtin_amdgcn_rcpf(1.0f + __expf(-v)); }
; __device__ __forceinline__ u32x4 pack8(const f32x4 a, const f32x4 b) { u32x4 w; w.x = cvt_pk_bf16(a[0], a[1]); w.y = cvt_pk_bf16(a[2], a[3]); w.z = cvt_pk_bf16(b[0], b[1]); w.w = cvt_pk_bf16(b[2], b[3]); return w; }
; #define MEMFENCE asm volatile("" ::: "memory")
; #define G_WAIT_V(n) asm volatile("s_waitcnt vmcnt(" #n ")" ::: "memory")
; #define G_BAR __builtin_amdgcn_s_barrier()
;     template <int KIND> __device__ __forceinline__ void run(f32x4 (&acc)[2][2][4][2], const Unit& u, int tid_in) const {
;     ...
;         if constexpr (KIND == K_FFI) { bf16_t* act = zb; float rs[8]; get_rs(u, wr, fr, rs);
; #pragma unroll
;             for (int ai = 0; ai < 2; ++ai)
; #pragma unroll
;                 for (int m = 0; m < 4; ++m) { int row = rbase + ai * 128 + m * 16; asm volatile("" : "+v"(row)); const float r = rs[ai * 4 + m]; f32x4 o[2];
; #pragma unroll
;                     for (int n = 0; n < 2; ++n) { const f32x4 g = acc[ai][0][m][n] * r, v = acc[ai][1][m][n] * r;
; #pragma unroll
;                         for (int j = 0; j < 4; ++j) o[n][j] = g[j] * sigmoidf_(g[j]) * v[j]; }
;                     *(u32x4*)(act + (size_t)row * ZW + u.pn * 128 + cl) = pack8(o[0], o[1]); MEMFENCE; }
;     ...
;         cur = nxt; cA = nA; cB = nB; ++ui;
;     }
;     G_WAIT_V(0);
;     if (wr == 0) G_BAR;
;     G_BAR;
	v_pk_mul_f32 v[54:55], v[54:55], v[250:251] op_sel_hi:[1,0]
	v_pk_mul_f32 v[50:51], v[50:51], v[250:251] op_sel_hi:[1,0]
	v_pk_mul_f32 v[218:219], v[54:55], s[2:3] op_sel_hi:[1,0]
	v_pk_mul_f32 v[44:45], v[44:45], v[250:251] op_sel_hi:[1,0]
	v_pk_mul_f32 v[40:41], v[40:41], v[250:251] op_sel_hi:[1,0]
	v_pk_mul_f32 v[220:221], v[44:45], s[2:3] op_sel_hi:[1,0]
	v_pk_mul_f32 v[46:47], v[46:47], v[250:251] op_sel_hi:[1,0]
	v_pk_mul_f32 v[42:43], v[42:43], v[250:251] op_sel_hi:[1,0]
	v_pk_mul_f32 v[222:223], v[46:47], s[2:3] op_sel_hi:[1,0]
	v_exp_f32_e32 v216, v216
	v_exp_f32_e32 v217, v217
	v_exp_f32_e32 v218, v218
	v_exp_f32_e32 v219, v219
	v_exp_f32_e32 v220, v220
	v_exp_f32_e32 v221, v221
	v_exp_f32_e32 v222, v222
	v_exp_f32_e32 v223, v223
	v_pk_add_f32 v[216:217], v[216:217], s[100:101] op_sel_hi:[1,0]
	v_pk_add_f32 v[218:219], v[218:219], s[100:101] op_sel_hi:[1,0]
	v_pk_add_f32 v[220:221], v[220:221], s[100:101] op_sel_hi:[1,0]
	v_pk_add_f32 v[222:223], v[222:223], s[100:101] op_sel_hi:[1,0]
	v_rcp_f32_e32 v216, v216
	v_rcp_f32_e32 v217, v217
	v_rcp_f32_e32 v218, v218
	v_rcp_f32_e32 v219, v219
	v_rcp_f32_e32 v220, v220
	v_rcp_f32_e32 v221, v221
	v_rcp_f32_e32 v222, v222
	v_rcp_f32_e32 v223, v223
	v_pk_mul_f32 v[52:53], v[52:53], v[216:217]
	v_pk_mul_f32 v[54:55], v[54:55], v[218:219]
	v_pk_mul_f32 v[44:45], v[44:45], v[220:221]
	v_pk_mul_f32 v[46:47], v[46:47], v[222:223]
	v_pk_mul_f32 v[52:53], v[52:53], v[48:49]
	v_pk_mul_f32 v[54:55], v[54:55], v[50:51]
	v_pk_mul_f32 v[44:45], v[44:45], v[40:41]
	v_pk_mul_f32 v[46:47], v[46:47], v[42:43]
	v_cvt_pk_bf16_f32 v236, v52, v53
	v_cvt_pk_bf16_f32 v237, v54, v55
	v_cvt_pk_bf16_f32 v238, v44, v45
	v_cvt_pk_bf16_f32 v239, v46, v47
	global_store_dwordx4 v140, v[236:239], s[4:5]
	s_add_u32 s4, s4, 0x16000
	s_addc_u32 s5, s5, 0
	v_pk_mul_f32 v[36:37], v[36:37], v[252:253] op_sel_hi:[1,0]
	v_pk_mul_f32 v[32:33], v[32:33], v[252:253] op_sel_hi:[1,0]
	v_pk_mul_f32 v[216:217], v[36:37], s[2:3] op_sel_hi:[1,0]
	v_pk_mul_f32 v[38:39], v[38:39], v[252:253] op_sel_hi:[1,0]
	v_pk_mul_f32 v[34:35], v[34:35], v[252:253] op_sel_hi:[1,0]
	v_pk_mul_f32 v[218:219], v[38:39], s[2:3] op_sel_hi:[1,0]
	v_pk_mul_f32 v[28:29], v[28:29], v[252:253] op_sel_hi:[1,0]
	v_pk_mul_f32 v[24:25], v[24:25], v[252:253] op_sel_hi:[1,0]
	v_pk_mul_f32 v[220:221], v[28:29], s[2:3] op_sel_hi:[1,0]
	v_pk_mul_f32 v[30:31], v[30:31], v[252:253] op_sel_hi:[1,0]
	v_pk_mul_f32 v[26:27], v[26:27], v[252:253] op_sel_hi:[1,0]
	v_pk_mul_f32 v[222:223], v[30:31], s[2:3] op_sel_hi:[1,0]
	v_exp_f32_e32 v216, v216
	v_exp_f32_e32 v217, v217
	v_exp_f32_e32 v218, v218
	v_exp_f32_e32 v219, v219
	v_exp_f32_e32 v220, v220
	v_exp_f32_e32 v221, v221
	v_exp_f32_e32 v222, v222
	v_exp_f32_e32 v223, v223
	v_pk_add_f32 v[216:217], v[216:217], s[100:101] op_sel_hi:[1,0]
	v_pk_add_f32 v[218:219], v[218:219], s[100:101] op_sel_hi:[1,0]
	v_pk_add_f32 v[220:221], v[220:221], s[100:101] op_sel_hi:[1,0]
	v_pk_add_f32 v[222:223], v[222:223], s[100:101] op_sel_hi:[1,0]
	v_rcp_f32_e32 v216, v216
	v_rcp_f32_e32 v217, v217
	v_rcp_f32_e32 v218, v218
	v_rcp_f32_e32 v219, v219
	v_rcp_f32_e32 v220, v220
	v_rcp_f32_e32 v221, v221
	v_rcp_f32_e32 v222, v222
	v_rcp_f32_e32 v223, v223
	v_pk_mul_f32 v[36:37], v[36:37], v[216:217]
	v_pk_mul_f32 v[38:39], v[38:39], v[218:219]
	v_pk_mul_f32 v[28:29], v[28:29], v[220:221]
	v_pk_mul_f32 v[30:31], v[30:31], v[222:223]
	v_pk_mul_f32 v[36:37], v[36:37], v[32:33]
	v_pk_mul_f32 v[38:39], v[38:39], v[34:35]
	v_pk_mul_f32 v[28:29], v[28:29], v[24:25]
	v_pk_mul_f32 v[30:31], v[30:31], v[26:27]
	v_cvt_pk_bf16_f32 v236, v36, v37
	v_cvt_pk_bf16_f32 v237, v38, v39
	v_cvt_pk_bf16_f32 v238, v28, v29
	v_cvt_pk_bf16_f32 v239, v30, v31
	global_store_dwordx4 v140, v[236:239], s[4:5]
	s_add_u32 s4, s4, 0x16000
	s_addc_u32 s5, s5, 0
	v_pk_mul_f32 v[20:21], v[20:21], v[254:255] op_sel_hi:[1,0]
	v_pk_mul_f32 v[16:17], v[16:17], v[254:255] op_sel_hi:[1,0]
	v_pk_mul_f32 v[216:217], v[20:21], s[2:3] op_sel_hi:[1,0]
	v_pk_mul_f32 v[22:23], v[22:23], v[254:255] op_sel_hi:[1,0]
	v_pk_mul_f32 v[18:19], v[18:19], v[254:255] op_sel_hi:[1,0]
	v_pk_mul_f32 v[218:219], v[22:23], s[2:3] op_sel_hi:[1,0]
	v_pk_mul_f32 v[12:13], v[12:13], v[254:255] op_sel_hi:[1,0]
	v_pk_mul_f32 v[8:9], v[8:9], v[254:255] op_sel_hi:[1,0]
	v_pk_mul_f32 v[220:221], v[12:13], s[2:3] op_sel_hi:[1,0]
	v_pk_mul_f32 v[14:15], v[14:15], v[254:255] op_sel_hi:[1,0]
	v_pk_mul_f32 v[10:11], v[10:11], v[254:255] op_sel_hi:[1,0]
	v_pk_mul_f32 v[222:223], v[14:15], s[2:3] op_sel_hi:[1,0]
	v_exp_f32_e32 v216, v216
	v_exp_f32_e32 v217, v217
	v_exp_f32_e32 v218, v218
	v_exp_f32_e32 v219, v219
	v_exp_f32_e32 v220, v220
	v_exp_f32_e32 v221, v221
	v_exp_f32_e32 v222, v222
	v_exp_f32_e32 v223, v223
	v_pk_add_f32 v[216:217], v[216:217], s[100:101] op_sel_hi:[1,0]
	v_pk_add_f32 v[218:219], v[218:219], s[100:101] op_sel_hi:[1,0]
	v_pk_add_f32 v[220:221], v[220:221], s[100:101] op_sel_hi:[1,0]
	v_pk_add_f32 v[222:223], v[222:223], s[100:101] op_sel_hi:[1,0]
	v_rcp_f32_e32 v216, v216
	v_rcp_f32_e32 v217, v217
	v_rcp_f32_e32 v218, v218
	v_rcp_f32_e32 v219, v219
	v_rcp_f32_e32 v220, v220
	v_rcp_f32_e32 v221, v221
	v_rcp_f32_e32 v222, v222
	v_rcp_f32_e32 v223, v223
	v_pk_mul_f32 v[20:21], v[20:21], v[216:217]
	v_pk_mul_f32 v[22:23], v[22:23], v[218:219]
	v_pk_mul_f32 v[12:13], v[12:13], v[220:221]
	v_pk_mul_f32 v[14:15], v[14:15], v[222:223]
	v_pk_mul_f32 v[20:21], v[20:21], v[16:17]
	v_pk_mul_f32 v[22:23], v[22:23], v[18:19]
	v_pk_mul_f32 v[12:13], v[12:13], v[8:9]
	v_pk_mul_f32 v[14:15], v[14:15], v[10:11]
	v_cvt_pk_bf16_f32 v236, v20, v21
	v_cvt_pk_bf16_f32 v237, v22, v23
	v_cvt_pk_bf16_f32 v238, v12, v13
	v_cvt_pk_bf16_f32 v239, v14, v15
	global_store_dwordx4 v140, v[236:239], s[4:5]
	s_mov_b32 s38, s11
	s_mov_b32 s37, s10
	s_mov_b64 s[18:19], s[14:15]
	s_mov_b64 s[16:17], s[12:13]
	s_mov_b32 s33, s36
	s_and_b64 vcc, exec, s[8:9]
	s_cbranch_vccz .LBB0_1115
	s_cmp_eq_u32 s101, 2
	s_cbranch_scc0 .Ldbj_FFI_pe
	s_barrier

; #define G_STAGE(bufoff, gbase, o0, h64) do { \
;         __builtin_amdgcn_global_load_lds((const unsigned*)((const char*)(gbase) + (o0)), (LAS unsigned*)(lds + (bufoff) + ldsw), 16, 0, 0); \
;         __builtin_amdgcn_global_load_lds((const unsigned*)((const char*)(gbase) + (h64) + (o0)), (LAS unsigned*)(lds + (bufoff) + ldsw + 8192), 16, 0, 0); } while (0)
; #define G_LDA(dst, b, h) do { _Pragma("unroll") for (int m = 0; m < 4; ++m) _Pragma("unroll") for (int k = 0; k < 2; ++k) dst[m][k] = *(const LAS bf16x8*)(lds + G_SA(b, h) + aoff + m * 2048 + k * 1024); } while (0)
; #define G_LDB(dst, b, h) do { _Pragma("unroll") for (int n = 0; n < 2; ++n) _Pragma("unroll") for (int k = 0; k < 2; ++k) dst[n][k] = *(const LAS bf16x8*)(lds + G_SB(b, h) + boff + n * 2048 + k * 1024); } while (0)
; #define G_WAIT_L(n) asm volatile("s_waitcnt lgkmcnt(" #n ")" ::: "memory")
; #define G_BAR __builtin_amdgcn_s_barrier()
; #define G_SCHED __builtin_amdgcn_sched_barrier(0)
;     ...
;         for (int t = 0; t < nt; t += 2) {
;             const bool last = (t == nt - 2);
;             const char* a1 = cA + (size_t)(t + 1) * ckA;
;             const char* a2 = last ? nA : cA + (size_t)(t + 2) * ckA; const char* b2 = last ? nB : cB + (size_t)(t + 2) * kB;
;             const char* a3 = a2 + ckA; const char* b3 = b2 + kB;
;             G_LDB(B0, 0, 0); G_SCHED; G_LDA(At, 0, 0); G_STAGE(G_SA(1, 1), a1 + chA, cA0, qA);
;             G_WAIT_L(8); G_BAR; G_WAIT_L(0); G_MMA(0, 0, At, B0); G_BAR; G_SCHED;
;             G_LDB(B1, 0, 1); G_STAGE(G_SB(0, 0), b2, cB0, qB);
;             G_BAR; G_WAIT_L(0); G_MMA(0, 1, At, B1); G_BAR;
;     ...
;         if (!(cs.kind == K_MG_B && cur.aux < 2))
; #pragma unroll
;         for (int a = 0; a < 2; ++a)
; #pragma unroll
;             for (int b = 0; b < 2; ++b)
; #pragma unroll
;                 for (int m = 0; m < 4; ++m)
; #pragma unroll
;                     for (int n = 0; n < 2; ++n) acc[a][b][m][n] = (f32x4){0.f, 0.f, 0.f, 0.f};
.LBB0_1184:
	s_add_u32 s2, s2, 0xb0080
	s_addc_u32 s3, s3, 0
	s_add_u32 s6, s6, 0x100
	s_waitcnt lgkmcnt(0)
	v_mov_b64_e32 v[8:9], 0
	s_addc_u32 s7, s7, 0
	s_mov_b32 s21, -2
	v_mov_b64_e32 v[10:11], 0
	v_mov_b64_e32 v[12:13], 0
	v_mov_b64_e32 v[14:15], 0
	v_mov_b64_e32 v[24:25], 0
	v_mov_b64_e32 v[26:27], 0
	v_mov_b64_e32 v[28:29], 0
	v_mov_b64_e32 v[30:31], 0
	v_mov_b64_e32 v[40:41], 0
	v_mov_b64_e32 v[42:43], 0
	v_mov_b64_e32 v[44:45], 0
	v_mov_b64_e32 v[46:47], 0
	v_mov_b64_e32 v[56:57], 0
	v_mov_b64_e32 v[58:59], 0
	v_mov_b64_e32 v[60:61], 0
	v_mov_b64_e32 v[62:63], 0
	v_mov_b64_e32 v[16:17], 0
	v_mov_b64_e32 v[18:19], 0
	v_mov_b64_e32 v[20:21], 0
	v_mov_b64_e32 v[22:23], 0
	v_mov_b64_e32 v[32:33], 0
	v_mov_b64_e32 v[34:35], 0
	v_mov_b64_e32 v[36:37], 0
	v_mov_b64_e32 v[38:39], 0
	v_mov_b64_e32 v[48:49], 0
	v_mov_b64_e32 v[50:51], 0
	v_mov_b64_e32 v[52:53], 0
	v_mov_b64_e32 v[54:55], 0
	v_mov_b64_e32 v[64:65], 0
	v_mov_b64_e32 v[66:67], 0
	v_mov_b64_e32 v[68:69], 0
	v_mov_b64_e32 v[70:71], 0
	v_mov_b64_e32 v[72:73], 0
	v_mov_b64_e32 v[74:75], 0
	v_mov_b64_e32 v[76:77], 0
	v_mov_b64_e32 v[78:79], 0
	v_mov_b64_e32 v[88:89], 0
	v_mov_b64_e32 v[90:91], 0
	v_mov_b64_e32 v[92:93], 0
	v_mov_b64_e32 v[94:95], 0
	v_mov_b64_e32 v[104:105], 0
	v_mov_b64_e32 v[106:107], 0
	v_mov_b64_e32 v[108:109], 0
	v_mov_b64_e32 v[110:111], 0
	v_mov_b64_e32 v[120:121], 0
	v_mov_b64_e32 v[122:123], 0
	v_mov_b64_e32 v[124:125], 0
	v_mov_b64_e32 v[126:127], 0
	v_mov_b64_e32 v[80:81], 0
	v_mov_b64_e32 v[82:83], 0
	v_mov_b64_e32 v[84:85], 0
	v_mov_b64_e32 v[86:87], 0
	v_mov_b64_e32 v[96:97], 0
	v_mov_b64_e32 v[98:99], 0
	v_mov_b64_e32 v[100:101], 0
	v_mov_b64_e32 v[102:103], 0
	v_mov_b64_e32 v[112:113], 0
	v_mov_b64_e32 v[114:115], 0
	v_mov_b64_e32 v[116:117], 0
	v_mov_b64_e32 v[118:119], 0
	v_mov_b64_e32 v[128:129], 0
	v_mov_b64_e32 v[130:131], 0
	v_mov_b64_e32 v[132:133], 0
	v_mov_b64_e32 v[134:135], 0
	s_mov_b64 s[52:53], 0xb0080
	s_mov_b64 s[54:55], 0x108080
	s_cmp_eq_u32 s101, 2
	s_cselect_b32 s101, 0, s101
.LBB0_1185:
	s_add_u32 s4, s2, 0xfff50080
	s_addc_u32 s5, s3, -1
	s_add_i32 s33, 0, 0x10000
	v_add_u32_e32 v0, s33, v185
	ds_read_b128 v[136:139], v0
	ds_read_b128 v[140:143], v0 offset:1024
	ds_read_b128 v[144:147], v0 offset:2048
	ds_read_b128 v[148:151], v0 offset:3072
	s_cmp_eq_u32 s21, 40
	s_cselect_b32 s5, s17, s5
	s_cselect_b32 s4, s16, s4
	s_cselect_b32 s23, s19, s7
	s_cselect_b32 s22, s18, s6
	v_lshl_add_u64 v[204:205], s[2:3], 0, v[174:175]
	s_add_i32 m0, s26, 0xc000
	ds_read_b128 v[152:155], v195
	ds_read_b128 v[156:159], v195 offset:1024
	ds_read_b128 v[160:163], v195 offset:2048
	ds_read_b128 v[164:167], v195 offset:3072
	ds_read_b128 v[176:179], v195 offset:4096
	ds_read_b128 v[180:183], v195 offset:5120
	ds_read_b128 v[196:199], v195 offset:6144
	ds_read_b128 v[200:203], v195 offset:7168
	global_load_lds_dwordx4 v[204:205], off
	v_lshl_add_u64 v[204:205], v[204:205], 0, s[86:87]
	s_add_i32 m0, s26, 0xe000
	s_nop 0
	global_load_lds_dwordx4 v[204:205], off
	s_waitcnt lgkmcnt(8)
	s_cmp_eq_u32 s101, 1
	s_cbranch_scc1 .Ldb_FFO_sk
	s_barrier
.Ldb_FFO_sk:
	s_mov_b32 s101, 0
	s_waitcnt lgkmcnt(0)
	v_mfma_f32_16x16x32_bf16 v[132:135], v[136:139], v[152:155], v[132:135]
	v_mfma_f32_16x16x32_bf16 v[128:131], v[144:147], v[152:155], v[128:131]
	v_mfma_f32_16x16x32_bf16 v[116:119], v[136:139], v[160:163], v[116:119]
	v_mfma_f32_16x16x32_bf16 v[112:115], v[144:147], v[160:163], v[112:115]
	v_mfma_f32_16x16x32_bf16 v[100:103], v[136:139], v[176:179], v[100:103]
	v_mfma_f32_16x16x32_bf16 v[96:99], v[144:147], v[176:179], v[96:99]
	v_mfma_f32_16x16x32_bf16 v[84:87], v[136:139], v[196:199], v[84:87]
	v_mfma_f32_16x16x32_bf16 v[80:83], v[144:147], v[196:199], v[80:83]
	v_mfma_f32_16x16x32_bf16 v[132:135], v[140:143], v[156:159], v[132:135]
	v_mfma_f32_16x16x32_bf16 v[128:131], v[148:151], v[156:159], v[128:131]
	v_mfma_f32_16x16x32_bf16 v[116:119], v[140:143], v[164:167], v[116:119]
	v_mfma_f32_16x16x32_bf16 v[112:115], v[148:151], v[164:167], v[112:115]
	v_mfma_f32_16x16x32_bf16 v[100:103], v[140:143], v[180:183], v[100:103]
	v_mfma_f32_16x16x32_bf16 v[96:99], v[148:151], v[180:183], v[96:99]
	v_mfma_f32_16x16x32_bf16 v[84:87], v[140:143], v[200:203], v[84:87]
	v_mfma_f32_16x16x32_bf16 v[80:83], v[148:151], v[200:203], v[80:83]
	s_barrier
	s_add_i32 s44, 0, 0x14000
	v_lshl_add_u64 v[220:221], s[22:23], 0, v[172:173]
	s_add_i32 s22, s33, s25
	v_add_u32_e32 v0, s44, v185
	s_mov_b32 m0, s22
	ds_read_b128 v[204:207], v0
	ds_read_b128 v[208:211], v0 offset:1024
	ds_read_b128 v[212:215], v0 offset:2048
	ds_read_b128 v[216:219], v0 offset:3072
	global_load_lds_dwordx4 v[220:221], off
	v_lshl_add_u64 v[222:223], v[220:221], 0, s[86:87]
	s_add_i32 m0, s22, 0x2000
	s_nop 0
	global_load_lds_dwordx4 v[222:223], off
	s_barrier
	s_waitcnt lgkmcnt(0)
	v_mfma_f32_16x16x32_bf16 v[124:127], v[204:207], v[152:155], v[124:127]
	v_mfma_f32_16x16x32_bf16 v[120:123], v[212:215], v[152:155], v[120:123]
	v_mfma_f32_16x16x32_bf16 v[108:111], v[204:207], v[160:163], v[108:111]
	v_mfma_f32_16x16x32_bf16 v[104:107], v[212:215], v[160:163], v[104:107]
	v_mfma_f32_16x16x32_bf16 v[92:95], v[204:207], v[176:179], v[92:95]
	v_mfma_f32_16x16x32_bf16 v[88:91], v[212:215], v[176:179], v[88:91]
	v_mfma_f32_16x16x32_bf16 v[76:79], v[204:207], v[196:199], v[76:79]
	v_mfma_f32_16x16x32_bf16 v[72:75], v[212:215], v[196:199], v[72:75]
	v_mfma_f32_16x16x32_bf16 v[124:127], v[208:211], v[156:159], v[124:127]
	v_mfma_f32_16x16x32_bf16 v[120:123], v[216:219], v[156:159], v[120:123]
	v_mfma_f32_16x16x32_bf16 v[108:111], v[208:211], v[164:167], v[108:111]
	v_mfma_f32_16x16x32_bf16 v[104:107], v[216:219], v[164:167], v[104:107]
	v_mfma_f32_16x16x32_bf16 v[92:95], v[208:211], v[180:183], v[92:95]
	v_mfma_f32_16x16x32_bf16 v[88:91], v[216:219], v[180:183], v[88:91]
	v_mfma_f32_16x16x32_bf16 v[76:79], v[208:211], v[200:203], v[76:79]
	v_mfma_f32_16x16x32_bf16 v[72:75], v[216:219], v[200:203], v[72:75]
	s_barrier
; #define G_STAGE(bufoff, gbase, o0, h64) do { \
;         __builtin_amdgcn_global_load_lds((const unsigned*)((const char*)(gbase) + (o0)), (LAS unsigned*)(lds + (bufoff) + ldsw), 16, 0, 0); \
;         __builtin_amdgcn_global_load_lds((const unsigned*)((const char*)(gbase) + (h64) + (o0)), (LAS unsigned*)(lds + (bufoff) + ldsw + 8192), 16, 0, 0); } while (0)
; #define G_LDA(dst, b, h) do { _Pragma("unroll") for (int m = 0; m < 4; ++m) _Pragma("unroll") for (int k = 0; k < 2; ++k) dst[m][k] = *(const LAS bf16x8*)(lds + G_SA(b, h) + aoff + m * 2048 + k * 1024); } while (0)
; #define G_LDB(dst, b, h) do { _Pragma("unroll") for (int n = 0; n < 2; ++n) _Pragma("unroll") for (int k = 0; k < 2; ++k) dst[n][k] = *(const LAS bf16x8*)(lds + G_SB(b, h) + boff + n * 2048 + k * 1024); } while (0)
; #define G_WAIT_V(n) asm volatile("s_waitcnt vmcnt(" #n ")" ::: "memory")
; #define G_WAIT_L(n) asm volatile("s_waitcnt lgkmcnt(" #n ")" ::: "memory")
; #define G_BAR __builtin_amdgcn_s_barrier()
; #define G_SCHED __builtin_amdgcn_sched_barrier(0)
;     ...
;             G_BAR; G_WAIT_L(0); G_MMA(0, 1, At, B1); G_BAR;
;             G_LDA(At, 0, 1); G_STAGE(G_SA(0, 0), a2, cA0, qA);
;             G_BAR; G_WAIT_L(0); G_MMA(1, 0, At, B0); G_BAR; G_SCHED;
;             G_STAGE(G_SB(0, 1), b2 + chB, cB0, qB);
;             G_WAIT_V(6); G_BAR; G_MMA(1, 1, At, B1); G_BAR;
;             G_LDB(B0, 1, 0); G_SCHED; G_LDA(At, 1, 0); G_STAGE(G_SA(0, 1), a2 + chA, cA0, qA);
;             G_WAIT_L(8); G_BAR; G_WAIT_L(0); G_MMA(0, 0, At, B0); G_BAR; G_SCHED;
	s_mov_b32 m0, s26
	v_lshl_add_u64 v[222:223], s[4:5], 0, v[2:3]
	ds_read_b128 v[152:155], v195 offset:16384
	ds_read_b128 v[156:159], v195 offset:17408
	ds_read_b128 v[160:163], v195 offset:18432
	ds_read_b128 v[164:167], v195 offset:19456
	ds_read_b128 v[176:179], v195 offset:20480
	ds_read_b128 v[180:183], v195 offset:21504
	ds_read_b128 v[196:199], v195 offset:22528
	ds_read_b128 v[200:203], v195 offset:23552
	global_load_lds_dwordx4 v[222:223], off
	v_lshl_add_u64 v[224:225], v[222:223], 0, s[86:87]
	s_mov_b32 m0, s27
	s_nop 0
	global_load_lds_dwordx4 v[224:225], off
	s_barrier
	s_waitcnt lgkmcnt(0)
	v_mfma_f32_16x16x32_bf16 v[68:71], v[136:139], v[152:155], v[68:71]
	v_mfma_f32_16x16x32_bf16 v[64:67], v[144:147], v[152:155], v[64:67]
	v_mfma_f32_16x16x32_bf16 v[52:55], v[136:139], v[160:163], v[52:55]
	v_mfma_f32_16x16x32_bf16 v[48:51], v[144:147], v[160:163], v[48:51]
	v_mfma_f32_16x16x32_bf16 v[36:39], v[136:139], v[176:179], v[36:39]
	v_mfma_f32_16x16x32_bf16 v[32:35], v[144:147], v[176:179], v[32:35]
	v_mfma_f32_16x16x32_bf16 v[20:23], v[136:139], v[196:199], v[20:23]
	v_mfma_f32_16x16x32_bf16 v[16:19], v[144:147], v[196:199], v[16:19]
	v_mfma_f32_16x16x32_bf16 v[68:71], v[140:143], v[156:159], v[68:71]
	v_mfma_f32_16x16x32_bf16 v[64:67], v[148:151], v[156:159], v[64:67]
	v_mfma_f32_16x16x32_bf16 v[52:55], v[140:143], v[164:167], v[52:55]
	v_mfma_f32_16x16x32_bf16 v[48:51], v[148:151], v[164:167], v[48:51]
	v_mfma_f32_16x16x32_bf16 v[36:39], v[140:143], v[180:183], v[36:39]
	v_mfma_f32_16x16x32_bf16 v[32:35], v[148:151], v[180:183], v[32:35]
	v_mfma_f32_16x16x32_bf16 v[20:23], v[140:143], v[200:203], v[20:23]
	v_mfma_f32_16x16x32_bf16 v[16:19], v[148:151], v[200:203], v[16:19]
	s_barrier
	s_add_i32 s4, s44, s25
	v_lshl_add_u64 v[136:137], v[220:221], 0, s[88:89]
	s_mov_b32 m0, s4
	s_nop 0
	global_load_lds_dwordx4 v[136:137], off
	v_lshl_add_u64 v[136:137], v[220:221], 0, s[64:65]
	s_add_i32 m0, s4, 0x2000
	s_nop 0
	global_load_lds_dwordx4 v[136:137], off
	s_waitcnt vmcnt(6)
	s_barrier
	v_mfma_f32_16x16x32_bf16 v[60:63], v[204:207], v[152:155], v[60:63]
	v_mfma_f32_16x16x32_bf16 v[56:59], v[212:215], v[152:155], v[56:59]
	v_mfma_f32_16x16x32_bf16 v[44:47], v[204:207], v[160:163], v[44:47]
	v_mfma_f32_16x16x32_bf16 v[40:43], v[212:215], v[160:163], v[40:43]
	v_mfma_f32_16x16x32_bf16 v[28:31], v[204:207], v[176:179], v[28:31]
	v_mfma_f32_16x16x32_bf16 v[24:27], v[212:215], v[176:179], v[24:27]
	v_mfma_f32_16x16x32_bf16 v[12:15], v[204:207], v[196:199], v[12:15]
	v_mfma_f32_16x16x32_bf16 v[8:11], v[212:215], v[196:199], v[8:11]
	v_mfma_f32_16x16x32_bf16 v[60:63], v[208:211], v[156:159], v[60:63]
	v_mfma_f32_16x16x32_bf16 v[56:59], v[216:219], v[156:159], v[56:59]
	v_mfma_f32_16x16x32_bf16 v[44:47], v[208:211], v[164:167], v[44:47]
	v_mfma_f32_16x16x32_bf16 v[40:43], v[216:219], v[164:167], v[40:43]
	v_mfma_f32_16x16x32_bf16 v[28:31], v[208:211], v[180:183], v[28:31]
	v_mfma_f32_16x16x32_bf16 v[24:27], v[216:219], v[180:183], v[24:27]
	v_mfma_f32_16x16x32_bf16 v[12:15], v[208:211], v[200:203], v[12:15]
	v_mfma_f32_16x16x32_bf16 v[8:11], v[216:219], v[200:203], v[8:11]
	s_barrier
	s_add_i32 s4, 0, 0x18000
	v_add_u32_e32 v0, s4, v185
	ds_read_b128 v[136:139], v0
	ds_read_b128 v[140:143], v0 offset:1024
	ds_read_b128 v[144:147], v0 offset:2048
	ds_read_b128 v[148:151], v0 offset:3072
	s_mov_b32 m0, s29
	v_lshl_add_u64 v[204:205], v[222:223], 0, s[88:89]
	ds_read_b128 v[152:155], v195 offset:32768
	ds_read_b128 v[156:159], v195 offset:33792
	ds_read_b128 v[160:163], v195 offset:34816
	ds_read_b128 v[164:167], v195 offset:35840
	ds_read_b128 v[176:179], v195 offset:36864
	ds_read_b128 v[180:183], v195 offset:37888
	ds_read_b128 v[196:199], v195 offset:38912
	ds_read_b128 v[200:203], v195 offset:39936
	global_load_lds_dwordx4 v[204:205], off
	v_lshl_add_u64 v[204:205], v[222:223], 0, s[64:65]
	s_mov_b32 m0, s30
	s_nop 0
	global_load_lds_dwordx4 v[204:205], off
	s_waitcnt lgkmcnt(8)
	s_barrier
	s_waitcnt lgkmcnt(0)
	v_mfma_f32_16x16x32_bf16 v[132:135], v[136:139], v[152:155], v[132:135]
	v_mfma_f32_16x16x32_bf16 v[128:131], v[144:147], v[152:155], v[128:131]
	v_mfma_f32_16x16x32_bf16 v[116:119], v[136:139], v[160:163], v[116:119]
	v_mfma_f32_16x16x32_bf16 v[112:115], v[144:147], v[160:163], v[112:115]
	v_mfma_f32_16x16x32_bf16 v[100:103], v[136:139], v[176:179], v[100:103]
	v_mfma_f32_16x16x32_bf16 v[96:99], v[144:147], v[176:179], v[96:99]
	v_mfma_f32_16x16x32_bf16 v[84:87], v[136:139], v[196:199], v[84:87]
	v_mfma_f32_16x16x32_bf16 v[80:83], v[144:147], v[196:199], v[80:83]
	v_mfma_f32_16x16x32_bf16 v[132:135], v[140:143], v[156:159], v[132:135]
	v_mfma_f32_16x16x32_bf16 v[128:131], v[148:151], v[156:159], v[128:131]
	v_mfma_f32_16x16x32_bf16 v[116:119], v[140:143], v[164:167], v[116:119]
	v_mfma_f32_16x16x32_bf16 v[112:115], v[148:151], v[164:167], v[112:115]
	v_mfma_f32_16x16x32_bf16 v[100:103], v[140:143], v[180:183], v[100:103]
	v_mfma_f32_16x16x32_bf16 v[96:99], v[148:151], v[180:183], v[96:99]
	v_mfma_f32_16x16x32_bf16 v[84:87], v[140:143], v[200:203], v[84:87]
	v_mfma_f32_16x16x32_bf16 v[80:83], v[148:151], v[200:203], v[80:83]
	s_barrier
; #define G_STAGE(bufoff, gbase, o0, h64) do { \
;         __builtin_amdgcn_global_load_lds((const unsigned*)((const char*)(gbase) + (o0)), (LAS unsigned*)(lds + (bufoff) + ldsw), 16, 0, 0); \
;         __builtin_amdgcn_global_load_lds((const unsigned*)((const char*)(gbase) + (h64) + (o0)), (LAS unsigned*)(lds + (bufoff) + ldsw + 8192), 16, 0, 0); } while (0)
; #define G_LDA(dst, b, h) do { _Pragma("unroll") for (int m = 0; m < 4; ++m) _Pragma("unroll") for (int k = 0; k < 2; ++k) dst[m][k] = *(const LAS bf16x8*)(lds + G_SA(b, h) + aoff + m * 2048 + k * 1024); } while (0)
; #define G_LDB(dst, b, h) do { _Pragma("unroll") for (int n = 0; n < 2; ++n) _Pragma("unroll") for (int k = 0; k < 2; ++k) dst[n][k] = *(const LAS bf16x8*)(lds + G_SB(b, h) + boff + n * 2048 + k * 1024); } while (0)
; #define G_WAIT_V(n) asm volatile("s_waitcnt vmcnt(" #n ")" ::: "memory")
; #define G_WAIT_L(n) asm volatile("s_waitcnt lgkmcnt(" #n ")" ::: "memory")
; #define G_BAR __builtin_amdgcn_s_barrier()
; #define G_SCHED __builtin_amdgcn_sched_barrier(0)
;     ...
;             G_WAIT_L(8); G_BAR; G_WAIT_L(0); G_MMA(0, 0, At, B0); G_BAR; G_SCHED;
;             G_LDB(B1, 1, 1); G_STAGE(G_SB(1, 0), b3, cB0, qB);
;             G_BAR; G_WAIT_L(0); G_MMA(0, 1, At, B1); G_BAR;
;             G_LDA(At, 1, 1); G_STAGE(G_SA(1, 0), a3, cA0, qA);
;             G_BAR; G_WAIT_L(0); G_MMA(1, 0, At, B0); G_BAR; G_SCHED;
;             G_STAGE(G_SB(1, 1), b3 + chB, cB0, qB);
;             G_WAIT_V(6); G_BAR; G_MMA(1, 1, At, B1); G_BAR;
;         }
	s_add_i32 s5, 0, 0x1c000
	s_add_i32 s4, s4, s25
	v_add_u32_e32 v0, s5, v185
	v_lshl_add_u64 v[224:225], v[220:221], 0, s[46:47]
	s_mov_b32 m0, s4
	ds_read_b128 v[204:207], v0
	ds_read_b128 v[208:211], v0 offset:1024
	ds_read_b128 v[212:215], v0 offset:2048
	ds_read_b128 v[216:219], v0 offset:3072
	global_load_lds_dwordx4 v[224:225], off
	v_lshl_add_u64 v[224:225], v[220:221], 0, s[66:67]
	s_add_i32 m0, s4, 0x2000
	s_nop 0
	global_load_lds_dwordx4 v[224:225], off
	s_barrier
	s_waitcnt lgkmcnt(0)
	v_mfma_f32_16x16x32_bf16 v[124:127], v[204:207], v[152:155], v[124:127]
	v_mfma_f32_16x16x32_bf16 v[120:123], v[212:215], v[152:155], v[120:123]
	v_mfma_f32_16x16x32_bf16 v[108:111], v[204:207], v[160:163], v[108:111]
	v_mfma_f32_16x16x32_bf16 v[104:107], v[212:215], v[160:163], v[104:107]
	v_mfma_f32_16x16x32_bf16 v[92:95], v[204:207], v[176:179], v[92:95]
	v_mfma_f32_16x16x32_bf16 v[88:91], v[212:215], v[176:179], v[88:91]
	v_mfma_f32_16x16x32_bf16 v[76:79], v[204:207], v[196:199], v[76:79]
	v_mfma_f32_16x16x32_bf16 v[72:75], v[212:215], v[196:199], v[72:75]
	v_mfma_f32_16x16x32_bf16 v[124:127], v[208:211], v[156:159], v[124:127]
	v_mfma_f32_16x16x32_bf16 v[120:123], v[216:219], v[156:159], v[120:123]
	v_mfma_f32_16x16x32_bf16 v[108:111], v[208:211], v[164:167], v[108:111]
	v_mfma_f32_16x16x32_bf16 v[104:107], v[216:219], v[164:167], v[104:107]
	v_mfma_f32_16x16x32_bf16 v[92:95], v[208:211], v[180:183], v[92:95]
	v_mfma_f32_16x16x32_bf16 v[88:91], v[216:219], v[180:183], v[88:91]
	v_mfma_f32_16x16x32_bf16 v[76:79], v[208:211], v[200:203], v[76:79]
	v_mfma_f32_16x16x32_bf16 v[72:75], v[216:219], v[200:203], v[72:75]
	s_barrier
	s_mov_b32 m0, s31
	v_lshl_add_u64 v[224:225], v[222:223], 0, s[46:47]
	ds_read_b128 v[152:155], v195 offset:49152
	ds_read_b128 v[156:159], v195 offset:50176
	ds_read_b128 v[160:163], v195 offset:51200
	ds_read_b128 v[164:167], v195 offset:52224
	ds_read_b128 v[176:179], v195 offset:53248
	ds_read_b128 v[180:183], v195 offset:54272
	ds_read_b128 v[196:199], v195 offset:55296
	ds_read_b128 v[200:203], v195 offset:56320
	global_load_lds_dwordx4 v[224:225], off
	v_lshl_add_u64 v[222:223], v[222:223], 0, s[66:67]
	s_mov_b32 m0, s34
	s_nop 0
	global_load_lds_dwordx4 v[222:223], off
	s_barrier
	s_waitcnt lgkmcnt(0)
	v_mfma_f32_16x16x32_bf16 v[68:71], v[136:139], v[152:155], v[68:71]
	v_mfma_f32_16x16x32_bf16 v[64:67], v[144:147], v[152:155], v[64:67]
	v_mfma_f32_16x16x32_bf16 v[52:55], v[136:139], v[160:163], v[52:55]
	v_mfma_f32_16x16x32_bf16 v[48:51], v[144:147], v[160:163], v[48:51]
	v_mfma_f32_16x16x32_bf16 v[36:39], v[136:139], v[176:179], v[36:39]
	v_mfma_f32_16x16x32_bf16 v[32:35], v[144:147], v[176:179], v[32:35]
	v_mfma_f32_16x16x32_bf16 v[20:23], v[136:139], v[196:199], v[20:23]
	v_mfma_f32_16x16x32_bf16 v[16:19], v[144:147], v[196:199], v[16:19]
	v_mfma_f32_16x16x32_bf16 v[68:71], v[140:143], v[156:159], v[68:71]
	v_mfma_f32_16x16x32_bf16 v[64:67], v[148:151], v[156:159], v[64:67]
	v_mfma_f32_16x16x32_bf16 v[52:55], v[140:143], v[164:167], v[52:55]
	v_mfma_f32_16x16x32_bf16 v[48:51], v[148:151], v[164:167], v[48:51]
	v_mfma_f32_16x16x32_bf16 v[36:39], v[140:143], v[180:183], v[36:39]
	v_mfma_f32_16x16x32_bf16 v[32:35], v[148:151], v[180:183], v[32:35]
	v_mfma_f32_16x16x32_bf16 v[20:23], v[140:143], v[200:203], v[20:23]
	v_mfma_f32_16x16x32_bf16 v[16:19], v[148:151], v[200:203], v[16:19]
	s_barrier
	s_add_i32 s4, s5, s25
	v_lshl_add_u64 v[136:137], v[220:221], 0, s[52:53]
	s_mov_b32 m0, s4
	s_nop 0
	global_load_lds_dwordx4 v[136:137], off
	v_lshl_add_u64 v[136:137], v[220:221], 0, s[54:55]
	s_add_i32 m0, s4, 0x2000
	s_nop 0
	global_load_lds_dwordx4 v[136:137], off
	s_add_i32 s21, s21, 2
	s_add_u32 s2, s2, 0x100
	s_addc_u32 s3, s3, 0
	s_add_u32 s6, s6, 0x100
	s_addc_u32 s7, s7, 0
	s_cmp_gt_u32 s21, 41
	s_waitcnt vmcnt(6)
	s_barrier
	v_mfma_f32_16x16x32_bf16 v[60:63], v[204:207], v[152:155], v[60:63]
	v_mfma_f32_16x16x32_bf16 v[56:59], v[212:215], v[152:155], v[56:59]
	v_mfma_f32_16x16x32_bf16 v[44:47], v[204:207], v[160:163], v[44:47]
	v_mfma_f32_16x16x32_bf16 v[40:43], v[212:215], v[160:163], v[40:43]
	v_mfma_f32_16x16x32_bf16 v[28:31], v[204:207], v[176:179], v[28:31]
	v_mfma_f32_16x16x32_bf16 v[24:27], v[212:215], v[176:179], v[24:27]
	v_mfma_f32_16x16x32_bf16 v[12:15], v[204:207], v[196:199], v[12:15]
	v_mfma_f32_16x16x32_bf16 v[8:11], v[212:215], v[196:199], v[8:11]
	v_mfma_f32_16x16x32_bf16 v[60:63], v[208:211], v[156:159], v[60:63]
	v_mfma_f32_16x16x32_bf16 v[56:59], v[216:219], v[156:159], v[56:59]
	v_mfma_f32_16x16x32_bf16 v[44:47], v[208:211], v[164:167], v[44:47]
	v_mfma_f32_16x16x32_bf16 v[40:43], v[216:219], v[164:167], v[40:43]
	v_mfma_f32_16x16x32_bf16 v[28:31], v[208:211], v[180:183], v[28:31]
	v_mfma_f32_16x16x32_bf16 v[24:27], v[216:219], v[180:183], v[24:27]
	v_mfma_f32_16x16x32_bf16 v[12:15], v[208:211], v[200:203], v[12:15]
	v_mfma_f32_16x16x32_bf16 v[8:11], v[216:219], v[200:203], v[8:11]
	s_cbranch_scc0 .Ldb_FFO_cont
	v_readfirstlane_b32 s101, v186
	s_cmpk_gt_u32 s101, 0xff
	s_cbranch_scc1 .Ldb_FFO_young
	s_barrier
	s_mov_b32 s101, 1
	s_branch .Ldb_FFO_exit

; #define G_STAGE(bufoff, gbase, o0, h64) do { \
;         __builtin_amdgcn_global_load_lds((const unsigned*)((const char*)(gbase) + (o0)), (LAS unsigned*)(lds + (bufoff) + ldsw), 16, 0, 0); \
;         __builtin_amdgcn_global_load_lds((const unsigned*)((const char*)(gbase) + (h64) + (o0)), (LAS unsigned*)(lds + (bufoff) + ldsw + 8192), 16, 0, 0); } while (0)
; #define G_LDA(dst, b, h) do { _Pragma("unroll") for (int m = 0; m < 4; ++m) _Pragma("unroll") for (int k = 0; k < 2; ++k) dst[m][k] = *(const LAS bf16x8*)(lds + G_SA(b, h) + aoff + m * 2048 + k * 1024); } while (0)
; #define G_LDB(dst, b, h) do { _Pragma("unroll") for (int n = 0; n < 2; ++n) _Pragma("unroll") for (int k = 0; k < 2; ++k) dst[n][k] = *(const LAS bf16x8*)(lds + G_SB(b, h) + boff + n * 2048 + k * 1024); } while (0)
; #define G_WAIT_L(n) asm volatile("s_waitcnt lgkmcnt(" #n ")" ::: "memory")
; #define G_BAR __builtin_amdgcn_s_barrier()
; #define G_SCHED __builtin_amdgcn_sched_barrier(0)
;     ...
;         for (int t = 0; t < nt; t += 2) {
;             const bool last = (t == nt - 2);
;             const char* a1 = cA + (size_t)(t + 1) * ckA;
;             const char* a2 = last ? nA : cA + (size_t)(t + 2) * ckA; const char* b2 = last ? nB : cB + (size_t)(t + 2) * kB;
;             const char* a3 = a2 + ckA; const char* b3 = b2 + kB;
;             G_LDB(B0, 0, 0); G_SCHED; G_LDA(At, 0, 0); G_STAGE(G_SA(1, 1), a1 + chA, cA0, qA);
;             G_WAIT_L(8); G_BAR; G_WAIT_L(0); G_MMA(0, 0, At, B0); G_BAR; G_SCHED;
;             G_LDB(B1, 0, 1); G_STAGE(G_SB(0, 0), b2, cB0, qB);
;             G_BAR; G_WAIT_L(0); G_MMA(0, 1, At, B1); G_BAR;
;     ...
;         if (!(cs.kind == K_MG_B && cur.aux < 2))
; #pragma unroll
;         for (int a = 0; a < 2; ++a)
; #pragma unroll
;             for (int b = 0; b < 2; ++b)
; #pragma unroll
;                 for (int m = 0; m < 4; ++m)
; #pragma unroll
;                     for (int n = 0; n < 2; ++n) acc[a][b][m][n] = (f32x4){0.f, 0.f, 0.f, 0.f};
.LBB0_1259:
	v_mov_b64_e32 v[8:9], 0
	s_mov_b64 s[18:19], 0
	s_mov_b64 s[14:15], -1
	s_mov_b64 s[16:17], 0
	v_mov_b64_e32 v[10:11], 0
	v_mov_b64_e32 v[12:13], 0
	v_mov_b64_e32 v[14:15], 0
	v_mov_b64_e32 v[16:17], 0
	v_mov_b64_e32 v[18:19], 0
	v_mov_b64_e32 v[24:25], 0
	v_mov_b64_e32 v[26:27], 0
	v_mov_b64_e32 v[32:33], 0
	v_mov_b64_e32 v[34:35], 0
	v_mov_b64_e32 v[40:41], 0
	v_mov_b64_e32 v[42:43], 0
	v_mov_b64_e32 v[48:49], 0
	v_mov_b64_e32 v[50:51], 0
	v_mov_b64_e32 v[56:57], 0
	v_mov_b64_e32 v[58:59], 0
	v_mov_b64_e32 v[20:21], 0
	v_mov_b64_e32 v[22:23], 0
	v_mov_b64_e32 v[28:29], 0
	v_mov_b64_e32 v[30:31], 0
	v_mov_b64_e32 v[36:37], 0
	v_mov_b64_e32 v[38:39], 0
	v_mov_b64_e32 v[44:45], 0
	v_mov_b64_e32 v[46:47], 0
	v_mov_b64_e32 v[52:53], 0
	v_mov_b64_e32 v[54:55], 0
	v_mov_b64_e32 v[60:61], 0
	v_mov_b64_e32 v[62:63], 0
	v_mov_b64_e32 v[64:65], 0
	v_mov_b64_e32 v[66:67], 0
	v_mov_b64_e32 v[68:69], 0
	v_mov_b64_e32 v[70:71], 0
	v_mov_b64_e32 v[72:73], 0
	v_mov_b64_e32 v[74:75], 0
	v_mov_b64_e32 v[76:77], 0
	v_mov_b64_e32 v[78:79], 0
	v_mov_b64_e32 v[80:81], 0
	v_mov_b64_e32 v[82:83], 0
	v_mov_b64_e32 v[88:89], 0
	v_mov_b64_e32 v[90:91], 0
	v_mov_b64_e32 v[96:97], 0
	v_mov_b64_e32 v[98:99], 0
	v_mov_b64_e32 v[104:105], 0
	v_mov_b64_e32 v[106:107], 0
	v_mov_b64_e32 v[112:113], 0
	v_mov_b64_e32 v[114:115], 0
	v_mov_b64_e32 v[120:121], 0
	v_mov_b64_e32 v[122:123], 0
	v_mov_b64_e32 v[84:85], 0
	v_mov_b64_e32 v[86:87], 0
	v_mov_b64_e32 v[92:93], 0
	v_mov_b64_e32 v[94:95], 0
	v_mov_b64_e32 v[100:101], 0
	v_mov_b64_e32 v[102:103], 0
	v_mov_b64_e32 v[108:109], 0
	v_mov_b64_e32 v[110:111], 0
	v_mov_b64_e32 v[116:117], 0
	v_mov_b64_e32 v[118:119], 0
	v_mov_b64_e32 v[124:125], 0
	v_mov_b64_e32 v[126:127], 0
	v_mov_b64_e32 v[128:129], 0
	v_mov_b64_e32 v[130:131], 0
	v_mov_b64_e32 v[132:133], 0
	v_mov_b64_e32 v[134:135], 0
	s_mov_b64 s[58:59], 0x10000
	s_cmp_eq_u32 s101, 2
	s_cselect_b32 s101, 0, s101
.LBB0_1260:
	s_add_u32 s22, s10, s18
	s_addc_u32 s23, s11, s19
	s_add_u32 s20, s22, 0x100
	s_addc_u32 s21, s23, 0
	s_and_b64 s[4:5], s[16:17], exec
	s_cselect_b32 s20, s6, s20
	s_cselect_b32 s21, s7, s21
	s_add_u32 s4, s12, s18
	s_addc_u32 s5, s13, s19
	s_add_u32 s18, s4, 0x100
	s_addc_u32 s19, s5, 0
	s_add_i32 s44, 0, 0x10000
	v_add_u32_e32 v139, s44, v137
	ds_read_b128 v[140:143], v139
	ds_read_b128 v[144:147], v139 offset:1024
	ds_read_b128 v[148:151], v139 offset:2048
	ds_read_b128 v[152:155], v139 offset:3072
	s_and_b64 s[4:5], s[16:17], exec
	s_cselect_b32 s16, s8, s18
	s_cselect_b32 s17, s9, s19
	s_add_i32 s5, 0, 0x14000
	s_add_i32 s43, 0, 0x18000
	s_add_i32 s18, 0, 0x1c000
	s_add_i32 s45, s44, s25
	s_add_i32 s51, s5, s25
	s_add_i32 s19, s43, s25
	s_add_i32 s53, s18, s25
	s_mov_b64 s[64:65], 0x8000
	s_mov_b64 s[62:63], 0x10080
	s_add_i32 m0, s31, 0xc000
	s_add_i32 s4, s31, 0xe000
	s_add_i32 s54, s45, 0x2000
	s_add_i32 s50, s51, 0x2000
	s_add_i32 s44, s19, 0x2000
	s_add_i32 s52, s53, 0x2000
	v_lshl_add_u64 v[184:185], s[22:23], 0, v[2:3]
	v_lshl_add_u64 v[204:205], v[184:185], 0, s[62:63]
	ds_read_b128 v[156:159], v138
	ds_read_b128 v[160:163], v138 offset:1024
	ds_read_b128 v[164:167], v138 offset:2048
	ds_read_b128 v[172:175], v138 offset:3072
	ds_read_b128 v[176:179], v138 offset:4096
	ds_read_b128 v[180:183], v138 offset:5120
	ds_read_b128 v[196:199], v138 offset:6144
	ds_read_b128 v[200:203], v138 offset:7168
	global_load_lds_dwordx4 v[204:205], off
	v_lshl_add_u64 v[184:185], v[184:185], 0, s[68:69]
	s_mov_b32 m0, s4
	s_nop 0
	global_load_lds_dwordx4 v[184:185], off
	s_waitcnt lgkmcnt(8)
	s_cmp_eq_u32 s101, 1
	s_cbranch_scc1 .Ldb_PLE0_sk
	s_barrier
.Ldb_PLE0_sk:
	s_mov_b32 s101, 0
	s_waitcnt lgkmcnt(0)
	v_mfma_f32_16x16x32_bf16 v[132:135], v[140:143], v[156:159], v[132:135]
	v_mfma_f32_16x16x32_bf16 v[128:131], v[148:151], v[156:159], v[128:131]
	v_mfma_f32_16x16x32_bf16 v[124:127], v[140:143], v[164:167], v[124:127]
	v_mfma_f32_16x16x32_bf16 v[116:119], v[148:151], v[164:167], v[116:119]
	v_mfma_f32_16x16x32_bf16 v[108:111], v[140:143], v[176:179], v[108:111]
	v_mfma_f32_16x16x32_bf16 v[100:103], v[148:151], v[176:179], v[100:103]
	v_mfma_f32_16x16x32_bf16 v[92:95], v[140:143], v[196:199], v[92:95]
	v_mfma_f32_16x16x32_bf16 v[84:87], v[148:151], v[196:199], v[84:87]
	v_mfma_f32_16x16x32_bf16 v[132:135], v[144:147], v[160:163], v[132:135]
	v_mfma_f32_16x16x32_bf16 v[128:131], v[152:155], v[160:163], v[128:131]
	v_mfma_f32_16x16x32_bf16 v[124:127], v[144:147], v[172:175], v[124:127]
	v_mfma_f32_16x16x32_bf16 v[116:119], v[152:155], v[172:175], v[116:119]
	v_mfma_f32_16x16x32_bf16 v[108:111], v[144:147], v[180:183], v[108:111]
	v_mfma_f32_16x16x32_bf16 v[100:103], v[152:155], v[180:183], v[100:103]
	v_mfma_f32_16x16x32_bf16 v[92:95], v[144:147], v[200:203], v[92:95]
	v_mfma_f32_16x16x32_bf16 v[84:87], v[152:155], v[200:203], v[84:87]
	s_barrier
	s_mov_b32 m0, s45
	v_add_u32_e32 v139, s5, v137
	v_lshl_add_u64 v[184:185], s[16:17], 0, v[0:1]
	ds_read_b128 v[204:207], v139
	ds_read_b128 v[208:211], v139 offset:1024
	ds_read_b128 v[212:215], v139 offset:2048
	ds_read_b128 v[216:219], v139 offset:3072
	global_load_lds_dwordx4 v[184:185], off
	v_lshl_add_u64 v[220:221], v[184:185], 0, s[64:65]
	s_mov_b32 m0, s54
	s_nop 0
	global_load_lds_dwordx4 v[220:221], off
	s_barrier
; #define G_STAGE(bufoff, gbase, o0, h64) do { \
;         __builtin_amdgcn_global_load_lds((const unsigned*)((const char*)(gbase) + (o0)), (LAS unsigned*)(lds + (bufoff) + ldsw), 16, 0, 0); \
;         __builtin_amdgcn_global_load_lds((const unsigned*)((const char*)(gbase) + (h64) + (o0)), (LAS unsigned*)(lds + (bufoff) + ldsw + 8192), 16, 0, 0); } while (0)
; #define G_LDA(dst, b, h) do { _Pragma("unroll") for (int m = 0; m < 4; ++m) _Pragma("unroll") for (int k = 0; k < 2; ++k) dst[m][k] = *(const LAS bf16x8*)(lds + G_SA(b, h) + aoff + m * 2048 + k * 1024); } while (0)
; #define G_LDB(dst, b, h) do { _Pragma("unroll") for (int n = 0; n < 2; ++n) _Pragma("unroll") for (int k = 0; k < 2; ++k) dst[n][k] = *(const LAS bf16x8*)(lds + G_SB(b, h) + boff + n * 2048 + k * 1024); } while (0)
; #define G_WAIT_V(n) asm volatile("s_waitcnt vmcnt(" #n ")" ::: "memory")
; #define G_WAIT_L(n) asm volatile("s_waitcnt lgkmcnt(" #n ")" ::: "memory")
; #define G_BAR __builtin_amdgcn_s_barrier()
; #define G_SCHED __builtin_amdgcn_sched_barrier(0)
;     ...
;             G_BAR; G_WAIT_L(0); G_MMA(0, 1, At, B1); G_BAR;
;             G_LDA(At, 0, 1); G_STAGE(G_SA(0, 0), a2, cA0, qA);
;             G_BAR; G_WAIT_L(0); G_MMA(1, 0, At, B0); G_BAR; G_SCHED;
;             G_STAGE(G_SB(0, 1), b2 + chB, cB0, qB);
;             G_WAIT_V(6); G_BAR; G_MMA(1, 1, At, B1); G_BAR;
;             G_LDB(B0, 1, 0); G_SCHED; G_LDA(At, 1, 0); G_STAGE(G_SA(0, 1), a2 + chA, cA0, qA);
;             G_WAIT_L(8); G_BAR; G_WAIT_L(0); G_MMA(0, 0, At, B0); G_BAR; G_SCHED;
;             G_LDB(B1, 1, 1); G_STAGE(G_SB(1, 0), b3, cB0, qB);
;             G_BAR; G_WAIT_L(0); G_MMA(0, 1, At, B1); G_BAR;
;             G_LDA(At, 1, 1); G_STAGE(G_SA(1, 0), a3, cA0, qA);
;             G_BAR; G_WAIT_L(0); G_MMA(1, 0, At, B0); G_BAR; G_SCHED;
	s_waitcnt lgkmcnt(0)
	v_mfma_f32_16x16x32_bf16 v[120:123], v[204:207], v[156:159], v[120:123]
	v_mfma_f32_16x16x32_bf16 v[112:115], v[212:215], v[156:159], v[112:115]
	v_mfma_f32_16x16x32_bf16 v[104:107], v[204:207], v[164:167], v[104:107]
	v_mfma_f32_16x16x32_bf16 v[96:99], v[212:215], v[164:167], v[96:99]
	v_mfma_f32_16x16x32_bf16 v[88:91], v[204:207], v[176:179], v[88:91]
	v_mfma_f32_16x16x32_bf16 v[80:83], v[212:215], v[176:179], v[80:83]
	v_mfma_f32_16x16x32_bf16 v[76:79], v[204:207], v[196:199], v[76:79]
	v_mfma_f32_16x16x32_bf16 v[72:75], v[212:215], v[196:199], v[72:75]
	v_mfma_f32_16x16x32_bf16 v[120:123], v[208:211], v[160:163], v[120:123]
	v_mfma_f32_16x16x32_bf16 v[112:115], v[216:219], v[160:163], v[112:115]
	v_mfma_f32_16x16x32_bf16 v[104:107], v[208:211], v[172:175], v[104:107]
	v_mfma_f32_16x16x32_bf16 v[96:99], v[216:219], v[172:175], v[96:99]
	v_mfma_f32_16x16x32_bf16 v[88:91], v[208:211], v[180:183], v[88:91]
	v_mfma_f32_16x16x32_bf16 v[80:83], v[216:219], v[180:183], v[80:83]
	v_mfma_f32_16x16x32_bf16 v[76:79], v[208:211], v[200:203], v[76:79]
	v_mfma_f32_16x16x32_bf16 v[72:75], v[216:219], v[200:203], v[72:75]
	s_barrier
	s_mov_b32 m0, s31
	v_lshl_add_u64 v[220:221], s[20:21], 0, v[2:3]
	s_mov_b64 s[4:5], 0x8000
	ds_read_b128 v[156:159], v138 offset:16384
	ds_read_b128 v[160:163], v138 offset:17408
	ds_read_b128 v[164:167], v138 offset:18432
	ds_read_b128 v[172:175], v138 offset:19456
	ds_read_b128 v[176:179], v138 offset:20480
	ds_read_b128 v[180:183], v138 offset:21504
	ds_read_b128 v[196:199], v138 offset:22528
	ds_read_b128 v[200:203], v138 offset:23552
	global_load_lds_dwordx4 v[220:221], off
	v_lshl_add_u64 v[222:223], v[220:221], 0, s[4:5]
	s_mov_b32 m0, s33
	s_mov_b64 s[16:17], 0x18000
	global_load_lds_dwordx4 v[222:223], off
	s_barrier
	s_waitcnt lgkmcnt(0)
	s_mov_b64 s[20:21], 0x8080
	s_waitcnt lgkmcnt(0)
	v_mfma_f32_16x16x32_bf16 v[68:71], v[140:143], v[156:159], v[68:71]
	v_mfma_f32_16x16x32_bf16 v[64:67], v[148:151], v[156:159], v[64:67]
	v_mfma_f32_16x16x32_bf16 v[60:63], v[140:143], v[164:167], v[60:63]
	v_mfma_f32_16x16x32_bf16 v[52:55], v[148:151], v[164:167], v[52:55]
	v_mfma_f32_16x16x32_bf16 v[44:47], v[140:143], v[176:179], v[44:47]
	v_mfma_f32_16x16x32_bf16 v[36:39], v[148:151], v[176:179], v[36:39]
	v_mfma_f32_16x16x32_bf16 v[28:31], v[140:143], v[196:199], v[28:31]
	v_mfma_f32_16x16x32_bf16 v[20:23], v[148:151], v[196:199], v[20:23]
	v_mfma_f32_16x16x32_bf16 v[68:71], v[144:147], v[160:163], v[68:71]
	v_mfma_f32_16x16x32_bf16 v[64:67], v[152:155], v[160:163], v[64:67]
	v_mfma_f32_16x16x32_bf16 v[60:63], v[144:147], v[172:175], v[60:63]
	v_mfma_f32_16x16x32_bf16 v[52:55], v[152:155], v[172:175], v[52:55]
	v_mfma_f32_16x16x32_bf16 v[44:47], v[144:147], v[180:183], v[44:47]
	v_mfma_f32_16x16x32_bf16 v[36:39], v[152:155], v[180:183], v[36:39]
	v_mfma_f32_16x16x32_bf16 v[28:31], v[144:147], v[200:203], v[28:31]
	v_mfma_f32_16x16x32_bf16 v[20:23], v[152:155], v[200:203], v[20:23]
	s_barrier
	s_mov_b32 m0, s51
	v_lshl_add_u64 v[140:141], v[184:185], 0, s[58:59]
	global_load_lds_dwordx4 v[140:141], off
	v_lshl_add_u64 v[140:141], v[184:185], 0, s[16:17]
	s_mov_b32 m0, s50
	s_nop 0
	global_load_lds_dwordx4 v[140:141], off
	s_waitcnt vmcnt(6)
	s_barrier
	v_mfma_f32_16x16x32_bf16 v[56:59], v[204:207], v[156:159], v[56:59]
	v_mfma_f32_16x16x32_bf16 v[48:51], v[212:215], v[156:159], v[48:51]
	v_mfma_f32_16x16x32_bf16 v[40:43], v[204:207], v[164:167], v[40:43]
	v_mfma_f32_16x16x32_bf16 v[32:35], v[212:215], v[164:167], v[32:35]
	v_mfma_f32_16x16x32_bf16 v[24:27], v[204:207], v[176:179], v[24:27]
	v_mfma_f32_16x16x32_bf16 v[16:19], v[212:215], v[176:179], v[16:19]
	v_mfma_f32_16x16x32_bf16 v[12:15], v[204:207], v[196:199], v[12:15]
	v_mfma_f32_16x16x32_bf16 v[8:11], v[212:215], v[196:199], v[8:11]
	v_mfma_f32_16x16x32_bf16 v[56:59], v[208:211], v[160:163], v[56:59]
	v_mfma_f32_16x16x32_bf16 v[48:51], v[216:219], v[160:163], v[48:51]
	v_mfma_f32_16x16x32_bf16 v[40:43], v[208:211], v[172:175], v[40:43]
	v_mfma_f32_16x16x32_bf16 v[32:35], v[216:219], v[172:175], v[32:35]
	v_mfma_f32_16x16x32_bf16 v[24:27], v[208:211], v[180:183], v[24:27]
	v_mfma_f32_16x16x32_bf16 v[16:19], v[216:219], v[180:183], v[16:19]
	v_mfma_f32_16x16x32_bf16 v[12:15], v[208:211], v[200:203], v[12:15]
	v_mfma_f32_16x16x32_bf16 v[8:11], v[216:219], v[200:203], v[8:11]
	s_barrier
	v_add_u32_e32 v139, s43, v137
	ds_read_b128 v[140:143], v139
	ds_read_b128 v[144:147], v139 offset:1024
	ds_read_b128 v[148:151], v139 offset:2048
	ds_read_b128 v[152:155], v139 offset:3072
	s_mov_b32 m0, s34
	v_lshl_add_u64 v[204:205], v[220:221], 0, s[58:59]
	ds_read_b128 v[156:159], v138 offset:32768
	ds_read_b128 v[160:163], v138 offset:33792
	ds_read_b128 v[164:167], v138 offset:34816
	ds_read_b128 v[172:175], v138 offset:35840
	ds_read_b128 v[176:179], v138 offset:36864
	ds_read_b128 v[180:183], v138 offset:37888
	ds_read_b128 v[196:199], v138 offset:38912
	ds_read_b128 v[200:203], v138 offset:39936
	global_load_lds_dwordx4 v[204:205], off
	v_lshl_add_u64 v[204:205], v[220:221], 0, s[16:17]
	s_mov_b32 m0, s35
	s_nop 0
	global_load_lds_dwordx4 v[204:205], off
	s_waitcnt lgkmcnt(8)
	s_barrier
; #define G_STAGE(bufoff, gbase, o0, h64) do { \
;         __builtin_amdgcn_global_load_lds((const unsigned*)((const char*)(gbase) + (o0)), (LAS unsigned*)(lds + (bufoff) + ldsw), 16, 0, 0); \
;         __builtin_amdgcn_global_load_lds((const unsigned*)((const char*)(gbase) + (h64) + (o0)), (LAS unsigned*)(lds + (bufoff) + ldsw + 8192), 16, 0, 0); } while (0)
; #define G_LDA(dst, b, h) do { _Pragma("unroll") for (int m = 0; m < 4; ++m) _Pragma("unroll") for (int k = 0; k < 2; ++k) dst[m][k] = *(const LAS bf16x8*)(lds + G_SA(b, h) + aoff + m * 2048 + k * 1024); } while (0)
; #define G_WAIT_V(n) asm volatile("s_waitcnt vmcnt(" #n ")" ::: "memory")
; #define G_WAIT_L(n) asm volatile("s_waitcnt lgkmcnt(" #n ")" ::: "memory")
; #define G_BAR __builtin_amdgcn_s_barrier()
; #define G_SCHED __builtin_amdgcn_sched_barrier(0)
;     ...
;             G_BAR; G_WAIT_L(0); G_MMA(0, 1, At, B1); G_BAR;
;             G_LDA(At, 1, 1); G_STAGE(G_SA(1, 0), a3, cA0, qA);
;             G_BAR; G_WAIT_L(0); G_MMA(1, 0, At, B0); G_BAR; G_SCHED;
;             G_STAGE(G_SB(1, 1), b3 + chB, cB0, qB);
;             G_WAIT_V(6); G_BAR; G_MMA(1, 1, At, B1); G_BAR;
;         }
;         E.template run<cs.kind>(acc, cur, tid);
;         if (!has_next) break;
	s_waitcnt lgkmcnt(0)
	v_mfma_f32_16x16x32_bf16 v[132:135], v[140:143], v[156:159], v[132:135]
	v_mfma_f32_16x16x32_bf16 v[128:131], v[148:151], v[156:159], v[128:131]
	v_mfma_f32_16x16x32_bf16 v[124:127], v[140:143], v[164:167], v[124:127]
	v_mfma_f32_16x16x32_bf16 v[116:119], v[148:151], v[164:167], v[116:119]
	v_mfma_f32_16x16x32_bf16 v[108:111], v[140:143], v[176:179], v[108:111]
	v_mfma_f32_16x16x32_bf16 v[100:103], v[148:151], v[176:179], v[100:103]
	v_mfma_f32_16x16x32_bf16 v[92:95], v[140:143], v[196:199], v[92:95]
	v_mfma_f32_16x16x32_bf16 v[84:87], v[148:151], v[196:199], v[84:87]
	v_mfma_f32_16x16x32_bf16 v[132:135], v[144:147], v[160:163], v[132:135]
	v_mfma_f32_16x16x32_bf16 v[128:131], v[152:155], v[160:163], v[128:131]
	v_mfma_f32_16x16x32_bf16 v[124:127], v[144:147], v[172:175], v[124:127]
	v_mfma_f32_16x16x32_bf16 v[116:119], v[152:155], v[172:175], v[116:119]
	v_mfma_f32_16x16x32_bf16 v[108:111], v[144:147], v[180:183], v[108:111]
	v_mfma_f32_16x16x32_bf16 v[100:103], v[152:155], v[180:183], v[100:103]
	v_mfma_f32_16x16x32_bf16 v[92:95], v[144:147], v[200:203], v[92:95]
	v_mfma_f32_16x16x32_bf16 v[84:87], v[152:155], v[200:203], v[84:87]
	s_barrier
	s_mov_b32 m0, s19
	v_add_u32_e32 v139, s18, v137
	v_lshl_add_u64 v[222:223], v[184:185], 0, s[46:47]
	ds_read_b128 v[204:207], v139
	ds_read_b128 v[208:211], v139 offset:1024
	ds_read_b128 v[212:215], v139 offset:2048
	ds_read_b128 v[216:219], v139 offset:3072
	global_load_lds_dwordx4 v[222:223], off
	v_lshl_add_u64 v[222:223], v[184:185], 0, s[20:21]
	s_mov_b32 m0, s44
	s_mov_b64 s[4:5], 0x10080
	global_load_lds_dwordx4 v[222:223], off
	s_barrier
	s_waitcnt lgkmcnt(0)
	v_mfma_f32_16x16x32_bf16 v[120:123], v[204:207], v[156:159], v[120:123]
	v_mfma_f32_16x16x32_bf16 v[112:115], v[212:215], v[156:159], v[112:115]
	v_mfma_f32_16x16x32_bf16 v[104:107], v[204:207], v[164:167], v[104:107]
	v_mfma_f32_16x16x32_bf16 v[96:99], v[212:215], v[164:167], v[96:99]
	v_mfma_f32_16x16x32_bf16 v[88:91], v[204:207], v[176:179], v[88:91]
	v_mfma_f32_16x16x32_bf16 v[80:83], v[212:215], v[176:179], v[80:83]
	v_mfma_f32_16x16x32_bf16 v[76:79], v[204:207], v[196:199], v[76:79]
	v_mfma_f32_16x16x32_bf16 v[72:75], v[212:215], v[196:199], v[72:75]
	v_mfma_f32_16x16x32_bf16 v[120:123], v[208:211], v[160:163], v[120:123]
	v_mfma_f32_16x16x32_bf16 v[112:115], v[216:219], v[160:163], v[112:115]
	v_mfma_f32_16x16x32_bf16 v[104:107], v[208:211], v[172:175], v[104:107]
	v_mfma_f32_16x16x32_bf16 v[96:99], v[216:219], v[172:175], v[96:99]
	v_mfma_f32_16x16x32_bf16 v[88:91], v[208:211], v[180:183], v[88:91]
	v_mfma_f32_16x16x32_bf16 v[80:83], v[216:219], v[180:183], v[80:83]
	v_mfma_f32_16x16x32_bf16 v[76:79], v[208:211], v[200:203], v[76:79]
	v_mfma_f32_16x16x32_bf16 v[72:75], v[216:219], v[200:203], v[72:75]
	s_barrier
	s_mov_b32 m0, s36
	v_lshl_add_u64 v[222:223], v[220:221], 0, s[46:47]
	ds_read_b128 v[156:159], v138 offset:49152
	ds_read_b128 v[160:163], v138 offset:50176
	ds_read_b128 v[164:167], v138 offset:51200
	ds_read_b128 v[172:175], v138 offset:52224
	ds_read_b128 v[176:179], v138 offset:53248
	ds_read_b128 v[180:183], v138 offset:54272
	ds_read_b128 v[196:199], v138 offset:55296
	ds_read_b128 v[200:203], v138 offset:56320
	global_load_lds_dwordx4 v[222:223], off
	v_lshl_add_u64 v[220:221], v[220:221], 0, s[20:21]
	s_mov_b32 m0, s37
	s_nop 0
	global_load_lds_dwordx4 v[220:221], off
	s_barrier
	s_waitcnt lgkmcnt(0)
	v_mfma_f32_16x16x32_bf16 v[68:71], v[140:143], v[156:159], v[68:71]
	v_mfma_f32_16x16x32_bf16 v[64:67], v[148:151], v[156:159], v[64:67]
	v_mfma_f32_16x16x32_bf16 v[60:63], v[140:143], v[164:167], v[60:63]
	v_mfma_f32_16x16x32_bf16 v[52:55], v[148:151], v[164:167], v[52:55]
	v_mfma_f32_16x16x32_bf16 v[44:47], v[140:143], v[176:179], v[44:47]
	v_mfma_f32_16x16x32_bf16 v[36:39], v[148:151], v[176:179], v[36:39]
	v_mfma_f32_16x16x32_bf16 v[28:31], v[140:143], v[196:199], v[28:31]
	v_mfma_f32_16x16x32_bf16 v[20:23], v[148:151], v[196:199], v[20:23]
	v_mfma_f32_16x16x32_bf16 v[68:71], v[144:147], v[160:163], v[68:71]
	v_mfma_f32_16x16x32_bf16 v[64:67], v[152:155], v[160:163], v[64:67]
	v_mfma_f32_16x16x32_bf16 v[60:63], v[144:147], v[172:175], v[60:63]
	v_mfma_f32_16x16x32_bf16 v[52:55], v[152:155], v[172:175], v[52:55]
	v_mfma_f32_16x16x32_bf16 v[44:47], v[144:147], v[180:183], v[44:47]
	v_mfma_f32_16x16x32_bf16 v[36:39], v[152:155], v[180:183], v[36:39]
	v_mfma_f32_16x16x32_bf16 v[28:31], v[144:147], v[200:203], v[28:31]
	v_mfma_f32_16x16x32_bf16 v[20:23], v[152:155], v[200:203], v[20:23]
	s_barrier
	s_mov_b32 m0, s53
	v_lshl_add_u64 v[140:141], v[184:185], 0, s[4:5]
	global_load_lds_dwordx4 v[140:141], off
	v_lshl_add_u64 v[140:141], v[184:185], 0, s[68:69]
	s_mov_b32 m0, s52
	s_nop 0
	global_load_lds_dwordx4 v[140:141], off
	s_waitcnt vmcnt(6)
	s_barrier
	v_mfma_f32_16x16x32_bf16 v[56:59], v[204:207], v[156:159], v[56:59]
	v_mfma_f32_16x16x32_bf16 v[48:51], v[212:215], v[156:159], v[48:51]
	v_mfma_f32_16x16x32_bf16 v[40:43], v[204:207], v[164:167], v[40:43]
	v_mfma_f32_16x16x32_bf16 v[32:35], v[212:215], v[164:167], v[32:35]
	v_mfma_f32_16x16x32_bf16 v[24:27], v[204:207], v[176:179], v[24:27]
	v_mfma_f32_16x16x32_bf16 v[16:19], v[212:215], v[176:179], v[16:19]
	v_mfma_f32_16x16x32_bf16 v[12:15], v[204:207], v[196:199], v[12:15]
	v_mfma_f32_16x16x32_bf16 v[8:11], v[212:215], v[196:199], v[8:11]
	v_mfma_f32_16x16x32_bf16 v[56:59], v[208:211], v[160:163], v[56:59]
	v_mfma_f32_16x16x32_bf16 v[48:51], v[216:219], v[160:163], v[48:51]
	v_mfma_f32_16x16x32_bf16 v[40:43], v[208:211], v[172:175], v[40:43]
	v_mfma_f32_16x16x32_bf16 v[32:35], v[216:219], v[172:175], v[32:35]
	v_mfma_f32_16x16x32_bf16 v[24:27], v[208:211], v[180:183], v[24:27]
	v_mfma_f32_16x16x32_bf16 v[16:19], v[216:219], v[180:183], v[16:19]
	v_mfma_f32_16x16x32_bf16 v[12:15], v[208:211], v[200:203], v[12:15]
	v_mfma_f32_16x16x32_bf16 v[8:11], v[216:219], v[200:203], v[8:11]
	s_andn2_b64 vcc, exec, s[14:15]
	s_mov_b64 s[16:17], -1
	s_mov_b64 s[14:15], 0
	s_mov_b64 s[18:19], 0x100
	s_cbranch_vccz .Ldb_PLE0_cont
	v_readfirstlane_b32 s101, v186
	s_cmpk_gt_u32 s101, 0xff
	s_cbranch_scc1 .Ldb_PLE0_young
	s_barrier
	s_mov_b32 s101, 1
	s_branch .Ldb_PLE0_exit

; __device__ __forceinline__ u32x4 pack8(const f32x4 a, const f32x4 b) { u32x4 w; w.x = cvt_pk_bf16(a[0], a[1]); w.y = cvt_pk_bf16(a[2], a[3]); w.z = cvt_pk_bf16(b[0], b[1]); w.w = cvt_pk_bf16(b[2], b[3]); return w; }
; #define MEMFENCE asm volatile("" ::: "memory")
; #define G_WAIT_V(n) asm volatile("s_waitcnt vmcnt(" #n ")" ::: "memory")
; #define G_BAR __builtin_amdgcn_s_barrier()
;     template <int KIND> __device__ __forceinline__ void run(f32x4 (&acc)[2][2][4][2], const Unit& u, int tid_in) const {
;     ...
;         if constexpr (KIND == K_PP) {
; #pragma unroll
;             for (int ai = 0; ai < 2; ++ai)
; #pragma unroll
;                 for (int m = 0; m < 4; ++m)
; #pragma unroll
;                     for (int bj = 0; bj < 2; ++bj) { scr[((ai * 4 + m) * 2 + bj) * 512 + tid] = pack8(acc[ai][bj][m][0], acc[ai][bj][m][1]); if (bj == 1) MEMFENCE; }
;         }
;     ...
;         cur = nxt; cA = nA; cB = nB; ++ui;
;     }
;     G_WAIT_V(0);
;     if (wr == 0) G_BAR;
;     G_BAR;
.Ldb_PLE0_exit:
	s_lshl_b32 s4, s42, 17
	s_and_b32 s4, s4, 0x20000
	v_mov_b32_e32 v140, v136
	s_add_u32 s4, s38, s4
	s_addc_u32 s5, s39, 0
	v_ashrrev_i32_e32 v141, 31, v140
	v_cvt_pk_bf16_f32 v132, v132, v133
	v_cvt_pk_bf16_f32 v133, v134, v135
	v_cvt_pk_bf16_f32 v134, v128, v129
	v_lshl_add_u64 v[128:129], v[140:141], 4, s[4:5]
	s_movk_i32 s4, 0x2000
	v_cvt_pk_bf16_f32 v135, v130, v131
	global_store_dwordx4 v[128:129], v[132:135], off
	v_cvt_pk_bf16_f32 v120, v120, v121
	v_cvt_pk_bf16_f32 v121, v122, v123
	v_cvt_pk_bf16_f32 v122, v112, v113
	v_add_co_u32_e32 v112, vcc, s4, v128
	v_cvt_pk_bf16_f32 v123, v114, v115
	s_movk_i32 s4, 0x6000
	s_nop 0
	v_addc_co_u32_e32 v113, vcc, 0, v129, vcc
	global_store_dwordx4 v[112:113], v[120:123], off
	v_cvt_pk_bf16_f32 v112, v124, v125
	v_cvt_pk_bf16_f32 v113, v126, v127
	v_cvt_pk_bf16_f32 v114, v116, v117
	v_add_co_u32_e32 v116, vcc, s49, v128
	v_cvt_pk_bf16_f32 v115, v118, v119
	s_mov_b32 s42, s41
	s_nop 0
	v_addc_co_u32_e32 v117, vcc, 0, v129, vcc
	global_store_dwordx4 v[116:117], v[112:115], off
	v_cvt_pk_bf16_f32 v104, v104, v105
	v_cvt_pk_bf16_f32 v105, v106, v107
	v_cvt_pk_bf16_f32 v106, v96, v97
	v_add_co_u32_e32 v96, vcc, s4, v128
	v_cvt_pk_bf16_f32 v107, v98, v99
	s_mov_b32 s4, 0xa000
	s_nop 0
	v_addc_co_u32_e32 v97, vcc, 0, v129, vcc
	global_store_dwordx4 v[96:97], v[104:107], off
	v_cvt_pk_bf16_f32 v96, v108, v109
	v_cvt_pk_bf16_f32 v97, v110, v111
	v_cvt_pk_bf16_f32 v98, v100, v101
	v_add_co_u32_e32 v100, vcc, s77, v128
	v_cvt_pk_bf16_f32 v99, v102, v103
	s_mov_b64 s[12:13], s[8:9]
	s_nop 0
	v_addc_co_u32_e32 v101, vcc, 0, v129, vcc
	global_store_dwordx4 v[100:101], v[96:99], off
	v_cvt_pk_bf16_f32 v88, v88, v89
	v_cvt_pk_bf16_f32 v89, v90, v91
	v_cvt_pk_bf16_f32 v90, v80, v81
	v_add_co_u32_e32 v80, vcc, s4, v128
	v_cvt_pk_bf16_f32 v91, v82, v83
	s_mov_b32 s4, 0xc000
	s_nop 0
	v_addc_co_u32_e32 v81, vcc, 0, v129, vcc
	global_store_dwordx4 v[80:81], v[88:91], off
	v_cvt_pk_bf16_f32 v80, v92, v93
	v_cvt_pk_bf16_f32 v81, v94, v95
	v_cvt_pk_bf16_f32 v82, v84, v85
	v_add_co_u32_e32 v84, vcc, s4, v128
	s_mov_b32 s4, 0xe000
	s_nop 0
	v_addc_co_u32_e32 v85, vcc, 0, v129, vcc
	v_cvt_pk_bf16_f32 v83, v86, v87
	global_store_dwordx4 v[84:85], v[80:83], off
	v_cvt_pk_bf16_f32 v76, v76, v77
	v_cvt_pk_bf16_f32 v77, v78, v79
	v_cvt_pk_bf16_f32 v78, v72, v73
	v_add_co_u32_e32 v72, vcc, s4, v128
	v_cvt_pk_bf16_f32 v79, v74, v75
	s_mov_b32 s4, 0x12000
	s_nop 0
	v_addc_co_u32_e32 v73, vcc, 0, v129, vcc
	global_store_dwordx4 v[72:73], v[76:79], off
	v_cvt_pk_bf16_f32 v68, v68, v69
	v_cvt_pk_bf16_f32 v69, v70, v71
	v_cvt_pk_bf16_f32 v70, v64, v65
	v_add_co_u32_e32 v64, vcc, s91, v128
	v_cvt_pk_bf16_f32 v71, v66, v67
	s_mov_b64 s[10:11], s[6:7]
	s_nop 0
	v_addc_co_u32_e32 v65, vcc, 0, v129, vcc
	global_store_dwordx4 v[64:65], v[68:71], off
	v_cvt_pk_bf16_f32 v56, v56, v57
	v_cvt_pk_bf16_f32 v57, v58, v59
	v_cvt_pk_bf16_f32 v58, v48, v49
	v_add_co_u32_e32 v48, vcc, s4, v128
	v_cvt_pk_bf16_f32 v59, v50, v51
	s_mov_b32 s4, 0x14000
	s_nop 0
	v_addc_co_u32_e32 v49, vcc, 0, v129, vcc
	global_store_dwordx4 v[48:49], v[56:59], off
	v_cvt_pk_bf16_f32 v48, v60, v61
	v_cvt_pk_bf16_f32 v49, v62, v63
	v_cvt_pk_bf16_f32 v50, v52, v53
	v_add_co_u32_e32 v52, vcc, s4, v128
	s_mov_b32 s4, 0x16000
	s_nop 0
	v_addc_co_u32_e32 v53, vcc, 0, v129, vcc
	v_cvt_pk_bf16_f32 v51, v54, v55
	global_store_dwordx4 v[52:53], v[48:51], off
	v_cvt_pk_bf16_f32 v40, v40, v41
	v_cvt_pk_bf16_f32 v41, v42, v43
	v_cvt_pk_bf16_f32 v42, v32, v33
	v_add_co_u32_e32 v32, vcc, s4, v128
	v_cvt_pk_bf16_f32 v43, v34, v35
	s_mov_b32 s4, 0x18000
	s_nop 0
	v_addc_co_u32_e32 v33, vcc, 0, v129, vcc
	global_store_dwordx4 v[32:33], v[40:43], off
	v_cvt_pk_bf16_f32 v32, v44, v45
	v_cvt_pk_bf16_f32 v33, v46, v47
	v_cvt_pk_bf16_f32 v34, v36, v37
	v_add_co_u32_e32 v36, vcc, s4, v128
	s_mov_b32 s4, 0x1a000
	s_nop 0
	v_addc_co_u32_e32 v37, vcc, 0, v129, vcc
	v_cvt_pk_bf16_f32 v35, v38, v39
	global_store_dwordx4 v[36:37], v[32:35], off
	v_cvt_pk_bf16_f32 v24, v24, v25
	v_cvt_pk_bf16_f32 v25, v26, v27
	v_cvt_pk_bf16_f32 v26, v16, v17
	v_add_co_u32_e32 v16, vcc, s4, v128
	v_cvt_pk_bf16_f32 v27, v18, v19
	s_mov_b32 s4, 0x1c000
	s_nop 0
	v_addc_co_u32_e32 v17, vcc, 0, v129, vcc
	global_store_dwordx4 v[16:17], v[24:27], off
	v_cvt_pk_bf16_f32 v16, v28, v29
	v_cvt_pk_bf16_f32 v17, v30, v31
	v_cvt_pk_bf16_f32 v18, v20, v21
	v_add_co_u32_e32 v20, vcc, s4, v128
	v_cvt_pk_bf16_f32 v19, v22, v23
	s_nop 1
	v_addc_co_u32_e32 v21, vcc, 0, v129, vcc
	global_store_dwordx4 v[20:21], v[16:19], off
	v_cvt_pk_bf16_f32 v12, v12, v13
	v_cvt_pk_bf16_f32 v13, v14, v15
	v_cvt_pk_bf16_f32 v14, v8, v9
	v_add_co_u32_e32 v8, vcc, 0x1e000, v128
	v_cvt_pk_bf16_f32 v15, v10, v11
	s_nop 1
	v_addc_co_u32_e32 v9, vcc, 0, v129, vcc
	global_store_dwordx4 v[8:9], v[12:15], off
	s_and_b64 vcc, exec, s[2:3]
	s_cbranch_vccz .LBB0_1257
	s_cmp_eq_u32 s101, 2
	s_cbranch_scc0 .Ldbj_PLE0_pe
	s_barrier

; #define G_STAGE(bufoff, gbase, o0, h64) do { \
;         __builtin_amdgcn_global_load_lds((const unsigned*)((const char*)(gbase) + (o0)), (LAS unsigned*)(lds + (bufoff) + ldsw), 16, 0, 0); \
;         __builtin_amdgcn_global_load_lds((const unsigned*)((const char*)(gbase) + (h64) + (o0)), (LAS unsigned*)(lds + (bufoff) + ldsw + 8192), 16, 0, 0); } while (0)
; #define G_LDA(dst, b, h) do { _Pragma("unroll") for (int m = 0; m < 4; ++m) _Pragma("unroll") for (int k = 0; k < 2; ++k) dst[m][k] = *(const LAS bf16x8*)(lds + G_SA(b, h) + aoff + m * 2048 + k * 1024); } while (0)
; #define G_LDB(dst, b, h) do { _Pragma("unroll") for (int n = 0; n < 2; ++n) _Pragma("unroll") for (int k = 0; k < 2; ++k) dst[n][k] = *(const LAS bf16x8*)(lds + G_SB(b, h) + boff + n * 2048 + k * 1024); } while (0)
; #define G_WAIT_L(n) asm volatile("s_waitcnt lgkmcnt(" #n ")" ::: "memory")
; #define G_BAR __builtin_amdgcn_s_barrier()
; #define G_SCHED __builtin_amdgcn_sched_barrier(0)
;     ...
;         for (int t = 0; t < nt; t += 2) {
;             const bool last = (t == nt - 2);
;             const char* a1 = cA + (size_t)(t + 1) * ckA;
;             const char* a2 = last ? nA : cA + (size_t)(t + 2) * ckA; const char* b2 = last ? nB : cB + (size_t)(t + 2) * kB;
;             const char* a3 = a2 + ckA; const char* b3 = b2 + kB;
;             G_LDB(B0, 0, 0); G_SCHED; G_LDA(At, 0, 0); G_STAGE(G_SA(1, 1), a1 + chA, cA0, qA);
;             G_WAIT_L(8); G_BAR; G_WAIT_L(0); G_MMA(0, 0, At, B0); G_BAR; G_SCHED;
;             G_LDB(B1, 0, 1); G_STAGE(G_SB(0, 0), b2, cB0, qB);
;             G_BAR; G_WAIT_L(0); G_MMA(0, 1, At, B1); G_BAR;
;     ...
;         if (!(cs.kind == K_MG_B && cur.aux < 2))
; #pragma unroll
;         for (int a = 0; a < 2; ++a)
; #pragma unroll
;             for (int b = 0; b < 2; ++b)
; #pragma unroll
;                 for (int m = 0; m < 4; ++m)
; #pragma unroll
;                     for (int n = 0; n < 2; ++n) acc[a][b][m][n] = (f32x4){0.f, 0.f, 0.f, 0.f};
.LBB0_1282:
	s_add_u32 s2, s24, 0x40080
	s_addc_u32 s3, s25, 0
	s_add_u32 s22, s22, 0x100
	s_waitcnt lgkmcnt(0)
	v_mov_b64_e32 v[8:9], 0
	s_addc_u32 s23, s23, 0
	s_mov_b32 s24, -2
	v_mov_b64_e32 v[10:11], 0
	v_mov_b64_e32 v[12:13], 0
	v_mov_b64_e32 v[14:15], 0
	v_mov_b64_e32 v[24:25], 0
	v_mov_b64_e32 v[26:27], 0
	v_mov_b64_e32 v[28:29], 0
	v_mov_b64_e32 v[30:31], 0
	v_mov_b64_e32 v[40:41], 0
	v_mov_b64_e32 v[42:43], 0
	v_mov_b64_e32 v[44:45], 0
	v_mov_b64_e32 v[46:47], 0
	v_mov_b64_e32 v[56:57], 0
	v_mov_b64_e32 v[58:59], 0
	v_mov_b64_e32 v[60:61], 0
	v_mov_b64_e32 v[62:63], 0
	v_mov_b64_e32 v[16:17], 0
	v_mov_b64_e32 v[18:19], 0
	v_mov_b64_e32 v[20:21], 0
	v_mov_b64_e32 v[22:23], 0
	v_mov_b64_e32 v[32:33], 0
	v_mov_b64_e32 v[34:35], 0
	v_mov_b64_e32 v[36:37], 0
	v_mov_b64_e32 v[38:39], 0
	v_mov_b64_e32 v[48:49], 0
	v_mov_b64_e32 v[50:51], 0
	v_mov_b64_e32 v[52:53], 0
	v_mov_b64_e32 v[54:55], 0
	v_mov_b64_e32 v[64:65], 0
	v_mov_b64_e32 v[66:67], 0
	v_mov_b64_e32 v[68:69], 0
	v_mov_b64_e32 v[70:71], 0
	v_mov_b64_e32 v[72:73], 0
	v_mov_b64_e32 v[74:75], 0
	v_mov_b64_e32 v[76:77], 0
	v_mov_b64_e32 v[78:79], 0
	v_mov_b64_e32 v[88:89], 0
	v_mov_b64_e32 v[90:91], 0
	v_mov_b64_e32 v[92:93], 0
	v_mov_b64_e32 v[94:95], 0
	v_mov_b64_e32 v[104:105], 0
	v_mov_b64_e32 v[106:107], 0
	v_mov_b64_e32 v[108:109], 0
	v_mov_b64_e32 v[110:111], 0
	v_mov_b64_e32 v[120:121], 0
	v_mov_b64_e32 v[122:123], 0
	v_mov_b64_e32 v[124:125], 0
	v_mov_b64_e32 v[126:127], 0
	v_mov_b64_e32 v[80:81], 0
	v_mov_b64_e32 v[82:83], 0
	v_mov_b64_e32 v[84:85], 0
	v_mov_b64_e32 v[86:87], 0
	v_mov_b64_e32 v[96:97], 0
	v_mov_b64_e32 v[98:99], 0
	v_mov_b64_e32 v[100:101], 0
	v_mov_b64_e32 v[102:103], 0
	v_mov_b64_e32 v[112:113], 0
	v_mov_b64_e32 v[114:115], 0
	v_mov_b64_e32 v[116:117], 0
	v_mov_b64_e32 v[118:119], 0
	v_mov_b64_e32 v[128:129], 0
	v_mov_b64_e32 v[130:131], 0
	v_mov_b64_e32 v[132:133], 0
	v_mov_b64_e32 v[134:135], 0
	s_mov_b64 s[54:55], 0x40000
	s_mov_b64 s[58:59], 0x60000
	s_mov_b64 s[62:63], 0x20080
	s_mov_b64 s[64:65], 0x40080
	s_mov_b64 s[66:67], 0x60080
	s_cmp_eq_u32 s101, 2
	s_cselect_b32 s101, 0, s101
.LBB0_1283:
	s_add_u32 s4, s2, 0xfffc0080
	s_addc_u32 s5, s3, -1
	s_add_i32 s25, 0, 0x10000
	v_add_u32_e32 v0, s25, v181
	ds_read_b128 v[136:139], v0
	ds_read_b128 v[140:143], v0 offset:1024
	ds_read_b128 v[144:147], v0 offset:2048
	ds_read_b128 v[148:151], v0 offset:3072
	s_cmp_eq_u32 s24, 12
	s_cselect_b32 s5, s19, s5
	s_cselect_b32 s4, s18, s4
	s_cselect_b32 s41, s21, s23
	s_cselect_b32 s40, s20, s22
	v_lshl_add_u64 v[184:185], s[2:3], 0, v[158:159]
	s_add_i32 m0, s29, 0xc000
	ds_read_b128 v[152:155], v182
	ds_read_b128 v[160:163], v182 offset:1024
	ds_read_b128 v[164:167], v182 offset:2048
	ds_read_b128 v[172:175], v182 offset:3072
	ds_read_b128 v[176:179], v182 offset:4096
	ds_read_b128 v[196:199], v182 offset:5120
	ds_read_b128 v[200:203], v182 offset:6144
	ds_read_b128 v[204:207], v182 offset:7168
	global_load_lds_dwordx4 v[184:185], off
	v_lshl_add_u64 v[184:185], v[184:185], 0, s[0:1]
	s_add_i32 m0, s29, 0xe000
	s_nop 0
	global_load_lds_dwordx4 v[184:185], off
	s_waitcnt lgkmcnt(8)
	s_cmp_eq_u32 s101, 1
	s_cbranch_scc1 .Ldb_PLE1_sk
	s_barrier
.Ldb_PLE1_sk:
	s_mov_b32 s101, 0
	s_waitcnt lgkmcnt(0)
	v_mfma_f32_16x16x32_bf16 v[132:135], v[136:139], v[152:155], v[132:135]
	v_mfma_f32_16x16x32_bf16 v[128:131], v[144:147], v[152:155], v[128:131]
	v_mfma_f32_16x16x32_bf16 v[116:119], v[136:139], v[164:167], v[116:119]
	v_mfma_f32_16x16x32_bf16 v[112:115], v[144:147], v[164:167], v[112:115]
	v_mfma_f32_16x16x32_bf16 v[100:103], v[136:139], v[176:179], v[100:103]
	v_mfma_f32_16x16x32_bf16 v[96:99], v[144:147], v[176:179], v[96:99]
	v_mfma_f32_16x16x32_bf16 v[84:87], v[136:139], v[200:203], v[84:87]
	v_mfma_f32_16x16x32_bf16 v[80:83], v[144:147], v[200:203], v[80:83]
	v_mfma_f32_16x16x32_bf16 v[132:135], v[140:143], v[160:163], v[132:135]
	v_mfma_f32_16x16x32_bf16 v[128:131], v[148:151], v[160:163], v[128:131]
	v_mfma_f32_16x16x32_bf16 v[116:119], v[140:143], v[172:175], v[116:119]
	v_mfma_f32_16x16x32_bf16 v[112:115], v[148:151], v[172:175], v[112:115]
	v_mfma_f32_16x16x32_bf16 v[100:103], v[140:143], v[196:199], v[100:103]
	v_mfma_f32_16x16x32_bf16 v[96:99], v[148:151], v[196:199], v[96:99]
	v_mfma_f32_16x16x32_bf16 v[84:87], v[140:143], v[204:207], v[84:87]
	v_mfma_f32_16x16x32_bf16 v[80:83], v[148:151], v[204:207], v[80:83]
	s_barrier
	s_add_i32 s44, 0, 0x14000
	s_add_i32 s25, s25, s27
	v_add_u32_e32 v0, s44, v181
	v_lshl_add_u64 v[184:185], s[40:41], 0, v[156:157]
	s_mov_b32 m0, s25
	ds_read_b128 v[208:211], v0
	ds_read_b128 v[212:215], v0 offset:1024
	ds_read_b128 v[216:219], v0 offset:2048
	ds_read_b128 v[220:223], v0 offset:3072
	global_load_lds_dwordx4 v[184:185], off
	v_lshl_add_u64 v[224:225], v[184:185], 0, s[0:1]
	s_add_i32 m0, s25, 0x2000
	s_nop 0
	global_load_lds_dwordx4 v[224:225], off
	s_barrier
	s_waitcnt lgkmcnt(0)
	v_mfma_f32_16x16x32_bf16 v[124:127], v[208:211], v[152:155], v[124:127]
	v_mfma_f32_16x16x32_bf16 v[120:123], v[216:219], v[152:155], v[120:123]
	v_mfma_f32_16x16x32_bf16 v[108:111], v[208:211], v[164:167], v[108:111]
	v_mfma_f32_16x16x32_bf16 v[104:107], v[216:219], v[164:167], v[104:107]
	v_mfma_f32_16x16x32_bf16 v[92:95], v[208:211], v[176:179], v[92:95]
	v_mfma_f32_16x16x32_bf16 v[88:91], v[216:219], v[176:179], v[88:91]
	v_mfma_f32_16x16x32_bf16 v[76:79], v[208:211], v[200:203], v[76:79]
	v_mfma_f32_16x16x32_bf16 v[72:75], v[216:219], v[200:203], v[72:75]
	v_mfma_f32_16x16x32_bf16 v[124:127], v[212:215], v[160:163], v[124:127]
	v_mfma_f32_16x16x32_bf16 v[120:123], v[220:223], v[160:163], v[120:123]
	v_mfma_f32_16x16x32_bf16 v[108:111], v[212:215], v[172:175], v[108:111]
	v_mfma_f32_16x16x32_bf16 v[104:107], v[220:223], v[172:175], v[104:107]
	v_mfma_f32_16x16x32_bf16 v[92:95], v[212:215], v[196:199], v[92:95]
	v_mfma_f32_16x16x32_bf16 v[88:91], v[220:223], v[196:199], v[88:91]
	v_mfma_f32_16x16x32_bf16 v[76:79], v[212:215], v[204:207], v[76:79]
	v_mfma_f32_16x16x32_bf16 v[72:75], v[220:223], v[204:207], v[72:75]
	s_barrier
; #define G_STAGE(bufoff, gbase, o0, h64) do { \
;         __builtin_amdgcn_global_load_lds((const unsigned*)((const char*)(gbase) + (o0)), (LAS unsigned*)(lds + (bufoff) + ldsw), 16, 0, 0); \
;         __builtin_amdgcn_global_load_lds((const unsigned*)((const char*)(gbase) + (h64) + (o0)), (LAS unsigned*)(lds + (bufoff) + ldsw + 8192), 16, 0, 0); } while (0)
; #define G_LDA(dst, b, h) do { _Pragma("unroll") for (int m = 0; m < 4; ++m) _Pragma("unroll") for (int k = 0; k < 2; ++k) dst[m][k] = *(const LAS bf16x8*)(lds + G_SA(b, h) + aoff + m * 2048 + k * 1024); } while (0)
; #define G_LDB(dst, b, h) do { _Pragma("unroll") for (int n = 0; n < 2; ++n) _Pragma("unroll") for (int k = 0; k < 2; ++k) dst[n][k] = *(const LAS bf16x8*)(lds + G_SB(b, h) + boff + n * 2048 + k * 1024); } while (0)
; #define G_WAIT_V(n) asm volatile("s_waitcnt vmcnt(" #n ")" ::: "memory")
; #define G_WAIT_L(n) asm volatile("s_waitcnt lgkmcnt(" #n ")" ::: "memory")
; #define G_BAR __builtin_amdgcn_s_barrier()
; #define G_SCHED __builtin_amdgcn_sched_barrier(0)
;     ...
;             G_BAR; G_WAIT_L(0); G_MMA(0, 1, At, B1); G_BAR;
;             G_LDA(At, 0, 1); G_STAGE(G_SA(0, 0), a2, cA0, qA);
;             G_BAR; G_WAIT_L(0); G_MMA(1, 0, At, B0); G_BAR; G_SCHED;
;             G_STAGE(G_SB(0, 1), b2 + chB, cB0, qB);
;             G_WAIT_V(6); G_BAR; G_MMA(1, 1, At, B1); G_BAR;
;             G_LDB(B0, 1, 0); G_SCHED; G_LDA(At, 1, 0); G_STAGE(G_SA(0, 1), a2 + chA, cA0, qA);
;             G_WAIT_L(8); G_BAR; G_WAIT_L(0); G_MMA(0, 0, At, B0); G_BAR; G_SCHED;
	s_mov_b32 m0, s29
	v_lshl_add_u64 v[224:225], s[4:5], 0, v[2:3]
	ds_read_b128 v[152:155], v182 offset:16384
	ds_read_b128 v[160:163], v182 offset:17408
	ds_read_b128 v[164:167], v182 offset:18432
	ds_read_b128 v[172:175], v182 offset:19456
	ds_read_b128 v[176:179], v182 offset:20480
	ds_read_b128 v[196:199], v182 offset:21504
	ds_read_b128 v[200:203], v182 offset:22528
	ds_read_b128 v[204:207], v182 offset:23552
	global_load_lds_dwordx4 v[224:225], off
	v_lshl_add_u64 v[226:227], v[224:225], 0, s[0:1]
	s_mov_b32 m0, s30
	s_nop 0
	global_load_lds_dwordx4 v[226:227], off
	s_barrier
	s_waitcnt lgkmcnt(0)
	v_mfma_f32_16x16x32_bf16 v[68:71], v[136:139], v[152:155], v[68:71]
	v_mfma_f32_16x16x32_bf16 v[64:67], v[144:147], v[152:155], v[64:67]
	v_mfma_f32_16x16x32_bf16 v[52:55], v[136:139], v[164:167], v[52:55]
	v_mfma_f32_16x16x32_bf16 v[48:51], v[144:147], v[164:167], v[48:51]
	v_mfma_f32_16x16x32_bf16 v[36:39], v[136:139], v[176:179], v[36:39]
	v_mfma_f32_16x16x32_bf16 v[32:35], v[144:147], v[176:179], v[32:35]
	v_mfma_f32_16x16x32_bf16 v[20:23], v[136:139], v[200:203], v[20:23]
	v_mfma_f32_16x16x32_bf16 v[16:19], v[144:147], v[200:203], v[16:19]
	v_mfma_f32_16x16x32_bf16 v[68:71], v[140:143], v[160:163], v[68:71]
	v_mfma_f32_16x16x32_bf16 v[64:67], v[148:151], v[160:163], v[64:67]
	v_mfma_f32_16x16x32_bf16 v[52:55], v[140:143], v[172:175], v[52:55]
	v_mfma_f32_16x16x32_bf16 v[48:51], v[148:151], v[172:175], v[48:51]
	v_mfma_f32_16x16x32_bf16 v[36:39], v[140:143], v[196:199], v[36:39]
	v_mfma_f32_16x16x32_bf16 v[32:35], v[148:151], v[196:199], v[32:35]
	v_mfma_f32_16x16x32_bf16 v[20:23], v[140:143], v[204:207], v[20:23]
	v_mfma_f32_16x16x32_bf16 v[16:19], v[148:151], v[204:207], v[16:19]
	s_barrier
	s_add_i32 s4, s44, s27
	v_lshl_add_u64 v[136:137], v[184:185], 0, s[54:55]
	s_mov_b32 m0, s4
	s_nop 0
	global_load_lds_dwordx4 v[136:137], off
	v_lshl_add_u64 v[136:137], v[184:185], 0, s[58:59]
	s_add_i32 m0, s4, 0x2000
	s_nop 0
	global_load_lds_dwordx4 v[136:137], off
	s_waitcnt vmcnt(6)
	s_barrier
	v_mfma_f32_16x16x32_bf16 v[60:63], v[208:211], v[152:155], v[60:63]
	v_mfma_f32_16x16x32_bf16 v[56:59], v[216:219], v[152:155], v[56:59]
	v_mfma_f32_16x16x32_bf16 v[44:47], v[208:211], v[164:167], v[44:47]
	v_mfma_f32_16x16x32_bf16 v[40:43], v[216:219], v[164:167], v[40:43]
	v_mfma_f32_16x16x32_bf16 v[28:31], v[208:211], v[176:179], v[28:31]
	v_mfma_f32_16x16x32_bf16 v[24:27], v[216:219], v[176:179], v[24:27]
	v_mfma_f32_16x16x32_bf16 v[12:15], v[208:211], v[200:203], v[12:15]
	v_mfma_f32_16x16x32_bf16 v[8:11], v[216:219], v[200:203], v[8:11]
	v_mfma_f32_16x16x32_bf16 v[60:63], v[212:215], v[160:163], v[60:63]
	v_mfma_f32_16x16x32_bf16 v[56:59], v[220:223], v[160:163], v[56:59]
	v_mfma_f32_16x16x32_bf16 v[44:47], v[212:215], v[172:175], v[44:47]
	v_mfma_f32_16x16x32_bf16 v[40:43], v[220:223], v[172:175], v[40:43]
	v_mfma_f32_16x16x32_bf16 v[28:31], v[212:215], v[196:199], v[28:31]
	v_mfma_f32_16x16x32_bf16 v[24:27], v[220:223], v[196:199], v[24:27]
	v_mfma_f32_16x16x32_bf16 v[12:15], v[212:215], v[204:207], v[12:15]
	v_mfma_f32_16x16x32_bf16 v[8:11], v[220:223], v[204:207], v[8:11]
	s_barrier
	s_add_i32 s4, 0, 0x18000
	v_add_u32_e32 v0, s4, v181
	ds_read_b128 v[136:139], v0
	ds_read_b128 v[140:143], v0 offset:1024
	ds_read_b128 v[144:147], v0 offset:2048
	ds_read_b128 v[148:151], v0 offset:3072
	s_mov_b32 m0, s31
	v_lshl_add_u64 v[208:209], v[224:225], 0, s[54:55]
	ds_read_b128 v[152:155], v182 offset:32768
	ds_read_b128 v[160:163], v182 offset:33792
	ds_read_b128 v[164:167], v182 offset:34816
	ds_read_b128 v[172:175], v182 offset:35840
	ds_read_b128 v[176:179], v182 offset:36864
	ds_read_b128 v[196:199], v182 offset:37888
	ds_read_b128 v[200:203], v182 offset:38912
	ds_read_b128 v[204:207], v182 offset:39936
	global_load_lds_dwordx4 v[208:209], off
	v_lshl_add_u64 v[208:209], v[224:225], 0, s[58:59]
	s_mov_b32 m0, s34
	s_nop 0
	global_load_lds_dwordx4 v[208:209], off
	s_waitcnt lgkmcnt(8)
	s_barrier
	s_waitcnt lgkmcnt(0)
	v_mfma_f32_16x16x32_bf16 v[132:135], v[136:139], v[152:155], v[132:135]
	v_mfma_f32_16x16x32_bf16 v[128:131], v[144:147], v[152:155], v[128:131]
	v_mfma_f32_16x16x32_bf16 v[116:119], v[136:139], v[164:167], v[116:119]
	v_mfma_f32_16x16x32_bf16 v[112:115], v[144:147], v[164:167], v[112:115]
	v_mfma_f32_16x16x32_bf16 v[100:103], v[136:139], v[176:179], v[100:103]
	v_mfma_f32_16x16x32_bf16 v[96:99], v[144:147], v[176:179], v[96:99]
	v_mfma_f32_16x16x32_bf16 v[84:87], v[136:139], v[200:203], v[84:87]
	v_mfma_f32_16x16x32_bf16 v[80:83], v[144:147], v[200:203], v[80:83]
	v_mfma_f32_16x16x32_bf16 v[132:135], v[140:143], v[160:163], v[132:135]
	v_mfma_f32_16x16x32_bf16 v[128:131], v[148:151], v[160:163], v[128:131]
	v_mfma_f32_16x16x32_bf16 v[116:119], v[140:143], v[172:175], v[116:119]
	v_mfma_f32_16x16x32_bf16 v[112:115], v[148:151], v[172:175], v[112:115]
	v_mfma_f32_16x16x32_bf16 v[100:103], v[140:143], v[196:199], v[100:103]
	v_mfma_f32_16x16x32_bf16 v[96:99], v[148:151], v[196:199], v[96:99]
	v_mfma_f32_16x16x32_bf16 v[84:87], v[140:143], v[204:207], v[84:87]
	v_mfma_f32_16x16x32_bf16 v[80:83], v[148:151], v[204:207], v[80:83]
	s_barrier
; #define G_STAGE(bufoff, gbase, o0, h64) do { \
;         __builtin_amdgcn_global_load_lds((const unsigned*)((const char*)(gbase) + (o0)), (LAS unsigned*)(lds + (bufoff) + ldsw), 16, 0, 0); \
;         __builtin_amdgcn_global_load_lds((const unsigned*)((const char*)(gbase) + (h64) + (o0)), (LAS unsigned*)(lds + (bufoff) + ldsw + 8192), 16, 0, 0); } while (0)
; #define G_LDA(dst, b, h) do { _Pragma("unroll") for (int m = 0; m < 4; ++m) _Pragma("unroll") for (int k = 0; k < 2; ++k) dst[m][k] = *(const LAS bf16x8*)(lds + G_SA(b, h) + aoff + m * 2048 + k * 1024); } while (0)
; #define G_LDB(dst, b, h) do { _Pragma("unroll") for (int n = 0; n < 2; ++n) _Pragma("unroll") for (int k = 0; k < 2; ++k) dst[n][k] = *(const LAS bf16x8*)(lds + G_SB(b, h) + boff + n * 2048 + k * 1024); } while (0)
; #define G_WAIT_V(n) asm volatile("s_waitcnt vmcnt(" #n ")" ::: "memory")
; #define G_WAIT_L(n) asm volatile("s_waitcnt lgkmcnt(" #n ")" ::: "memory")
; #define G_BAR __builtin_amdgcn_s_barrier()
; #define G_SCHED __builtin_amdgcn_sched_barrier(0)
;     ...
;             G_WAIT_L(8); G_BAR; G_WAIT_L(0); G_MMA(0, 0, At, B0); G_BAR; G_SCHED;
;             G_LDB(B1, 1, 1); G_STAGE(G_SB(1, 0), b3, cB0, qB);
;             G_BAR; G_WAIT_L(0); G_MMA(0, 1, At, B1); G_BAR;
;             G_LDA(At, 1, 1); G_STAGE(G_SA(1, 0), a3, cA0, qA);
;             G_BAR; G_WAIT_L(0); G_MMA(1, 0, At, B0); G_BAR; G_SCHED;
;             G_STAGE(G_SB(1, 1), b3 + chB, cB0, qB);
;             G_WAIT_V(6); G_BAR; G_MMA(1, 1, At, B1); G_BAR;
;         }
	s_add_i32 s5, 0, 0x1c000
	s_add_i32 s4, s4, s27
	v_add_u32_e32 v0, s5, v181
	v_lshl_add_u64 v[226:227], v[184:185], 0, s[46:47]
	s_mov_b32 m0, s4
	ds_read_b128 v[208:211], v0
	ds_read_b128 v[212:215], v0 offset:1024
	ds_read_b128 v[216:219], v0 offset:2048
	ds_read_b128 v[220:223], v0 offset:3072
	global_load_lds_dwordx4 v[226:227], off
	v_lshl_add_u64 v[226:227], v[184:185], 0, s[62:63]
	s_add_i32 m0, s4, 0x2000
	s_nop 0
	global_load_lds_dwordx4 v[226:227], off
	s_barrier
	s_waitcnt lgkmcnt(0)
	v_mfma_f32_16x16x32_bf16 v[124:127], v[208:211], v[152:155], v[124:127]
	v_mfma_f32_16x16x32_bf16 v[120:123], v[216:219], v[152:155], v[120:123]
	v_mfma_f32_16x16x32_bf16 v[108:111], v[208:211], v[164:167], v[108:111]
	v_mfma_f32_16x16x32_bf16 v[104:107], v[216:219], v[164:167], v[104:107]
	v_mfma_f32_16x16x32_bf16 v[92:95], v[208:211], v[176:179], v[92:95]
	v_mfma_f32_16x16x32_bf16 v[88:91], v[216:219], v[176:179], v[88:91]
	v_mfma_f32_16x16x32_bf16 v[76:79], v[208:211], v[200:203], v[76:79]
	v_mfma_f32_16x16x32_bf16 v[72:75], v[216:219], v[200:203], v[72:75]
	v_mfma_f32_16x16x32_bf16 v[124:127], v[212:215], v[160:163], v[124:127]
	v_mfma_f32_16x16x32_bf16 v[120:123], v[220:223], v[160:163], v[120:123]
	v_mfma_f32_16x16x32_bf16 v[108:111], v[212:215], v[172:175], v[108:111]
	v_mfma_f32_16x16x32_bf16 v[104:107], v[220:223], v[172:175], v[104:107]
	v_mfma_f32_16x16x32_bf16 v[92:95], v[212:215], v[196:199], v[92:95]
	v_mfma_f32_16x16x32_bf16 v[88:91], v[220:223], v[196:199], v[88:91]
	v_mfma_f32_16x16x32_bf16 v[76:79], v[212:215], v[204:207], v[76:79]
	v_mfma_f32_16x16x32_bf16 v[72:75], v[220:223], v[204:207], v[72:75]
	s_barrier
	s_mov_b32 m0, s35
	v_lshl_add_u64 v[226:227], v[224:225], 0, s[46:47]
	ds_read_b128 v[152:155], v182 offset:49152
	ds_read_b128 v[160:163], v182 offset:50176
	ds_read_b128 v[164:167], v182 offset:51200
	ds_read_b128 v[172:175], v182 offset:52224
	ds_read_b128 v[176:179], v182 offset:53248
	ds_read_b128 v[196:199], v182 offset:54272
	ds_read_b128 v[200:203], v182 offset:55296
	ds_read_b128 v[204:207], v182 offset:56320
	global_load_lds_dwordx4 v[226:227], off
	v_lshl_add_u64 v[224:225], v[224:225], 0, s[62:63]
	s_mov_b32 m0, s36
	s_nop 0
	global_load_lds_dwordx4 v[224:225], off
	s_barrier
	s_waitcnt lgkmcnt(0)
	v_mfma_f32_16x16x32_bf16 v[68:71], v[136:139], v[152:155], v[68:71]
	v_mfma_f32_16x16x32_bf16 v[64:67], v[144:147], v[152:155], v[64:67]
	v_mfma_f32_16x16x32_bf16 v[52:55], v[136:139], v[164:167], v[52:55]
	v_mfma_f32_16x16x32_bf16 v[48:51], v[144:147], v[164:167], v[48:51]
	v_mfma_f32_16x16x32_bf16 v[36:39], v[136:139], v[176:179], v[36:39]
	v_mfma_f32_16x16x32_bf16 v[32:35], v[144:147], v[176:179], v[32:35]
	v_mfma_f32_16x16x32_bf16 v[20:23], v[136:139], v[200:203], v[20:23]
	v_mfma_f32_16x16x32_bf16 v[16:19], v[144:147], v[200:203], v[16:19]
	v_mfma_f32_16x16x32_bf16 v[68:71], v[140:143], v[160:163], v[68:71]
	v_mfma_f32_16x16x32_bf16 v[64:67], v[148:151], v[160:163], v[64:67]
	v_mfma_f32_16x16x32_bf16 v[52:55], v[140:143], v[172:175], v[52:55]
	v_mfma_f32_16x16x32_bf16 v[48:51], v[148:151], v[172:175], v[48:51]
	v_mfma_f32_16x16x32_bf16 v[36:39], v[140:143], v[196:199], v[36:39]
	v_mfma_f32_16x16x32_bf16 v[32:35], v[148:151], v[196:199], v[32:35]
	v_mfma_f32_16x16x32_bf16 v[20:23], v[140:143], v[204:207], v[20:23]
	v_mfma_f32_16x16x32_bf16 v[16:19], v[148:151], v[204:207], v[16:19]
	s_barrier
	s_add_i32 s4, s5, s27
	v_lshl_add_u64 v[136:137], v[184:185], 0, s[64:65]
	s_mov_b32 m0, s4
	s_nop 0
	global_load_lds_dwordx4 v[136:137], off
	v_lshl_add_u64 v[136:137], v[184:185], 0, s[66:67]
	s_add_i32 m0, s4, 0x2000
	s_nop 0
	global_load_lds_dwordx4 v[136:137], off
	s_add_i32 s24, s24, 2
	s_add_u32 s2, s2, 0x100
	s_addc_u32 s3, s3, 0
	s_add_u32 s22, s22, 0x100
	s_addc_u32 s23, s23, 0
	s_cmp_gt_u32 s24, 13
	s_waitcnt vmcnt(6)
	s_barrier
	v_mfma_f32_16x16x32_bf16 v[60:63], v[208:211], v[152:155], v[60:63]
	v_mfma_f32_16x16x32_bf16 v[56:59], v[216:219], v[152:155], v[56:59]
	v_mfma_f32_16x16x32_bf16 v[44:47], v[208:211], v[164:167], v[44:47]
	v_mfma_f32_16x16x32_bf16 v[40:43], v[216:219], v[164:167], v[40:43]
	v_mfma_f32_16x16x32_bf16 v[28:31], v[208:211], v[176:179], v[28:31]
	v_mfma_f32_16x16x32_bf16 v[24:27], v[216:219], v[176:179], v[24:27]
	v_mfma_f32_16x16x32_bf16 v[12:15], v[208:211], v[200:203], v[12:15]
	v_mfma_f32_16x16x32_bf16 v[8:11], v[216:219], v[200:203], v[8:11]
	v_mfma_f32_16x16x32_bf16 v[60:63], v[212:215], v[160:163], v[60:63]
	v_mfma_f32_16x16x32_bf16 v[56:59], v[220:223], v[160:163], v[56:59]
	v_mfma_f32_16x16x32_bf16 v[44:47], v[212:215], v[172:175], v[44:47]
	v_mfma_f32_16x16x32_bf16 v[40:43], v[220:223], v[172:175], v[40:43]
	v_mfma_f32_16x16x32_bf16 v[28:31], v[212:215], v[196:199], v[28:31]
	v_mfma_f32_16x16x32_bf16 v[24:27], v[220:223], v[196:199], v[24:27]
	v_mfma_f32_16x16x32_bf16 v[12:15], v[212:215], v[204:207], v[12:15]
	v_mfma_f32_16x16x32_bf16 v[8:11], v[220:223], v[204:207], v[8:11]
	s_cbranch_scc0 .Ldb_PLE1_cont
	v_readfirstlane_b32 s101, v186
	s_cmpk_gt_u32 s101, 0xff
	s_cbranch_scc1 .Ldb_PLE1_young
	s_barrier
	s_mov_b32 s101, 1
	s_branch .Ldb_PLE1_exit

; #define G_WAIT_V(n) asm volatile("s_waitcnt vmcnt(" #n ")" ::: "memory")
; #define G_BAR __builtin_amdgcn_s_barrier()
;     ...
;     G_WAIT_V(0);
;     if (wr == 0) G_BAR;
;     G_BAR;
.Ldbj_PLE1_pe:
	s_mov_b32 s101, 0
	s_waitcnt vmcnt(0)
	s_cmpk_gt_u32 s26, 0xff
	s_cbranch_scc1 .LBB0_1302
	s_barrier
